# barshift2
# baseline (speedup 1.0000x reference)
; #define STAGE(P, BASE, LD, br, kt) do { const char* _g = (const char*)((BASE) + (size_t)(br) * (LD) + (size_t)(kt) * 64); \
;     for (int _i = 0; _i < 2; ++_i) { int _b = tidx * 16 + _i * 8192; int _r, _c; stage_rc(_b, _r, _c); \
;       __builtin_amdgcn_global_load_lds((const unsigned*)(_g + (unsigned)((_r * (LD) + _c) * 2)), (unsigned*)((char*)(P) + _b), 16, 0, 0); } } while (0)
; #define LDA(dst, b, h) for (int m = 0; m < 4; ++m) for (int k = 0; k < 2; ++k) \
;     dst[m][k] = *reinterpret_cast<const bf16x8*>((char*)SA(b, h) + lds_byte(wr * 64 + m * 16 + fr, k * 32 + fq * 8))
; #define LDB(dst, b, h) for (int n = 0; n < 2; ++n) for (int k = 0; k < 2; ++k) \
;     dst[n][k] = *reinterpret_cast<const bf16x8*>((char*)SB(b, h) + lds_byte(wc * 32 + n * 16 + fr, k * 32 + fq * 8))
; #define MMA(ai, bj, At_, Bt_) do { __builtin_amdgcn_s_setprio(1); \
;     for (int k = 0; k < 2; ++k) for (int m = 0; m < 4; ++m) for (int n = 0; n < 2; ++n) \
;       acc[ai][bj][m][n] = __builtin_amdgcn_mfma_f32_16x16x32_bf16(At_[m][k], Bt_[n][k], acc[ai][bj][m][n], 0, 0, 0); \
;     __builtin_amdgcn_s_setprio(0); } while (0)
; #define WAIT_L(n) asm volatile("s_waitcnt lgkmcnt(" #n ")" ::: "memory")
; #define BAR __builtin_amdgcn_s_barrier()
; #define SCHED __builtin_amdgcn_sched_barrier(0)
; template <int EPI, int lda, int ldb, int N, int K>
; __device__ __forceinline__ void gemm_phase(const u16* __restrict__ A, const u16* __restrict__ Bt, const GemmEpi ep, int wv) {
;     ...
;       LDB(B0, 0, 0); SCHED; LDA(At, 0, 0); STAGE(SA(1, 1), Ab, lda, brow + HALF, t + 1);
;       WAIT_L(8); BAR; WAIT_L(0); MMA(0, 0, At, B0); BAR; SCHED;
;       LDB(B1, 0, 1); STAGE(SB(0, 0), Bt, ldb, bcol, t + 2);
;       BAR; WAIT_L(0); MMA(0, 1, At, B1); BAR;
;       LDA(At, 0, 1); STAGE(SA(0, 0), Ab, lda, brow, t + 2);
;       BAR; WAIT_L(0); MMA(1, 0, At, B0); BAR; SCHED;
;       STAGE(SB(0, 1), Bt, ldb, bcol + HALF, t + 2);
.LBB0_53:
	ds_read_b128 v[172:175], v161
	ds_read_b128 v[176:179], v161 offset:1024
	ds_read_b128 v[180:183], v161 offset:2048
	ds_read_b128 v[184:187], v161 offset:3072
	v_add_u32_e32 v169, 0xc000, v148
	v_lshl_add_u64 v[236:237], v[136:137], 0, s[42:43]
	v_readfirstlane_b32 s45, v169
	v_add_u32_e32 v170, 0xe000, v148
	v_lshl_add_u64 v[162:163], v[236:237], 0, s[14:15]
	s_mov_b32 m0, s45
	v_lshl_add_u64 v[238:239], v[134:135], 0, s[42:43]
	v_readfirstlane_b32 s45, v170
	ds_read_b128 v[164:167], v152
	ds_read_b128 v[188:191], v152 offset:1024
	ds_read_b128 v[192:195], v151
	ds_read_b128 v[196:199], v151 offset:1024
	ds_read_b128 v[200:203], v150
	ds_read_b128 v[204:207], v150 offset:1024
	ds_read_b128 v[208:211], v149
	ds_read_b128 v[212:215], v149 offset:1024
	global_load_lds_dwordx4 v[162:163], off
	v_lshl_add_u64 v[162:163], v[238:239], 0, s[14:15]
	s_mov_b32 m0, s45
	s_nop 0
	global_load_lds_dwordx4 v[162:163], off
	s_waitcnt lgkmcnt(8)
	s_barrier
	s_waitcnt lgkmcnt(0)
	v_mfma_f32_16x16x32_bf16 v[124:127], v[172:175], v[164:167], v[124:127]
	v_mfma_f32_16x16x32_bf16 v[120:123], v[180:183], v[164:167], v[120:123]
	v_mfma_f32_16x16x32_bf16 v[116:119], v[172:175], v[192:195], v[116:119]
	v_mfma_f32_16x16x32_bf16 v[112:115], v[180:183], v[192:195], v[112:115]
	v_mfma_f32_16x16x32_bf16 v[108:111], v[172:175], v[200:203], v[108:111]
	v_mfma_f32_16x16x32_bf16 v[104:107], v[180:183], v[200:203], v[104:107]
	v_mfma_f32_16x16x32_bf16 v[100:103], v[172:175], v[208:211], v[100:103]
	v_mfma_f32_16x16x32_bf16 v[96:99], v[180:183], v[208:211], v[96:99]
	v_mfma_f32_16x16x32_bf16 v[124:127], v[176:179], v[188:191], v[124:127]
	v_mfma_f32_16x16x32_bf16 v[120:123], v[184:187], v[188:191], v[120:123]
	v_mfma_f32_16x16x32_bf16 v[116:119], v[176:179], v[196:199], v[116:119]
	v_mfma_f32_16x16x32_bf16 v[112:115], v[184:187], v[196:199], v[112:115]
	v_mfma_f32_16x16x32_bf16 v[108:111], v[176:179], v[204:207], v[108:111]
	v_mfma_f32_16x16x32_bf16 v[104:107], v[184:187], v[204:207], v[104:107]
	s_barrier
	v_mfma_f32_16x16x32_bf16 v[100:103], v[176:179], v[212:215], v[100:103]
	v_mfma_f32_16x16x32_bf16 v[96:99], v[184:187], v[212:215], v[96:99]
	v_add_u32_e32 v162, s54, v153
	v_lshl_add_u64 v[240:241], v[140:141], 0, s[42:43]
	v_readfirstlane_b32 s45, v162
	v_add_u32_e32 v163, 0x2000, v162
	v_lshl_add_u64 v[232:233], v[240:241], 0, s[16:17]
	s_mov_b32 m0, s45
	v_lshl_add_u64 v[242:243], v[138:139], 0, s[42:43]
	v_readfirstlane_b32 s45, v163
	ds_read_b128 v[216:219], v160
	ds_read_b128 v[220:223], v160 offset:1024
	ds_read_b128 v[224:227], v160 offset:2048
	ds_read_b128 v[228:231], v160 offset:3072
	global_load_lds_dwordx4 v[232:233], off
	v_lshl_add_u64 v[232:233], v[242:243], 0, s[16:17]
	s_mov_b32 m0, s45
	s_nop 0
	global_load_lds_dwordx4 v[232:233], off
	s_barrier
	s_waitcnt lgkmcnt(0)
	v_mfma_f32_16x16x32_bf16 v[92:95], v[216:219], v[164:167], v[92:95]
	v_mfma_f32_16x16x32_bf16 v[88:91], v[224:227], v[164:167], v[88:91]
	v_mfma_f32_16x16x32_bf16 v[84:87], v[216:219], v[192:195], v[84:87]
	v_mfma_f32_16x16x32_bf16 v[80:83], v[224:227], v[192:195], v[80:83]
	v_mfma_f32_16x16x32_bf16 v[76:79], v[216:219], v[200:203], v[76:79]
	v_mfma_f32_16x16x32_bf16 v[72:75], v[224:227], v[200:203], v[72:75]
	v_mfma_f32_16x16x32_bf16 v[68:71], v[216:219], v[208:211], v[68:71]
	v_mfma_f32_16x16x32_bf16 v[64:67], v[224:227], v[208:211], v[64:67]
	v_mfma_f32_16x16x32_bf16 v[92:95], v[220:223], v[188:191], v[92:95]
	v_mfma_f32_16x16x32_bf16 v[88:91], v[228:231], v[188:191], v[88:91]
	v_mfma_f32_16x16x32_bf16 v[84:87], v[220:223], v[196:199], v[84:87]
	v_mfma_f32_16x16x32_bf16 v[80:83], v[228:231], v[196:199], v[80:83]
	v_mfma_f32_16x16x32_bf16 v[76:79], v[220:223], v[204:207], v[76:79]
	v_mfma_f32_16x16x32_bf16 v[72:75], v[228:231], v[204:207], v[72:75]
	s_barrier
	v_mfma_f32_16x16x32_bf16 v[68:71], v[220:223], v[212:215], v[68:71]
	v_mfma_f32_16x16x32_bf16 v[64:67], v[228:231], v[212:215], v[64:67]
	v_readfirstlane_b32 s45, v148
	v_lshl_add_u64 v[164:165], v[236:237], 0, s[18:19]
	s_mov_b32 m0, s45
	ds_read_b128 v[188:191], v152 offset:16384
	ds_read_b128 v[192:195], v152 offset:17408
	ds_read_b128 v[196:199], v151 offset:16384
	ds_read_b128 v[200:203], v151 offset:17408
	ds_read_b128 v[204:207], v150 offset:16384
	ds_read_b128 v[208:211], v150 offset:17408
	ds_read_b128 v[212:215], v149 offset:16384
	ds_read_b128 v[232:235], v149 offset:17408
	global_load_lds_dwordx4 v[164:165], off
	v_add_u32_e32 v164, 0x2000, v148
	v_lshl_add_u64 v[166:167], v[238:239], 0, s[18:19]
	v_readfirstlane_b32 s45, v164
	s_mov_b32 m0, s45
	s_nop 0
	global_load_lds_dwordx4 v[166:167], off
	s_barrier
	s_waitcnt lgkmcnt(0)
	v_mfma_f32_16x16x32_bf16 v[60:63], v[172:175], v[188:191], v[60:63]
	v_mfma_f32_16x16x32_bf16 v[56:59], v[180:183], v[188:191], v[56:59]
	v_mfma_f32_16x16x32_bf16 v[52:55], v[172:175], v[196:199], v[52:55]
	v_mfma_f32_16x16x32_bf16 v[48:51], v[180:183], v[196:199], v[48:51]
	v_mfma_f32_16x16x32_bf16 v[44:47], v[172:175], v[204:207], v[44:47]
	v_mfma_f32_16x16x32_bf16 v[40:43], v[180:183], v[204:207], v[40:43]
	v_mfma_f32_16x16x32_bf16 v[36:39], v[172:175], v[212:215], v[36:39]
	v_mfma_f32_16x16x32_bf16 v[32:35], v[180:183], v[212:215], v[32:35]
	v_mfma_f32_16x16x32_bf16 v[60:63], v[176:179], v[192:195], v[60:63]
	v_mfma_f32_16x16x32_bf16 v[56:59], v[184:187], v[192:195], v[56:59]
	v_mfma_f32_16x16x32_bf16 v[52:55], v[176:179], v[200:203], v[52:55]
	v_mfma_f32_16x16x32_bf16 v[48:51], v[184:187], v[200:203], v[48:51]
	v_mfma_f32_16x16x32_bf16 v[44:47], v[176:179], v[208:211], v[44:47]
	v_mfma_f32_16x16x32_bf16 v[40:43], v[184:187], v[208:211], v[40:43]
	s_barrier
; #define STAGE(P, BASE, LD, br, kt) do { const char* _g = (const char*)((BASE) + (size_t)(br) * (LD) + (size_t)(kt) * 64); \
;     for (int _i = 0; _i < 2; ++_i) { int _b = tidx * 16 + _i * 8192; int _r, _c; stage_rc(_b, _r, _c); \
;       __builtin_amdgcn_global_load_lds((const unsigned*)(_g + (unsigned)((_r * (LD) + _c) * 2)), (unsigned*)((char*)(P) + _b), 16, 0, 0); } } while (0)
; #define LDA(dst, b, h) for (int m = 0; m < 4; ++m) for (int k = 0; k < 2; ++k) \
;     dst[m][k] = *reinterpret_cast<const bf16x8*>((char*)SA(b, h) + lds_byte(wr * 64 + m * 16 + fr, k * 32 + fq * 8))
; #define LDB(dst, b, h) for (int n = 0; n < 2; ++n) for (int k = 0; k < 2; ++k) \
;     dst[n][k] = *reinterpret_cast<const bf16x8*>((char*)SB(b, h) + lds_byte(wc * 32 + n * 16 + fr, k * 32 + fq * 8))
; #define MMA(ai, bj, At_, Bt_) do { __builtin_amdgcn_s_setprio(1); \
;     for (int k = 0; k < 2; ++k) for (int m = 0; m < 4; ++m) for (int n = 0; n < 2; ++n) \
;       acc[ai][bj][m][n] = __builtin_amdgcn_mfma_f32_16x16x32_bf16(At_[m][k], Bt_[n][k], acc[ai][bj][m][n], 0, 0, 0); \
;     __builtin_amdgcn_s_setprio(0); } while (0)
; #define WAIT_V(n) asm volatile("s_waitcnt vmcnt(" #n ")" ::: "memory")
; #define WAIT_L(n) asm volatile("s_waitcnt lgkmcnt(" #n ")" ::: "memory")
; #define BAR __builtin_amdgcn_s_barrier()
; #define SCHED __builtin_amdgcn_sched_barrier(0)
; template <int EPI, int lda, int ldb, int N, int K>
; __device__ __forceinline__ void gemm_phase(const u16* __restrict__ A, const u16* __restrict__ Bt, const GemmEpi ep, int wv) {
;     ...
;       STAGE(SB(0, 1), Bt, ldb, bcol + HALF, t + 2);
;       WAIT_V(6); BAR; MMA(1, 1, At, B1); BAR;
;       LDB(B0, 1, 0); SCHED; LDA(At, 1, 0); STAGE(SA(0, 1), Ab, lda, brow + HALF, t + 2);
;       WAIT_L(8); BAR; WAIT_L(0); MMA(0, 0, At, B0); BAR; SCHED;
;       LDB(B1, 1, 1); STAGE(SB(1, 0), Bt, ldb, bcol, t + 3);
;       BAR; WAIT_L(0); MMA(0, 1, At, B1); BAR;
;       LDA(At, 1, 1); STAGE(SA(1, 0), Ab, lda, brow, t + 3);
;       BAR; WAIT_L(0); MMA(1, 0, At, B0); BAR; SCHED;
	v_mfma_f32_16x16x32_bf16 v[36:39], v[176:179], v[232:235], v[36:39]
	v_mfma_f32_16x16x32_bf16 v[32:35], v[184:187], v[232:235], v[32:35]
	v_add_u32_e32 v165, s55, v153
	v_lshl_add_u64 v[166:167], v[240:241], 0, s[20:21]
	v_readfirstlane_b32 s45, v165
	s_mov_b32 m0, s45
	v_lshl_add_u64 v[172:173], v[242:243], 0, s[20:21]
	global_load_lds_dwordx4 v[166:167], off
	v_add_u32_e32 v166, 0x2000, v165
	s_nop 0
	v_readfirstlane_b32 s45, v166
	s_mov_b32 m0, s45
	s_nop 0
	global_load_lds_dwordx4 v[172:173], off
	s_waitcnt vmcnt(6)
	s_barrier
	v_mfma_f32_16x16x32_bf16 v[28:31], v[216:219], v[188:191], v[28:31]
	v_mfma_f32_16x16x32_bf16 v[24:27], v[224:227], v[188:191], v[24:27]
	v_mfma_f32_16x16x32_bf16 v[20:23], v[216:219], v[196:199], v[20:23]
	v_mfma_f32_16x16x32_bf16 v[16:19], v[224:227], v[196:199], v[16:19]
	v_mfma_f32_16x16x32_bf16 v[12:15], v[216:219], v[204:207], v[12:15]
	v_mfma_f32_16x16x32_bf16 v[8:11], v[224:227], v[204:207], v[8:11]
	v_mfma_f32_16x16x32_bf16 v[4:7], v[216:219], v[212:215], v[4:7]
	v_mfma_f32_16x16x32_bf16 v[0:3], v[224:227], v[212:215], v[0:3]
	v_mfma_f32_16x16x32_bf16 v[28:31], v[220:223], v[192:195], v[28:31]
	v_mfma_f32_16x16x32_bf16 v[24:27], v[228:231], v[192:195], v[24:27]
	v_mfma_f32_16x16x32_bf16 v[20:23], v[220:223], v[200:203], v[20:23]
	v_mfma_f32_16x16x32_bf16 v[16:19], v[228:231], v[200:203], v[16:19]
	v_mfma_f32_16x16x32_bf16 v[12:15], v[220:223], v[208:211], v[12:15]
	v_mfma_f32_16x16x32_bf16 v[8:11], v[228:231], v[208:211], v[8:11]
	s_barrier
	v_mfma_f32_16x16x32_bf16 v[4:7], v[220:223], v[232:235], v[4:7]
	v_mfma_f32_16x16x32_bf16 v[0:3], v[228:231], v[232:235], v[0:3]
	ds_read_b128 v[172:175], v156
	ds_read_b128 v[176:179], v156 offset:1024
	ds_read_b128 v[180:183], v156 offset:2048
	ds_read_b128 v[184:187], v156 offset:3072
	v_add_u32_e32 v167, 0x4000, v148
	v_add_u32_e32 v168, 0x6000, v148
	v_readfirstlane_b32 s45, v167
	v_lshl_add_u64 v[220:221], v[236:237], 0, s[22:23]
	s_mov_b32 m0, s45
	v_readfirstlane_b32 s45, v168
	ds_read_b128 v[188:191], v152 offset:32768
	ds_read_b128 v[192:195], v152 offset:33792
	ds_read_b128 v[196:199], v151 offset:32768
	ds_read_b128 v[200:203], v151 offset:33792
	ds_read_b128 v[204:207], v150 offset:32768
	ds_read_b128 v[208:211], v150 offset:33792
	ds_read_b128 v[212:215], v149 offset:32768
	ds_read_b128 v[216:219], v149 offset:33792
	global_load_lds_dwordx4 v[220:221], off
	v_lshl_add_u64 v[220:221], v[238:239], 0, s[22:23]
	s_mov_b32 m0, s45
	s_nop 0
	global_load_lds_dwordx4 v[220:221], off
	s_waitcnt lgkmcnt(8)
	s_barrier
	s_waitcnt lgkmcnt(0)
	v_mfma_f32_16x16x32_bf16 v[124:127], v[172:175], v[188:191], v[124:127]
	v_mfma_f32_16x16x32_bf16 v[120:123], v[180:183], v[188:191], v[120:123]
	v_mfma_f32_16x16x32_bf16 v[116:119], v[172:175], v[196:199], v[116:119]
	v_mfma_f32_16x16x32_bf16 v[112:115], v[180:183], v[196:199], v[112:115]
	v_mfma_f32_16x16x32_bf16 v[108:111], v[172:175], v[204:207], v[108:111]
	v_mfma_f32_16x16x32_bf16 v[104:107], v[180:183], v[204:207], v[104:107]
	v_mfma_f32_16x16x32_bf16 v[100:103], v[172:175], v[212:215], v[100:103]
	v_mfma_f32_16x16x32_bf16 v[96:99], v[180:183], v[212:215], v[96:99]
	v_mfma_f32_16x16x32_bf16 v[124:127], v[176:179], v[192:195], v[124:127]
	v_mfma_f32_16x16x32_bf16 v[120:123], v[184:187], v[192:195], v[120:123]
	v_mfma_f32_16x16x32_bf16 v[116:119], v[176:179], v[200:203], v[116:119]
	v_mfma_f32_16x16x32_bf16 v[112:115], v[184:187], v[200:203], v[112:115]
	v_mfma_f32_16x16x32_bf16 v[108:111], v[176:179], v[208:211], v[108:111]
	v_mfma_f32_16x16x32_bf16 v[104:107], v[184:187], v[208:211], v[104:107]
	s_barrier
	v_mfma_f32_16x16x32_bf16 v[100:103], v[176:179], v[216:219], v[100:103]
	v_mfma_f32_16x16x32_bf16 v[96:99], v[184:187], v[216:219], v[96:99]
	v_readfirstlane_b32 s45, v155
	v_add_u32_e32 v171, 0x2000, v155
	v_lshl_add_u64 v[244:245], v[240:241], 0, s[24:25]
	s_mov_b32 m0, s45
	v_readfirstlane_b32 s45, v171
	ds_read_b128 v[220:223], v154
	ds_read_b128 v[224:227], v154 offset:1024
	ds_read_b128 v[228:231], v154 offset:2048
	ds_read_b128 v[232:235], v154 offset:3072
	global_load_lds_dwordx4 v[244:245], off
	v_lshl_add_u64 v[244:245], v[242:243], 0, s[24:25]
	s_mov_b32 m0, s45
	s_nop 0
	global_load_lds_dwordx4 v[244:245], off
	s_barrier
	s_waitcnt lgkmcnt(0)
	v_mfma_f32_16x16x32_bf16 v[92:95], v[220:223], v[188:191], v[92:95]
	v_mfma_f32_16x16x32_bf16 v[88:91], v[228:231], v[188:191], v[88:91]
	v_mfma_f32_16x16x32_bf16 v[84:87], v[220:223], v[196:199], v[84:87]
	v_mfma_f32_16x16x32_bf16 v[80:83], v[228:231], v[196:199], v[80:83]
	v_mfma_f32_16x16x32_bf16 v[76:79], v[220:223], v[204:207], v[76:79]
	v_mfma_f32_16x16x32_bf16 v[72:75], v[228:231], v[204:207], v[72:75]
	v_mfma_f32_16x16x32_bf16 v[68:71], v[220:223], v[212:215], v[68:71]
	v_mfma_f32_16x16x32_bf16 v[64:67], v[228:231], v[212:215], v[64:67]
	v_mfma_f32_16x16x32_bf16 v[92:95], v[224:227], v[192:195], v[92:95]
	v_mfma_f32_16x16x32_bf16 v[88:91], v[232:235], v[192:195], v[88:91]
	v_mfma_f32_16x16x32_bf16 v[84:87], v[224:227], v[200:203], v[84:87]
	v_mfma_f32_16x16x32_bf16 v[80:83], v[232:235], v[200:203], v[80:83]
	v_mfma_f32_16x16x32_bf16 v[76:79], v[224:227], v[208:211], v[76:79]
	v_mfma_f32_16x16x32_bf16 v[72:75], v[232:235], v[208:211], v[72:75]
	s_barrier
	v_mfma_f32_16x16x32_bf16 v[68:71], v[224:227], v[216:219], v[68:71]
	v_mfma_f32_16x16x32_bf16 v[64:67], v[232:235], v[216:219], v[64:67]
	v_readfirstlane_b32 s45, v157
	v_lshl_add_u64 v[236:237], v[236:237], 0, s[26:27]
	s_mov_b32 m0, s45
	v_readfirstlane_b32 s45, v158
	ds_read_b128 v[188:191], v152 offset:49152
	ds_read_b128 v[192:195], v152 offset:50176
	ds_read_b128 v[196:199], v151 offset:49152
	ds_read_b128 v[200:203], v151 offset:50176
	ds_read_b128 v[204:207], v150 offset:49152
	ds_read_b128 v[208:211], v150 offset:50176
	ds_read_b128 v[212:215], v149 offset:49152
	ds_read_b128 v[216:219], v149 offset:50176
	global_load_lds_dwordx4 v[236:237], off
	v_lshl_add_u64 v[236:237], v[238:239], 0, s[26:27]
	s_mov_b32 m0, s45
	s_nop 0
	global_load_lds_dwordx4 v[236:237], off
	s_barrier
; #define STAGE(P, BASE, LD, br, kt) do { const char* _g = (const char*)((BASE) + (size_t)(br) * (LD) + (size_t)(kt) * 64); \
;     for (int _i = 0; _i < 2; ++_i) { int _b = tidx * 16 + _i * 8192; int _r, _c; stage_rc(_b, _r, _c); \
;       __builtin_amdgcn_global_load_lds((const unsigned*)(_g + (unsigned)((_r * (LD) + _c) * 2)), (unsigned*)((char*)(P) + _b), 16, 0, 0); } } while (0)
; #define LDA(dst, b, h) for (int m = 0; m < 4; ++m) for (int k = 0; k < 2; ++k) \
;     dst[m][k] = *reinterpret_cast<const bf16x8*>((char*)SA(b, h) + lds_byte(wr * 64 + m * 16 + fr, k * 32 + fq * 8))
; #define LDB(dst, b, h) for (int n = 0; n < 2; ++n) for (int k = 0; k < 2; ++k) \
;     dst[n][k] = *reinterpret_cast<const bf16x8*>((char*)SB(b, h) + lds_byte(wc * 32 + n * 16 + fr, k * 32 + fq * 8))
; #define MMA(ai, bj, At_, Bt_) do { __builtin_amdgcn_s_setprio(1); \
;     for (int k = 0; k < 2; ++k) for (int m = 0; m < 4; ++m) for (int n = 0; n < 2; ++n) \
;       acc[ai][bj][m][n] = __builtin_amdgcn_mfma_f32_16x16x32_bf16(At_[m][k], Bt_[n][k], acc[ai][bj][m][n], 0, 0, 0); \
;     __builtin_amdgcn_s_setprio(0); } while (0)
; #define WAIT_V(n) asm volatile("s_waitcnt vmcnt(" #n ")" ::: "memory")
; #define WAIT_L(n) asm volatile("s_waitcnt lgkmcnt(" #n ")" ::: "memory")
; #define BAR __builtin_amdgcn_s_barrier()
; #define SCHED __builtin_amdgcn_sched_barrier(0)
; template <int EPI, int lda, int ldb, int N, int K>
; __device__ __forceinline__ void gemm_phase(const u16* __restrict__ A, const u16* __restrict__ Bt, const GemmEpi ep, int wv) {
;     ...
;       BAR; WAIT_L(0); MMA(1, 0, At, B0); BAR; SCHED;
;       STAGE(SB(1, 1), Bt, ldb, bcol + HALF, t + 3);
;       WAIT_V(6); BAR; MMA(1, 1, At, B1); BAR;
;     }
;     { LDB(B0, 0, 0); LDA(At, 0, 0); STAGE(SA(1, 1), Ab, lda, brow + HALF, nt - 1);
;       BAR; WAIT_L(0); MMA(0, 0, At, B0); BAR;
;       LDB(B1, 0, 1); BAR; WAIT_L(0); MMA(0, 1, At, B1); BAR;
;       LDA(At, 0, 1); WAIT_V(4); BAR; WAIT_L(0); MMA(1, 0, At, B0); MMA(1, 1, At, B1); BAR; }
	s_waitcnt lgkmcnt(0)
	v_mfma_f32_16x16x32_bf16 v[60:63], v[172:175], v[188:191], v[60:63]
	v_mfma_f32_16x16x32_bf16 v[56:59], v[180:183], v[188:191], v[56:59]
	v_mfma_f32_16x16x32_bf16 v[52:55], v[172:175], v[196:199], v[52:55]
	v_mfma_f32_16x16x32_bf16 v[48:51], v[180:183], v[196:199], v[48:51]
	v_mfma_f32_16x16x32_bf16 v[44:47], v[172:175], v[204:207], v[44:47]
	v_mfma_f32_16x16x32_bf16 v[40:43], v[180:183], v[204:207], v[40:43]
	v_mfma_f32_16x16x32_bf16 v[36:39], v[172:175], v[212:215], v[36:39]
	v_mfma_f32_16x16x32_bf16 v[32:35], v[180:183], v[212:215], v[32:35]
	v_mfma_f32_16x16x32_bf16 v[60:63], v[176:179], v[192:195], v[60:63]
	v_mfma_f32_16x16x32_bf16 v[56:59], v[184:187], v[192:195], v[56:59]
	v_mfma_f32_16x16x32_bf16 v[52:55], v[176:179], v[200:203], v[52:55]
	v_mfma_f32_16x16x32_bf16 v[48:51], v[184:187], v[200:203], v[48:51]
	v_mfma_f32_16x16x32_bf16 v[44:47], v[176:179], v[208:211], v[44:47]
	v_mfma_f32_16x16x32_bf16 v[40:43], v[184:187], v[208:211], v[40:43]
	s_barrier
	v_mfma_f32_16x16x32_bf16 v[36:39], v[176:179], v[216:219], v[36:39]
	v_mfma_f32_16x16x32_bf16 v[32:35], v[184:187], v[216:219], v[32:35]
	v_readfirstlane_b32 s45, v159
	v_add_u32_e32 v171, 0x2000, v159
	v_lshl_add_u64 v[172:173], v[240:241], 0, s[34:35]
	s_mov_b32 m0, s45
	v_readfirstlane_b32 s45, v171
	global_load_lds_dwordx4 v[172:173], off
	v_lshl_add_u64 v[172:173], v[242:243], 0, s[34:35]
	s_mov_b32 m0, s45
	s_nop 0
	global_load_lds_dwordx4 v[172:173], off
	s_waitcnt vmcnt(6)
	s_barrier
	v_mfma_f32_16x16x32_bf16 v[28:31], v[220:223], v[188:191], v[28:31]
	v_mfma_f32_16x16x32_bf16 v[24:27], v[228:231], v[188:191], v[24:27]
	v_mfma_f32_16x16x32_bf16 v[20:23], v[220:223], v[196:199], v[20:23]
	v_mfma_f32_16x16x32_bf16 v[16:19], v[228:231], v[196:199], v[16:19]
	v_mfma_f32_16x16x32_bf16 v[12:15], v[220:223], v[204:207], v[12:15]
	v_mfma_f32_16x16x32_bf16 v[8:11], v[228:231], v[204:207], v[8:11]
	v_mfma_f32_16x16x32_bf16 v[4:7], v[220:223], v[212:215], v[4:7]
	v_mfma_f32_16x16x32_bf16 v[0:3], v[228:231], v[212:215], v[0:3]
	v_mfma_f32_16x16x32_bf16 v[28:31], v[224:227], v[192:195], v[28:31]
	v_mfma_f32_16x16x32_bf16 v[24:27], v[232:235], v[192:195], v[24:27]
	v_mfma_f32_16x16x32_bf16 v[20:23], v[224:227], v[200:203], v[20:23]
	v_mfma_f32_16x16x32_bf16 v[16:19], v[232:235], v[200:203], v[16:19]
	v_mfma_f32_16x16x32_bf16 v[12:15], v[224:227], v[208:211], v[12:15]
	v_mfma_f32_16x16x32_bf16 v[8:11], v[232:235], v[208:211], v[8:11]
	s_barrier
	v_mfma_f32_16x16x32_bf16 v[4:7], v[224:227], v[216:219], v[4:7]
	v_mfma_f32_16x16x32_bf16 v[0:3], v[232:235], v[216:219], v[0:3]
	s_add_i32 s44, s44, 2
	s_add_u32 s42, s42, 0x100
	s_addc_u32 s43, s43, 0
	s_cmp_gt_u32 s44, 27
	s_cbranch_scc0 .LBB0_53
	s_add_i32 s42, s38, 0x80
	s_mul_hi_i32 s43, s42, 0x1080
	s_mulk_i32 s42, 0x1080
	s_add_u32 s42, s51, s42
	s_addc_u32 s43, s52, s43
	v_lshl_add_u64 v[158:159], s[42:43], 0, v[128:129]
	v_readfirstlane_b32 s44, v169
	v_lshl_add_u64 v[158:159], v[158:159], 0, s[36:37]
	s_mov_b32 m0, s44
	ds_read_b128 v[134:137], v161
	ds_read_b128 v[138:141], v161 offset:1024
	ds_read_b128 v[172:175], v161 offset:2048
	ds_read_b128 v[176:179], v161 offset:3072
	ds_read_b128 v[180:183], v152
	ds_read_b128 v[184:187], v152 offset:1024
	ds_read_b128 v[188:191], v151
	ds_read_b128 v[192:195], v151 offset:1024
	ds_read_b128 v[196:199], v150
	ds_read_b128 v[200:203], v150 offset:1024
	ds_read_b128 v[204:207], v149
	ds_read_b128 v[208:211], v149 offset:1024
	global_load_lds_dwordx4 v[158:159], off
	v_lshl_add_u64 v[158:159], s[42:43], 0, v[132:133]
	v_readfirstlane_b32 s42, v170
	v_lshl_add_u64 v[158:159], v[158:159], 0, s[36:37]
	s_mov_b32 m0, s42
	s_nop 0
	global_load_lds_dwordx4 v[158:159], off
	s_barrier
	s_waitcnt lgkmcnt(0)
	v_mfma_f32_16x16x32_bf16 v[124:127], v[134:137], v[180:183], v[124:127]
	v_mfma_f32_16x16x32_bf16 v[120:123], v[172:175], v[180:183], v[120:123]
	v_mfma_f32_16x16x32_bf16 v[116:119], v[134:137], v[188:191], v[116:119]
	v_mfma_f32_16x16x32_bf16 v[112:115], v[172:175], v[188:191], v[112:115]
	v_mfma_f32_16x16x32_bf16 v[108:111], v[134:137], v[196:199], v[108:111]
	v_mfma_f32_16x16x32_bf16 v[104:107], v[172:175], v[196:199], v[104:107]
	v_mfma_f32_16x16x32_bf16 v[100:103], v[134:137], v[204:207], v[100:103]
	v_mfma_f32_16x16x32_bf16 v[96:99], v[172:175], v[204:207], v[96:99]
	v_mfma_f32_16x16x32_bf16 v[124:127], v[138:141], v[184:187], v[124:127]
	v_mfma_f32_16x16x32_bf16 v[120:123], v[176:179], v[184:187], v[120:123]
	v_mfma_f32_16x16x32_bf16 v[116:119], v[138:141], v[192:195], v[116:119]
	v_mfma_f32_16x16x32_bf16 v[112:115], v[176:179], v[192:195], v[112:115]
	v_mfma_f32_16x16x32_bf16 v[108:111], v[138:141], v[200:203], v[108:111]
	v_mfma_f32_16x16x32_bf16 v[104:107], v[176:179], v[200:203], v[104:107]
	s_barrier
	v_mfma_f32_16x16x32_bf16 v[100:103], v[138:141], v[208:211], v[100:103]
	v_mfma_f32_16x16x32_bf16 v[96:99], v[176:179], v[208:211], v[96:99]
	ds_read_b128 v[212:215], v160
	ds_read_b128 v[216:219], v160 offset:1024
	ds_read_b128 v[220:223], v160 offset:2048
	ds_read_b128 v[158:161], v160 offset:3072
	s_barrier
	s_waitcnt lgkmcnt(0)
	v_mfma_f32_16x16x32_bf16 v[92:95], v[212:215], v[180:183], v[92:95]
	v_mfma_f32_16x16x32_bf16 v[88:91], v[220:223], v[180:183], v[88:91]
	v_mfma_f32_16x16x32_bf16 v[76:79], v[212:215], v[196:199], v[76:79]
	v_mfma_f32_16x16x32_bf16 v[72:75], v[220:223], v[196:199], v[72:75]
	v_mfma_f32_16x16x32_bf16 v[84:87], v[212:215], v[188:191], v[84:87]
	v_mfma_f32_16x16x32_bf16 v[80:83], v[220:223], v[188:191], v[80:83]
	v_mfma_f32_16x16x32_bf16 v[68:71], v[212:215], v[204:207], v[68:71]
	v_mfma_f32_16x16x32_bf16 v[64:67], v[220:223], v[204:207], v[64:67]
	v_mfma_f32_16x16x32_bf16 v[92:95], v[216:219], v[184:187], v[92:95]
	v_mfma_f32_16x16x32_bf16 v[88:91], v[158:161], v[184:187], v[88:91]
	v_mfma_f32_16x16x32_bf16 v[76:79], v[216:219], v[200:203], v[76:79]
	v_mfma_f32_16x16x32_bf16 v[72:75], v[158:161], v[200:203], v[72:75]
	v_mfma_f32_16x16x32_bf16 v[180:183], v[216:219], v[192:195], v[84:87]
	v_mfma_f32_16x16x32_bf16 v[184:187], v[158:161], v[192:195], v[80:83]
	s_barrier
; #define LDA(dst, b, h) for (int m = 0; m < 4; ++m) for (int k = 0; k < 2; ++k) \
;     dst[m][k] = *reinterpret_cast<const bf16x8*>((char*)SA(b, h) + lds_byte(wr * 64 + m * 16 + fr, k * 32 + fq * 8))
; #define LDB(dst, b, h) for (int n = 0; n < 2; ++n) for (int k = 0; k < 2; ++k) \
;     dst[n][k] = *reinterpret_cast<const bf16x8*>((char*)SB(b, h) + lds_byte(wc * 32 + n * 16 + fr, k * 32 + fq * 8))
; #define MMA(ai, bj, At_, Bt_) do { __builtin_amdgcn_s_setprio(1); \
;     for (int k = 0; k < 2; ++k) for (int m = 0; m < 4; ++m) for (int n = 0; n < 2; ++n) \
;       acc[ai][bj][m][n] = __builtin_amdgcn_mfma_f32_16x16x32_bf16(At_[m][k], Bt_[n][k], acc[ai][bj][m][n], 0, 0, 0); \
;     __builtin_amdgcn_s_setprio(0); } while (0)
; #define WAIT_V(n) asm volatile("s_waitcnt vmcnt(" #n ")" ::: "memory")
; #define WAIT_L(n) asm volatile("s_waitcnt lgkmcnt(" #n ")" ::: "memory")
; #define BAR __builtin_amdgcn_s_barrier()
; template <int EPI, int lda, int ldb, int N, int K>
; __device__ __forceinline__ void gemm_phase(const u16* __restrict__ A, const u16* __restrict__ Bt, const GemmEpi ep, int wv) {
;     ...
;       LDB(B1, 0, 1); BAR; WAIT_L(0); MMA(0, 1, At, B1); BAR;
;       LDA(At, 0, 1); WAIT_V(4); BAR; WAIT_L(0); MMA(1, 0, At, B0); MMA(1, 1, At, B1); BAR; }
;     { LDB(B0, 1, 0); LDA(At, 1, 0); WAIT_V(2); BAR; WAIT_L(0); MMA(0, 0, At, B0); BAR;
	v_mfma_f32_16x16x32_bf16 v[188:191], v[216:219], v[208:211], v[68:71]
	v_mfma_f32_16x16x32_bf16 v[192:195], v[158:161], v[208:211], v[64:67]
	s_nop 0
	ds_read_b128 v[64:67], v152 offset:16384
	ds_read_b128 v[68:71], v152 offset:17408
	ds_read_b128 v[80:83], v151 offset:16384
	ds_read_b128 v[84:87], v151 offset:17408
	ds_read_b128 v[196:199], v150 offset:16384
	ds_read_b128 v[200:203], v150 offset:17408
	ds_read_b128 v[204:207], v149 offset:16384
	ds_read_b128 v[208:211], v149 offset:17408
	s_waitcnt vmcnt(4)
	s_barrier
	s_waitcnt lgkmcnt(0)
	v_mfma_f32_16x16x32_bf16 v[60:63], v[134:137], v[64:67], v[60:63]
	v_mfma_f32_16x16x32_bf16 v[56:59], v[172:175], v[64:67], v[56:59]
	v_mfma_f32_16x16x32_bf16 v[52:55], v[134:137], v[80:83], v[52:55]
	v_mfma_f32_16x16x32_bf16 v[48:51], v[172:175], v[80:83], v[48:51]
	v_mfma_f32_16x16x32_bf16 v[44:47], v[134:137], v[196:199], v[44:47]
	v_mfma_f32_16x16x32_bf16 v[40:43], v[172:175], v[196:199], v[40:43]
	v_mfma_f32_16x16x32_bf16 v[36:39], v[134:137], v[204:207], v[36:39]
	v_mfma_f32_16x16x32_bf16 v[32:35], v[172:175], v[204:207], v[32:35]
	v_mfma_f32_16x16x32_bf16 v[60:63], v[138:141], v[68:71], v[60:63]
	v_mfma_f32_16x16x32_bf16 v[56:59], v[176:179], v[68:71], v[56:59]
	v_mfma_f32_16x16x32_bf16 v[52:55], v[138:141], v[84:87], v[52:55]
	v_mfma_f32_16x16x32_bf16 v[48:51], v[176:179], v[84:87], v[48:51]
	v_mfma_f32_16x16x32_bf16 v[44:47], v[138:141], v[200:203], v[44:47]
	v_mfma_f32_16x16x32_bf16 v[40:43], v[176:179], v[200:203], v[40:43]
	v_mfma_f32_16x16x32_bf16 v[36:39], v[138:141], v[208:211], v[36:39]
	v_mfma_f32_16x16x32_bf16 v[32:35], v[176:179], v[208:211], v[32:35]
	v_mfma_f32_16x16x32_bf16 v[28:31], v[212:215], v[64:67], v[28:31]
	v_mfma_f32_16x16x32_bf16 v[24:27], v[220:223], v[64:67], v[24:27]
	v_mfma_f32_16x16x32_bf16 v[12:15], v[212:215], v[196:199], v[12:15]
	v_mfma_f32_16x16x32_bf16 v[8:11], v[220:223], v[196:199], v[8:11]
	v_mfma_f32_16x16x32_bf16 v[20:23], v[212:215], v[80:83], v[20:23]
	v_mfma_f32_16x16x32_bf16 v[16:19], v[220:223], v[80:83], v[16:19]
	v_mfma_f32_16x16x32_bf16 v[4:7], v[212:215], v[204:207], v[4:7]
	v_mfma_f32_16x16x32_bf16 v[0:3], v[220:223], v[204:207], v[0:3]
	v_mfma_f32_16x16x32_bf16 v[28:31], v[216:219], v[68:71], v[28:31]
	v_mfma_f32_16x16x32_bf16 v[24:27], v[158:161], v[68:71], v[24:27]
	v_mfma_f32_16x16x32_bf16 v[12:15], v[216:219], v[200:203], v[12:15]
	v_mfma_f32_16x16x32_bf16 v[8:11], v[158:161], v[200:203], v[8:11]
	v_mfma_f32_16x16x32_bf16 v[134:137], v[216:219], v[84:87], v[20:23]
	v_mfma_f32_16x16x32_bf16 v[138:141], v[158:161], v[84:87], v[16:19]
	s_barrier
	v_mfma_f32_16x16x32_bf16 v[170:173], v[216:219], v[208:211], v[4:7]
	v_mfma_f32_16x16x32_bf16 v[158:161], v[158:161], v[208:211], v[0:3]
	s_nop 0
	ds_read_b128 v[0:3], v156
	ds_read_b128 v[4:7], v156 offset:1024
	ds_read_b128 v[16:19], v156 offset:2048
	ds_read_b128 v[174:177], v156 offset:3072
	ds_read_b128 v[20:23], v152 offset:32768
	ds_read_b128 v[196:199], v152 offset:33792
	ds_read_b128 v[200:203], v151 offset:32768
	ds_read_b128 v[204:207], v151 offset:33792
	ds_read_b128 v[208:211], v150 offset:32768
	ds_read_b128 v[212:215], v150 offset:33792
	ds_read_b128 v[216:219], v149 offset:32768
	ds_read_b128 v[220:223], v149 offset:33792
	s_waitcnt vmcnt(2)
	s_barrier
	s_waitcnt lgkmcnt(0)
	v_mfma_f32_16x16x32_bf16 v[64:67], v[0:3], v[20:23], v[124:127]
	v_mfma_f32_16x16x32_bf16 v[68:71], v[16:19], v[20:23], v[120:123]
	v_mfma_f32_16x16x32_bf16 v[80:83], v[0:3], v[200:203], v[116:119]
	v_mfma_f32_16x16x32_bf16 v[84:87], v[16:19], v[200:203], v[112:115]
	v_mfma_f32_16x16x32_bf16 v[108:111], v[0:3], v[208:211], v[108:111]
	v_mfma_f32_16x16x32_bf16 v[104:107], v[16:19], v[208:211], v[104:107]
	v_mfma_f32_16x16x32_bf16 v[120:123], v[0:3], v[216:219], v[100:103]
	v_mfma_f32_16x16x32_bf16 v[124:127], v[16:19], v[216:219], v[96:99]
	v_mfma_f32_16x16x32_bf16 v[116:119], v[4:7], v[196:199], v[64:67]
	v_mfma_f32_16x16x32_bf16 v[112:115], v[174:177], v[196:199], v[68:71]
	v_mfma_f32_16x16x32_bf16 v[100:103], v[4:7], v[204:207], v[80:83]
	v_mfma_f32_16x16x32_bf16 v[96:99], v[174:177], v[204:207], v[84:87]
	v_mfma_f32_16x16x32_bf16 v[84:87], v[4:7], v[212:215], v[108:111]
	v_mfma_f32_16x16x32_bf16 v[80:83], v[174:177], v[212:215], v[104:107]
	s_barrier
; #define LDA(dst, b, h) for (int m = 0; m < 4; ++m) for (int k = 0; k < 2; ++k) \
;     dst[m][k] = *reinterpret_cast<const bf16x8*>((char*)SA(b, h) + lds_byte(wr * 64 + m * 16 + fr, k * 32 + fq * 8))
; #define LDB(dst, b, h) for (int n = 0; n < 2; ++n) for (int k = 0; k < 2; ++k) \
;     dst[n][k] = *reinterpret_cast<const bf16x8*>((char*)SB(b, h) + lds_byte(wc * 32 + n * 16 + fr, k * 32 + fq * 8))
; #define MMA(ai, bj, At_, Bt_) do { __builtin_amdgcn_s_setprio(1); \
;     for (int k = 0; k < 2; ++k) for (int m = 0; m < 4; ++m) for (int n = 0; n < 2; ++n) \
;       acc[ai][bj][m][n] = __builtin_amdgcn_mfma_f32_16x16x32_bf16(At_[m][k], Bt_[n][k], acc[ai][bj][m][n], 0, 0, 0); \
;     __builtin_amdgcn_s_setprio(0); } while (0)
; #define WAIT_V(n) asm volatile("s_waitcnt vmcnt(" #n ")" ::: "memory")
; #define WAIT_L(n) asm volatile("s_waitcnt lgkmcnt(" #n ")" ::: "memory")
; #define BAR __builtin_amdgcn_s_barrier()
; template <int EPI, int lda, int ldb, int N, int K>
; __device__ __forceinline__ void gemm_phase(const u16* __restrict__ A, const u16* __restrict__ Bt, const GemmEpi ep, int wv) {
;     ...
;     { LDB(B0, 1, 0); LDA(At, 1, 0); WAIT_V(2); BAR; WAIT_L(0); MMA(0, 0, At, B0); BAR;
;       LDB(B1, 1, 1); WAIT_V(0); BAR; WAIT_L(0); MMA(0, 1, At, B1); BAR;
;       LDA(At, 1, 1); BAR; WAIT_L(0); MMA(1, 0, At, B0); MMA(1, 1, At, B1); BAR; }
;     if (wr == 0) BAR;
	v_mfma_f32_16x16x32_bf16 v[68:71], v[4:7], v[220:223], v[120:123]
	v_mfma_f32_16x16x32_bf16 v[64:67], v[174:177], v[220:223], v[124:127]
	ds_read_b128 v[224:227], v154
	ds_read_b128 v[228:231], v154 offset:1024
	ds_read_b128 v[232:235], v154 offset:2048
	ds_read_b128 v[154:157], v154 offset:3072
	s_waitcnt vmcnt(0)
	s_barrier
	s_waitcnt lgkmcnt(0)
	v_mfma_f32_16x16x32_bf16 v[92:95], v[224:227], v[20:23], v[92:95]
	v_mfma_f32_16x16x32_bf16 v[20:23], v[232:235], v[20:23], v[88:91]
	v_mfma_f32_16x16x32_bf16 v[88:91], v[224:227], v[200:203], v[180:183]
	v_mfma_f32_16x16x32_bf16 v[104:107], v[232:235], v[200:203], v[184:187]
	v_mfma_f32_16x16x32_bf16 v[76:79], v[224:227], v[208:211], v[76:79]
	v_mfma_f32_16x16x32_bf16 v[72:75], v[232:235], v[208:211], v[72:75]
	v_mfma_f32_16x16x32_bf16 v[178:181], v[224:227], v[216:219], v[188:191]
	v_mfma_f32_16x16x32_bf16 v[182:185], v[232:235], v[216:219], v[192:195]
	v_mfma_f32_16x16x32_bf16 v[124:127], v[228:231], v[196:199], v[92:95]
	v_mfma_f32_16x16x32_bf16 v[120:123], v[154:157], v[196:199], v[20:23]
	v_mfma_f32_16x16x32_bf16 v[108:111], v[228:231], v[204:207], v[88:91]
	v_mfma_f32_16x16x32_bf16 v[104:107], v[154:157], v[204:207], v[104:107]
	v_mfma_f32_16x16x32_bf16 v[92:95], v[228:231], v[212:215], v[76:79]
	v_mfma_f32_16x16x32_bf16 v[88:91], v[154:157], v[212:215], v[72:75]
	s_barrier
	v_mfma_f32_16x16x32_bf16 v[76:79], v[228:231], v[220:223], v[178:181]
	v_mfma_f32_16x16x32_bf16 v[72:75], v[154:157], v[220:223], v[182:185]
	ds_read_b128 v[178:181], v152 offset:49152
	ds_read_b128 v[182:185], v152 offset:50176
	ds_read_b128 v[186:189], v151 offset:49152
	ds_read_b128 v[190:193], v151 offset:50176
	ds_read_b128 v[194:197], v150 offset:49152
	ds_read_b128 v[150:153], v150 offset:50176
	ds_read_b128 v[198:201], v149 offset:49152
	ds_read_b128 v[202:205], v149 offset:50176
	s_barrier
	s_waitcnt lgkmcnt(0)
	v_mfma_f32_16x16x32_bf16 v[20:23], v[0:3], v[178:181], v[60:63]
	v_mfma_f32_16x16x32_bf16 v[56:59], v[16:19], v[178:181], v[56:59]
	v_mfma_f32_16x16x32_bf16 v[60:63], v[0:3], v[186:189], v[52:55]
	v_mfma_f32_16x16x32_bf16 v[206:209], v[16:19], v[186:189], v[48:51]
	v_mfma_f32_16x16x32_bf16 v[44:47], v[0:3], v[194:197], v[44:47]
	v_mfma_f32_16x16x32_bf16 v[40:43], v[16:19], v[194:197], v[40:43]
	v_mfma_f32_16x16x32_bf16 v[0:3], v[0:3], v[198:201], v[36:39]
	v_mfma_f32_16x16x32_bf16 v[210:213], v[16:19], v[198:201], v[32:35]
	v_mfma_f32_16x16x32_bf16 v[52:55], v[4:7], v[182:185], v[20:23]
	v_mfma_f32_16x16x32_bf16 v[48:51], v[174:177], v[182:185], v[56:59]
	v_mfma_f32_16x16x32_bf16 v[36:39], v[4:7], v[190:193], v[60:63]
	v_mfma_f32_16x16x32_bf16 v[32:35], v[174:177], v[190:193], v[206:209]
	v_mfma_f32_16x16x32_bf16 v[20:23], v[4:7], v[150:153], v[44:47]
	v_mfma_f32_16x16x32_bf16 v[16:19], v[174:177], v[150:153], v[40:43]
	v_mfma_f32_16x16x32_bf16 v[4:7], v[4:7], v[202:205], v[0:3]
	v_mfma_f32_16x16x32_bf16 v[0:3], v[174:177], v[202:205], v[210:213]
	v_mfma_f32_16x16x32_bf16 v[28:31], v[224:227], v[178:181], v[28:31]
	v_mfma_f32_16x16x32_bf16 v[24:27], v[232:235], v[178:181], v[24:27]
	v_mfma_f32_16x16x32_bf16 v[40:43], v[224:227], v[186:189], v[134:137]
	v_mfma_f32_16x16x32_bf16 v[134:137], v[232:235], v[186:189], v[138:141]
	v_mfma_f32_16x16x32_bf16 v[12:15], v[224:227], v[194:197], v[12:15]
	v_mfma_f32_16x16x32_bf16 v[8:11], v[232:235], v[194:197], v[8:11]
	v_mfma_f32_16x16x32_bf16 v[138:141], v[224:227], v[198:201], v[170:173]
	v_mfma_f32_16x16x32_bf16 v[158:161], v[232:235], v[198:201], v[158:161]
	v_mfma_f32_16x16x32_bf16 v[60:63], v[228:231], v[182:185], v[28:31]
	v_mfma_f32_16x16x32_bf16 v[56:59], v[154:157], v[182:185], v[24:27]
	v_mfma_f32_16x16x32_bf16 v[44:47], v[228:231], v[190:193], v[40:43]
	v_mfma_f32_16x16x32_bf16 v[40:43], v[154:157], v[190:193], v[134:137]
	v_mfma_f32_16x16x32_bf16 v[28:31], v[228:231], v[150:153], v[12:15]
	v_mfma_f32_16x16x32_bf16 v[24:27], v[154:157], v[150:153], v[8:11]
	s_barrier
	v_mfma_f32_16x16x32_bf16 v[12:15], v[228:231], v[202:205], v[138:141]
	v_mfma_f32_16x16x32_bf16 v[8:11], v[154:157], v[202:205], v[158:161]
	v_cmp_gt_u32_e32 vcc, s56, v130
	s_and_saveexec_b64 s[42:43], vcc
	s_cbranch_execz .LBB0_56
	s_barrier

; #define STAGE(P, BASE, LD, br, kt) do { const char* _g = (const char*)((BASE) + (size_t)(br) * (LD) + (size_t)(kt) * 64); \
;     for (int _i = 0; _i < 2; ++_i) { int _b = tidx * 16 + _i * 8192; int _r, _c; stage_rc(_b, _r, _c); \
;       __builtin_amdgcn_global_load_lds((const unsigned*)(_g + (unsigned)((_r * (LD) + _c) * 2)), (unsigned*)((char*)(P) + _b), 16, 0, 0); } } while (0)
; #define LDA(dst, b, h) for (int m = 0; m < 4; ++m) for (int k = 0; k < 2; ++k) \
;     dst[m][k] = *reinterpret_cast<const bf16x8*>((char*)SA(b, h) + lds_byte(wr * 64 + m * 16 + fr, k * 32 + fq * 8))
; #define LDB(dst, b, h) for (int n = 0; n < 2; ++n) for (int k = 0; k < 2; ++k) \
;     dst[n][k] = *reinterpret_cast<const bf16x8*>((char*)SB(b, h) + lds_byte(wc * 32 + n * 16 + fr, k * 32 + fq * 8))
; #define MMA(ai, bj, At_, Bt_) do { __builtin_amdgcn_s_setprio(1); \
;     for (int k = 0; k < 2; ++k) for (int m = 0; m < 4; ++m) for (int n = 0; n < 2; ++n) \
;       acc[ai][bj][m][n] = __builtin_amdgcn_mfma_f32_16x16x32_bf16(At_[m][k], Bt_[n][k], acc[ai][bj][m][n], 0, 0, 0); \
;     __builtin_amdgcn_s_setprio(0); } while (0)
; #define WAIT_L(n) asm volatile("s_waitcnt lgkmcnt(" #n ")" ::: "memory")
; #define BAR __builtin_amdgcn_s_barrier()
; #define SCHED __builtin_amdgcn_sched_barrier(0)
; template <int EPI, int lda, int ldb, int N, int K>
; __device__ __forceinline__ void gemm_phase(const u16* __restrict__ A, const u16* __restrict__ Bt, const GemmEpi ep, int wv) {
;     ...
;       LDB(B0, 0, 0); SCHED; LDA(At, 0, 0); STAGE(SA(1, 1), Ab, lda, brow + HALF, t + 1);
;       WAIT_L(8); BAR; WAIT_L(0); MMA(0, 0, At, B0); BAR; SCHED;
;       LDB(B1, 0, 1); STAGE(SB(0, 0), Bt, ldb, bcol, t + 2);
;       BAR; WAIT_L(0); MMA(0, 1, At, B1); BAR;
;       LDA(At, 0, 1); STAGE(SA(0, 0), Ab, lda, brow, t + 2);
;       BAR; WAIT_L(0); MMA(1, 0, At, B0); BAR; SCHED;
.LBB0_224:
	ds_read_b128 v[168:171], v164
	ds_read_b128 v[174:177], v164 offset:1024
	ds_read_b128 v[178:181], v164 offset:2048
	ds_read_b128 v[182:185], v164 offset:3072
	v_add_u32_e32 v172, 0xc000, v147
	v_lshl_add_u64 v[238:239], v[136:137], 0, s[44:45]
	v_readfirstlane_b32 s66, v172
	v_add_u32_e32 v173, 0xe000, v147
	v_lshl_add_u64 v[166:167], v[238:239], 0, s[18:19]
	s_mov_b32 m0, s66
	v_lshl_add_u64 v[240:241], v[134:135], 0, s[44:45]
	v_readfirstlane_b32 s66, v173
	ds_read_b128 v[186:189], v155
	ds_read_b128 v[190:193], v155 offset:1024
	ds_read_b128 v[194:197], v154
	ds_read_b128 v[198:201], v154 offset:1024
	ds_read_b128 v[202:205], v153
	ds_read_b128 v[206:209], v153 offset:1024
	ds_read_b128 v[210:213], v152
	ds_read_b128 v[214:217], v152 offset:1024
	global_load_lds_dwordx4 v[166:167], off
	v_lshl_add_u64 v[166:167], v[240:241], 0, s[18:19]
	s_mov_b32 m0, s66
	s_nop 0
	global_load_lds_dwordx4 v[166:167], off
	s_waitcnt lgkmcnt(8)
	s_barrier
	s_waitcnt lgkmcnt(0)
	v_mfma_f32_16x16x32_bf16 v[124:127], v[168:171], v[186:189], v[124:127]
	v_mfma_f32_16x16x32_bf16 v[120:123], v[178:181], v[186:189], v[120:123]
	v_mfma_f32_16x16x32_bf16 v[116:119], v[168:171], v[194:197], v[116:119]
	v_mfma_f32_16x16x32_bf16 v[112:115], v[178:181], v[194:197], v[112:115]
	v_mfma_f32_16x16x32_bf16 v[108:111], v[168:171], v[202:205], v[108:111]
	v_mfma_f32_16x16x32_bf16 v[104:107], v[178:181], v[202:205], v[104:107]
	v_mfma_f32_16x16x32_bf16 v[100:103], v[168:171], v[210:213], v[100:103]
	v_mfma_f32_16x16x32_bf16 v[96:99], v[178:181], v[210:213], v[96:99]
	v_mfma_f32_16x16x32_bf16 v[124:127], v[174:177], v[190:193], v[124:127]
	v_mfma_f32_16x16x32_bf16 v[120:123], v[182:185], v[190:193], v[120:123]
	v_mfma_f32_16x16x32_bf16 v[116:119], v[174:177], v[198:201], v[116:119]
	v_mfma_f32_16x16x32_bf16 v[112:115], v[182:185], v[198:201], v[112:115]
	v_mfma_f32_16x16x32_bf16 v[108:111], v[174:177], v[206:209], v[108:111]
	v_mfma_f32_16x16x32_bf16 v[104:107], v[182:185], v[206:209], v[104:107]
	s_barrier
	v_mfma_f32_16x16x32_bf16 v[100:103], v[174:177], v[214:217], v[100:103]
	v_mfma_f32_16x16x32_bf16 v[96:99], v[182:185], v[214:217], v[96:99]
	v_add_u32_e32 v165, s55, v156
	v_lshl_add_u64 v[242:243], v[144:145], 0, s[44:45]
	v_readfirstlane_b32 s66, v165
	v_lshl_add_u64 v[166:167], v[242:243], 0, s[20:21]
	s_mov_b32 m0, s66
	ds_read_b128 v[218:221], v163
	ds_read_b128 v[222:225], v163 offset:1024
	ds_read_b128 v[226:229], v163 offset:2048
	ds_read_b128 v[230:233], v163 offset:3072
	global_load_lds_dwordx4 v[166:167], off
	v_add_u32_e32 v166, 0x2000, v165
	v_lshl_add_u64 v[244:245], v[142:143], 0, s[44:45]
	v_readfirstlane_b32 s66, v166
	v_lshl_add_u64 v[234:235], v[244:245], 0, s[20:21]
	s_mov_b32 m0, s66
	s_nop 0
	global_load_lds_dwordx4 v[234:235], off
	s_barrier
	s_waitcnt lgkmcnt(0)
	v_mfma_f32_16x16x32_bf16 v[92:95], v[218:221], v[186:189], v[92:95]
	v_mfma_f32_16x16x32_bf16 v[88:91], v[226:229], v[186:189], v[88:91]
	v_mfma_f32_16x16x32_bf16 v[84:87], v[218:221], v[194:197], v[84:87]
	v_mfma_f32_16x16x32_bf16 v[80:83], v[226:229], v[194:197], v[80:83]
	v_mfma_f32_16x16x32_bf16 v[76:79], v[218:221], v[202:205], v[76:79]
	v_mfma_f32_16x16x32_bf16 v[72:75], v[226:229], v[202:205], v[72:75]
	v_mfma_f32_16x16x32_bf16 v[68:71], v[218:221], v[210:213], v[68:71]
	v_mfma_f32_16x16x32_bf16 v[64:67], v[226:229], v[210:213], v[64:67]
	v_mfma_f32_16x16x32_bf16 v[92:95], v[222:225], v[190:193], v[92:95]
	v_mfma_f32_16x16x32_bf16 v[88:91], v[230:233], v[190:193], v[88:91]
	v_mfma_f32_16x16x32_bf16 v[84:87], v[222:225], v[198:201], v[84:87]
	v_mfma_f32_16x16x32_bf16 v[80:83], v[230:233], v[198:201], v[80:83]
	v_mfma_f32_16x16x32_bf16 v[76:79], v[222:225], v[206:209], v[76:79]
	v_mfma_f32_16x16x32_bf16 v[72:75], v[230:233], v[206:209], v[72:75]
	s_barrier
	v_mfma_f32_16x16x32_bf16 v[68:71], v[222:225], v[214:217], v[68:71]
	v_mfma_f32_16x16x32_bf16 v[64:67], v[230:233], v[214:217], v[64:67]
	v_readfirstlane_b32 s66, v147
	v_add_u32_e32 v167, 0x2000, v147
	v_lshl_add_u64 v[234:235], v[238:239], 0, s[22:23]
	s_mov_b32 m0, s66
	v_readfirstlane_b32 s66, v167
	ds_read_b128 v[186:189], v155 offset:16384
	ds_read_b128 v[190:193], v155 offset:17408
	ds_read_b128 v[194:197], v154 offset:16384
	ds_read_b128 v[198:201], v154 offset:17408
	ds_read_b128 v[202:205], v153 offset:16384
	ds_read_b128 v[206:209], v153 offset:17408
	ds_read_b128 v[210:213], v152 offset:16384
	ds_read_b128 v[214:217], v152 offset:17408
	global_load_lds_dwordx4 v[234:235], off
	v_lshl_add_u64 v[234:235], v[240:241], 0, s[22:23]
	s_mov_b32 m0, s66
	s_nop 0
	global_load_lds_dwordx4 v[234:235], off
	s_barrier
	s_waitcnt lgkmcnt(0)
	v_mfma_f32_16x16x32_bf16 v[60:63], v[168:171], v[186:189], v[60:63]
	v_mfma_f32_16x16x32_bf16 v[56:59], v[178:181], v[186:189], v[56:59]
	v_mfma_f32_16x16x32_bf16 v[52:55], v[168:171], v[194:197], v[52:55]
	v_mfma_f32_16x16x32_bf16 v[48:51], v[178:181], v[194:197], v[48:51]
	v_mfma_f32_16x16x32_bf16 v[44:47], v[168:171], v[202:205], v[44:47]
	v_mfma_f32_16x16x32_bf16 v[40:43], v[178:181], v[202:205], v[40:43]
	v_mfma_f32_16x16x32_bf16 v[36:39], v[168:171], v[210:213], v[36:39]
	v_mfma_f32_16x16x32_bf16 v[32:35], v[178:181], v[210:213], v[32:35]
	v_mfma_f32_16x16x32_bf16 v[60:63], v[174:177], v[190:193], v[60:63]
	v_mfma_f32_16x16x32_bf16 v[56:59], v[182:185], v[190:193], v[56:59]
	v_mfma_f32_16x16x32_bf16 v[52:55], v[174:177], v[198:201], v[52:55]
	v_mfma_f32_16x16x32_bf16 v[48:51], v[182:185], v[198:201], v[48:51]
	v_mfma_f32_16x16x32_bf16 v[44:47], v[174:177], v[206:209], v[44:47]
	v_mfma_f32_16x16x32_bf16 v[40:43], v[182:185], v[206:209], v[40:43]
	s_barrier
; #define STAGE(P, BASE, LD, br, kt) do { const char* _g = (const char*)((BASE) + (size_t)(br) * (LD) + (size_t)(kt) * 64); \
;     for (int _i = 0; _i < 2; ++_i) { int _b = tidx * 16 + _i * 8192; int _r, _c; stage_rc(_b, _r, _c); \
;       __builtin_amdgcn_global_load_lds((const unsigned*)(_g + (unsigned)((_r * (LD) + _c) * 2)), (unsigned*)((char*)(P) + _b), 16, 0, 0); } } while (0)
; #define LDA(dst, b, h) for (int m = 0; m < 4; ++m) for (int k = 0; k < 2; ++k) \
;     dst[m][k] = *reinterpret_cast<const bf16x8*>((char*)SA(b, h) + lds_byte(wr * 64 + m * 16 + fr, k * 32 + fq * 8))
; #define LDB(dst, b, h) for (int n = 0; n < 2; ++n) for (int k = 0; k < 2; ++k) \
;     dst[n][k] = *reinterpret_cast<const bf16x8*>((char*)SB(b, h) + lds_byte(wc * 32 + n * 16 + fr, k * 32 + fq * 8))
; #define MMA(ai, bj, At_, Bt_) do { __builtin_amdgcn_s_setprio(1); \
;     for (int k = 0; k < 2; ++k) for (int m = 0; m < 4; ++m) for (int n = 0; n < 2; ++n) \
;       acc[ai][bj][m][n] = __builtin_amdgcn_mfma_f32_16x16x32_bf16(At_[m][k], Bt_[n][k], acc[ai][bj][m][n], 0, 0, 0); \
;     __builtin_amdgcn_s_setprio(0); } while (0)
; #define WAIT_V(n) asm volatile("s_waitcnt vmcnt(" #n ")" ::: "memory")
; #define WAIT_L(n) asm volatile("s_waitcnt lgkmcnt(" #n ")" ::: "memory")
; #define BAR __builtin_amdgcn_s_barrier()
; #define SCHED __builtin_amdgcn_sched_barrier(0)
; template <int EPI, int lda, int ldb, int N, int K>
; __device__ __forceinline__ void gemm_phase(const u16* __restrict__ A, const u16* __restrict__ Bt, const GemmEpi ep, int wv) {
;     ...
;       BAR; WAIT_L(0); MMA(1, 0, At, B0); BAR; SCHED;
;       STAGE(SB(0, 1), Bt, ldb, bcol + HALF, t + 2);
;       WAIT_V(6); BAR; MMA(1, 1, At, B1); BAR;
;       LDB(B0, 1, 0); SCHED; LDA(At, 1, 0); STAGE(SA(0, 1), Ab, lda, brow + HALF, t + 2);
;       WAIT_L(8); BAR; WAIT_L(0); MMA(0, 0, At, B0); BAR; SCHED;
;       LDB(B1, 1, 1); STAGE(SB(1, 0), Bt, ldb, bcol, t + 3);
;       BAR; WAIT_L(0); MMA(0, 1, At, B1); BAR;
	v_mfma_f32_16x16x32_bf16 v[36:39], v[174:177], v[214:217], v[36:39]
	v_mfma_f32_16x16x32_bf16 v[32:35], v[182:185], v[214:217], v[32:35]
	v_add_u32_e32 v168, s56, v156
	v_lshl_add_u64 v[246:247], v[140:141], 0, s[44:45]
	v_readfirstlane_b32 s66, v168
	v_add_u32_e32 v169, 0x2000, v168
	v_lshl_add_u64 v[170:171], v[246:247], 0, s[24:25]
	s_mov_b32 m0, s66
	v_lshl_add_u64 v[248:249], v[138:139], 0, s[44:45]
	v_readfirstlane_b32 s66, v169
	global_load_lds_dwordx4 v[170:171], off
	v_lshl_add_u64 v[170:171], v[248:249], 0, s[24:25]
	s_mov_b32 m0, s66
	s_nop 0
	global_load_lds_dwordx4 v[170:171], off
	s_waitcnt vmcnt(6)
	s_barrier
	v_mfma_f32_16x16x32_bf16 v[28:31], v[218:221], v[186:189], v[28:31]
	v_mfma_f32_16x16x32_bf16 v[24:27], v[226:229], v[186:189], v[24:27]
	v_mfma_f32_16x16x32_bf16 v[20:23], v[218:221], v[194:197], v[20:23]
	v_mfma_f32_16x16x32_bf16 v[16:19], v[226:229], v[194:197], v[16:19]
	v_mfma_f32_16x16x32_bf16 v[12:15], v[218:221], v[202:205], v[12:15]
	v_mfma_f32_16x16x32_bf16 v[8:11], v[226:229], v[202:205], v[8:11]
	v_mfma_f32_16x16x32_bf16 v[4:7], v[218:221], v[210:213], v[4:7]
	v_mfma_f32_16x16x32_bf16 v[0:3], v[226:229], v[210:213], v[0:3]
	v_mfma_f32_16x16x32_bf16 v[28:31], v[222:225], v[190:193], v[28:31]
	v_mfma_f32_16x16x32_bf16 v[24:27], v[230:233], v[190:193], v[24:27]
	v_mfma_f32_16x16x32_bf16 v[20:23], v[222:225], v[198:201], v[20:23]
	v_mfma_f32_16x16x32_bf16 v[16:19], v[230:233], v[198:201], v[16:19]
	v_mfma_f32_16x16x32_bf16 v[12:15], v[222:225], v[206:209], v[12:15]
	v_mfma_f32_16x16x32_bf16 v[8:11], v[230:233], v[206:209], v[8:11]
	s_barrier
	v_mfma_f32_16x16x32_bf16 v[4:7], v[222:225], v[214:217], v[4:7]
	v_mfma_f32_16x16x32_bf16 v[0:3], v[230:233], v[214:217], v[0:3]
	ds_read_b128 v[174:177], v159
	ds_read_b128 v[178:181], v159 offset:1024
	ds_read_b128 v[182:185], v159 offset:2048
	ds_read_b128 v[186:189], v159 offset:3072
	v_add_u32_e32 v170, 0x4000, v147
	v_add_u32_e32 v171, 0x6000, v147
	v_readfirstlane_b32 s66, v170
	v_lshl_add_u64 v[222:223], v[238:239], 0, s[26:27]
	s_mov_b32 m0, s66
	v_readfirstlane_b32 s66, v171
	ds_read_b128 v[190:193], v155 offset:32768
	ds_read_b128 v[194:197], v155 offset:33792
	ds_read_b128 v[198:201], v154 offset:32768
	ds_read_b128 v[202:205], v154 offset:33792
	ds_read_b128 v[206:209], v153 offset:32768
	ds_read_b128 v[210:213], v153 offset:33792
	ds_read_b128 v[214:217], v152 offset:32768
	ds_read_b128 v[218:221], v152 offset:33792
	global_load_lds_dwordx4 v[222:223], off
	v_lshl_add_u64 v[222:223], v[240:241], 0, s[26:27]
	s_mov_b32 m0, s66
	s_nop 0
	global_load_lds_dwordx4 v[222:223], off
	s_waitcnt lgkmcnt(8)
	s_barrier
	s_waitcnt lgkmcnt(0)
	v_mfma_f32_16x16x32_bf16 v[124:127], v[174:177], v[190:193], v[124:127]
	v_mfma_f32_16x16x32_bf16 v[120:123], v[182:185], v[190:193], v[120:123]
	v_mfma_f32_16x16x32_bf16 v[116:119], v[174:177], v[198:201], v[116:119]
	v_mfma_f32_16x16x32_bf16 v[112:115], v[182:185], v[198:201], v[112:115]
	v_mfma_f32_16x16x32_bf16 v[108:111], v[174:177], v[206:209], v[108:111]
	v_mfma_f32_16x16x32_bf16 v[104:107], v[182:185], v[206:209], v[104:107]
	v_mfma_f32_16x16x32_bf16 v[100:103], v[174:177], v[214:217], v[100:103]
	v_mfma_f32_16x16x32_bf16 v[96:99], v[182:185], v[214:217], v[96:99]
	v_mfma_f32_16x16x32_bf16 v[124:127], v[178:181], v[194:197], v[124:127]
	v_mfma_f32_16x16x32_bf16 v[120:123], v[186:189], v[194:197], v[120:123]
	v_mfma_f32_16x16x32_bf16 v[116:119], v[178:181], v[202:205], v[116:119]
	v_mfma_f32_16x16x32_bf16 v[112:115], v[186:189], v[202:205], v[112:115]
	v_mfma_f32_16x16x32_bf16 v[108:111], v[178:181], v[210:213], v[108:111]
	v_mfma_f32_16x16x32_bf16 v[104:107], v[186:189], v[210:213], v[104:107]
	s_barrier
	v_mfma_f32_16x16x32_bf16 v[100:103], v[178:181], v[218:221], v[100:103]
	v_mfma_f32_16x16x32_bf16 v[96:99], v[186:189], v[218:221], v[96:99]
	v_readfirstlane_b32 s66, v158
	v_lshl_add_u64 v[242:243], v[242:243], 0, s[36:37]
	s_mov_b32 m0, s66
	ds_read_b128 v[222:225], v157
	ds_read_b128 v[226:229], v157 offset:1024
	ds_read_b128 v[230:233], v157 offset:2048
	ds_read_b128 v[234:237], v157 offset:3072
	global_load_lds_dwordx4 v[242:243], off
	v_lshl_add_u64 v[242:243], v[244:245], 0, s[36:37]
	v_add_u32_e32 v244, 0x2000, v158
	s_nop 0
	v_readfirstlane_b32 s66, v244
	s_mov_b32 m0, s66
	s_nop 0
	global_load_lds_dwordx4 v[242:243], off
	s_barrier
	s_waitcnt lgkmcnt(0)
	v_mfma_f32_16x16x32_bf16 v[92:95], v[222:225], v[190:193], v[92:95]
	v_mfma_f32_16x16x32_bf16 v[88:91], v[230:233], v[190:193], v[88:91]
	v_mfma_f32_16x16x32_bf16 v[84:87], v[222:225], v[198:201], v[84:87]
	v_mfma_f32_16x16x32_bf16 v[80:83], v[230:233], v[198:201], v[80:83]
	v_mfma_f32_16x16x32_bf16 v[76:79], v[222:225], v[206:209], v[76:79]
	v_mfma_f32_16x16x32_bf16 v[72:75], v[230:233], v[206:209], v[72:75]
	v_mfma_f32_16x16x32_bf16 v[68:71], v[222:225], v[214:217], v[68:71]
	v_mfma_f32_16x16x32_bf16 v[64:67], v[230:233], v[214:217], v[64:67]
	v_mfma_f32_16x16x32_bf16 v[92:95], v[226:229], v[194:197], v[92:95]
	v_mfma_f32_16x16x32_bf16 v[88:91], v[234:237], v[194:197], v[88:91]
	v_mfma_f32_16x16x32_bf16 v[84:87], v[226:229], v[202:205], v[84:87]
	v_mfma_f32_16x16x32_bf16 v[80:83], v[234:237], v[202:205], v[80:83]
	v_mfma_f32_16x16x32_bf16 v[76:79], v[226:229], v[210:213], v[76:79]
	v_mfma_f32_16x16x32_bf16 v[72:75], v[234:237], v[210:213], v[72:75]
	s_barrier
; #define STAGE(P, BASE, LD, br, kt) do { const char* _g = (const char*)((BASE) + (size_t)(br) * (LD) + (size_t)(kt) * 64); \
;     for (int _i = 0; _i < 2; ++_i) { int _b = tidx * 16 + _i * 8192; int _r, _c; stage_rc(_b, _r, _c); \
;       __builtin_amdgcn_global_load_lds((const unsigned*)(_g + (unsigned)((_r * (LD) + _c) * 2)), (unsigned*)((char*)(P) + _b), 16, 0, 0); } } while (0)
; #define LDA(dst, b, h) for (int m = 0; m < 4; ++m) for (int k = 0; k < 2; ++k) \
;     dst[m][k] = *reinterpret_cast<const bf16x8*>((char*)SA(b, h) + lds_byte(wr * 64 + m * 16 + fr, k * 32 + fq * 8))
; #define LDB(dst, b, h) for (int n = 0; n < 2; ++n) for (int k = 0; k < 2; ++k) \
;     dst[n][k] = *reinterpret_cast<const bf16x8*>((char*)SB(b, h) + lds_byte(wc * 32 + n * 16 + fr, k * 32 + fq * 8))
; #define MMA(ai, bj, At_, Bt_) do { __builtin_amdgcn_s_setprio(1); \
;     for (int k = 0; k < 2; ++k) for (int m = 0; m < 4; ++m) for (int n = 0; n < 2; ++n) \
;       acc[ai][bj][m][n] = __builtin_amdgcn_mfma_f32_16x16x32_bf16(At_[m][k], Bt_[n][k], acc[ai][bj][m][n], 0, 0, 0); \
;     __builtin_amdgcn_s_setprio(0); } while (0)
; #define WAIT_V(n) asm volatile("s_waitcnt vmcnt(" #n ")" ::: "memory")
; #define WAIT_L(n) asm volatile("s_waitcnt lgkmcnt(" #n ")" ::: "memory")
; #define BAR __builtin_amdgcn_s_barrier()
; #define SCHED __builtin_amdgcn_sched_barrier(0)
; template <int EPI, int lda, int ldb, int N, int K>
; __device__ __forceinline__ void gemm_phase(const u16* __restrict__ A, const u16* __restrict__ Bt, const GemmEpi ep, int wv) {
;     ...
;       WAIT_V(6); BAR; MMA(1, 1, At, B1); BAR;
;       LDB(B0, 1, 0); SCHED; LDA(At, 1, 0); STAGE(SA(0, 1), Ab, lda, brow + HALF, t + 2);
;       WAIT_L(8); BAR; WAIT_L(0); MMA(0, 0, At, B0); BAR; SCHED;
;       LDB(B1, 1, 1); STAGE(SB(1, 0), Bt, ldb, bcol, t + 3);
;       BAR; WAIT_L(0); MMA(0, 1, At, B1); BAR;
;       LDA(At, 1, 1); STAGE(SA(1, 0), Ab, lda, brow, t + 3);
;       BAR; WAIT_L(0); MMA(1, 0, At, B0); BAR; SCHED;
;       STAGE(SB(1, 1), Bt, ldb, bcol + HALF, t + 3);
;       WAIT_V(6); BAR; MMA(1, 1, At, B1); BAR;
;     }
;     { LDB(B0, 0, 0); LDA(At, 0, 0); STAGE(SA(1, 1), Ab, lda, brow + HALF, nt - 1);
;       BAR; WAIT_L(0); MMA(0, 0, At, B0); BAR;
	v_mfma_f32_16x16x32_bf16 v[68:71], v[226:229], v[218:221], v[68:71]
	v_mfma_f32_16x16x32_bf16 v[64:67], v[234:237], v[218:221], v[64:67]
	v_readfirstlane_b32 s66, v160
	v_lshl_add_u64 v[238:239], v[238:239], 0, s[38:39]
	s_mov_b32 m0, s66
	v_readfirstlane_b32 s66, v161
	ds_read_b128 v[190:193], v155 offset:49152
	ds_read_b128 v[194:197], v155 offset:50176
	ds_read_b128 v[198:201], v154 offset:49152
	ds_read_b128 v[202:205], v154 offset:50176
	ds_read_b128 v[206:209], v153 offset:49152
	ds_read_b128 v[210:213], v153 offset:50176
	ds_read_b128 v[214:217], v152 offset:49152
	ds_read_b128 v[218:221], v152 offset:50176
	global_load_lds_dwordx4 v[238:239], off
	v_lshl_add_u64 v[238:239], v[240:241], 0, s[38:39]
	s_mov_b32 m0, s66
	s_nop 0
	global_load_lds_dwordx4 v[238:239], off
	s_barrier
	s_waitcnt lgkmcnt(0)
	v_mfma_f32_16x16x32_bf16 v[60:63], v[174:177], v[190:193], v[60:63]
	v_mfma_f32_16x16x32_bf16 v[56:59], v[182:185], v[190:193], v[56:59]
	v_mfma_f32_16x16x32_bf16 v[52:55], v[174:177], v[198:201], v[52:55]
	v_mfma_f32_16x16x32_bf16 v[48:51], v[182:185], v[198:201], v[48:51]
	v_mfma_f32_16x16x32_bf16 v[44:47], v[174:177], v[206:209], v[44:47]
	v_mfma_f32_16x16x32_bf16 v[40:43], v[182:185], v[206:209], v[40:43]
	v_mfma_f32_16x16x32_bf16 v[36:39], v[174:177], v[214:217], v[36:39]
	v_mfma_f32_16x16x32_bf16 v[32:35], v[182:185], v[214:217], v[32:35]
	v_mfma_f32_16x16x32_bf16 v[60:63], v[178:181], v[194:197], v[60:63]
	v_mfma_f32_16x16x32_bf16 v[56:59], v[186:189], v[194:197], v[56:59]
	v_mfma_f32_16x16x32_bf16 v[52:55], v[178:181], v[202:205], v[52:55]
	v_mfma_f32_16x16x32_bf16 v[48:51], v[186:189], v[202:205], v[48:51]
	v_mfma_f32_16x16x32_bf16 v[44:47], v[178:181], v[210:213], v[44:47]
	v_mfma_f32_16x16x32_bf16 v[40:43], v[186:189], v[210:213], v[40:43]
	s_barrier
	v_mfma_f32_16x16x32_bf16 v[36:39], v[178:181], v[218:221], v[36:39]
	v_mfma_f32_16x16x32_bf16 v[32:35], v[186:189], v[218:221], v[32:35]
	v_readfirstlane_b32 s66, v162
	v_add_u32_e32 v176, 0x2000, v162
	v_lshl_add_u64 v[174:175], v[246:247], 0, s[42:43]
	s_mov_b32 m0, s66
	v_readfirstlane_b32 s66, v176
	global_load_lds_dwordx4 v[174:175], off
	v_lshl_add_u64 v[174:175], v[248:249], 0, s[42:43]
	s_mov_b32 m0, s66
	s_nop 0
	global_load_lds_dwordx4 v[174:175], off
	s_waitcnt vmcnt(6)
	s_barrier
	v_mfma_f32_16x16x32_bf16 v[28:31], v[222:225], v[190:193], v[28:31]
	v_mfma_f32_16x16x32_bf16 v[24:27], v[230:233], v[190:193], v[24:27]
	v_mfma_f32_16x16x32_bf16 v[20:23], v[222:225], v[198:201], v[20:23]
	v_mfma_f32_16x16x32_bf16 v[16:19], v[230:233], v[198:201], v[16:19]
	v_mfma_f32_16x16x32_bf16 v[12:15], v[222:225], v[206:209], v[12:15]
	v_mfma_f32_16x16x32_bf16 v[8:11], v[230:233], v[206:209], v[8:11]
	v_mfma_f32_16x16x32_bf16 v[4:7], v[222:225], v[214:217], v[4:7]
	v_mfma_f32_16x16x32_bf16 v[0:3], v[230:233], v[214:217], v[0:3]
	v_mfma_f32_16x16x32_bf16 v[28:31], v[226:229], v[194:197], v[28:31]
	v_mfma_f32_16x16x32_bf16 v[24:27], v[234:237], v[194:197], v[24:27]
	v_mfma_f32_16x16x32_bf16 v[20:23], v[226:229], v[202:205], v[20:23]
	v_mfma_f32_16x16x32_bf16 v[16:19], v[234:237], v[202:205], v[16:19]
	v_mfma_f32_16x16x32_bf16 v[12:15], v[226:229], v[210:213], v[12:15]
	v_mfma_f32_16x16x32_bf16 v[8:11], v[234:237], v[210:213], v[8:11]
	s_barrier
	v_mfma_f32_16x16x32_bf16 v[4:7], v[226:229], v[218:221], v[4:7]
	v_mfma_f32_16x16x32_bf16 v[0:3], v[234:237], v[218:221], v[0:3]
	s_add_i32 s65, s65, 2
	s_add_u32 s44, s44, 0x100
	s_addc_u32 s45, s45, 0
	s_cmpk_gt_u32 s65, 0x51
	s_cbranch_scc0 .LBB0_224
	s_add_i32 s44, s14, 0x80
	s_mul_hi_i32 s45, s44, 0x2b00
	s_mulk_i32 s44, 0x2b00
	s_add_u32 s44, s48, s44
	s_addc_u32 s45, s49, s45
	s_add_u32 s44, s44, 0x2a80
	s_addc_u32 s45, s45, 0
	v_readfirstlane_b32 s65, v172
	v_lshl_add_u64 v[160:161], s[44:45], 0, v[128:129]
	s_mov_b32 m0, s65
	ds_read_b128 v[134:137], v164
	ds_read_b128 v[138:141], v164 offset:1024
	ds_read_b128 v[142:145], v164 offset:2048
	ds_read_b128 v[174:177], v164 offset:3072
	ds_read_b128 v[178:181], v155
	ds_read_b128 v[182:185], v155 offset:1024
	ds_read_b128 v[186:189], v154
	ds_read_b128 v[190:193], v154 offset:1024
	ds_read_b128 v[194:197], v153
	ds_read_b128 v[198:201], v153 offset:1024
	ds_read_b128 v[202:205], v152
	ds_read_b128 v[206:209], v152 offset:1024
	global_load_lds_dwordx4 v[160:161], off
	v_lshl_add_u64 v[160:161], s[44:45], 0, v[132:133]
	v_readfirstlane_b32 s44, v173
	s_mov_b32 m0, s44
	s_nop 0
	global_load_lds_dwordx4 v[160:161], off
	s_barrier
	s_waitcnt lgkmcnt(0)
	v_mfma_f32_16x16x32_bf16 v[124:127], v[134:137], v[178:181], v[124:127]
	v_mfma_f32_16x16x32_bf16 v[120:123], v[142:145], v[178:181], v[120:123]
	v_mfma_f32_16x16x32_bf16 v[116:119], v[134:137], v[186:189], v[116:119]
	v_mfma_f32_16x16x32_bf16 v[112:115], v[142:145], v[186:189], v[112:115]
	v_mfma_f32_16x16x32_bf16 v[108:111], v[134:137], v[194:197], v[108:111]
	v_mfma_f32_16x16x32_bf16 v[104:107], v[142:145], v[194:197], v[104:107]
	v_mfma_f32_16x16x32_bf16 v[100:103], v[134:137], v[202:205], v[100:103]
	v_mfma_f32_16x16x32_bf16 v[96:99], v[142:145], v[202:205], v[96:99]
	v_mfma_f32_16x16x32_bf16 v[124:127], v[138:141], v[182:185], v[124:127]
	v_mfma_f32_16x16x32_bf16 v[120:123], v[174:177], v[182:185], v[120:123]
	v_mfma_f32_16x16x32_bf16 v[116:119], v[138:141], v[190:193], v[116:119]
	v_mfma_f32_16x16x32_bf16 v[112:115], v[174:177], v[190:193], v[112:115]
	v_mfma_f32_16x16x32_bf16 v[108:111], v[138:141], v[198:201], v[108:111]
	v_mfma_f32_16x16x32_bf16 v[104:107], v[174:177], v[198:201], v[104:107]
	s_barrier
; #define STAGE(P, BASE, LD, br, kt) do { const char* _g = (const char*)((BASE) + (size_t)(br) * (LD) + (size_t)(kt) * 64); \
;     for (int _i = 0; _i < 2; ++_i) { int _b = tidx * 16 + _i * 8192; int _r, _c; stage_rc(_b, _r, _c); \
;       __builtin_amdgcn_global_load_lds((const unsigned*)(_g + (unsigned)((_r * (LD) + _c) * 2)), (unsigned*)((char*)(P) + _b), 16, 0, 0); } } while (0)
; #define LDA(dst, b, h) for (int m = 0; m < 4; ++m) for (int k = 0; k < 2; ++k) \
;     dst[m][k] = *reinterpret_cast<const bf16x8*>((char*)SA(b, h) + lds_byte(wr * 64 + m * 16 + fr, k * 32 + fq * 8))
; #define LDB(dst, b, h) for (int n = 0; n < 2; ++n) for (int k = 0; k < 2; ++k) \
;     dst[n][k] = *reinterpret_cast<const bf16x8*>((char*)SB(b, h) + lds_byte(wc * 32 + n * 16 + fr, k * 32 + fq * 8))
; #define MMA(ai, bj, At_, Bt_) do { __builtin_amdgcn_s_setprio(1); \
;     for (int k = 0; k < 2; ++k) for (int m = 0; m < 4; ++m) for (int n = 0; n < 2; ++n) \
;       acc[ai][bj][m][n] = __builtin_amdgcn_mfma_f32_16x16x32_bf16(At_[m][k], Bt_[n][k], acc[ai][bj][m][n], 0, 0, 0); \
;     __builtin_amdgcn_s_setprio(0); } while (0)
; #define WAIT_V(n) asm volatile("s_waitcnt vmcnt(" #n ")" ::: "memory")
; #define WAIT_L(n) asm volatile("s_waitcnt lgkmcnt(" #n ")" ::: "memory")
; #define BAR __builtin_amdgcn_s_barrier()
; template <int EPI, int lda, int ldb, int N, int K>
; __device__ __forceinline__ void gemm_phase(const u16* __restrict__ A, const u16* __restrict__ Bt, const GemmEpi ep, int wv) {
;     ...
;     { LDB(B0, 0, 0); LDA(At, 0, 0); STAGE(SA(1, 1), Ab, lda, brow + HALF, nt - 1);
;       BAR; WAIT_L(0); MMA(0, 0, At, B0); BAR;
;       LDB(B1, 0, 1); BAR; WAIT_L(0); MMA(0, 1, At, B1); BAR;
;       LDA(At, 0, 1); WAIT_V(4); BAR; WAIT_L(0); MMA(1, 0, At, B0); MMA(1, 1, At, B1); BAR; }
;     { LDB(B0, 1, 0); LDA(At, 1, 0); WAIT_V(2); BAR; WAIT_L(0); MMA(0, 0, At, B0); BAR;
	v_mfma_f32_16x16x32_bf16 v[100:103], v[138:141], v[206:209], v[100:103]
	v_mfma_f32_16x16x32_bf16 v[96:99], v[174:177], v[206:209], v[96:99]
	ds_read_b128 v[210:213], v163
	ds_read_b128 v[214:217], v163 offset:1024
	ds_read_b128 v[218:221], v163 offset:2048
	ds_read_b128 v[160:163], v163 offset:3072
	s_barrier
	s_waitcnt lgkmcnt(0)
	v_mfma_f32_16x16x32_bf16 v[92:95], v[210:213], v[178:181], v[92:95]
	v_mfma_f32_16x16x32_bf16 v[88:91], v[218:221], v[178:181], v[88:91]
	v_mfma_f32_16x16x32_bf16 v[76:79], v[210:213], v[194:197], v[76:79]
	v_mfma_f32_16x16x32_bf16 v[72:75], v[218:221], v[194:197], v[72:75]
	v_mfma_f32_16x16x32_bf16 v[84:87], v[210:213], v[186:189], v[84:87]
	v_mfma_f32_16x16x32_bf16 v[80:83], v[218:221], v[186:189], v[80:83]
	v_mfma_f32_16x16x32_bf16 v[68:71], v[210:213], v[202:205], v[68:71]
	v_mfma_f32_16x16x32_bf16 v[64:67], v[218:221], v[202:205], v[64:67]
	v_mfma_f32_16x16x32_bf16 v[92:95], v[214:217], v[182:185], v[92:95]
	v_mfma_f32_16x16x32_bf16 v[88:91], v[160:163], v[182:185], v[88:91]
	v_mfma_f32_16x16x32_bf16 v[76:79], v[214:217], v[198:201], v[76:79]
	v_mfma_f32_16x16x32_bf16 v[72:75], v[160:163], v[198:201], v[72:75]
	v_mfma_f32_16x16x32_bf16 v[178:181], v[214:217], v[190:193], v[84:87]
	v_mfma_f32_16x16x32_bf16 v[182:185], v[160:163], v[190:193], v[80:83]
	s_barrier
	v_mfma_f32_16x16x32_bf16 v[186:189], v[214:217], v[206:209], v[68:71]
	v_mfma_f32_16x16x32_bf16 v[190:193], v[160:163], v[206:209], v[64:67]
	s_nop 0
	ds_read_b128 v[64:67], v155 offset:16384
	ds_read_b128 v[68:71], v155 offset:17408
	ds_read_b128 v[80:83], v154 offset:16384
	ds_read_b128 v[84:87], v154 offset:17408
	ds_read_b128 v[194:197], v153 offset:16384
	ds_read_b128 v[198:201], v153 offset:17408
	ds_read_b128 v[202:205], v152 offset:16384
	ds_read_b128 v[206:209], v152 offset:17408
	s_waitcnt vmcnt(4)
	s_barrier
	s_waitcnt lgkmcnt(0)
	v_mfma_f32_16x16x32_bf16 v[60:63], v[134:137], v[64:67], v[60:63]
	v_mfma_f32_16x16x32_bf16 v[56:59], v[142:145], v[64:67], v[56:59]
	v_mfma_f32_16x16x32_bf16 v[52:55], v[134:137], v[80:83], v[52:55]
	v_mfma_f32_16x16x32_bf16 v[48:51], v[142:145], v[80:83], v[48:51]
	v_mfma_f32_16x16x32_bf16 v[44:47], v[134:137], v[194:197], v[44:47]
	v_mfma_f32_16x16x32_bf16 v[40:43], v[142:145], v[194:197], v[40:43]
	v_mfma_f32_16x16x32_bf16 v[36:39], v[134:137], v[202:205], v[36:39]
	v_mfma_f32_16x16x32_bf16 v[32:35], v[142:145], v[202:205], v[32:35]
	v_mfma_f32_16x16x32_bf16 v[60:63], v[138:141], v[68:71], v[60:63]
	v_mfma_f32_16x16x32_bf16 v[56:59], v[174:177], v[68:71], v[56:59]
	v_mfma_f32_16x16x32_bf16 v[52:55], v[138:141], v[84:87], v[52:55]
	v_mfma_f32_16x16x32_bf16 v[48:51], v[174:177], v[84:87], v[48:51]
	v_mfma_f32_16x16x32_bf16 v[44:47], v[138:141], v[198:201], v[44:47]
	v_mfma_f32_16x16x32_bf16 v[40:43], v[174:177], v[198:201], v[40:43]
	v_mfma_f32_16x16x32_bf16 v[36:39], v[138:141], v[206:209], v[36:39]
	v_mfma_f32_16x16x32_bf16 v[32:35], v[174:177], v[206:209], v[32:35]
	v_mfma_f32_16x16x32_bf16 v[28:31], v[210:213], v[64:67], v[28:31]
	v_mfma_f32_16x16x32_bf16 v[16:19], v[218:221], v[80:83], v[16:19]
	v_mfma_f32_16x16x32_bf16 v[12:15], v[210:213], v[194:197], v[12:15]
	v_mfma_f32_16x16x32_bf16 v[0:3], v[218:221], v[202:205], v[0:3]
	v_mfma_f32_16x16x32_bf16 v[24:27], v[218:221], v[64:67], v[24:27]
	v_mfma_f32_16x16x32_bf16 v[20:23], v[210:213], v[80:83], v[20:23]
	v_mfma_f32_16x16x32_bf16 v[8:11], v[218:221], v[194:197], v[8:11]
	v_mfma_f32_16x16x32_bf16 v[4:7], v[210:213], v[202:205], v[4:7]
	v_mfma_f32_16x16x32_bf16 v[28:31], v[214:217], v[68:71], v[28:31]
	v_mfma_f32_16x16x32_bf16 v[16:19], v[160:163], v[84:87], v[16:19]
	v_mfma_f32_16x16x32_bf16 v[12:15], v[214:217], v[198:201], v[12:15]
	v_mfma_f32_16x16x32_bf16 v[0:3], v[160:163], v[206:209], v[0:3]
	v_mfma_f32_16x16x32_bf16 v[134:137], v[160:163], v[68:71], v[24:27]
	v_mfma_f32_16x16x32_bf16 v[138:141], v[214:217], v[84:87], v[20:23]
	s_barrier
	v_mfma_f32_16x16x32_bf16 v[142:145], v[160:163], v[198:201], v[8:11]
	v_mfma_f32_16x16x32_bf16 v[172:175], v[214:217], v[206:209], v[4:7]
	s_nop 0
	ds_read_b128 v[4:7], v159
	ds_read_b128 v[8:11], v159 offset:1024
	ds_read_b128 v[20:23], v159 offset:2048
	ds_read_b128 v[158:161], v159 offset:3072
	ds_read_b128 v[24:27], v155 offset:32768
	ds_read_b128 v[194:197], v155 offset:33792
	ds_read_b128 v[198:201], v154 offset:32768
	ds_read_b128 v[202:205], v154 offset:33792
	ds_read_b128 v[206:209], v153 offset:32768
	ds_read_b128 v[210:213], v153 offset:33792
	ds_read_b128 v[214:217], v152 offset:32768
	ds_read_b128 v[218:221], v152 offset:33792
	s_waitcnt vmcnt(2)
	s_barrier
; #define LDA(dst, b, h) for (int m = 0; m < 4; ++m) for (int k = 0; k < 2; ++k) \
;     dst[m][k] = *reinterpret_cast<const bf16x8*>((char*)SA(b, h) + lds_byte(wr * 64 + m * 16 + fr, k * 32 + fq * 8))
; #define LDB(dst, b, h) for (int n = 0; n < 2; ++n) for (int k = 0; k < 2; ++k) \
;     dst[n][k] = *reinterpret_cast<const bf16x8*>((char*)SB(b, h) + lds_byte(wc * 32 + n * 16 + fr, k * 32 + fq * 8))
; #define MMA(ai, bj, At_, Bt_) do { __builtin_amdgcn_s_setprio(1); \
;     for (int k = 0; k < 2; ++k) for (int m = 0; m < 4; ++m) for (int n = 0; n < 2; ++n) \
;       acc[ai][bj][m][n] = __builtin_amdgcn_mfma_f32_16x16x32_bf16(At_[m][k], Bt_[n][k], acc[ai][bj][m][n], 0, 0, 0); \
;     __builtin_amdgcn_s_setprio(0); } while (0)
; #define WAIT_V(n) asm volatile("s_waitcnt vmcnt(" #n ")" ::: "memory")
; #define WAIT_L(n) asm volatile("s_waitcnt lgkmcnt(" #n ")" ::: "memory")
; #define BAR __builtin_amdgcn_s_barrier()
; template <int EPI, int lda, int ldb, int N, int K>
; __device__ __forceinline__ void gemm_phase(const u16* __restrict__ A, const u16* __restrict__ Bt, const GemmEpi ep, int wv) {
;     ...
;       LDA(At, 0, 1); WAIT_V(4); BAR; WAIT_L(0); MMA(1, 0, At, B0); MMA(1, 1, At, B1); BAR; }
;     { LDB(B0, 1, 0); LDA(At, 1, 0); WAIT_V(2); BAR; WAIT_L(0); MMA(0, 0, At, B0); BAR;
;       LDB(B1, 1, 1); WAIT_V(0); BAR; WAIT_L(0); MMA(0, 1, At, B1); BAR;
;       LDA(At, 1, 1); BAR; WAIT_L(0); MMA(1, 0, At, B0); MMA(1, 1, At, B1); BAR; }
;     if (wr == 0) BAR;
	s_waitcnt lgkmcnt(0)
	v_mfma_f32_16x16x32_bf16 v[64:67], v[4:7], v[24:27], v[124:127]
	v_mfma_f32_16x16x32_bf16 v[68:71], v[20:23], v[24:27], v[120:123]
	v_mfma_f32_16x16x32_bf16 v[80:83], v[4:7], v[198:201], v[116:119]
	v_mfma_f32_16x16x32_bf16 v[84:87], v[20:23], v[198:201], v[112:115]
	v_mfma_f32_16x16x32_bf16 v[108:111], v[4:7], v[206:209], v[108:111]
	v_mfma_f32_16x16x32_bf16 v[104:107], v[20:23], v[206:209], v[104:107]
	v_mfma_f32_16x16x32_bf16 v[120:123], v[4:7], v[214:217], v[100:103]
	v_mfma_f32_16x16x32_bf16 v[124:127], v[20:23], v[214:217], v[96:99]
	v_mfma_f32_16x16x32_bf16 v[116:119], v[8:11], v[194:197], v[64:67]
	v_mfma_f32_16x16x32_bf16 v[112:115], v[158:161], v[194:197], v[68:71]
	v_mfma_f32_16x16x32_bf16 v[100:103], v[8:11], v[202:205], v[80:83]
	v_mfma_f32_16x16x32_bf16 v[96:99], v[158:161], v[202:205], v[84:87]
	v_mfma_f32_16x16x32_bf16 v[84:87], v[8:11], v[210:213], v[108:111]
	v_mfma_f32_16x16x32_bf16 v[80:83], v[158:161], v[210:213], v[104:107]
	s_barrier
	v_mfma_f32_16x16x32_bf16 v[68:71], v[8:11], v[218:221], v[120:123]
	v_mfma_f32_16x16x32_bf16 v[64:67], v[158:161], v[218:221], v[124:127]
	ds_read_b128 v[222:225], v157
	ds_read_b128 v[226:229], v157 offset:1024
	ds_read_b128 v[230:233], v157 offset:2048
	ds_read_b128 v[234:237], v157 offset:3072
	s_waitcnt vmcnt(0)
	s_barrier
	s_waitcnt lgkmcnt(0)
	v_mfma_f32_16x16x32_bf16 v[92:95], v[222:225], v[24:27], v[92:95]
	v_mfma_f32_16x16x32_bf16 v[24:27], v[230:233], v[24:27], v[88:91]
	v_mfma_f32_16x16x32_bf16 v[88:91], v[222:225], v[198:201], v[178:181]
	v_mfma_f32_16x16x32_bf16 v[104:107], v[230:233], v[198:201], v[182:185]
	v_mfma_f32_16x16x32_bf16 v[76:79], v[222:225], v[206:209], v[76:79]
	v_mfma_f32_16x16x32_bf16 v[72:75], v[230:233], v[206:209], v[72:75]
	v_mfma_f32_16x16x32_bf16 v[176:179], v[222:225], v[214:217], v[186:189]
	v_mfma_f32_16x16x32_bf16 v[180:183], v[230:233], v[214:217], v[190:193]
	v_mfma_f32_16x16x32_bf16 v[124:127], v[226:229], v[194:197], v[92:95]
	v_mfma_f32_16x16x32_bf16 v[120:123], v[234:237], v[194:197], v[24:27]
	v_mfma_f32_16x16x32_bf16 v[108:111], v[226:229], v[202:205], v[88:91]
	v_mfma_f32_16x16x32_bf16 v[104:107], v[234:237], v[202:205], v[104:107]
	v_mfma_f32_16x16x32_bf16 v[92:95], v[226:229], v[210:213], v[76:79]
	v_mfma_f32_16x16x32_bf16 v[88:91], v[234:237], v[210:213], v[72:75]
	s_barrier
	v_mfma_f32_16x16x32_bf16 v[76:79], v[226:229], v[218:221], v[176:179]
	v_mfma_f32_16x16x32_bf16 v[72:75], v[234:237], v[218:221], v[180:183]
	ds_read_b128 v[176:179], v155 offset:49152
	ds_read_b128 v[180:183], v155 offset:50176
	ds_read_b128 v[184:187], v154 offset:49152
	ds_read_b128 v[154:157], v154 offset:50176
	ds_read_b128 v[188:191], v153 offset:49152
	ds_read_b128 v[192:195], v153 offset:50176
	ds_read_b128 v[196:199], v152 offset:49152
	ds_read_b128 v[200:203], v152 offset:50176
	s_barrier
	s_waitcnt lgkmcnt(0)
	v_mfma_f32_16x16x32_bf16 v[24:27], v[4:7], v[176:179], v[60:63]
	v_mfma_f32_16x16x32_bf16 v[60:63], v[20:23], v[176:179], v[56:59]
	v_mfma_f32_16x16x32_bf16 v[204:207], v[4:7], v[184:187], v[52:55]
	v_mfma_f32_16x16x32_bf16 v[48:51], v[20:23], v[184:187], v[48:51]
	v_mfma_f32_16x16x32_bf16 v[44:47], v[4:7], v[188:191], v[44:47]
	v_mfma_f32_16x16x32_bf16 v[208:211], v[20:23], v[188:191], v[40:43]
	v_mfma_f32_16x16x32_bf16 v[4:7], v[4:7], v[196:199], v[36:39]
	v_mfma_f32_16x16x32_bf16 v[32:35], v[20:23], v[196:199], v[32:35]
	v_mfma_f32_16x16x32_bf16 v[56:59], v[8:11], v[180:183], v[24:27]
	v_mfma_f32_16x16x32_bf16 v[52:55], v[158:161], v[180:183], v[60:63]
	v_mfma_f32_16x16x32_bf16 v[40:43], v[8:11], v[154:157], v[204:207]
	v_mfma_f32_16x16x32_bf16 v[36:39], v[158:161], v[154:157], v[48:51]
	v_mfma_f32_16x16x32_bf16 v[24:27], v[8:11], v[192:195], v[44:47]
	v_mfma_f32_16x16x32_bf16 v[20:23], v[158:161], v[192:195], v[208:211]
	v_mfma_f32_16x16x32_bf16 v[8:11], v[8:11], v[200:203], v[4:7]
	v_mfma_f32_16x16x32_bf16 v[4:7], v[158:161], v[200:203], v[32:35]
	v_mfma_f32_16x16x32_bf16 v[28:31], v[222:225], v[176:179], v[28:31]
	v_mfma_f32_16x16x32_bf16 v[32:35], v[230:233], v[176:179], v[134:137]
	v_mfma_f32_16x16x32_bf16 v[44:47], v[222:225], v[184:187], v[138:141]
	v_mfma_f32_16x16x32_bf16 v[16:19], v[230:233], v[184:187], v[16:19]
	v_mfma_f32_16x16x32_bf16 v[12:15], v[222:225], v[188:191], v[12:15]
	v_mfma_f32_16x16x32_bf16 v[134:137], v[230:233], v[188:191], v[142:145]
	v_mfma_f32_16x16x32_bf16 v[138:141], v[222:225], v[196:199], v[172:175]
	v_mfma_f32_16x16x32_bf16 v[0:3], v[230:233], v[196:199], v[0:3]
	v_mfma_f32_16x16x32_bf16 v[60:63], v[226:229], v[180:183], v[28:31]
	v_mfma_f32_16x16x32_bf16 v[48:51], v[234:237], v[180:183], v[32:35]
	v_mfma_f32_16x16x32_bf16 v[44:47], v[226:229], v[154:157], v[44:47]
	v_mfma_f32_16x16x32_bf16 v[32:35], v[234:237], v[154:157], v[16:19]
	v_mfma_f32_16x16x32_bf16 v[28:31], v[226:229], v[192:195], v[12:15]
	v_mfma_f32_16x16x32_bf16 v[16:19], v[234:237], v[192:195], v[134:137]
	s_barrier
	v_mfma_f32_16x16x32_bf16 v[12:15], v[226:229], v[200:203], v[138:141]
	v_mfma_f32_16x16x32_bf16 v[0:3], v[234:237], v[200:203], v[0:3]
	v_cmp_gt_u32_e32 vcc, s62, v130
	s_and_saveexec_b64 s[44:45], vcc
	s_cbranch_execz .LBB0_227
	s_barrier

; #define STAGE(P, BASE, LD, br, kt) do { const char* _g = (const char*)((BASE) + (size_t)(br) * (LD) + (size_t)(kt) * 64); \
;     for (int _i = 0; _i < 2; ++_i) { int _b = tidx * 16 + _i * 8192; int _r, _c; stage_rc(_b, _r, _c); \
;       __builtin_amdgcn_global_load_lds((const unsigned*)(_g + (unsigned)((_r * (LD) + _c) * 2)), (unsigned*)((char*)(P) + _b), 16, 0, 0); } } while (0)
; #define LDA(dst, b, h) for (int m = 0; m < 4; ++m) for (int k = 0; k < 2; ++k) \
;     dst[m][k] = *reinterpret_cast<const bf16x8*>((char*)SA(b, h) + lds_byte(wr * 64 + m * 16 + fr, k * 32 + fq * 8))
; #define LDB(dst, b, h) for (int n = 0; n < 2; ++n) for (int k = 0; k < 2; ++k) \
;     dst[n][k] = *reinterpret_cast<const bf16x8*>((char*)SB(b, h) + lds_byte(wc * 32 + n * 16 + fr, k * 32 + fq * 8))
; #define MMA(ai, bj, At_, Bt_) do { __builtin_amdgcn_s_setprio(1); \
;     for (int k = 0; k < 2; ++k) for (int m = 0; m < 4; ++m) for (int n = 0; n < 2; ++n) \
;       acc[ai][bj][m][n] = __builtin_amdgcn_mfma_f32_16x16x32_bf16(At_[m][k], Bt_[n][k], acc[ai][bj][m][n], 0, 0, 0); \
;     __builtin_amdgcn_s_setprio(0); } while (0)
; #define WAIT_L(n) asm volatile("s_waitcnt lgkmcnt(" #n ")" ::: "memory")
; #define BAR __builtin_amdgcn_s_barrier()
; #define SCHED __builtin_amdgcn_sched_barrier(0)
; template <int EPI, int lda, int ldb, int N, int K>
; __device__ __forceinline__ void gemm_phase(const u16* __restrict__ A, const u16* __restrict__ Bt, const GemmEpi ep, int wv) {
;     ...
;       LDB(B0, 0, 0); SCHED; LDA(At, 0, 0); STAGE(SA(1, 1), Ab, lda, brow + HALF, t + 1);
;       WAIT_L(8); BAR; WAIT_L(0); MMA(0, 0, At, B0); BAR; SCHED;
;       LDB(B1, 0, 1); STAGE(SB(0, 0), Bt, ldb, bcol, t + 2);
;       BAR; WAIT_L(0); MMA(0, 1, At, B1); BAR;
;       LDA(At, 0, 1); STAGE(SA(0, 0), Ab, lda, brow, t + 2);
;       BAR; WAIT_L(0); MMA(1, 0, At, B0); BAR; SCHED;
.LBB0_340:
	ds_read_b128 v[166:169], v162
	ds_read_b128 v[172:175], v162 offset:1024
	ds_read_b128 v[176:179], v162 offset:2048
	ds_read_b128 v[180:183], v162 offset:3072
	v_add_u32_e32 v170, 0xc000, v149
	v_lshl_add_u64 v[236:237], v[138:139], 0, s[48:49]
	v_readfirstlane_b32 s51, v170
	v_add_u32_e32 v171, 0xe000, v149
	v_lshl_add_u64 v[164:165], v[236:237], 0, s[18:19]
	s_mov_b32 m0, s51
	v_lshl_add_u64 v[238:239], v[140:141], 0, s[48:49]
	v_readfirstlane_b32 s51, v171
	ds_read_b128 v[184:187], v153
	ds_read_b128 v[188:191], v153 offset:1024
	ds_read_b128 v[192:195], v152
	ds_read_b128 v[196:199], v152 offset:1024
	ds_read_b128 v[200:203], v151
	ds_read_b128 v[204:207], v151 offset:1024
	ds_read_b128 v[208:211], v150
	ds_read_b128 v[212:215], v150 offset:1024
	global_load_lds_dwordx4 v[164:165], off
	v_lshl_add_u64 v[164:165], v[238:239], 0, s[18:19]
	s_mov_b32 m0, s51
	s_nop 0
	global_load_lds_dwordx4 v[164:165], off
	s_waitcnt lgkmcnt(8)
	s_barrier
	s_waitcnt lgkmcnt(0)
	v_mfma_f32_16x16x32_bf16 v[124:127], v[184:187], v[166:169], v[124:127]
	v_mfma_f32_16x16x32_bf16 v[120:123], v[184:187], v[176:179], v[120:123]
	v_mfma_f32_16x16x32_bf16 v[116:119], v[192:195], v[166:169], v[116:119]
	v_mfma_f32_16x16x32_bf16 v[112:115], v[192:195], v[176:179], v[112:115]
	v_mfma_f32_16x16x32_bf16 v[108:111], v[200:203], v[166:169], v[108:111]
	v_mfma_f32_16x16x32_bf16 v[104:107], v[200:203], v[176:179], v[104:107]
	v_mfma_f32_16x16x32_bf16 v[100:103], v[208:211], v[166:169], v[100:103]
	v_mfma_f32_16x16x32_bf16 v[96:99], v[208:211], v[176:179], v[96:99]
	v_mfma_f32_16x16x32_bf16 v[124:127], v[188:191], v[172:175], v[124:127]
	v_mfma_f32_16x16x32_bf16 v[120:123], v[188:191], v[180:183], v[120:123]
	v_mfma_f32_16x16x32_bf16 v[116:119], v[196:199], v[172:175], v[116:119]
	v_mfma_f32_16x16x32_bf16 v[112:115], v[196:199], v[180:183], v[112:115]
	v_mfma_f32_16x16x32_bf16 v[108:111], v[204:207], v[172:175], v[108:111]
	v_mfma_f32_16x16x32_bf16 v[104:107], v[204:207], v[180:183], v[104:107]
	s_barrier
	v_mfma_f32_16x16x32_bf16 v[100:103], v[212:215], v[172:175], v[100:103]
	v_mfma_f32_16x16x32_bf16 v[96:99], v[212:215], v[180:183], v[96:99]
	v_add_u32_e32 v163, s62, v155
	v_lshl_add_u64 v[240:241], v[134:135], 0, s[48:49]
	v_readfirstlane_b32 s51, v163
	v_lshl_add_u64 v[164:165], v[240:241], 0, s[20:21]
	s_mov_b32 m0, s51
	ds_read_b128 v[216:219], v161
	ds_read_b128 v[220:223], v161 offset:1024
	ds_read_b128 v[224:227], v161 offset:2048
	ds_read_b128 v[228:231], v161 offset:3072
	global_load_lds_dwordx4 v[164:165], off
	v_add_u32_e32 v164, 0x2000, v163
	v_lshl_add_u64 v[242:243], v[136:137], 0, s[48:49]
	v_readfirstlane_b32 s51, v164
	v_lshl_add_u64 v[232:233], v[242:243], 0, s[20:21]
	s_mov_b32 m0, s51
	s_nop 0
	global_load_lds_dwordx4 v[232:233], off
	s_barrier
	s_waitcnt lgkmcnt(0)
	v_mfma_f32_16x16x32_bf16 v[92:95], v[184:187], v[216:219], v[92:95]
	v_mfma_f32_16x16x32_bf16 v[88:91], v[184:187], v[224:227], v[88:91]
	v_mfma_f32_16x16x32_bf16 v[84:87], v[192:195], v[216:219], v[84:87]
	v_mfma_f32_16x16x32_bf16 v[80:83], v[192:195], v[224:227], v[80:83]
	v_mfma_f32_16x16x32_bf16 v[76:79], v[200:203], v[216:219], v[76:79]
	v_mfma_f32_16x16x32_bf16 v[72:75], v[200:203], v[224:227], v[72:75]
	v_mfma_f32_16x16x32_bf16 v[68:71], v[208:211], v[216:219], v[68:71]
	v_mfma_f32_16x16x32_bf16 v[64:67], v[208:211], v[224:227], v[64:67]
	v_mfma_f32_16x16x32_bf16 v[92:95], v[188:191], v[220:223], v[92:95]
	v_mfma_f32_16x16x32_bf16 v[88:91], v[188:191], v[228:231], v[88:91]
	v_mfma_f32_16x16x32_bf16 v[84:87], v[196:199], v[220:223], v[84:87]
	v_mfma_f32_16x16x32_bf16 v[80:83], v[196:199], v[228:231], v[80:83]
	v_mfma_f32_16x16x32_bf16 v[76:79], v[204:207], v[220:223], v[76:79]
	v_mfma_f32_16x16x32_bf16 v[72:75], v[204:207], v[228:231], v[72:75]
	s_barrier
	v_mfma_f32_16x16x32_bf16 v[68:71], v[212:215], v[220:223], v[68:71]
	v_mfma_f32_16x16x32_bf16 v[64:67], v[212:215], v[228:231], v[64:67]
	v_readfirstlane_b32 s51, v149
	v_add_u32_e32 v165, 0x2000, v149
	v_lshl_add_u64 v[232:233], v[236:237], 0, s[22:23]
	s_mov_b32 m0, s51
	v_readfirstlane_b32 s51, v165
	ds_read_b128 v[184:187], v153 offset:16384
	ds_read_b128 v[188:191], v153 offset:17408
	ds_read_b128 v[192:195], v152 offset:16384
	ds_read_b128 v[196:199], v152 offset:17408
	ds_read_b128 v[200:203], v151 offset:16384
	ds_read_b128 v[204:207], v151 offset:17408
	ds_read_b128 v[208:211], v150 offset:16384
	ds_read_b128 v[212:215], v150 offset:17408
	global_load_lds_dwordx4 v[232:233], off
	v_lshl_add_u64 v[232:233], v[238:239], 0, s[22:23]
	s_mov_b32 m0, s51
	s_nop 0
	global_load_lds_dwordx4 v[232:233], off
	s_barrier
	s_waitcnt lgkmcnt(0)
	v_mfma_f32_16x16x32_bf16 v[60:63], v[184:187], v[166:169], v[60:63]
	v_mfma_f32_16x16x32_bf16 v[56:59], v[184:187], v[176:179], v[56:59]
	v_mfma_f32_16x16x32_bf16 v[52:55], v[192:195], v[166:169], v[52:55]
	v_mfma_f32_16x16x32_bf16 v[48:51], v[192:195], v[176:179], v[48:51]
	v_mfma_f32_16x16x32_bf16 v[44:47], v[200:203], v[166:169], v[44:47]
	v_mfma_f32_16x16x32_bf16 v[40:43], v[200:203], v[176:179], v[40:43]
	v_mfma_f32_16x16x32_bf16 v[36:39], v[208:211], v[166:169], v[36:39]
	v_mfma_f32_16x16x32_bf16 v[32:35], v[208:211], v[176:179], v[32:35]
	v_mfma_f32_16x16x32_bf16 v[60:63], v[188:191], v[172:175], v[60:63]
	v_mfma_f32_16x16x32_bf16 v[56:59], v[188:191], v[180:183], v[56:59]
	v_mfma_f32_16x16x32_bf16 v[52:55], v[196:199], v[172:175], v[52:55]
	v_mfma_f32_16x16x32_bf16 v[48:51], v[196:199], v[180:183], v[48:51]
	v_mfma_f32_16x16x32_bf16 v[44:47], v[204:207], v[172:175], v[44:47]
	v_mfma_f32_16x16x32_bf16 v[40:43], v[204:207], v[180:183], v[40:43]
	s_barrier
; #define STAGE(P, BASE, LD, br, kt) do { const char* _g = (const char*)((BASE) + (size_t)(br) * (LD) + (size_t)(kt) * 64); \
;     for (int _i = 0; _i < 2; ++_i) { int _b = tidx * 16 + _i * 8192; int _r, _c; stage_rc(_b, _r, _c); \
;       __builtin_amdgcn_global_load_lds((const unsigned*)(_g + (unsigned)((_r * (LD) + _c) * 2)), (unsigned*)((char*)(P) + _b), 16, 0, 0); } } while (0)
; #define LDA(dst, b, h) for (int m = 0; m < 4; ++m) for (int k = 0; k < 2; ++k) \
;     dst[m][k] = *reinterpret_cast<const bf16x8*>((char*)SA(b, h) + lds_byte(wr * 64 + m * 16 + fr, k * 32 + fq * 8))
; #define LDB(dst, b, h) for (int n = 0; n < 2; ++n) for (int k = 0; k < 2; ++k) \
;     dst[n][k] = *reinterpret_cast<const bf16x8*>((char*)SB(b, h) + lds_byte(wc * 32 + n * 16 + fr, k * 32 + fq * 8))
; #define MMA(ai, bj, At_, Bt_) do { __builtin_amdgcn_s_setprio(1); \
;     for (int k = 0; k < 2; ++k) for (int m = 0; m < 4; ++m) for (int n = 0; n < 2; ++n) \
;       acc[ai][bj][m][n] = __builtin_amdgcn_mfma_f32_16x16x32_bf16(At_[m][k], Bt_[n][k], acc[ai][bj][m][n], 0, 0, 0); \
;     __builtin_amdgcn_s_setprio(0); } while (0)
; #define WAIT_V(n) asm volatile("s_waitcnt vmcnt(" #n ")" ::: "memory")
; #define WAIT_L(n) asm volatile("s_waitcnt lgkmcnt(" #n ")" ::: "memory")
; #define BAR __builtin_amdgcn_s_barrier()
; #define SCHED __builtin_amdgcn_sched_barrier(0)
; template <int EPI, int lda, int ldb, int N, int K>
; __device__ __forceinline__ void gemm_phase(const u16* __restrict__ A, const u16* __restrict__ Bt, const GemmEpi ep, int wv) {
;     ...
;       BAR; WAIT_L(0); MMA(1, 0, At, B0); BAR; SCHED;
;       STAGE(SB(0, 1), Bt, ldb, bcol + HALF, t + 2);
;       WAIT_V(6); BAR; MMA(1, 1, At, B1); BAR;
;       LDB(B0, 1, 0); SCHED; LDA(At, 1, 0); STAGE(SA(0, 1), Ab, lda, brow + HALF, t + 2);
;       WAIT_L(8); BAR; WAIT_L(0); MMA(0, 0, At, B0); BAR; SCHED;
;       LDB(B1, 1, 1); STAGE(SB(1, 0), Bt, ldb, bcol, t + 3);
;       BAR; WAIT_L(0); MMA(0, 1, At, B1); BAR;
	v_mfma_f32_16x16x32_bf16 v[36:39], v[212:215], v[172:175], v[36:39]
	v_mfma_f32_16x16x32_bf16 v[32:35], v[212:215], v[180:183], v[32:35]
	v_add_u32_e32 v166, s63, v155
	v_add_u32_e32 v167, 0x2000, v166
	v_readfirstlane_b32 s51, v166
	v_lshl_add_u64 v[168:169], v[240:241], 0, s[24:25]
	s_mov_b32 m0, s51
	v_readfirstlane_b32 s51, v167
	global_load_lds_dwordx4 v[168:169], off
	v_lshl_add_u64 v[168:169], v[242:243], 0, s[24:25]
	s_mov_b32 m0, s51
	s_nop 0
	global_load_lds_dwordx4 v[168:169], off
	s_waitcnt vmcnt(6)
	s_barrier
	v_mfma_f32_16x16x32_bf16 v[28:31], v[184:187], v[216:219], v[28:31]
	v_mfma_f32_16x16x32_bf16 v[24:27], v[184:187], v[224:227], v[24:27]
	v_mfma_f32_16x16x32_bf16 v[20:23], v[192:195], v[216:219], v[20:23]
	v_mfma_f32_16x16x32_bf16 v[16:19], v[192:195], v[224:227], v[16:19]
	v_mfma_f32_16x16x32_bf16 v[12:15], v[200:203], v[216:219], v[12:15]
	v_mfma_f32_16x16x32_bf16 v[8:11], v[200:203], v[224:227], v[8:11]
	v_mfma_f32_16x16x32_bf16 v[4:7], v[208:211], v[216:219], v[4:7]
	v_mfma_f32_16x16x32_bf16 v[0:3], v[208:211], v[224:227], v[0:3]
	v_mfma_f32_16x16x32_bf16 v[28:31], v[188:191], v[220:223], v[28:31]
	v_mfma_f32_16x16x32_bf16 v[24:27], v[188:191], v[228:231], v[24:27]
	v_mfma_f32_16x16x32_bf16 v[20:23], v[196:199], v[220:223], v[20:23]
	v_mfma_f32_16x16x32_bf16 v[16:19], v[196:199], v[228:231], v[16:19]
	v_mfma_f32_16x16x32_bf16 v[12:15], v[204:207], v[220:223], v[12:15]
	v_mfma_f32_16x16x32_bf16 v[8:11], v[204:207], v[228:231], v[8:11]
	s_barrier
	v_mfma_f32_16x16x32_bf16 v[4:7], v[212:215], v[220:223], v[4:7]
	v_mfma_f32_16x16x32_bf16 v[0:3], v[212:215], v[228:231], v[0:3]
	ds_read_b128 v[172:175], v156
	ds_read_b128 v[176:179], v156 offset:1024
	ds_read_b128 v[180:183], v156 offset:2048
	ds_read_b128 v[184:187], v156 offset:3072
	v_add_u32_e32 v168, 0x4000, v149
	v_add_u32_e32 v169, 0x6000, v149
	v_readfirstlane_b32 s51, v168
	v_lshl_add_u64 v[220:221], v[236:237], 0, s[26:27]
	s_mov_b32 m0, s51
	v_readfirstlane_b32 s51, v169
	ds_read_b128 v[188:191], v153 offset:32768
	ds_read_b128 v[192:195], v153 offset:33792
	ds_read_b128 v[196:199], v152 offset:32768
	ds_read_b128 v[200:203], v152 offset:33792
	ds_read_b128 v[204:207], v151 offset:32768
	ds_read_b128 v[208:211], v151 offset:33792
	ds_read_b128 v[212:215], v150 offset:32768
	ds_read_b128 v[216:219], v150 offset:33792
	global_load_lds_dwordx4 v[220:221], off
	v_lshl_add_u64 v[220:221], v[238:239], 0, s[26:27]
	s_mov_b32 m0, s51
	s_nop 0
	global_load_lds_dwordx4 v[220:221], off
	s_waitcnt lgkmcnt(8)
	s_barrier
	s_waitcnt lgkmcnt(0)
	v_mfma_f32_16x16x32_bf16 v[124:127], v[188:191], v[172:175], v[124:127]
	v_mfma_f32_16x16x32_bf16 v[120:123], v[188:191], v[180:183], v[120:123]
	v_mfma_f32_16x16x32_bf16 v[116:119], v[196:199], v[172:175], v[116:119]
	v_mfma_f32_16x16x32_bf16 v[112:115], v[196:199], v[180:183], v[112:115]
	v_mfma_f32_16x16x32_bf16 v[108:111], v[204:207], v[172:175], v[108:111]
	v_mfma_f32_16x16x32_bf16 v[104:107], v[204:207], v[180:183], v[104:107]
	v_mfma_f32_16x16x32_bf16 v[100:103], v[212:215], v[172:175], v[100:103]
	v_mfma_f32_16x16x32_bf16 v[96:99], v[212:215], v[180:183], v[96:99]
	v_mfma_f32_16x16x32_bf16 v[124:127], v[192:195], v[176:179], v[124:127]
	v_mfma_f32_16x16x32_bf16 v[120:123], v[192:195], v[184:187], v[120:123]
	v_mfma_f32_16x16x32_bf16 v[116:119], v[200:203], v[176:179], v[116:119]
	v_mfma_f32_16x16x32_bf16 v[112:115], v[200:203], v[184:187], v[112:115]
	v_mfma_f32_16x16x32_bf16 v[108:111], v[208:211], v[176:179], v[108:111]
	v_mfma_f32_16x16x32_bf16 v[104:107], v[208:211], v[184:187], v[104:107]
	s_barrier
	v_mfma_f32_16x16x32_bf16 v[100:103], v[216:219], v[176:179], v[100:103]
	v_mfma_f32_16x16x32_bf16 v[96:99], v[216:219], v[184:187], v[96:99]
	v_readfirstlane_b32 s51, v157
	v_add_u32_e32 v246, 0x2000, v157
	v_lshl_add_u64 v[244:245], v[240:241], 0, s[36:37]
	s_mov_b32 m0, s51
	v_readfirstlane_b32 s51, v246
	ds_read_b128 v[220:223], v154
	ds_read_b128 v[224:227], v154 offset:1024
	ds_read_b128 v[228:231], v154 offset:2048
	ds_read_b128 v[232:235], v154 offset:3072
	global_load_lds_dwordx4 v[244:245], off
	v_lshl_add_u64 v[244:245], v[242:243], 0, s[36:37]
	s_mov_b32 m0, s51
	s_nop 0
	global_load_lds_dwordx4 v[244:245], off
	s_barrier
	s_waitcnt lgkmcnt(0)
	v_mfma_f32_16x16x32_bf16 v[92:95], v[188:191], v[220:223], v[92:95]
	v_mfma_f32_16x16x32_bf16 v[88:91], v[188:191], v[228:231], v[88:91]
	v_mfma_f32_16x16x32_bf16 v[84:87], v[196:199], v[220:223], v[84:87]
	v_mfma_f32_16x16x32_bf16 v[80:83], v[196:199], v[228:231], v[80:83]
	v_mfma_f32_16x16x32_bf16 v[76:79], v[204:207], v[220:223], v[76:79]
	v_mfma_f32_16x16x32_bf16 v[72:75], v[204:207], v[228:231], v[72:75]
	v_mfma_f32_16x16x32_bf16 v[68:71], v[212:215], v[220:223], v[68:71]
	v_mfma_f32_16x16x32_bf16 v[64:67], v[212:215], v[228:231], v[64:67]
	v_mfma_f32_16x16x32_bf16 v[92:95], v[192:195], v[224:227], v[92:95]
	v_mfma_f32_16x16x32_bf16 v[88:91], v[192:195], v[232:235], v[88:91]
	v_mfma_f32_16x16x32_bf16 v[84:87], v[200:203], v[224:227], v[84:87]
	v_mfma_f32_16x16x32_bf16 v[80:83], v[200:203], v[232:235], v[80:83]
	v_mfma_f32_16x16x32_bf16 v[76:79], v[208:211], v[224:227], v[76:79]
	v_mfma_f32_16x16x32_bf16 v[72:75], v[208:211], v[232:235], v[72:75]
	s_barrier
	v_mfma_f32_16x16x32_bf16 v[68:71], v[216:219], v[224:227], v[68:71]
	v_mfma_f32_16x16x32_bf16 v[64:67], v[216:219], v[232:235], v[64:67]
	v_readfirstlane_b32 s51, v158
	v_lshl_add_u64 v[236:237], v[236:237], 0, s[38:39]
	s_mov_b32 m0, s51
	v_readfirstlane_b32 s51, v159
	ds_read_b128 v[188:191], v153 offset:49152
	ds_read_b128 v[192:195], v153 offset:50176
	ds_read_b128 v[196:199], v152 offset:49152
	ds_read_b128 v[200:203], v152 offset:50176
	ds_read_b128 v[204:207], v151 offset:49152
	ds_read_b128 v[208:211], v151 offset:50176
	ds_read_b128 v[212:215], v150 offset:49152
	ds_read_b128 v[216:219], v150 offset:50176
	global_load_lds_dwordx4 v[236:237], off
	v_lshl_add_u64 v[236:237], v[238:239], 0, s[38:39]
	s_mov_b32 m0, s51
	s_nop 0
	global_load_lds_dwordx4 v[236:237], off
	s_barrier
; #define STAGE(P, BASE, LD, br, kt) do { const char* _g = (const char*)((BASE) + (size_t)(br) * (LD) + (size_t)(kt) * 64); \
;     for (int _i = 0; _i < 2; ++_i) { int _b = tidx * 16 + _i * 8192; int _r, _c; stage_rc(_b, _r, _c); \
;       __builtin_amdgcn_global_load_lds((const unsigned*)(_g + (unsigned)((_r * (LD) + _c) * 2)), (unsigned*)((char*)(P) + _b), 16, 0, 0); } } while (0)
; #define LDA(dst, b, h) for (int m = 0; m < 4; ++m) for (int k = 0; k < 2; ++k) \
;     dst[m][k] = *reinterpret_cast<const bf16x8*>((char*)SA(b, h) + lds_byte(wr * 64 + m * 16 + fr, k * 32 + fq * 8))
; #define LDB(dst, b, h) for (int n = 0; n < 2; ++n) for (int k = 0; k < 2; ++k) \
;     dst[n][k] = *reinterpret_cast<const bf16x8*>((char*)SB(b, h) + lds_byte(wc * 32 + n * 16 + fr, k * 32 + fq * 8))
; #define MMA(ai, bj, At_, Bt_) do { __builtin_amdgcn_s_setprio(1); \
;     for (int k = 0; k < 2; ++k) for (int m = 0; m < 4; ++m) for (int n = 0; n < 2; ++n) \
;       acc[ai][bj][m][n] = __builtin_amdgcn_mfma_f32_16x16x32_bf16(At_[m][k], Bt_[n][k], acc[ai][bj][m][n], 0, 0, 0); \
;     __builtin_amdgcn_s_setprio(0); } while (0)
; #define WAIT_V(n) asm volatile("s_waitcnt vmcnt(" #n ")" ::: "memory")
; #define WAIT_L(n) asm volatile("s_waitcnt lgkmcnt(" #n ")" ::: "memory")
; #define BAR __builtin_amdgcn_s_barrier()
; #define SCHED __builtin_amdgcn_sched_barrier(0)
; template <int EPI, int lda, int ldb, int N, int K>
; __device__ __forceinline__ void gemm_phase(const u16* __restrict__ A, const u16* __restrict__ Bt, const GemmEpi ep, int wv) {
;     ...
;       BAR; WAIT_L(0); MMA(0, 1, At, B1); BAR;
;       LDA(At, 1, 1); STAGE(SA(1, 0), Ab, lda, brow, t + 3);
;       BAR; WAIT_L(0); MMA(1, 0, At, B0); BAR; SCHED;
;       STAGE(SB(1, 1), Bt, ldb, bcol + HALF, t + 3);
;       WAIT_V(6); BAR; MMA(1, 1, At, B1); BAR;
;     }
;     { LDB(B0, 0, 0); LDA(At, 0, 0); STAGE(SA(1, 1), Ab, lda, brow + HALF, nt - 1);
;       BAR; WAIT_L(0); MMA(0, 0, At, B0); BAR;
;       LDB(B1, 0, 1); BAR; WAIT_L(0); MMA(0, 1, At, B1); BAR;
	s_waitcnt lgkmcnt(0)
	v_mfma_f32_16x16x32_bf16 v[60:63], v[188:191], v[172:175], v[60:63]
	v_mfma_f32_16x16x32_bf16 v[56:59], v[188:191], v[180:183], v[56:59]
	v_mfma_f32_16x16x32_bf16 v[52:55], v[196:199], v[172:175], v[52:55]
	v_mfma_f32_16x16x32_bf16 v[48:51], v[196:199], v[180:183], v[48:51]
	v_mfma_f32_16x16x32_bf16 v[44:47], v[204:207], v[172:175], v[44:47]
	v_mfma_f32_16x16x32_bf16 v[40:43], v[204:207], v[180:183], v[40:43]
	v_mfma_f32_16x16x32_bf16 v[36:39], v[212:215], v[172:175], v[36:39]
	v_mfma_f32_16x16x32_bf16 v[32:35], v[212:215], v[180:183], v[32:35]
	v_mfma_f32_16x16x32_bf16 v[60:63], v[192:195], v[176:179], v[60:63]
	v_mfma_f32_16x16x32_bf16 v[56:59], v[192:195], v[184:187], v[56:59]
	v_mfma_f32_16x16x32_bf16 v[52:55], v[200:203], v[176:179], v[52:55]
	v_mfma_f32_16x16x32_bf16 v[48:51], v[200:203], v[184:187], v[48:51]
	v_mfma_f32_16x16x32_bf16 v[44:47], v[208:211], v[176:179], v[44:47]
	v_mfma_f32_16x16x32_bf16 v[40:43], v[208:211], v[184:187], v[40:43]
	s_barrier
	v_mfma_f32_16x16x32_bf16 v[36:39], v[216:219], v[176:179], v[36:39]
	v_mfma_f32_16x16x32_bf16 v[32:35], v[216:219], v[184:187], v[32:35]
	v_readfirstlane_b32 s51, v160
	v_add_u32_e32 v174, 0x2000, v160
	v_lshl_add_u64 v[172:173], v[240:241], 0, s[42:43]
	s_mov_b32 m0, s51
	v_readfirstlane_b32 s51, v174
	global_load_lds_dwordx4 v[172:173], off
	v_lshl_add_u64 v[172:173], v[242:243], 0, s[42:43]
	s_mov_b32 m0, s51
	s_nop 0
	global_load_lds_dwordx4 v[172:173], off
	s_waitcnt vmcnt(6)
	s_barrier
	v_mfma_f32_16x16x32_bf16 v[28:31], v[188:191], v[220:223], v[28:31]
	v_mfma_f32_16x16x32_bf16 v[24:27], v[188:191], v[228:231], v[24:27]
	v_mfma_f32_16x16x32_bf16 v[20:23], v[196:199], v[220:223], v[20:23]
	v_mfma_f32_16x16x32_bf16 v[16:19], v[196:199], v[228:231], v[16:19]
	v_mfma_f32_16x16x32_bf16 v[12:15], v[204:207], v[220:223], v[12:15]
	v_mfma_f32_16x16x32_bf16 v[8:11], v[204:207], v[228:231], v[8:11]
	v_mfma_f32_16x16x32_bf16 v[4:7], v[212:215], v[220:223], v[4:7]
	v_mfma_f32_16x16x32_bf16 v[0:3], v[212:215], v[228:231], v[0:3]
	v_mfma_f32_16x16x32_bf16 v[28:31], v[192:195], v[224:227], v[28:31]
	v_mfma_f32_16x16x32_bf16 v[24:27], v[192:195], v[232:235], v[24:27]
	v_mfma_f32_16x16x32_bf16 v[20:23], v[200:203], v[224:227], v[20:23]
	v_mfma_f32_16x16x32_bf16 v[16:19], v[200:203], v[232:235], v[16:19]
	v_mfma_f32_16x16x32_bf16 v[12:15], v[208:211], v[224:227], v[12:15]
	v_mfma_f32_16x16x32_bf16 v[8:11], v[208:211], v[232:235], v[8:11]
	s_barrier
	v_mfma_f32_16x16x32_bf16 v[4:7], v[216:219], v[224:227], v[4:7]
	v_mfma_f32_16x16x32_bf16 v[0:3], v[216:219], v[232:235], v[0:3]
	s_add_i32 s50, s50, 2
	s_add_u32 s48, s48, 0x100
	s_addc_u32 s49, s49, 0
	s_cmp_gt_u32 s50, 27
	s_cbranch_scc0 .LBB0_340
	s_add_i32 s48, s46, 0x80
	s_mul_hi_i32 s49, s48, 0x1080
	s_mulk_i32 s48, 0x1080
	s_add_u32 s48, s31, s48
	s_addc_u32 s49, s56, s49
	v_lshl_add_u64 v[158:159], s[48:49], 0, v[128:129]
	v_readfirstlane_b32 s50, v170
	v_lshl_add_u64 v[158:159], v[158:159], 0, s[44:45]
	s_mov_b32 m0, s50
	ds_read_b128 v[134:137], v162
	ds_read_b128 v[138:141], v162 offset:1024
	ds_read_b128 v[172:175], v162 offset:2048
	ds_read_b128 v[176:179], v162 offset:3072
	ds_read_b128 v[180:183], v153
	ds_read_b128 v[184:187], v153 offset:1024
	ds_read_b128 v[188:191], v152
	ds_read_b128 v[192:195], v152 offset:1024
	ds_read_b128 v[196:199], v151
	ds_read_b128 v[200:203], v151 offset:1024
	ds_read_b128 v[204:207], v150
	ds_read_b128 v[208:211], v150 offset:1024
	global_load_lds_dwordx4 v[158:159], off
	v_lshl_add_u64 v[158:159], s[48:49], 0, v[132:133]
	v_readfirstlane_b32 s48, v171
	v_lshl_add_u64 v[158:159], v[158:159], 0, s[44:45]
	s_mov_b32 m0, s48
	s_nop 0
	global_load_lds_dwordx4 v[158:159], off
	s_barrier
	s_waitcnt lgkmcnt(0)
	v_mfma_f32_16x16x32_bf16 v[124:127], v[180:183], v[134:137], v[124:127]
	v_mfma_f32_16x16x32_bf16 v[120:123], v[180:183], v[172:175], v[120:123]
	v_mfma_f32_16x16x32_bf16 v[116:119], v[188:191], v[134:137], v[116:119]
	v_mfma_f32_16x16x32_bf16 v[112:115], v[188:191], v[172:175], v[112:115]
	v_mfma_f32_16x16x32_bf16 v[108:111], v[196:199], v[134:137], v[108:111]
	v_mfma_f32_16x16x32_bf16 v[104:107], v[196:199], v[172:175], v[104:107]
	v_mfma_f32_16x16x32_bf16 v[100:103], v[204:207], v[134:137], v[100:103]
	v_mfma_f32_16x16x32_bf16 v[96:99], v[204:207], v[172:175], v[96:99]
	v_mfma_f32_16x16x32_bf16 v[124:127], v[184:187], v[138:141], v[124:127]
	v_mfma_f32_16x16x32_bf16 v[120:123], v[184:187], v[176:179], v[120:123]
	v_mfma_f32_16x16x32_bf16 v[116:119], v[192:195], v[138:141], v[116:119]
	v_mfma_f32_16x16x32_bf16 v[112:115], v[192:195], v[176:179], v[112:115]
	v_mfma_f32_16x16x32_bf16 v[108:111], v[200:203], v[138:141], v[108:111]
	v_mfma_f32_16x16x32_bf16 v[104:107], v[200:203], v[176:179], v[104:107]
	s_barrier
	v_mfma_f32_16x16x32_bf16 v[100:103], v[208:211], v[138:141], v[100:103]
	v_mfma_f32_16x16x32_bf16 v[96:99], v[208:211], v[176:179], v[96:99]
	ds_read_b128 v[212:215], v161
	ds_read_b128 v[216:219], v161 offset:1024
	ds_read_b128 v[220:223], v161 offset:2048
	ds_read_b128 v[158:161], v161 offset:3072
	s_barrier
	s_waitcnt lgkmcnt(0)
	v_mfma_f32_16x16x32_bf16 v[92:95], v[180:183], v[212:215], v[92:95]
	v_mfma_f32_16x16x32_bf16 v[88:91], v[180:183], v[220:223], v[88:91]
	v_mfma_f32_16x16x32_bf16 v[76:79], v[196:199], v[212:215], v[76:79]
	v_mfma_f32_16x16x32_bf16 v[72:75], v[196:199], v[220:223], v[72:75]
	v_mfma_f32_16x16x32_bf16 v[68:71], v[204:207], v[212:215], v[68:71]
	v_mfma_f32_16x16x32_bf16 v[64:67], v[204:207], v[220:223], v[64:67]
	v_mfma_f32_16x16x32_bf16 v[84:87], v[188:191], v[212:215], v[84:87]
	v_mfma_f32_16x16x32_bf16 v[80:83], v[188:191], v[220:223], v[80:83]
	v_mfma_f32_16x16x32_bf16 v[92:95], v[184:187], v[216:219], v[92:95]
	v_mfma_f32_16x16x32_bf16 v[88:91], v[184:187], v[158:161], v[88:91]
	v_mfma_f32_16x16x32_bf16 v[76:79], v[200:203], v[216:219], v[76:79]
	v_mfma_f32_16x16x32_bf16 v[72:75], v[200:203], v[158:161], v[72:75]
	v_mfma_f32_16x16x32_bf16 v[68:71], v[208:211], v[216:219], v[68:71]
	v_mfma_f32_16x16x32_bf16 v[64:67], v[208:211], v[158:161], v[64:67]
	s_barrier
; #define LDA(dst, b, h) for (int m = 0; m < 4; ++m) for (int k = 0; k < 2; ++k) \
;     dst[m][k] = *reinterpret_cast<const bf16x8*>((char*)SA(b, h) + lds_byte(wr * 64 + m * 16 + fr, k * 32 + fq * 8))
; #define LDB(dst, b, h) for (int n = 0; n < 2; ++n) for (int k = 0; k < 2; ++k) \
;     dst[n][k] = *reinterpret_cast<const bf16x8*>((char*)SB(b, h) + lds_byte(wc * 32 + n * 16 + fr, k * 32 + fq * 8))
; #define MMA(ai, bj, At_, Bt_) do { __builtin_amdgcn_s_setprio(1); \
;     for (int k = 0; k < 2; ++k) for (int m = 0; m < 4; ++m) for (int n = 0; n < 2; ++n) \
;       acc[ai][bj][m][n] = __builtin_amdgcn_mfma_f32_16x16x32_bf16(At_[m][k], Bt_[n][k], acc[ai][bj][m][n], 0, 0, 0); \
;     __builtin_amdgcn_s_setprio(0); } while (0)
; #define WAIT_V(n) asm volatile("s_waitcnt vmcnt(" #n ")" ::: "memory")
; #define WAIT_L(n) asm volatile("s_waitcnt lgkmcnt(" #n ")" ::: "memory")
; #define BAR __builtin_amdgcn_s_barrier()
; template <int EPI, int lda, int ldb, int N, int K>
; __device__ __forceinline__ void gemm_phase(const u16* __restrict__ A, const u16* __restrict__ Bt, const GemmEpi ep, int wv) {
;     ...
;       LDB(B1, 0, 1); BAR; WAIT_L(0); MMA(0, 1, At, B1); BAR;
;       LDA(At, 0, 1); WAIT_V(4); BAR; WAIT_L(0); MMA(1, 0, At, B0); MMA(1, 1, At, B1); BAR; }
;     { LDB(B0, 1, 0); LDA(At, 1, 0); WAIT_V(2); BAR; WAIT_L(0); MMA(0, 0, At, B0); BAR;
	v_mfma_f32_16x16x32_bf16 v[180:183], v[192:195], v[216:219], v[84:87]
	v_mfma_f32_16x16x32_bf16 v[184:187], v[192:195], v[158:161], v[80:83]
	s_nop 0
	ds_read_b128 v[80:83], v153 offset:16384
	ds_read_b128 v[84:87], v153 offset:17408
	ds_read_b128 v[188:191], v152 offset:16384
	ds_read_b128 v[192:195], v152 offset:17408
	ds_read_b128 v[196:199], v151 offset:16384
	ds_read_b128 v[200:203], v151 offset:17408
	ds_read_b128 v[204:207], v150 offset:16384
	ds_read_b128 v[208:211], v150 offset:17408
	s_waitcnt vmcnt(4)
	s_barrier
	s_waitcnt lgkmcnt(0)
	v_mfma_f32_16x16x32_bf16 v[60:63], v[80:83], v[134:137], v[60:63]
	v_mfma_f32_16x16x32_bf16 v[44:47], v[196:199], v[134:137], v[44:47]
	v_mfma_f32_16x16x32_bf16 v[40:43], v[196:199], v[172:175], v[40:43]
	v_mfma_f32_16x16x32_bf16 v[36:39], v[204:207], v[134:137], v[36:39]
	v_mfma_f32_16x16x32_bf16 v[32:35], v[204:207], v[172:175], v[32:35]
	v_mfma_f32_16x16x32_bf16 v[56:59], v[80:83], v[172:175], v[56:59]
	v_mfma_f32_16x16x32_bf16 v[52:55], v[188:191], v[134:137], v[52:55]
	v_mfma_f32_16x16x32_bf16 v[48:51], v[188:191], v[172:175], v[48:51]
	v_mfma_f32_16x16x32_bf16 v[60:63], v[84:87], v[138:141], v[60:63]
	v_mfma_f32_16x16x32_bf16 v[44:47], v[200:203], v[138:141], v[44:47]
	v_mfma_f32_16x16x32_bf16 v[40:43], v[200:203], v[176:179], v[40:43]
	v_mfma_f32_16x16x32_bf16 v[36:39], v[208:211], v[138:141], v[36:39]
	v_mfma_f32_16x16x32_bf16 v[32:35], v[208:211], v[176:179], v[32:35]
	v_mfma_f32_16x16x32_bf16 v[134:137], v[84:87], v[176:179], v[56:59]
	v_mfma_f32_16x16x32_bf16 v[170:173], v[192:195], v[138:141], v[52:55]
	v_mfma_f32_16x16x32_bf16 v[224:227], v[192:195], v[176:179], v[48:51]
	v_mfma_f32_16x16x32_bf16 v[28:31], v[80:83], v[212:215], v[28:31]
	v_mfma_f32_16x16x32_bf16 v[20:23], v[188:191], v[212:215], v[20:23]
	v_mfma_f32_16x16x32_bf16 v[12:15], v[196:199], v[212:215], v[12:15]
	v_mfma_f32_16x16x32_bf16 v[4:7], v[204:207], v[212:215], v[4:7]
	v_mfma_f32_16x16x32_bf16 v[24:27], v[80:83], v[220:223], v[24:27]
	v_mfma_f32_16x16x32_bf16 v[16:19], v[188:191], v[220:223], v[16:19]
	v_mfma_f32_16x16x32_bf16 v[8:11], v[196:199], v[220:223], v[8:11]
	v_mfma_f32_16x16x32_bf16 v[0:3], v[204:207], v[220:223], v[0:3]
	v_mfma_f32_16x16x32_bf16 v[28:31], v[84:87], v[216:219], v[28:31]
	v_mfma_f32_16x16x32_bf16 v[20:23], v[192:195], v[216:219], v[20:23]
	v_mfma_f32_16x16x32_bf16 v[12:15], v[200:203], v[216:219], v[12:15]
	v_mfma_f32_16x16x32_bf16 v[4:7], v[208:211], v[216:219], v[4:7]
	v_mfma_f32_16x16x32_bf16 v[138:141], v[84:87], v[158:161], v[24:27]
	v_mfma_f32_16x16x32_bf16 v[174:177], v[192:195], v[158:161], v[16:19]
	s_barrier
	v_mfma_f32_16x16x32_bf16 v[188:191], v[200:203], v[158:161], v[8:11]
	v_mfma_f32_16x16x32_bf16 v[158:161], v[208:211], v[158:161], v[0:3]
	s_nop 0
	ds_read_b128 v[0:3], v156
	ds_read_b128 v[8:11], v156 offset:1024
	ds_read_b128 v[16:19], v156 offset:2048
	ds_read_b128 v[192:195], v156 offset:3072
	ds_read_b128 v[24:27], v153 offset:32768
	ds_read_b128 v[56:59], v153 offset:33792
	ds_read_b128 v[196:199], v152 offset:32768
	ds_read_b128 v[200:203], v152 offset:33792
	ds_read_b128 v[204:207], v151 offset:32768
	ds_read_b128 v[208:211], v151 offset:33792
	ds_read_b128 v[212:215], v150 offset:32768
	ds_read_b128 v[216:219], v150 offset:33792
	s_waitcnt vmcnt(2)
	s_barrier
	s_waitcnt lgkmcnt(0)
	v_mfma_f32_16x16x32_bf16 v[48:51], v[24:27], v[0:3], v[124:127]
	v_mfma_f32_16x16x32_bf16 v[52:55], v[24:27], v[16:19], v[120:123]
	v_mfma_f32_16x16x32_bf16 v[80:83], v[196:199], v[0:3], v[116:119]
	v_mfma_f32_16x16x32_bf16 v[84:87], v[196:199], v[16:19], v[112:115]
	v_mfma_f32_16x16x32_bf16 v[108:111], v[204:207], v[0:3], v[108:111]
	v_mfma_f32_16x16x32_bf16 v[104:107], v[204:207], v[16:19], v[104:107]
	v_mfma_f32_16x16x32_bf16 v[112:115], v[212:215], v[0:3], v[100:103]
	v_mfma_f32_16x16x32_bf16 v[120:123], v[212:215], v[16:19], v[96:99]
	v_mfma_f32_16x16x32_bf16 v[124:127], v[56:59], v[8:11], v[48:51]
	v_mfma_f32_16x16x32_bf16 v[116:119], v[56:59], v[192:195], v[52:55]
	v_mfma_f32_16x16x32_bf16 v[100:103], v[200:203], v[8:11], v[80:83]
	v_mfma_f32_16x16x32_bf16 v[96:99], v[200:203], v[192:195], v[84:87]
	v_mfma_f32_16x16x32_bf16 v[84:87], v[208:211], v[8:11], v[108:111]
	v_mfma_f32_16x16x32_bf16 v[80:83], v[208:211], v[192:195], v[104:107]
	s_barrier
; #define LDA(dst, b, h) for (int m = 0; m < 4; ++m) for (int k = 0; k < 2; ++k) \
;     dst[m][k] = *reinterpret_cast<const bf16x8*>((char*)SA(b, h) + lds_byte(wr * 64 + m * 16 + fr, k * 32 + fq * 8))
; #define LDB(dst, b, h) for (int n = 0; n < 2; ++n) for (int k = 0; k < 2; ++k) \
;     dst[n][k] = *reinterpret_cast<const bf16x8*>((char*)SB(b, h) + lds_byte(wc * 32 + n * 16 + fr, k * 32 + fq * 8))
; #define MMA(ai, bj, At_, Bt_) do { __builtin_amdgcn_s_setprio(1); \
;     for (int k = 0; k < 2; ++k) for (int m = 0; m < 4; ++m) for (int n = 0; n < 2; ++n) \
;       acc[ai][bj][m][n] = __builtin_amdgcn_mfma_f32_16x16x32_bf16(At_[m][k], Bt_[n][k], acc[ai][bj][m][n], 0, 0, 0); \
;     __builtin_amdgcn_s_setprio(0); } while (0)
; #define WAIT_V(n) asm volatile("s_waitcnt vmcnt(" #n ")" ::: "memory")
; #define WAIT_L(n) asm volatile("s_waitcnt lgkmcnt(" #n ")" ::: "memory")
; #define BAR __builtin_amdgcn_s_barrier()
; template <int EPI, int lda, int ldb, int N, int K>
; __device__ __forceinline__ void gemm_phase(const u16* __restrict__ A, const u16* __restrict__ Bt, const GemmEpi ep, int wv) {
;     ...
;     { LDB(B0, 1, 0); LDA(At, 1, 0); WAIT_V(2); BAR; WAIT_L(0); MMA(0, 0, At, B0); BAR;
;       LDB(B1, 1, 1); WAIT_V(0); BAR; WAIT_L(0); MMA(0, 1, At, B1); BAR;
;       LDA(At, 1, 1); BAR; WAIT_L(0); MMA(1, 0, At, B0); MMA(1, 1, At, B1); BAR; }
;     if (wr == 0) BAR;
	v_mfma_f32_16x16x32_bf16 v[52:55], v[216:219], v[8:11], v[112:115]
	v_mfma_f32_16x16x32_bf16 v[48:51], v[216:219], v[192:195], v[120:123]
	ds_read_b128 v[220:223], v154
	ds_read_b128 v[228:231], v154 offset:1024
	ds_read_b128 v[232:235], v154 offset:2048
	ds_read_b128 v[154:157], v154 offset:3072
	s_waitcnt vmcnt(0)
	s_barrier
	s_waitcnt lgkmcnt(0)
	v_mfma_f32_16x16x32_bf16 v[92:95], v[24:27], v[220:223], v[92:95]
	v_mfma_f32_16x16x32_bf16 v[24:27], v[24:27], v[232:235], v[88:91]
	v_mfma_f32_16x16x32_bf16 v[88:91], v[196:199], v[220:223], v[180:183]
	v_mfma_f32_16x16x32_bf16 v[104:107], v[196:199], v[232:235], v[184:187]
	v_mfma_f32_16x16x32_bf16 v[76:79], v[204:207], v[220:223], v[76:79]
	v_mfma_f32_16x16x32_bf16 v[72:75], v[204:207], v[232:235], v[72:75]
	v_mfma_f32_16x16x32_bf16 v[68:71], v[212:215], v[220:223], v[68:71]
	v_mfma_f32_16x16x32_bf16 v[64:67], v[212:215], v[232:235], v[64:67]
	v_mfma_f32_16x16x32_bf16 v[120:123], v[56:59], v[228:231], v[92:95]
	v_mfma_f32_16x16x32_bf16 v[112:115], v[56:59], v[154:157], v[24:27]
	v_mfma_f32_16x16x32_bf16 v[108:111], v[200:203], v[228:231], v[88:91]
	v_mfma_f32_16x16x32_bf16 v[104:107], v[200:203], v[154:157], v[104:107]
	v_mfma_f32_16x16x32_bf16 v[92:95], v[208:211], v[228:231], v[76:79]
	v_mfma_f32_16x16x32_bf16 v[88:91], v[208:211], v[154:157], v[72:75]
	s_barrier
	v_mfma_f32_16x16x32_bf16 v[68:71], v[216:219], v[228:231], v[68:71]
	v_mfma_f32_16x16x32_bf16 v[56:59], v[216:219], v[154:157], v[64:67]
	s_nop 0
	ds_read_b128 v[64:67], v153 offset:49152
	ds_read_b128 v[178:181], v153 offset:50176
	ds_read_b128 v[76:79], v152 offset:49152
	ds_read_b128 v[182:185], v152 offset:50176
	ds_read_b128 v[196:199], v151 offset:49152
	ds_read_b128 v[200:203], v151 offset:50176
	ds_read_b128 v[204:207], v150 offset:49152
	ds_read_b128 v[150:153], v150 offset:50176
	s_barrier
	s_waitcnt lgkmcnt(0)
	v_mfma_f32_16x16x32_bf16 v[24:27], v[64:67], v[0:3], v[60:63]
	v_mfma_f32_16x16x32_bf16 v[60:63], v[64:67], v[16:19], v[134:137]
	v_mfma_f32_16x16x32_bf16 v[134:137], v[76:79], v[0:3], v[170:173]
	v_mfma_f32_16x16x32_bf16 v[170:173], v[76:79], v[16:19], v[224:227]
	v_mfma_f32_16x16x32_bf16 v[44:47], v[196:199], v[0:3], v[44:47]
	v_mfma_f32_16x16x32_bf16 v[208:211], v[196:199], v[16:19], v[40:43]
	v_mfma_f32_16x16x32_bf16 v[0:3], v[204:207], v[0:3], v[36:39]
	v_mfma_f32_16x16x32_bf16 v[36:39], v[204:207], v[16:19], v[32:35]
	v_mfma_f32_16x16x32_bf16 v[72:75], v[178:181], v[8:11], v[24:27]
	v_mfma_f32_16x16x32_bf16 v[60:63], v[178:181], v[192:195], v[60:63]
	v_mfma_f32_16x16x32_bf16 v[40:43], v[182:185], v[8:11], v[134:137]
	v_mfma_f32_16x16x32_bf16 v[32:35], v[182:185], v[192:195], v[170:173]
	v_mfma_f32_16x16x32_bf16 v[24:27], v[200:203], v[8:11], v[44:47]
	v_mfma_f32_16x16x32_bf16 v[16:19], v[200:203], v[192:195], v[208:211]
	v_mfma_f32_16x16x32_bf16 v[8:11], v[150:153], v[8:11], v[0:3]
	v_mfma_f32_16x16x32_bf16 v[0:3], v[150:153], v[192:195], v[36:39]
	v_mfma_f32_16x16x32_bf16 v[28:31], v[64:67], v[220:223], v[28:31]
	v_mfma_f32_16x16x32_bf16 v[36:39], v[64:67], v[232:235], v[138:141]
	v_mfma_f32_16x16x32_bf16 v[20:23], v[76:79], v[220:223], v[20:23]
	v_mfma_f32_16x16x32_bf16 v[134:137], v[76:79], v[232:235], v[174:177]
	v_mfma_f32_16x16x32_bf16 v[12:15], v[196:199], v[220:223], v[12:15]
	v_mfma_f32_16x16x32_bf16 v[138:141], v[196:199], v[232:235], v[188:191]
	v_mfma_f32_16x16x32_bf16 v[4:7], v[204:207], v[220:223], v[4:7]
	v_mfma_f32_16x16x32_bf16 v[158:161], v[204:207], v[232:235], v[158:161]
	v_mfma_f32_16x16x32_bf16 v[76:79], v[178:181], v[228:231], v[28:31]
	v_mfma_f32_16x16x32_bf16 v[64:67], v[178:181], v[154:157], v[36:39]
	v_mfma_f32_16x16x32_bf16 v[44:47], v[182:185], v[228:231], v[20:23]
	v_mfma_f32_16x16x32_bf16 v[36:39], v[182:185], v[154:157], v[134:137]
	v_mfma_f32_16x16x32_bf16 v[28:31], v[200:203], v[228:231], v[12:15]
	v_mfma_f32_16x16x32_bf16 v[20:23], v[200:203], v[154:157], v[138:141]
	s_barrier
	v_mfma_f32_16x16x32_bf16 v[12:15], v[150:153], v[228:231], v[4:7]
	v_mfma_f32_16x16x32_bf16 v[4:7], v[150:153], v[154:157], v[158:161]
	v_cmp_gt_u32_e32 vcc, s64, v130
	s_and_saveexec_b64 s[48:49], vcc
	s_cbranch_execz .LBB0_343
	s_barrier

; #define STAGE(P, BASE, LD, br, kt) do { const char* _g = (const char*)((BASE) + (size_t)(br) * (LD) + (size_t)(kt) * 64); \
;     for (int _i = 0; _i < 2; ++_i) { int _b = tidx * 16 + _i * 8192; int _r, _c; stage_rc(_b, _r, _c); \
;       __builtin_amdgcn_global_load_lds((const unsigned*)(_g + (unsigned)((_r * (LD) + _c) * 2)), (unsigned*)((char*)(P) + _b), 16, 0, 0); } } while (0)
; #define LDA(dst, b, h) for (int m = 0; m < 4; ++m) for (int k = 0; k < 2; ++k) \
;     dst[m][k] = *reinterpret_cast<const bf16x8*>((char*)SA(b, h) + lds_byte(wr * 64 + m * 16 + fr, k * 32 + fq * 8))
; #define LDB(dst, b, h) for (int n = 0; n < 2; ++n) for (int k = 0; k < 2; ++k) \
;     dst[n][k] = *reinterpret_cast<const bf16x8*>((char*)SB(b, h) + lds_byte(wc * 32 + n * 16 + fr, k * 32 + fq * 8))
; #define MMA(ai, bj, At_, Bt_) do { __builtin_amdgcn_s_setprio(1); \
;     for (int k = 0; k < 2; ++k) for (int m = 0; m < 4; ++m) for (int n = 0; n < 2; ++n) \
;       acc[ai][bj][m][n] = __builtin_amdgcn_mfma_f32_16x16x32_bf16(At_[m][k], Bt_[n][k], acc[ai][bj][m][n], 0, 0, 0); \
;     __builtin_amdgcn_s_setprio(0); } while (0)
; #define WAIT_L(n) asm volatile("s_waitcnt lgkmcnt(" #n ")" ::: "memory")
; #define BAR __builtin_amdgcn_s_barrier()
; #define SCHED __builtin_amdgcn_sched_barrier(0)
; template <int EPI, int lda, int ldb, int N, int K>
; __device__ __forceinline__ void gemm_phase(const u16* __restrict__ A, const u16* __restrict__ Bt, const GemmEpi ep, int wv) {
;     ...
;       LDB(B0, 0, 0); SCHED; LDA(At, 0, 0); STAGE(SA(1, 1), Ab, lda, brow + HALF, t + 1);
;       WAIT_L(8); BAR; WAIT_L(0); MMA(0, 0, At, B0); BAR; SCHED;
;       LDB(B1, 0, 1); STAGE(SB(0, 0), Bt, ldb, bcol, t + 2);
;       BAR; WAIT_L(0); MMA(0, 1, At, B1); BAR;
;       LDA(At, 0, 1); STAGE(SA(0, 0), Ab, lda, brow, t + 2);
;       BAR; WAIT_L(0); MMA(1, 0, At, B0); BAR; SCHED;
.LBB0_654:
	ds_read_b128 v[164:167], v160
	ds_read_b128 v[170:173], v160 offset:1024
	ds_read_b128 v[174:177], v160 offset:2048
	ds_read_b128 v[178:181], v160 offset:3072
	v_add_u32_e32 v168, 0xc000, v143
	v_lshl_add_u64 v[234:235], v[138:139], 0, s[52:53]
	v_readfirstlane_b32 s55, v168
	v_add_u32_e32 v169, 0xe000, v143
	v_lshl_add_u64 v[162:163], v[234:235], 0, s[20:21]
	s_mov_b32 m0, s55
	v_lshl_add_u64 v[236:237], v[140:141], 0, s[52:53]
	v_readfirstlane_b32 s55, v169
	ds_read_b128 v[182:185], v151
	ds_read_b128 v[186:189], v151 offset:1024
	ds_read_b128 v[190:193], v150
	ds_read_b128 v[194:197], v150 offset:1024
	ds_read_b128 v[198:201], v149
	ds_read_b128 v[202:205], v149 offset:1024
	ds_read_b128 v[206:209], v148
	ds_read_b128 v[210:213], v148 offset:1024
	global_load_lds_dwordx4 v[162:163], off
	v_lshl_add_u64 v[162:163], v[236:237], 0, s[20:21]
	s_mov_b32 m0, s55
	s_nop 0
	global_load_lds_dwordx4 v[162:163], off
	s_waitcnt lgkmcnt(8)
	s_barrier
	s_waitcnt lgkmcnt(0)
	v_mfma_f32_16x16x32_bf16 v[124:127], v[164:167], v[182:185], v[124:127]
	v_mfma_f32_16x16x32_bf16 v[120:123], v[174:177], v[182:185], v[120:123]
	v_mfma_f32_16x16x32_bf16 v[116:119], v[164:167], v[190:193], v[116:119]
	v_mfma_f32_16x16x32_bf16 v[112:115], v[174:177], v[190:193], v[112:115]
	v_mfma_f32_16x16x32_bf16 v[108:111], v[164:167], v[198:201], v[108:111]
	v_mfma_f32_16x16x32_bf16 v[104:107], v[174:177], v[198:201], v[104:107]
	v_mfma_f32_16x16x32_bf16 v[100:103], v[164:167], v[206:209], v[100:103]
	v_mfma_f32_16x16x32_bf16 v[96:99], v[174:177], v[206:209], v[96:99]
	v_mfma_f32_16x16x32_bf16 v[124:127], v[170:173], v[186:189], v[124:127]
	v_mfma_f32_16x16x32_bf16 v[120:123], v[178:181], v[186:189], v[120:123]
	v_mfma_f32_16x16x32_bf16 v[116:119], v[170:173], v[194:197], v[116:119]
	v_mfma_f32_16x16x32_bf16 v[112:115], v[178:181], v[194:197], v[112:115]
	v_mfma_f32_16x16x32_bf16 v[108:111], v[170:173], v[202:205], v[108:111]
	v_mfma_f32_16x16x32_bf16 v[104:107], v[178:181], v[202:205], v[104:107]
	s_barrier
	v_mfma_f32_16x16x32_bf16 v[100:103], v[170:173], v[210:213], v[100:103]
	v_mfma_f32_16x16x32_bf16 v[96:99], v[178:181], v[210:213], v[96:99]
	v_add_u32_e32 v161, s65, v153
	v_lshl_add_u64 v[238:239], v[134:135], 0, s[52:53]
	v_readfirstlane_b32 s55, v161
	v_lshl_add_u64 v[162:163], v[238:239], 0, s[22:23]
	s_mov_b32 m0, s55
	ds_read_b128 v[214:217], v159
	ds_read_b128 v[218:221], v159 offset:1024
	ds_read_b128 v[222:225], v159 offset:2048
	ds_read_b128 v[226:229], v159 offset:3072
	global_load_lds_dwordx4 v[162:163], off
	v_add_u32_e32 v162, 0x2000, v161
	v_lshl_add_u64 v[240:241], v[136:137], 0, s[52:53]
	v_readfirstlane_b32 s55, v162
	v_lshl_add_u64 v[230:231], v[240:241], 0, s[22:23]
	s_mov_b32 m0, s55
	s_nop 0
	global_load_lds_dwordx4 v[230:231], off
	s_barrier
	s_waitcnt lgkmcnt(0)
	v_mfma_f32_16x16x32_bf16 v[92:95], v[214:217], v[182:185], v[92:95]
	v_mfma_f32_16x16x32_bf16 v[88:91], v[222:225], v[182:185], v[88:91]
	v_mfma_f32_16x16x32_bf16 v[84:87], v[214:217], v[190:193], v[84:87]
	v_mfma_f32_16x16x32_bf16 v[80:83], v[222:225], v[190:193], v[80:83]
	v_mfma_f32_16x16x32_bf16 v[76:79], v[214:217], v[198:201], v[76:79]
	v_mfma_f32_16x16x32_bf16 v[72:75], v[222:225], v[198:201], v[72:75]
	v_mfma_f32_16x16x32_bf16 v[68:71], v[214:217], v[206:209], v[68:71]
	v_mfma_f32_16x16x32_bf16 v[64:67], v[222:225], v[206:209], v[64:67]
	v_mfma_f32_16x16x32_bf16 v[92:95], v[218:221], v[186:189], v[92:95]
	v_mfma_f32_16x16x32_bf16 v[88:91], v[226:229], v[186:189], v[88:91]
	v_mfma_f32_16x16x32_bf16 v[84:87], v[218:221], v[194:197], v[84:87]
	v_mfma_f32_16x16x32_bf16 v[80:83], v[226:229], v[194:197], v[80:83]
	v_mfma_f32_16x16x32_bf16 v[76:79], v[218:221], v[202:205], v[76:79]
	v_mfma_f32_16x16x32_bf16 v[72:75], v[226:229], v[202:205], v[72:75]
	s_barrier
	v_mfma_f32_16x16x32_bf16 v[68:71], v[218:221], v[210:213], v[68:71]
	v_mfma_f32_16x16x32_bf16 v[64:67], v[226:229], v[210:213], v[64:67]
	v_readfirstlane_b32 s55, v143
	v_add_u32_e32 v163, 0x2000, v143
	v_lshl_add_u64 v[230:231], v[234:235], 0, s[24:25]
	s_mov_b32 m0, s55
	v_readfirstlane_b32 s55, v163
	ds_read_b128 v[182:185], v151 offset:16384
	ds_read_b128 v[186:189], v151 offset:17408
	ds_read_b128 v[190:193], v150 offset:16384
	ds_read_b128 v[194:197], v150 offset:17408
	ds_read_b128 v[198:201], v149 offset:16384
	ds_read_b128 v[202:205], v149 offset:17408
	ds_read_b128 v[206:209], v148 offset:16384
	ds_read_b128 v[210:213], v148 offset:17408
	global_load_lds_dwordx4 v[230:231], off
	v_lshl_add_u64 v[230:231], v[236:237], 0, s[24:25]
	s_mov_b32 m0, s55
	s_nop 0
	global_load_lds_dwordx4 v[230:231], off
	s_barrier
	s_waitcnt lgkmcnt(0)
	v_mfma_f32_16x16x32_bf16 v[60:63], v[164:167], v[182:185], v[60:63]
	v_mfma_f32_16x16x32_bf16 v[56:59], v[174:177], v[182:185], v[56:59]
	v_mfma_f32_16x16x32_bf16 v[52:55], v[164:167], v[190:193], v[52:55]
	v_mfma_f32_16x16x32_bf16 v[48:51], v[174:177], v[190:193], v[48:51]
	v_mfma_f32_16x16x32_bf16 v[44:47], v[164:167], v[198:201], v[44:47]
	v_mfma_f32_16x16x32_bf16 v[40:43], v[174:177], v[198:201], v[40:43]
	v_mfma_f32_16x16x32_bf16 v[36:39], v[164:167], v[206:209], v[36:39]
	v_mfma_f32_16x16x32_bf16 v[32:35], v[174:177], v[206:209], v[32:35]
	v_mfma_f32_16x16x32_bf16 v[60:63], v[170:173], v[186:189], v[60:63]
	v_mfma_f32_16x16x32_bf16 v[56:59], v[178:181], v[186:189], v[56:59]
	v_mfma_f32_16x16x32_bf16 v[52:55], v[170:173], v[194:197], v[52:55]
	v_mfma_f32_16x16x32_bf16 v[48:51], v[178:181], v[194:197], v[48:51]
	v_mfma_f32_16x16x32_bf16 v[44:47], v[170:173], v[202:205], v[44:47]
	v_mfma_f32_16x16x32_bf16 v[40:43], v[178:181], v[202:205], v[40:43]
	s_barrier
; #define STAGE(P, BASE, LD, br, kt) do { const char* _g = (const char*)((BASE) + (size_t)(br) * (LD) + (size_t)(kt) * 64); \
;     for (int _i = 0; _i < 2; ++_i) { int _b = tidx * 16 + _i * 8192; int _r, _c; stage_rc(_b, _r, _c); \
;       __builtin_amdgcn_global_load_lds((const unsigned*)(_g + (unsigned)((_r * (LD) + _c) * 2)), (unsigned*)((char*)(P) + _b), 16, 0, 0); } } while (0)
; #define LDA(dst, b, h) for (int m = 0; m < 4; ++m) for (int k = 0; k < 2; ++k) \
;     dst[m][k] = *reinterpret_cast<const bf16x8*>((char*)SA(b, h) + lds_byte(wr * 64 + m * 16 + fr, k * 32 + fq * 8))
; #define LDB(dst, b, h) for (int n = 0; n < 2; ++n) for (int k = 0; k < 2; ++k) \
;     dst[n][k] = *reinterpret_cast<const bf16x8*>((char*)SB(b, h) + lds_byte(wc * 32 + n * 16 + fr, k * 32 + fq * 8))
; #define MMA(ai, bj, At_, Bt_) do { __builtin_amdgcn_s_setprio(1); \
;     for (int k = 0; k < 2; ++k) for (int m = 0; m < 4; ++m) for (int n = 0; n < 2; ++n) \
;       acc[ai][bj][m][n] = __builtin_amdgcn_mfma_f32_16x16x32_bf16(At_[m][k], Bt_[n][k], acc[ai][bj][m][n], 0, 0, 0); \
;     __builtin_amdgcn_s_setprio(0); } while (0)
; #define WAIT_V(n) asm volatile("s_waitcnt vmcnt(" #n ")" ::: "memory")
; #define WAIT_L(n) asm volatile("s_waitcnt lgkmcnt(" #n ")" ::: "memory")
; #define BAR __builtin_amdgcn_s_barrier()
; #define SCHED __builtin_amdgcn_sched_barrier(0)
; template <int EPI, int lda, int ldb, int N, int K>
; __device__ __forceinline__ void gemm_phase(const u16* __restrict__ A, const u16* __restrict__ Bt, const GemmEpi ep, int wv) {
;     ...
;       BAR; WAIT_L(0); MMA(1, 0, At, B0); BAR; SCHED;
;       STAGE(SB(0, 1), Bt, ldb, bcol + HALF, t + 2);
;       WAIT_V(6); BAR; MMA(1, 1, At, B1); BAR;
;       LDB(B0, 1, 0); SCHED; LDA(At, 1, 0); STAGE(SA(0, 1), Ab, lda, brow + HALF, t + 2);
;       WAIT_L(8); BAR; WAIT_L(0); MMA(0, 0, At, B0); BAR; SCHED;
;       LDB(B1, 1, 1); STAGE(SB(1, 0), Bt, ldb, bcol, t + 3);
;       BAR; WAIT_L(0); MMA(0, 1, At, B1); BAR;
	v_mfma_f32_16x16x32_bf16 v[36:39], v[170:173], v[210:213], v[36:39]
	v_mfma_f32_16x16x32_bf16 v[32:35], v[178:181], v[210:213], v[32:35]
	v_add_u32_e32 v164, s66, v153
	v_add_u32_e32 v165, 0x2000, v164
	v_readfirstlane_b32 s55, v164
	v_lshl_add_u64 v[166:167], v[238:239], 0, s[26:27]
	s_mov_b32 m0, s55
	v_readfirstlane_b32 s55, v165
	global_load_lds_dwordx4 v[166:167], off
	v_lshl_add_u64 v[166:167], v[240:241], 0, s[26:27]
	s_mov_b32 m0, s55
	s_nop 0
	global_load_lds_dwordx4 v[166:167], off
	s_waitcnt vmcnt(6)
	s_barrier
	v_mfma_f32_16x16x32_bf16 v[28:31], v[214:217], v[182:185], v[28:31]
	v_mfma_f32_16x16x32_bf16 v[24:27], v[222:225], v[182:185], v[24:27]
	v_mfma_f32_16x16x32_bf16 v[20:23], v[214:217], v[190:193], v[20:23]
	v_mfma_f32_16x16x32_bf16 v[16:19], v[222:225], v[190:193], v[16:19]
	v_mfma_f32_16x16x32_bf16 v[12:15], v[214:217], v[198:201], v[12:15]
	v_mfma_f32_16x16x32_bf16 v[8:11], v[222:225], v[198:201], v[8:11]
	v_mfma_f32_16x16x32_bf16 v[4:7], v[214:217], v[206:209], v[4:7]
	v_mfma_f32_16x16x32_bf16 v[0:3], v[222:225], v[206:209], v[0:3]
	v_mfma_f32_16x16x32_bf16 v[28:31], v[218:221], v[186:189], v[28:31]
	v_mfma_f32_16x16x32_bf16 v[24:27], v[226:229], v[186:189], v[24:27]
	v_mfma_f32_16x16x32_bf16 v[20:23], v[218:221], v[194:197], v[20:23]
	v_mfma_f32_16x16x32_bf16 v[16:19], v[226:229], v[194:197], v[16:19]
	v_mfma_f32_16x16x32_bf16 v[12:15], v[218:221], v[202:205], v[12:15]
	v_mfma_f32_16x16x32_bf16 v[8:11], v[226:229], v[202:205], v[8:11]
	s_barrier
	v_mfma_f32_16x16x32_bf16 v[4:7], v[218:221], v[210:213], v[4:7]
	v_mfma_f32_16x16x32_bf16 v[0:3], v[226:229], v[210:213], v[0:3]
	ds_read_b128 v[170:173], v154
	ds_read_b128 v[174:177], v154 offset:1024
	ds_read_b128 v[178:181], v154 offset:2048
	ds_read_b128 v[182:185], v154 offset:3072
	v_add_u32_e32 v166, 0x4000, v143
	v_add_u32_e32 v167, 0x6000, v143
	v_readfirstlane_b32 s55, v166
	v_lshl_add_u64 v[218:219], v[234:235], 0, s[42:43]
	s_mov_b32 m0, s55
	v_readfirstlane_b32 s55, v167
	ds_read_b128 v[186:189], v151 offset:32768
	ds_read_b128 v[190:193], v151 offset:33792
	ds_read_b128 v[194:197], v150 offset:32768
	ds_read_b128 v[198:201], v150 offset:33792
	ds_read_b128 v[202:205], v149 offset:32768
	ds_read_b128 v[206:209], v149 offset:33792
	ds_read_b128 v[210:213], v148 offset:32768
	ds_read_b128 v[214:217], v148 offset:33792
	global_load_lds_dwordx4 v[218:219], off
	v_lshl_add_u64 v[218:219], v[236:237], 0, s[42:43]
	s_mov_b32 m0, s55
	s_nop 0
	global_load_lds_dwordx4 v[218:219], off
	s_waitcnt lgkmcnt(8)
	s_barrier
	s_waitcnt lgkmcnt(0)
	v_mfma_f32_16x16x32_bf16 v[124:127], v[170:173], v[186:189], v[124:127]
	v_mfma_f32_16x16x32_bf16 v[120:123], v[178:181], v[186:189], v[120:123]
	v_mfma_f32_16x16x32_bf16 v[116:119], v[170:173], v[194:197], v[116:119]
	v_mfma_f32_16x16x32_bf16 v[112:115], v[178:181], v[194:197], v[112:115]
	v_mfma_f32_16x16x32_bf16 v[108:111], v[170:173], v[202:205], v[108:111]
	v_mfma_f32_16x16x32_bf16 v[104:107], v[178:181], v[202:205], v[104:107]
	v_mfma_f32_16x16x32_bf16 v[100:103], v[170:173], v[210:213], v[100:103]
	v_mfma_f32_16x16x32_bf16 v[96:99], v[178:181], v[210:213], v[96:99]
	v_mfma_f32_16x16x32_bf16 v[124:127], v[174:177], v[190:193], v[124:127]
	v_mfma_f32_16x16x32_bf16 v[120:123], v[182:185], v[190:193], v[120:123]
	v_mfma_f32_16x16x32_bf16 v[116:119], v[174:177], v[198:201], v[116:119]
	v_mfma_f32_16x16x32_bf16 v[112:115], v[182:185], v[198:201], v[112:115]
	v_mfma_f32_16x16x32_bf16 v[108:111], v[174:177], v[206:209], v[108:111]
	v_mfma_f32_16x16x32_bf16 v[104:107], v[182:185], v[206:209], v[104:107]
	s_barrier
	v_mfma_f32_16x16x32_bf16 v[100:103], v[174:177], v[214:217], v[100:103]
	v_mfma_f32_16x16x32_bf16 v[96:99], v[182:185], v[214:217], v[96:99]
	v_readfirstlane_b32 s55, v155
	v_add_u32_e32 v244, 0x2000, v155
	v_lshl_add_u64 v[242:243], v[238:239], 0, s[44:45]
	s_mov_b32 m0, s55
	v_readfirstlane_b32 s55, v244
	ds_read_b128 v[218:221], v152
	ds_read_b128 v[222:225], v152 offset:1024
	ds_read_b128 v[226:229], v152 offset:2048
	ds_read_b128 v[230:233], v152 offset:3072
	global_load_lds_dwordx4 v[242:243], off
	v_lshl_add_u64 v[242:243], v[240:241], 0, s[44:45]
	s_mov_b32 m0, s55
	s_nop 0
	global_load_lds_dwordx4 v[242:243], off
	s_barrier
	s_waitcnt lgkmcnt(0)
	v_mfma_f32_16x16x32_bf16 v[92:95], v[218:221], v[186:189], v[92:95]
	v_mfma_f32_16x16x32_bf16 v[88:91], v[226:229], v[186:189], v[88:91]
	v_mfma_f32_16x16x32_bf16 v[84:87], v[218:221], v[194:197], v[84:87]
	v_mfma_f32_16x16x32_bf16 v[80:83], v[226:229], v[194:197], v[80:83]
	v_mfma_f32_16x16x32_bf16 v[76:79], v[218:221], v[202:205], v[76:79]
	v_mfma_f32_16x16x32_bf16 v[72:75], v[226:229], v[202:205], v[72:75]
	v_mfma_f32_16x16x32_bf16 v[68:71], v[218:221], v[210:213], v[68:71]
	v_mfma_f32_16x16x32_bf16 v[64:67], v[226:229], v[210:213], v[64:67]
	v_mfma_f32_16x16x32_bf16 v[92:95], v[222:225], v[190:193], v[92:95]
	v_mfma_f32_16x16x32_bf16 v[88:91], v[230:233], v[190:193], v[88:91]
	v_mfma_f32_16x16x32_bf16 v[84:87], v[222:225], v[198:201], v[84:87]
	v_mfma_f32_16x16x32_bf16 v[80:83], v[230:233], v[198:201], v[80:83]
	v_mfma_f32_16x16x32_bf16 v[76:79], v[222:225], v[206:209], v[76:79]
	v_mfma_f32_16x16x32_bf16 v[72:75], v[230:233], v[206:209], v[72:75]
	s_barrier
	v_mfma_f32_16x16x32_bf16 v[68:71], v[222:225], v[214:217], v[68:71]
	v_mfma_f32_16x16x32_bf16 v[64:67], v[230:233], v[214:217], v[64:67]
	v_readfirstlane_b32 s55, v156
	v_lshl_add_u64 v[234:235], v[234:235], 0, s[46:47]
	s_mov_b32 m0, s55
	v_readfirstlane_b32 s55, v157
	ds_read_b128 v[186:189], v151 offset:49152
	ds_read_b128 v[190:193], v151 offset:50176
	ds_read_b128 v[194:197], v150 offset:49152
	ds_read_b128 v[198:201], v150 offset:50176
	ds_read_b128 v[202:205], v149 offset:49152
	ds_read_b128 v[206:209], v149 offset:50176
	ds_read_b128 v[210:213], v148 offset:49152
	ds_read_b128 v[214:217], v148 offset:50176
	global_load_lds_dwordx4 v[234:235], off
	v_lshl_add_u64 v[234:235], v[236:237], 0, s[46:47]
	s_mov_b32 m0, s55
	s_nop 0
	global_load_lds_dwordx4 v[234:235], off
	s_barrier
; #define STAGE(P, BASE, LD, br, kt) do { const char* _g = (const char*)((BASE) + (size_t)(br) * (LD) + (size_t)(kt) * 64); \
;     for (int _i = 0; _i < 2; ++_i) { int _b = tidx * 16 + _i * 8192; int _r, _c; stage_rc(_b, _r, _c); \
;       __builtin_amdgcn_global_load_lds((const unsigned*)(_g + (unsigned)((_r * (LD) + _c) * 2)), (unsigned*)((char*)(P) + _b), 16, 0, 0); } } while (0)
; #define LDA(dst, b, h) for (int m = 0; m < 4; ++m) for (int k = 0; k < 2; ++k) \
;     dst[m][k] = *reinterpret_cast<const bf16x8*>((char*)SA(b, h) + lds_byte(wr * 64 + m * 16 + fr, k * 32 + fq * 8))
; #define LDB(dst, b, h) for (int n = 0; n < 2; ++n) for (int k = 0; k < 2; ++k) \
;     dst[n][k] = *reinterpret_cast<const bf16x8*>((char*)SB(b, h) + lds_byte(wc * 32 + n * 16 + fr, k * 32 + fq * 8))
; #define MMA(ai, bj, At_, Bt_) do { __builtin_amdgcn_s_setprio(1); \
;     for (int k = 0; k < 2; ++k) for (int m = 0; m < 4; ++m) for (int n = 0; n < 2; ++n) \
;       acc[ai][bj][m][n] = __builtin_amdgcn_mfma_f32_16x16x32_bf16(At_[m][k], Bt_[n][k], acc[ai][bj][m][n], 0, 0, 0); \
;     __builtin_amdgcn_s_setprio(0); } while (0)
; #define WAIT_V(n) asm volatile("s_waitcnt vmcnt(" #n ")" ::: "memory")
; #define WAIT_L(n) asm volatile("s_waitcnt lgkmcnt(" #n ")" ::: "memory")
; #define BAR __builtin_amdgcn_s_barrier()
; #define SCHED __builtin_amdgcn_sched_barrier(0)
; template <int EPI, int lda, int ldb, int N, int K>
; __device__ __forceinline__ void gemm_phase(const u16* __restrict__ A, const u16* __restrict__ Bt, const GemmEpi ep, int wv) {
;     ...
;       BAR; WAIT_L(0); MMA(0, 1, At, B1); BAR;
;       LDA(At, 1, 1); STAGE(SA(1, 0), Ab, lda, brow, t + 3);
;       BAR; WAIT_L(0); MMA(1, 0, At, B0); BAR; SCHED;
;       STAGE(SB(1, 1), Bt, ldb, bcol + HALF, t + 3);
;       WAIT_V(6); BAR; MMA(1, 1, At, B1); BAR;
;     }
;     { LDB(B0, 0, 0); LDA(At, 0, 0); STAGE(SA(1, 1), Ab, lda, brow + HALF, nt - 1);
;       BAR; WAIT_L(0); MMA(0, 0, At, B0); BAR;
;       LDB(B1, 0, 1); BAR; WAIT_L(0); MMA(0, 1, At, B1); BAR;
	s_waitcnt lgkmcnt(0)
	v_mfma_f32_16x16x32_bf16 v[60:63], v[170:173], v[186:189], v[60:63]
	v_mfma_f32_16x16x32_bf16 v[56:59], v[178:181], v[186:189], v[56:59]
	v_mfma_f32_16x16x32_bf16 v[52:55], v[170:173], v[194:197], v[52:55]
	v_mfma_f32_16x16x32_bf16 v[48:51], v[178:181], v[194:197], v[48:51]
	v_mfma_f32_16x16x32_bf16 v[44:47], v[170:173], v[202:205], v[44:47]
	v_mfma_f32_16x16x32_bf16 v[40:43], v[178:181], v[202:205], v[40:43]
	v_mfma_f32_16x16x32_bf16 v[36:39], v[170:173], v[210:213], v[36:39]
	v_mfma_f32_16x16x32_bf16 v[32:35], v[178:181], v[210:213], v[32:35]
	v_mfma_f32_16x16x32_bf16 v[60:63], v[174:177], v[190:193], v[60:63]
	v_mfma_f32_16x16x32_bf16 v[56:59], v[182:185], v[190:193], v[56:59]
	v_mfma_f32_16x16x32_bf16 v[52:55], v[174:177], v[198:201], v[52:55]
	v_mfma_f32_16x16x32_bf16 v[48:51], v[182:185], v[198:201], v[48:51]
	v_mfma_f32_16x16x32_bf16 v[44:47], v[174:177], v[206:209], v[44:47]
	v_mfma_f32_16x16x32_bf16 v[40:43], v[182:185], v[206:209], v[40:43]
	s_barrier
	v_mfma_f32_16x16x32_bf16 v[36:39], v[174:177], v[214:217], v[36:39]
	v_mfma_f32_16x16x32_bf16 v[32:35], v[182:185], v[214:217], v[32:35]
	v_readfirstlane_b32 s55, v158
	v_add_u32_e32 v172, 0x2000, v158
	v_lshl_add_u64 v[170:171], v[238:239], 0, s[48:49]
	s_mov_b32 m0, s55
	v_readfirstlane_b32 s55, v172
	global_load_lds_dwordx4 v[170:171], off
	v_lshl_add_u64 v[170:171], v[240:241], 0, s[48:49]
	s_mov_b32 m0, s55
	s_nop 0
	global_load_lds_dwordx4 v[170:171], off
	s_waitcnt vmcnt(6)
	s_barrier
	v_mfma_f32_16x16x32_bf16 v[28:31], v[218:221], v[186:189], v[28:31]
	v_mfma_f32_16x16x32_bf16 v[24:27], v[226:229], v[186:189], v[24:27]
	v_mfma_f32_16x16x32_bf16 v[20:23], v[218:221], v[194:197], v[20:23]
	v_mfma_f32_16x16x32_bf16 v[16:19], v[226:229], v[194:197], v[16:19]
	v_mfma_f32_16x16x32_bf16 v[12:15], v[218:221], v[202:205], v[12:15]
	v_mfma_f32_16x16x32_bf16 v[8:11], v[226:229], v[202:205], v[8:11]
	v_mfma_f32_16x16x32_bf16 v[4:7], v[218:221], v[210:213], v[4:7]
	v_mfma_f32_16x16x32_bf16 v[0:3], v[226:229], v[210:213], v[0:3]
	v_mfma_f32_16x16x32_bf16 v[28:31], v[222:225], v[190:193], v[28:31]
	v_mfma_f32_16x16x32_bf16 v[24:27], v[230:233], v[190:193], v[24:27]
	v_mfma_f32_16x16x32_bf16 v[20:23], v[222:225], v[198:201], v[20:23]
	v_mfma_f32_16x16x32_bf16 v[16:19], v[230:233], v[198:201], v[16:19]
	v_mfma_f32_16x16x32_bf16 v[12:15], v[222:225], v[206:209], v[12:15]
	v_mfma_f32_16x16x32_bf16 v[8:11], v[230:233], v[206:209], v[8:11]
	s_barrier
	v_mfma_f32_16x16x32_bf16 v[4:7], v[222:225], v[214:217], v[4:7]
	v_mfma_f32_16x16x32_bf16 v[0:3], v[230:233], v[214:217], v[0:3]
	s_add_i32 s54, s54, 2
	s_add_u32 s52, s52, 0x100
	s_addc_u32 s53, s53, 0
	s_cmp_gt_u32 s54, 27
	s_cbranch_scc0 .LBB0_654
	s_lshl_b64 s[52:53], s[16:17], 12
	s_add_u32 s52, s14, s52
	s_addc_u32 s53, s15, s53
	s_add_u32 s52, s52, 0x80000
	s_addc_u32 s53, s53, 0
	v_lshl_add_u64 v[156:157], s[52:53], 0, v[128:129]
	v_readfirstlane_b32 s54, v168
	v_lshl_add_u64 v[156:157], v[156:157], 0, s[50:51]
	s_mov_b32 m0, s54
	ds_read_b128 v[134:137], v160
	ds_read_b128 v[138:141], v160 offset:1024
	ds_read_b128 v[170:173], v160 offset:2048
	ds_read_b128 v[174:177], v160 offset:3072
	ds_read_b128 v[178:181], v151
	ds_read_b128 v[182:185], v151 offset:1024
	ds_read_b128 v[186:189], v150
	ds_read_b128 v[190:193], v150 offset:1024
	ds_read_b128 v[194:197], v149
	ds_read_b128 v[198:201], v149 offset:1024
	ds_read_b128 v[202:205], v148
	ds_read_b128 v[206:209], v148 offset:1024
	global_load_lds_dwordx4 v[156:157], off
	v_lshl_add_u64 v[156:157], s[52:53], 0, v[132:133]
	v_readfirstlane_b32 s52, v169
	v_lshl_add_u64 v[156:157], v[156:157], 0, s[50:51]
	s_mov_b32 m0, s52
	s_nop 0
	global_load_lds_dwordx4 v[156:157], off
	s_barrier
	s_waitcnt lgkmcnt(0)
	v_mfma_f32_16x16x32_bf16 v[124:127], v[134:137], v[178:181], v[124:127]
	v_mfma_f32_16x16x32_bf16 v[120:123], v[170:173], v[178:181], v[120:123]
	v_mfma_f32_16x16x32_bf16 v[116:119], v[134:137], v[186:189], v[116:119]
	v_mfma_f32_16x16x32_bf16 v[112:115], v[170:173], v[186:189], v[112:115]
	v_mfma_f32_16x16x32_bf16 v[108:111], v[134:137], v[194:197], v[108:111]
	v_mfma_f32_16x16x32_bf16 v[104:107], v[170:173], v[194:197], v[104:107]
	v_mfma_f32_16x16x32_bf16 v[100:103], v[134:137], v[202:205], v[100:103]
	v_mfma_f32_16x16x32_bf16 v[96:99], v[170:173], v[202:205], v[96:99]
	v_mfma_f32_16x16x32_bf16 v[124:127], v[138:141], v[182:185], v[124:127]
	v_mfma_f32_16x16x32_bf16 v[120:123], v[174:177], v[182:185], v[120:123]
	v_mfma_f32_16x16x32_bf16 v[116:119], v[138:141], v[190:193], v[116:119]
	v_mfma_f32_16x16x32_bf16 v[112:115], v[174:177], v[190:193], v[112:115]
	v_mfma_f32_16x16x32_bf16 v[108:111], v[138:141], v[198:201], v[108:111]
	v_mfma_f32_16x16x32_bf16 v[104:107], v[174:177], v[198:201], v[104:107]
	s_barrier
	v_mfma_f32_16x16x32_bf16 v[100:103], v[138:141], v[206:209], v[100:103]
	v_mfma_f32_16x16x32_bf16 v[96:99], v[174:177], v[206:209], v[96:99]
	ds_read_b128 v[210:213], v159
	ds_read_b128 v[214:217], v159 offset:1024
	ds_read_b128 v[218:221], v159 offset:2048
	ds_read_b128 v[156:159], v159 offset:3072
	s_barrier
	s_waitcnt lgkmcnt(0)
	v_mfma_f32_16x16x32_bf16 v[92:95], v[210:213], v[178:181], v[92:95]
	v_mfma_f32_16x16x32_bf16 v[88:91], v[218:221], v[178:181], v[88:91]
	v_mfma_f32_16x16x32_bf16 v[76:79], v[210:213], v[194:197], v[76:79]
	v_mfma_f32_16x16x32_bf16 v[72:75], v[218:221], v[194:197], v[72:75]
	v_mfma_f32_16x16x32_bf16 v[84:87], v[210:213], v[186:189], v[84:87]
	v_mfma_f32_16x16x32_bf16 v[80:83], v[218:221], v[186:189], v[80:83]
	v_mfma_f32_16x16x32_bf16 v[68:71], v[210:213], v[202:205], v[68:71]
	v_mfma_f32_16x16x32_bf16 v[64:67], v[218:221], v[202:205], v[64:67]
	v_mfma_f32_16x16x32_bf16 v[92:95], v[214:217], v[182:185], v[92:95]
	v_mfma_f32_16x16x32_bf16 v[88:91], v[156:159], v[182:185], v[88:91]
	v_mfma_f32_16x16x32_bf16 v[76:79], v[214:217], v[198:201], v[76:79]
	v_mfma_f32_16x16x32_bf16 v[72:75], v[156:159], v[198:201], v[72:75]
	v_mfma_f32_16x16x32_bf16 v[178:181], v[214:217], v[190:193], v[84:87]
	v_mfma_f32_16x16x32_bf16 v[182:185], v[156:159], v[190:193], v[80:83]
	s_barrier
; #define LDA(dst, b, h) for (int m = 0; m < 4; ++m) for (int k = 0; k < 2; ++k) \
;     dst[m][k] = *reinterpret_cast<const bf16x8*>((char*)SA(b, h) + lds_byte(wr * 64 + m * 16 + fr, k * 32 + fq * 8))
; #define LDB(dst, b, h) for (int n = 0; n < 2; ++n) for (int k = 0; k < 2; ++k) \
;     dst[n][k] = *reinterpret_cast<const bf16x8*>((char*)SB(b, h) + lds_byte(wc * 32 + n * 16 + fr, k * 32 + fq * 8))
; #define MMA(ai, bj, At_, Bt_) do { __builtin_amdgcn_s_setprio(1); \
;     for (int k = 0; k < 2; ++k) for (int m = 0; m < 4; ++m) for (int n = 0; n < 2; ++n) \
;       acc[ai][bj][m][n] = __builtin_amdgcn_mfma_f32_16x16x32_bf16(At_[m][k], Bt_[n][k], acc[ai][bj][m][n], 0, 0, 0); \
;     __builtin_amdgcn_s_setprio(0); } while (0)
; #define WAIT_V(n) asm volatile("s_waitcnt vmcnt(" #n ")" ::: "memory")
; #define WAIT_L(n) asm volatile("s_waitcnt lgkmcnt(" #n ")" ::: "memory")
; #define BAR __builtin_amdgcn_s_barrier()
; template <int EPI, int lda, int ldb, int N, int K>
; __device__ __forceinline__ void gemm_phase(const u16* __restrict__ A, const u16* __restrict__ Bt, const GemmEpi ep, int wv) {
;     ...
;       LDB(B1, 0, 1); BAR; WAIT_L(0); MMA(0, 1, At, B1); BAR;
;       LDA(At, 0, 1); WAIT_V(4); BAR; WAIT_L(0); MMA(1, 0, At, B0); MMA(1, 1, At, B1); BAR; }
;     { LDB(B0, 1, 0); LDA(At, 1, 0); WAIT_V(2); BAR; WAIT_L(0); MMA(0, 0, At, B0); BAR;
	v_mfma_f32_16x16x32_bf16 v[186:189], v[214:217], v[206:209], v[68:71]
	v_mfma_f32_16x16x32_bf16 v[190:193], v[156:159], v[206:209], v[64:67]
	s_nop 0
	ds_read_b128 v[64:67], v151 offset:16384
	ds_read_b128 v[68:71], v151 offset:17408
	ds_read_b128 v[80:83], v150 offset:16384
	ds_read_b128 v[84:87], v150 offset:17408
	ds_read_b128 v[194:197], v149 offset:16384
	ds_read_b128 v[198:201], v149 offset:17408
	ds_read_b128 v[202:205], v148 offset:16384
	ds_read_b128 v[206:209], v148 offset:17408
	s_waitcnt vmcnt(4)
	s_barrier
	s_waitcnt lgkmcnt(0)
	v_mfma_f32_16x16x32_bf16 v[60:63], v[134:137], v[64:67], v[60:63]
	v_mfma_f32_16x16x32_bf16 v[56:59], v[170:173], v[64:67], v[56:59]
	v_mfma_f32_16x16x32_bf16 v[52:55], v[134:137], v[80:83], v[52:55]
	v_mfma_f32_16x16x32_bf16 v[48:51], v[170:173], v[80:83], v[48:51]
	v_mfma_f32_16x16x32_bf16 v[44:47], v[134:137], v[194:197], v[44:47]
	v_mfma_f32_16x16x32_bf16 v[40:43], v[170:173], v[194:197], v[40:43]
	v_mfma_f32_16x16x32_bf16 v[36:39], v[134:137], v[202:205], v[36:39]
	v_mfma_f32_16x16x32_bf16 v[32:35], v[170:173], v[202:205], v[32:35]
	v_mfma_f32_16x16x32_bf16 v[60:63], v[138:141], v[68:71], v[60:63]
	v_mfma_f32_16x16x32_bf16 v[56:59], v[174:177], v[68:71], v[56:59]
	v_mfma_f32_16x16x32_bf16 v[52:55], v[138:141], v[84:87], v[52:55]
	v_mfma_f32_16x16x32_bf16 v[48:51], v[174:177], v[84:87], v[48:51]
	v_mfma_f32_16x16x32_bf16 v[44:47], v[138:141], v[198:201], v[44:47]
	v_mfma_f32_16x16x32_bf16 v[40:43], v[174:177], v[198:201], v[40:43]
	v_mfma_f32_16x16x32_bf16 v[36:39], v[138:141], v[206:209], v[36:39]
	v_mfma_f32_16x16x32_bf16 v[32:35], v[174:177], v[206:209], v[32:35]
	v_mfma_f32_16x16x32_bf16 v[28:31], v[210:213], v[64:67], v[28:31]
	v_mfma_f32_16x16x32_bf16 v[20:23], v[210:213], v[80:83], v[20:23]
	v_mfma_f32_16x16x32_bf16 v[12:15], v[210:213], v[194:197], v[12:15]
	v_mfma_f32_16x16x32_bf16 v[4:7], v[210:213], v[202:205], v[4:7]
	v_mfma_f32_16x16x32_bf16 v[24:27], v[218:221], v[64:67], v[24:27]
	v_mfma_f32_16x16x32_bf16 v[16:19], v[218:221], v[80:83], v[16:19]
	v_mfma_f32_16x16x32_bf16 v[8:11], v[218:221], v[194:197], v[8:11]
	v_mfma_f32_16x16x32_bf16 v[0:3], v[218:221], v[202:205], v[0:3]
	v_mfma_f32_16x16x32_bf16 v[28:31], v[214:217], v[68:71], v[28:31]
	v_mfma_f32_16x16x32_bf16 v[20:23], v[214:217], v[84:87], v[20:23]
	v_mfma_f32_16x16x32_bf16 v[12:15], v[214:217], v[198:201], v[12:15]
	v_mfma_f32_16x16x32_bf16 v[4:7], v[214:217], v[206:209], v[4:7]
	v_mfma_f32_16x16x32_bf16 v[134:137], v[156:159], v[68:71], v[24:27]
	v_mfma_f32_16x16x32_bf16 v[138:141], v[156:159], v[84:87], v[16:19]
	s_barrier
	v_mfma_f32_16x16x32_bf16 v[168:171], v[156:159], v[198:201], v[8:11]
	v_mfma_f32_16x16x32_bf16 v[156:159], v[156:159], v[206:209], v[0:3]
	s_nop 0
	ds_read_b128 v[0:3], v154
	ds_read_b128 v[8:11], v154 offset:1024
	ds_read_b128 v[16:19], v154 offset:2048
	ds_read_b128 v[172:175], v154 offset:3072
	ds_read_b128 v[24:27], v151 offset:32768
	ds_read_b128 v[194:197], v151 offset:33792
	ds_read_b128 v[198:201], v150 offset:32768
	ds_read_b128 v[202:205], v150 offset:33792
	ds_read_b128 v[206:209], v149 offset:32768
	ds_read_b128 v[210:213], v149 offset:33792
	ds_read_b128 v[214:217], v148 offset:32768
	ds_read_b128 v[218:221], v148 offset:33792
	s_waitcnt vmcnt(2)
	s_barrier
	s_waitcnt lgkmcnt(0)
	v_mfma_f32_16x16x32_bf16 v[64:67], v[0:3], v[24:27], v[124:127]
	v_mfma_f32_16x16x32_bf16 v[68:71], v[16:19], v[24:27], v[120:123]
	v_mfma_f32_16x16x32_bf16 v[80:83], v[0:3], v[198:201], v[116:119]
	v_mfma_f32_16x16x32_bf16 v[84:87], v[16:19], v[198:201], v[112:115]
	v_mfma_f32_16x16x32_bf16 v[108:111], v[0:3], v[206:209], v[108:111]
	v_mfma_f32_16x16x32_bf16 v[104:107], v[16:19], v[206:209], v[104:107]
	v_mfma_f32_16x16x32_bf16 v[120:123], v[0:3], v[214:217], v[100:103]
	v_mfma_f32_16x16x32_bf16 v[124:127], v[16:19], v[214:217], v[96:99]
	v_mfma_f32_16x16x32_bf16 v[116:119], v[8:11], v[194:197], v[64:67]
	v_mfma_f32_16x16x32_bf16 v[112:115], v[172:175], v[194:197], v[68:71]
	v_mfma_f32_16x16x32_bf16 v[100:103], v[8:11], v[202:205], v[80:83]
	v_mfma_f32_16x16x32_bf16 v[96:99], v[172:175], v[202:205], v[84:87]
	v_mfma_f32_16x16x32_bf16 v[84:87], v[8:11], v[210:213], v[108:111]
	v_mfma_f32_16x16x32_bf16 v[80:83], v[172:175], v[210:213], v[104:107]
	s_barrier
; #define LDA(dst, b, h) for (int m = 0; m < 4; ++m) for (int k = 0; k < 2; ++k) \
;     dst[m][k] = *reinterpret_cast<const bf16x8*>((char*)SA(b, h) + lds_byte(wr * 64 + m * 16 + fr, k * 32 + fq * 8))
; #define LDB(dst, b, h) for (int n = 0; n < 2; ++n) for (int k = 0; k < 2; ++k) \
;     dst[n][k] = *reinterpret_cast<const bf16x8*>((char*)SB(b, h) + lds_byte(wc * 32 + n * 16 + fr, k * 32 + fq * 8))
; #define MMA(ai, bj, At_, Bt_) do { __builtin_amdgcn_s_setprio(1); \
;     for (int k = 0; k < 2; ++k) for (int m = 0; m < 4; ++m) for (int n = 0; n < 2; ++n) \
;       acc[ai][bj][m][n] = __builtin_amdgcn_mfma_f32_16x16x32_bf16(At_[m][k], Bt_[n][k], acc[ai][bj][m][n], 0, 0, 0); \
;     __builtin_amdgcn_s_setprio(0); } while (0)
; #define WAIT_V(n) asm volatile("s_waitcnt vmcnt(" #n ")" ::: "memory")
; #define WAIT_L(n) asm volatile("s_waitcnt lgkmcnt(" #n ")" ::: "memory")
; #define BAR __builtin_amdgcn_s_barrier()
; template <int EPI, int lda, int ldb, int N, int K>
; __device__ __forceinline__ void gemm_phase(const u16* __restrict__ A, const u16* __restrict__ Bt, const GemmEpi ep, int wv) {
;     ...
;     { LDB(B0, 1, 0); LDA(At, 1, 0); WAIT_V(2); BAR; WAIT_L(0); MMA(0, 0, At, B0); BAR;
;       LDB(B1, 1, 1); WAIT_V(0); BAR; WAIT_L(0); MMA(0, 1, At, B1); BAR;
;       LDA(At, 1, 1); BAR; WAIT_L(0); MMA(1, 0, At, B0); MMA(1, 1, At, B1); BAR; }
;     if (wr == 0) BAR;
	v_mfma_f32_16x16x32_bf16 v[68:71], v[8:11], v[218:221], v[120:123]
	v_mfma_f32_16x16x32_bf16 v[64:67], v[172:175], v[218:221], v[124:127]
	ds_read_b128 v[222:225], v152
	ds_read_b128 v[226:229], v152 offset:1024
	ds_read_b128 v[230:233], v152 offset:2048
	ds_read_b128 v[152:155], v152 offset:3072
	s_waitcnt vmcnt(0)
	s_barrier
	s_waitcnt lgkmcnt(0)
	v_mfma_f32_16x16x32_bf16 v[92:95], v[222:225], v[24:27], v[92:95]
	v_mfma_f32_16x16x32_bf16 v[24:27], v[230:233], v[24:27], v[88:91]
	v_mfma_f32_16x16x32_bf16 v[88:91], v[222:225], v[198:201], v[178:181]
	v_mfma_f32_16x16x32_bf16 v[104:107], v[230:233], v[198:201], v[182:185]
	v_mfma_f32_16x16x32_bf16 v[76:79], v[222:225], v[206:209], v[76:79]
	v_mfma_f32_16x16x32_bf16 v[72:75], v[230:233], v[206:209], v[72:75]
	v_mfma_f32_16x16x32_bf16 v[176:179], v[222:225], v[214:217], v[186:189]
	v_mfma_f32_16x16x32_bf16 v[180:183], v[230:233], v[214:217], v[190:193]
	v_mfma_f32_16x16x32_bf16 v[124:127], v[226:229], v[194:197], v[92:95]
	v_mfma_f32_16x16x32_bf16 v[120:123], v[152:155], v[194:197], v[24:27]
	v_mfma_f32_16x16x32_bf16 v[108:111], v[226:229], v[202:205], v[88:91]
	v_mfma_f32_16x16x32_bf16 v[104:107], v[152:155], v[202:205], v[104:107]
	v_mfma_f32_16x16x32_bf16 v[92:95], v[226:229], v[210:213], v[76:79]
	v_mfma_f32_16x16x32_bf16 v[88:91], v[152:155], v[210:213], v[72:75]
	s_barrier
	v_mfma_f32_16x16x32_bf16 v[76:79], v[226:229], v[218:221], v[176:179]
	v_mfma_f32_16x16x32_bf16 v[72:75], v[152:155], v[218:221], v[180:183]
	ds_read_b128 v[176:179], v151 offset:49152
	ds_read_b128 v[180:183], v151 offset:50176
	ds_read_b128 v[184:187], v150 offset:49152
	ds_read_b128 v[188:191], v150 offset:50176
	ds_read_b128 v[192:195], v149 offset:49152
	ds_read_b128 v[196:199], v149 offset:50176
	ds_read_b128 v[200:203], v148 offset:49152
	ds_read_b128 v[148:151], v148 offset:50176
	s_barrier
	s_waitcnt lgkmcnt(0)
	v_mfma_f32_16x16x32_bf16 v[24:27], v[0:3], v[176:179], v[60:63]
	v_mfma_f32_16x16x32_bf16 v[60:63], v[16:19], v[176:179], v[56:59]
	v_mfma_f32_16x16x32_bf16 v[52:55], v[0:3], v[184:187], v[52:55]
	v_mfma_f32_16x16x32_bf16 v[204:207], v[16:19], v[184:187], v[48:51]
	v_mfma_f32_16x16x32_bf16 v[44:47], v[0:3], v[192:195], v[44:47]
	v_mfma_f32_16x16x32_bf16 v[208:211], v[16:19], v[192:195], v[40:43]
	v_mfma_f32_16x16x32_bf16 v[0:3], v[0:3], v[200:203], v[36:39]
	v_mfma_f32_16x16x32_bf16 v[36:39], v[16:19], v[200:203], v[32:35]
	v_mfma_f32_16x16x32_bf16 v[56:59], v[8:11], v[180:183], v[24:27]
	v_mfma_f32_16x16x32_bf16 v[48:51], v[172:175], v[180:183], v[60:63]
	v_mfma_f32_16x16x32_bf16 v[40:43], v[8:11], v[188:191], v[52:55]
	v_mfma_f32_16x16x32_bf16 v[32:35], v[172:175], v[188:191], v[204:207]
	v_mfma_f32_16x16x32_bf16 v[24:27], v[8:11], v[196:199], v[44:47]
	v_mfma_f32_16x16x32_bf16 v[16:19], v[172:175], v[196:199], v[208:211]
	v_mfma_f32_16x16x32_bf16 v[8:11], v[8:11], v[148:151], v[0:3]
	v_mfma_f32_16x16x32_bf16 v[0:3], v[172:175], v[148:151], v[36:39]
	v_mfma_f32_16x16x32_bf16 v[28:31], v[222:225], v[176:179], v[28:31]
	v_mfma_f32_16x16x32_bf16 v[36:39], v[230:233], v[176:179], v[134:137]
	v_mfma_f32_16x16x32_bf16 v[20:23], v[222:225], v[184:187], v[20:23]
	v_mfma_f32_16x16x32_bf16 v[134:137], v[230:233], v[184:187], v[138:141]
	v_mfma_f32_16x16x32_bf16 v[12:15], v[222:225], v[192:195], v[12:15]
	v_mfma_f32_16x16x32_bf16 v[138:141], v[230:233], v[192:195], v[168:171]
	v_mfma_f32_16x16x32_bf16 v[4:7], v[222:225], v[200:203], v[4:7]
	v_mfma_f32_16x16x32_bf16 v[156:159], v[230:233], v[200:203], v[156:159]
	v_mfma_f32_16x16x32_bf16 v[60:63], v[226:229], v[180:183], v[28:31]
	v_mfma_f32_16x16x32_bf16 v[52:55], v[152:155], v[180:183], v[36:39]
	v_mfma_f32_16x16x32_bf16 v[44:47], v[226:229], v[188:191], v[20:23]
	v_mfma_f32_16x16x32_bf16 v[36:39], v[152:155], v[188:191], v[134:137]
	v_mfma_f32_16x16x32_bf16 v[28:31], v[226:229], v[196:199], v[12:15]
	v_mfma_f32_16x16x32_bf16 v[20:23], v[152:155], v[196:199], v[138:141]
	s_barrier
	v_mfma_f32_16x16x32_bf16 v[12:15], v[226:229], v[148:151], v[4:7]
	v_mfma_f32_16x16x32_bf16 v[4:7], v[152:155], v[148:151], v[156:159]
	v_cmp_gt_u32_e32 vcc, s70, v130
	s_and_saveexec_b64 s[52:53], vcc
	s_cbranch_execz .LBB0_657
	s_barrier

; #define STAGE(P, BASE, LD, br, kt) do { const char* _g = (const char*)((BASE) + (size_t)(br) * (LD) + (size_t)(kt) * 64); \
;     for (int _i = 0; _i < 2; ++_i) { int _b = tidx * 16 + _i * 8192; int _r, _c; stage_rc(_b, _r, _c); \
;       __builtin_amdgcn_global_load_lds((const unsigned*)(_g + (unsigned)((_r * (LD) + _c) * 2)), (unsigned*)((char*)(P) + _b), 16, 0, 0); } } while (0)
; #define LDA(dst, b, h) for (int m = 0; m < 4; ++m) for (int k = 0; k < 2; ++k) \
;     dst[m][k] = *reinterpret_cast<const bf16x8*>((char*)SA(b, h) + lds_byte(wr * 64 + m * 16 + fr, k * 32 + fq * 8))
; #define LDB(dst, b, h) for (int n = 0; n < 2; ++n) for (int k = 0; k < 2; ++k) \
;     dst[n][k] = *reinterpret_cast<const bf16x8*>((char*)SB(b, h) + lds_byte(wc * 32 + n * 16 + fr, k * 32 + fq * 8))
; #define MMA(ai, bj, At_, Bt_) do { __builtin_amdgcn_s_setprio(1); \
;     for (int k = 0; k < 2; ++k) for (int m = 0; m < 4; ++m) for (int n = 0; n < 2; ++n) \
;       acc[ai][bj][m][n] = __builtin_amdgcn_mfma_f32_16x16x32_bf16(At_[m][k], Bt_[n][k], acc[ai][bj][m][n], 0, 0, 0); \
;     __builtin_amdgcn_s_setprio(0); } while (0)
; #define WAIT_L(n) asm volatile("s_waitcnt lgkmcnt(" #n ")" ::: "memory")
; #define BAR __builtin_amdgcn_s_barrier()
; #define SCHED __builtin_amdgcn_sched_barrier(0)
; template <int EPI, int lda, int ldb, int N, int K>
; __device__ __forceinline__ void gemm_phase(const u16* __restrict__ A, const u16* __restrict__ Bt, const GemmEpi ep, int wv) {
;     ...
;       LDB(B0, 0, 0); SCHED; LDA(At, 0, 0); STAGE(SA(1, 1), Ab, lda, brow + HALF, t + 1);
;       WAIT_L(8); BAR; WAIT_L(0); MMA(0, 0, At, B0); BAR; SCHED;
;       LDB(B1, 0, 1); STAGE(SB(0, 0), Bt, ldb, bcol, t + 2);
;       BAR; WAIT_L(0); MMA(0, 1, At, B1); BAR;
;       LDA(At, 0, 1); STAGE(SA(0, 0), Ab, lda, brow, t + 2);
;       BAR; WAIT_L(0); MMA(1, 0, At, B0); BAR; SCHED;
.LBB0_770:
	ds_read_b128 v[172:175], v161
	ds_read_b128 v[176:179], v161 offset:1024
	ds_read_b128 v[180:183], v161 offset:2048
	ds_read_b128 v[184:187], v161 offset:3072
	v_add_u32_e32 v169, 0xc000, v148
	v_lshl_add_u64 v[236:237], v[136:137], 0, s[50:51]
	v_readfirstlane_b32 s53, v169
	v_add_u32_e32 v170, 0xe000, v148
	v_lshl_add_u64 v[162:163], v[236:237], 0, s[18:19]
	s_mov_b32 m0, s53
	v_lshl_add_u64 v[238:239], v[134:135], 0, s[50:51]
	v_readfirstlane_b32 s53, v170
	ds_read_b128 v[164:167], v152
	ds_read_b128 v[188:191], v152 offset:1024
	ds_read_b128 v[192:195], v151
	ds_read_b128 v[196:199], v151 offset:1024
	ds_read_b128 v[200:203], v150
	ds_read_b128 v[204:207], v150 offset:1024
	ds_read_b128 v[208:211], v149
	ds_read_b128 v[212:215], v149 offset:1024
	global_load_lds_dwordx4 v[162:163], off
	v_lshl_add_u64 v[162:163], v[238:239], 0, s[18:19]
	s_mov_b32 m0, s53
	s_nop 0
	global_load_lds_dwordx4 v[162:163], off
	s_waitcnt lgkmcnt(8)
	s_barrier
	s_waitcnt lgkmcnt(0)
	v_mfma_f32_16x16x32_bf16 v[124:127], v[172:175], v[164:167], v[124:127]
	v_mfma_f32_16x16x32_bf16 v[120:123], v[180:183], v[164:167], v[120:123]
	v_mfma_f32_16x16x32_bf16 v[116:119], v[172:175], v[192:195], v[116:119]
	v_mfma_f32_16x16x32_bf16 v[112:115], v[180:183], v[192:195], v[112:115]
	v_mfma_f32_16x16x32_bf16 v[108:111], v[172:175], v[200:203], v[108:111]
	v_mfma_f32_16x16x32_bf16 v[104:107], v[180:183], v[200:203], v[104:107]
	v_mfma_f32_16x16x32_bf16 v[100:103], v[172:175], v[208:211], v[100:103]
	v_mfma_f32_16x16x32_bf16 v[96:99], v[180:183], v[208:211], v[96:99]
	v_mfma_f32_16x16x32_bf16 v[124:127], v[176:179], v[188:191], v[124:127]
	v_mfma_f32_16x16x32_bf16 v[120:123], v[184:187], v[188:191], v[120:123]
	v_mfma_f32_16x16x32_bf16 v[116:119], v[176:179], v[196:199], v[116:119]
	v_mfma_f32_16x16x32_bf16 v[112:115], v[184:187], v[196:199], v[112:115]
	v_mfma_f32_16x16x32_bf16 v[108:111], v[176:179], v[204:207], v[108:111]
	v_mfma_f32_16x16x32_bf16 v[104:107], v[184:187], v[204:207], v[104:107]
	s_barrier
	v_mfma_f32_16x16x32_bf16 v[100:103], v[176:179], v[212:215], v[100:103]
	v_mfma_f32_16x16x32_bf16 v[96:99], v[184:187], v[212:215], v[96:99]
	v_add_u32_e32 v162, s64, v153
	v_lshl_add_u64 v[240:241], v[140:141], 0, s[50:51]
	v_readfirstlane_b32 s53, v162
	v_add_u32_e32 v163, 0x2000, v162
	v_lshl_add_u64 v[232:233], v[240:241], 0, s[20:21]
	s_mov_b32 m0, s53
	v_lshl_add_u64 v[242:243], v[138:139], 0, s[50:51]
	v_readfirstlane_b32 s53, v163
	ds_read_b128 v[216:219], v160
	ds_read_b128 v[220:223], v160 offset:1024
	ds_read_b128 v[224:227], v160 offset:2048
	ds_read_b128 v[228:231], v160 offset:3072
	global_load_lds_dwordx4 v[232:233], off
	v_lshl_add_u64 v[232:233], v[242:243], 0, s[20:21]
	s_mov_b32 m0, s53
	s_nop 0
	global_load_lds_dwordx4 v[232:233], off
	s_barrier
	s_waitcnt lgkmcnt(0)
	v_mfma_f32_16x16x32_bf16 v[92:95], v[216:219], v[164:167], v[92:95]
	v_mfma_f32_16x16x32_bf16 v[88:91], v[224:227], v[164:167], v[88:91]
	v_mfma_f32_16x16x32_bf16 v[84:87], v[216:219], v[192:195], v[84:87]
	v_mfma_f32_16x16x32_bf16 v[80:83], v[224:227], v[192:195], v[80:83]
	v_mfma_f32_16x16x32_bf16 v[76:79], v[216:219], v[200:203], v[76:79]
	v_mfma_f32_16x16x32_bf16 v[72:75], v[224:227], v[200:203], v[72:75]
	v_mfma_f32_16x16x32_bf16 v[68:71], v[216:219], v[208:211], v[68:71]
	v_mfma_f32_16x16x32_bf16 v[64:67], v[224:227], v[208:211], v[64:67]
	v_mfma_f32_16x16x32_bf16 v[92:95], v[220:223], v[188:191], v[92:95]
	v_mfma_f32_16x16x32_bf16 v[88:91], v[228:231], v[188:191], v[88:91]
	v_mfma_f32_16x16x32_bf16 v[84:87], v[220:223], v[196:199], v[84:87]
	v_mfma_f32_16x16x32_bf16 v[80:83], v[228:231], v[196:199], v[80:83]
	v_mfma_f32_16x16x32_bf16 v[76:79], v[220:223], v[204:207], v[76:79]
	v_mfma_f32_16x16x32_bf16 v[72:75], v[228:231], v[204:207], v[72:75]
	s_barrier
	v_mfma_f32_16x16x32_bf16 v[68:71], v[220:223], v[212:215], v[68:71]
	v_mfma_f32_16x16x32_bf16 v[64:67], v[228:231], v[212:215], v[64:67]
	v_readfirstlane_b32 s53, v148
	v_lshl_add_u64 v[164:165], v[236:237], 0, s[22:23]
	s_mov_b32 m0, s53
	ds_read_b128 v[188:191], v152 offset:16384
	ds_read_b128 v[192:195], v152 offset:17408
	ds_read_b128 v[196:199], v151 offset:16384
	ds_read_b128 v[200:203], v151 offset:17408
	ds_read_b128 v[204:207], v150 offset:16384
	ds_read_b128 v[208:211], v150 offset:17408
	ds_read_b128 v[212:215], v149 offset:16384
	ds_read_b128 v[232:235], v149 offset:17408
	global_load_lds_dwordx4 v[164:165], off
	v_add_u32_e32 v164, 0x2000, v148
	v_lshl_add_u64 v[166:167], v[238:239], 0, s[22:23]
	v_readfirstlane_b32 s53, v164
	s_mov_b32 m0, s53
	s_nop 0
	global_load_lds_dwordx4 v[166:167], off
	s_barrier
	s_waitcnt lgkmcnt(0)
	v_mfma_f32_16x16x32_bf16 v[60:63], v[172:175], v[188:191], v[60:63]
	v_mfma_f32_16x16x32_bf16 v[56:59], v[180:183], v[188:191], v[56:59]
	v_mfma_f32_16x16x32_bf16 v[52:55], v[172:175], v[196:199], v[52:55]
	v_mfma_f32_16x16x32_bf16 v[48:51], v[180:183], v[196:199], v[48:51]
	v_mfma_f32_16x16x32_bf16 v[44:47], v[172:175], v[204:207], v[44:47]
	v_mfma_f32_16x16x32_bf16 v[40:43], v[180:183], v[204:207], v[40:43]
	v_mfma_f32_16x16x32_bf16 v[36:39], v[172:175], v[212:215], v[36:39]
	v_mfma_f32_16x16x32_bf16 v[32:35], v[180:183], v[212:215], v[32:35]
	v_mfma_f32_16x16x32_bf16 v[60:63], v[176:179], v[192:195], v[60:63]
	v_mfma_f32_16x16x32_bf16 v[56:59], v[184:187], v[192:195], v[56:59]
	v_mfma_f32_16x16x32_bf16 v[52:55], v[176:179], v[200:203], v[52:55]
	v_mfma_f32_16x16x32_bf16 v[48:51], v[184:187], v[200:203], v[48:51]
	v_mfma_f32_16x16x32_bf16 v[44:47], v[176:179], v[208:211], v[44:47]
	v_mfma_f32_16x16x32_bf16 v[40:43], v[184:187], v[208:211], v[40:43]
	s_barrier
; #define STAGE(P, BASE, LD, br, kt) do { const char* _g = (const char*)((BASE) + (size_t)(br) * (LD) + (size_t)(kt) * 64); \
;     for (int _i = 0; _i < 2; ++_i) { int _b = tidx * 16 + _i * 8192; int _r, _c; stage_rc(_b, _r, _c); \
;       __builtin_amdgcn_global_load_lds((const unsigned*)(_g + (unsigned)((_r * (LD) + _c) * 2)), (unsigned*)((char*)(P) + _b), 16, 0, 0); } } while (0)
; #define LDA(dst, b, h) for (int m = 0; m < 4; ++m) for (int k = 0; k < 2; ++k) \
;     dst[m][k] = *reinterpret_cast<const bf16x8*>((char*)SA(b, h) + lds_byte(wr * 64 + m * 16 + fr, k * 32 + fq * 8))
; #define LDB(dst, b, h) for (int n = 0; n < 2; ++n) for (int k = 0; k < 2; ++k) \
;     dst[n][k] = *reinterpret_cast<const bf16x8*>((char*)SB(b, h) + lds_byte(wc * 32 + n * 16 + fr, k * 32 + fq * 8))
; #define MMA(ai, bj, At_, Bt_) do { __builtin_amdgcn_s_setprio(1); \
;     for (int k = 0; k < 2; ++k) for (int m = 0; m < 4; ++m) for (int n = 0; n < 2; ++n) \
;       acc[ai][bj][m][n] = __builtin_amdgcn_mfma_f32_16x16x32_bf16(At_[m][k], Bt_[n][k], acc[ai][bj][m][n], 0, 0, 0); \
;     __builtin_amdgcn_s_setprio(0); } while (0)
; #define WAIT_V(n) asm volatile("s_waitcnt vmcnt(" #n ")" ::: "memory")
; #define WAIT_L(n) asm volatile("s_waitcnt lgkmcnt(" #n ")" ::: "memory")
; #define BAR __builtin_amdgcn_s_barrier()
; #define SCHED __builtin_amdgcn_sched_barrier(0)
; template <int EPI, int lda, int ldb, int N, int K>
; __device__ __forceinline__ void gemm_phase(const u16* __restrict__ A, const u16* __restrict__ Bt, const GemmEpi ep, int wv) {
;     ...
;       BAR; WAIT_L(0); MMA(1, 0, At, B0); BAR; SCHED;
;       STAGE(SB(0, 1), Bt, ldb, bcol + HALF, t + 2);
;       WAIT_V(6); BAR; MMA(1, 1, At, B1); BAR;
;       LDB(B0, 1, 0); SCHED; LDA(At, 1, 0); STAGE(SA(0, 1), Ab, lda, brow + HALF, t + 2);
;       WAIT_L(8); BAR; WAIT_L(0); MMA(0, 0, At, B0); BAR; SCHED;
;       LDB(B1, 1, 1); STAGE(SB(1, 0), Bt, ldb, bcol, t + 3);
;       BAR; WAIT_L(0); MMA(0, 1, At, B1); BAR;
	v_mfma_f32_16x16x32_bf16 v[36:39], v[176:179], v[232:235], v[36:39]
	v_mfma_f32_16x16x32_bf16 v[32:35], v[184:187], v[232:235], v[32:35]
	v_add_u32_e32 v165, s65, v153
	v_lshl_add_u64 v[166:167], v[240:241], 0, s[24:25]
	v_readfirstlane_b32 s53, v165
	s_mov_b32 m0, s53
	v_lshl_add_u64 v[172:173], v[242:243], 0, s[24:25]
	global_load_lds_dwordx4 v[166:167], off
	v_add_u32_e32 v166, 0x2000, v165
	s_nop 0
	v_readfirstlane_b32 s53, v166
	s_mov_b32 m0, s53
	s_nop 0
	global_load_lds_dwordx4 v[172:173], off
	s_waitcnt vmcnt(6)
	s_barrier
	v_mfma_f32_16x16x32_bf16 v[28:31], v[216:219], v[188:191], v[28:31]
	v_mfma_f32_16x16x32_bf16 v[24:27], v[224:227], v[188:191], v[24:27]
	v_mfma_f32_16x16x32_bf16 v[20:23], v[216:219], v[196:199], v[20:23]
	v_mfma_f32_16x16x32_bf16 v[16:19], v[224:227], v[196:199], v[16:19]
	v_mfma_f32_16x16x32_bf16 v[12:15], v[216:219], v[204:207], v[12:15]
	v_mfma_f32_16x16x32_bf16 v[8:11], v[224:227], v[204:207], v[8:11]
	v_mfma_f32_16x16x32_bf16 v[4:7], v[216:219], v[212:215], v[4:7]
	v_mfma_f32_16x16x32_bf16 v[0:3], v[224:227], v[212:215], v[0:3]
	v_mfma_f32_16x16x32_bf16 v[28:31], v[220:223], v[192:195], v[28:31]
	v_mfma_f32_16x16x32_bf16 v[24:27], v[228:231], v[192:195], v[24:27]
	v_mfma_f32_16x16x32_bf16 v[20:23], v[220:223], v[200:203], v[20:23]
	v_mfma_f32_16x16x32_bf16 v[16:19], v[228:231], v[200:203], v[16:19]
	v_mfma_f32_16x16x32_bf16 v[12:15], v[220:223], v[208:211], v[12:15]
	v_mfma_f32_16x16x32_bf16 v[8:11], v[228:231], v[208:211], v[8:11]
	s_barrier
	v_mfma_f32_16x16x32_bf16 v[4:7], v[220:223], v[232:235], v[4:7]
	v_mfma_f32_16x16x32_bf16 v[0:3], v[228:231], v[232:235], v[0:3]
	ds_read_b128 v[172:175], v156
	ds_read_b128 v[176:179], v156 offset:1024
	ds_read_b128 v[180:183], v156 offset:2048
	ds_read_b128 v[184:187], v156 offset:3072
	v_add_u32_e32 v167, 0x4000, v148
	v_add_u32_e32 v168, 0x6000, v148
	v_readfirstlane_b32 s53, v167
	v_lshl_add_u64 v[220:221], v[236:237], 0, s[26:27]
	s_mov_b32 m0, s53
	v_readfirstlane_b32 s53, v168
	ds_read_b128 v[188:191], v152 offset:32768
	ds_read_b128 v[192:195], v152 offset:33792
	ds_read_b128 v[196:199], v151 offset:32768
	ds_read_b128 v[200:203], v151 offset:33792
	ds_read_b128 v[204:207], v150 offset:32768
	ds_read_b128 v[208:211], v150 offset:33792
	ds_read_b128 v[212:215], v149 offset:32768
	ds_read_b128 v[216:219], v149 offset:33792
	global_load_lds_dwordx4 v[220:221], off
	v_lshl_add_u64 v[220:221], v[238:239], 0, s[26:27]
	s_mov_b32 m0, s53
	s_nop 0
	global_load_lds_dwordx4 v[220:221], off
	s_waitcnt lgkmcnt(8)
	s_barrier
	s_waitcnt lgkmcnt(0)
	v_mfma_f32_16x16x32_bf16 v[124:127], v[172:175], v[188:191], v[124:127]
	v_mfma_f32_16x16x32_bf16 v[120:123], v[180:183], v[188:191], v[120:123]
	v_mfma_f32_16x16x32_bf16 v[116:119], v[172:175], v[196:199], v[116:119]
	v_mfma_f32_16x16x32_bf16 v[112:115], v[180:183], v[196:199], v[112:115]
	v_mfma_f32_16x16x32_bf16 v[108:111], v[172:175], v[204:207], v[108:111]
	v_mfma_f32_16x16x32_bf16 v[104:107], v[180:183], v[204:207], v[104:107]
	v_mfma_f32_16x16x32_bf16 v[100:103], v[172:175], v[212:215], v[100:103]
	v_mfma_f32_16x16x32_bf16 v[96:99], v[180:183], v[212:215], v[96:99]
	v_mfma_f32_16x16x32_bf16 v[124:127], v[176:179], v[192:195], v[124:127]
	v_mfma_f32_16x16x32_bf16 v[120:123], v[184:187], v[192:195], v[120:123]
	v_mfma_f32_16x16x32_bf16 v[116:119], v[176:179], v[200:203], v[116:119]
	v_mfma_f32_16x16x32_bf16 v[112:115], v[184:187], v[200:203], v[112:115]
	v_mfma_f32_16x16x32_bf16 v[108:111], v[176:179], v[208:211], v[108:111]
	v_mfma_f32_16x16x32_bf16 v[104:107], v[184:187], v[208:211], v[104:107]
	s_barrier
	v_mfma_f32_16x16x32_bf16 v[100:103], v[176:179], v[216:219], v[100:103]
	v_mfma_f32_16x16x32_bf16 v[96:99], v[184:187], v[216:219], v[96:99]
	v_readfirstlane_b32 s53, v155
	v_add_u32_e32 v171, 0x2000, v155
	v_lshl_add_u64 v[244:245], v[240:241], 0, s[40:41]
	s_mov_b32 m0, s53
	v_readfirstlane_b32 s53, v171
	ds_read_b128 v[220:223], v154
	ds_read_b128 v[224:227], v154 offset:1024
	ds_read_b128 v[228:231], v154 offset:2048
	ds_read_b128 v[232:235], v154 offset:3072
	global_load_lds_dwordx4 v[244:245], off
	v_lshl_add_u64 v[244:245], v[242:243], 0, s[40:41]
	s_mov_b32 m0, s53
	s_nop 0
	global_load_lds_dwordx4 v[244:245], off
	s_barrier
	s_waitcnt lgkmcnt(0)
	v_mfma_f32_16x16x32_bf16 v[92:95], v[220:223], v[188:191], v[92:95]
	v_mfma_f32_16x16x32_bf16 v[88:91], v[228:231], v[188:191], v[88:91]
	v_mfma_f32_16x16x32_bf16 v[84:87], v[220:223], v[196:199], v[84:87]
	v_mfma_f32_16x16x32_bf16 v[80:83], v[228:231], v[196:199], v[80:83]
	v_mfma_f32_16x16x32_bf16 v[76:79], v[220:223], v[204:207], v[76:79]
	v_mfma_f32_16x16x32_bf16 v[72:75], v[228:231], v[204:207], v[72:75]
	v_mfma_f32_16x16x32_bf16 v[68:71], v[220:223], v[212:215], v[68:71]
	v_mfma_f32_16x16x32_bf16 v[64:67], v[228:231], v[212:215], v[64:67]
	v_mfma_f32_16x16x32_bf16 v[92:95], v[224:227], v[192:195], v[92:95]
	v_mfma_f32_16x16x32_bf16 v[88:91], v[232:235], v[192:195], v[88:91]
	v_mfma_f32_16x16x32_bf16 v[84:87], v[224:227], v[200:203], v[84:87]
	v_mfma_f32_16x16x32_bf16 v[80:83], v[232:235], v[200:203], v[80:83]
	v_mfma_f32_16x16x32_bf16 v[76:79], v[224:227], v[208:211], v[76:79]
	v_mfma_f32_16x16x32_bf16 v[72:75], v[232:235], v[208:211], v[72:75]
	s_barrier
	v_mfma_f32_16x16x32_bf16 v[68:71], v[224:227], v[216:219], v[68:71]
	v_mfma_f32_16x16x32_bf16 v[64:67], v[232:235], v[216:219], v[64:67]
	v_readfirstlane_b32 s53, v157
	v_lshl_add_u64 v[236:237], v[236:237], 0, s[42:43]
	s_mov_b32 m0, s53
	v_readfirstlane_b32 s53, v158
	ds_read_b128 v[188:191], v152 offset:49152
	ds_read_b128 v[192:195], v152 offset:50176
	ds_read_b128 v[196:199], v151 offset:49152
	ds_read_b128 v[200:203], v151 offset:50176
	ds_read_b128 v[204:207], v150 offset:49152
	ds_read_b128 v[208:211], v150 offset:50176
	ds_read_b128 v[212:215], v149 offset:49152
	ds_read_b128 v[216:219], v149 offset:50176
	global_load_lds_dwordx4 v[236:237], off
	v_lshl_add_u64 v[236:237], v[238:239], 0, s[42:43]
	s_mov_b32 m0, s53
	s_nop 0
	global_load_lds_dwordx4 v[236:237], off
	s_barrier
; #define STAGE(P, BASE, LD, br, kt) do { const char* _g = (const char*)((BASE) + (size_t)(br) * (LD) + (size_t)(kt) * 64); \
;     for (int _i = 0; _i < 2; ++_i) { int _b = tidx * 16 + _i * 8192; int _r, _c; stage_rc(_b, _r, _c); \
;       __builtin_amdgcn_global_load_lds((const unsigned*)(_g + (unsigned)((_r * (LD) + _c) * 2)), (unsigned*)((char*)(P) + _b), 16, 0, 0); } } while (0)
; #define LDA(dst, b, h) for (int m = 0; m < 4; ++m) for (int k = 0; k < 2; ++k) \
;     dst[m][k] = *reinterpret_cast<const bf16x8*>((char*)SA(b, h) + lds_byte(wr * 64 + m * 16 + fr, k * 32 + fq * 8))
; #define LDB(dst, b, h) for (int n = 0; n < 2; ++n) for (int k = 0; k < 2; ++k) \
;     dst[n][k] = *reinterpret_cast<const bf16x8*>((char*)SB(b, h) + lds_byte(wc * 32 + n * 16 + fr, k * 32 + fq * 8))
; #define MMA(ai, bj, At_, Bt_) do { __builtin_amdgcn_s_setprio(1); \
;     for (int k = 0; k < 2; ++k) for (int m = 0; m < 4; ++m) for (int n = 0; n < 2; ++n) \
;       acc[ai][bj][m][n] = __builtin_amdgcn_mfma_f32_16x16x32_bf16(At_[m][k], Bt_[n][k], acc[ai][bj][m][n], 0, 0, 0); \
;     __builtin_amdgcn_s_setprio(0); } while (0)
; #define WAIT_V(n) asm volatile("s_waitcnt vmcnt(" #n ")" ::: "memory")
; #define WAIT_L(n) asm volatile("s_waitcnt lgkmcnt(" #n ")" ::: "memory")
; #define BAR __builtin_amdgcn_s_barrier()
; #define SCHED __builtin_amdgcn_sched_barrier(0)
; template <int EPI, int lda, int ldb, int N, int K>
; __device__ __forceinline__ void gemm_phase(const u16* __restrict__ A, const u16* __restrict__ Bt, const GemmEpi ep, int wv) {
;     ...
;       BAR; WAIT_L(0); MMA(0, 1, At, B1); BAR;
;       LDA(At, 1, 1); STAGE(SA(1, 0), Ab, lda, brow, t + 3);
;       BAR; WAIT_L(0); MMA(1, 0, At, B0); BAR; SCHED;
;       STAGE(SB(1, 1), Bt, ldb, bcol + HALF, t + 3);
;       WAIT_V(6); BAR; MMA(1, 1, At, B1); BAR;
;     }
;     { LDB(B0, 0, 0); LDA(At, 0, 0); STAGE(SA(1, 1), Ab, lda, brow + HALF, nt - 1);
;       BAR; WAIT_L(0); MMA(0, 0, At, B0); BAR;
;       LDB(B1, 0, 1); BAR; WAIT_L(0); MMA(0, 1, At, B1); BAR;
	s_waitcnt lgkmcnt(0)
	v_mfma_f32_16x16x32_bf16 v[60:63], v[172:175], v[188:191], v[60:63]
	v_mfma_f32_16x16x32_bf16 v[56:59], v[180:183], v[188:191], v[56:59]
	v_mfma_f32_16x16x32_bf16 v[52:55], v[172:175], v[196:199], v[52:55]
	v_mfma_f32_16x16x32_bf16 v[48:51], v[180:183], v[196:199], v[48:51]
	v_mfma_f32_16x16x32_bf16 v[44:47], v[172:175], v[204:207], v[44:47]
	v_mfma_f32_16x16x32_bf16 v[40:43], v[180:183], v[204:207], v[40:43]
	v_mfma_f32_16x16x32_bf16 v[36:39], v[172:175], v[212:215], v[36:39]
	v_mfma_f32_16x16x32_bf16 v[32:35], v[180:183], v[212:215], v[32:35]
	v_mfma_f32_16x16x32_bf16 v[60:63], v[176:179], v[192:195], v[60:63]
	v_mfma_f32_16x16x32_bf16 v[56:59], v[184:187], v[192:195], v[56:59]
	v_mfma_f32_16x16x32_bf16 v[52:55], v[176:179], v[200:203], v[52:55]
	v_mfma_f32_16x16x32_bf16 v[48:51], v[184:187], v[200:203], v[48:51]
	v_mfma_f32_16x16x32_bf16 v[44:47], v[176:179], v[208:211], v[44:47]
	v_mfma_f32_16x16x32_bf16 v[40:43], v[184:187], v[208:211], v[40:43]
	s_barrier
	v_mfma_f32_16x16x32_bf16 v[36:39], v[176:179], v[216:219], v[36:39]
	v_mfma_f32_16x16x32_bf16 v[32:35], v[184:187], v[216:219], v[32:35]
	v_readfirstlane_b32 s53, v159
	v_add_u32_e32 v171, 0x2000, v159
	v_lshl_add_u64 v[172:173], v[240:241], 0, s[44:45]
	s_mov_b32 m0, s53
	v_readfirstlane_b32 s53, v171
	global_load_lds_dwordx4 v[172:173], off
	v_lshl_add_u64 v[172:173], v[242:243], 0, s[44:45]
	s_mov_b32 m0, s53
	s_nop 0
	global_load_lds_dwordx4 v[172:173], off
	s_waitcnt vmcnt(6)
	s_barrier
	v_mfma_f32_16x16x32_bf16 v[28:31], v[220:223], v[188:191], v[28:31]
	v_mfma_f32_16x16x32_bf16 v[24:27], v[228:231], v[188:191], v[24:27]
	v_mfma_f32_16x16x32_bf16 v[20:23], v[220:223], v[196:199], v[20:23]
	v_mfma_f32_16x16x32_bf16 v[16:19], v[228:231], v[196:199], v[16:19]
	v_mfma_f32_16x16x32_bf16 v[12:15], v[220:223], v[204:207], v[12:15]
	v_mfma_f32_16x16x32_bf16 v[8:11], v[228:231], v[204:207], v[8:11]
	v_mfma_f32_16x16x32_bf16 v[4:7], v[220:223], v[212:215], v[4:7]
	v_mfma_f32_16x16x32_bf16 v[0:3], v[228:231], v[212:215], v[0:3]
	v_mfma_f32_16x16x32_bf16 v[28:31], v[224:227], v[192:195], v[28:31]
	v_mfma_f32_16x16x32_bf16 v[24:27], v[232:235], v[192:195], v[24:27]
	v_mfma_f32_16x16x32_bf16 v[20:23], v[224:227], v[200:203], v[20:23]
	v_mfma_f32_16x16x32_bf16 v[16:19], v[232:235], v[200:203], v[16:19]
	v_mfma_f32_16x16x32_bf16 v[12:15], v[224:227], v[208:211], v[12:15]
	v_mfma_f32_16x16x32_bf16 v[8:11], v[232:235], v[208:211], v[8:11]
	s_barrier
	v_mfma_f32_16x16x32_bf16 v[4:7], v[224:227], v[216:219], v[4:7]
	v_mfma_f32_16x16x32_bf16 v[0:3], v[232:235], v[216:219], v[0:3]
	s_add_i32 s52, s52, 2
	s_add_u32 s50, s50, 0x100
	s_addc_u32 s51, s51, 0
	s_cmp_gt_u32 s52, 27
	s_cbranch_scc0 .LBB0_770
	s_add_i32 s50, s48, 0x80
	s_mul_hi_i32 s51, s50, 0x1080
	s_mulk_i32 s50, 0x1080
	s_add_u32 s50, s61, s50
	s_addc_u32 s51, s62, s51
	v_lshl_add_u64 v[158:159], s[50:51], 0, v[128:129]
	v_readfirstlane_b32 s52, v169
	v_lshl_add_u64 v[158:159], v[158:159], 0, s[46:47]
	s_mov_b32 m0, s52
	ds_read_b128 v[134:137], v161
	ds_read_b128 v[138:141], v161 offset:1024
	ds_read_b128 v[172:175], v161 offset:2048
	ds_read_b128 v[176:179], v161 offset:3072
	ds_read_b128 v[180:183], v152
	ds_read_b128 v[184:187], v152 offset:1024
	ds_read_b128 v[188:191], v151
	ds_read_b128 v[192:195], v151 offset:1024
	ds_read_b128 v[196:199], v150
	ds_read_b128 v[200:203], v150 offset:1024
	ds_read_b128 v[204:207], v149
	ds_read_b128 v[208:211], v149 offset:1024
	global_load_lds_dwordx4 v[158:159], off
	v_lshl_add_u64 v[158:159], s[50:51], 0, v[132:133]
	v_readfirstlane_b32 s50, v170
	v_lshl_add_u64 v[158:159], v[158:159], 0, s[46:47]
	s_mov_b32 m0, s50
	s_nop 0
	global_load_lds_dwordx4 v[158:159], off
	s_barrier
	s_waitcnt lgkmcnt(0)
	v_mfma_f32_16x16x32_bf16 v[124:127], v[134:137], v[180:183], v[124:127]
	v_mfma_f32_16x16x32_bf16 v[120:123], v[172:175], v[180:183], v[120:123]
	v_mfma_f32_16x16x32_bf16 v[116:119], v[134:137], v[188:191], v[116:119]
	v_mfma_f32_16x16x32_bf16 v[112:115], v[172:175], v[188:191], v[112:115]
	v_mfma_f32_16x16x32_bf16 v[108:111], v[134:137], v[196:199], v[108:111]
	v_mfma_f32_16x16x32_bf16 v[104:107], v[172:175], v[196:199], v[104:107]
	v_mfma_f32_16x16x32_bf16 v[100:103], v[134:137], v[204:207], v[100:103]
	v_mfma_f32_16x16x32_bf16 v[96:99], v[172:175], v[204:207], v[96:99]
	v_mfma_f32_16x16x32_bf16 v[124:127], v[138:141], v[184:187], v[124:127]
	v_mfma_f32_16x16x32_bf16 v[120:123], v[176:179], v[184:187], v[120:123]
	v_mfma_f32_16x16x32_bf16 v[116:119], v[138:141], v[192:195], v[116:119]
	v_mfma_f32_16x16x32_bf16 v[112:115], v[176:179], v[192:195], v[112:115]
	v_mfma_f32_16x16x32_bf16 v[108:111], v[138:141], v[200:203], v[108:111]
	v_mfma_f32_16x16x32_bf16 v[104:107], v[176:179], v[200:203], v[104:107]
	s_barrier
	v_mfma_f32_16x16x32_bf16 v[100:103], v[138:141], v[208:211], v[100:103]
	v_mfma_f32_16x16x32_bf16 v[96:99], v[176:179], v[208:211], v[96:99]
	ds_read_b128 v[212:215], v160
	ds_read_b128 v[216:219], v160 offset:1024
	ds_read_b128 v[220:223], v160 offset:2048
	ds_read_b128 v[158:161], v160 offset:3072
	s_barrier
	s_waitcnt lgkmcnt(0)
	v_mfma_f32_16x16x32_bf16 v[92:95], v[212:215], v[180:183], v[92:95]
	v_mfma_f32_16x16x32_bf16 v[88:91], v[220:223], v[180:183], v[88:91]
	v_mfma_f32_16x16x32_bf16 v[76:79], v[212:215], v[196:199], v[76:79]
	v_mfma_f32_16x16x32_bf16 v[72:75], v[220:223], v[196:199], v[72:75]
	v_mfma_f32_16x16x32_bf16 v[84:87], v[212:215], v[188:191], v[84:87]
	v_mfma_f32_16x16x32_bf16 v[80:83], v[220:223], v[188:191], v[80:83]
	v_mfma_f32_16x16x32_bf16 v[68:71], v[212:215], v[204:207], v[68:71]
	v_mfma_f32_16x16x32_bf16 v[64:67], v[220:223], v[204:207], v[64:67]
	v_mfma_f32_16x16x32_bf16 v[92:95], v[216:219], v[184:187], v[92:95]
	v_mfma_f32_16x16x32_bf16 v[88:91], v[158:161], v[184:187], v[88:91]
	v_mfma_f32_16x16x32_bf16 v[76:79], v[216:219], v[200:203], v[76:79]
	v_mfma_f32_16x16x32_bf16 v[72:75], v[158:161], v[200:203], v[72:75]
	v_mfma_f32_16x16x32_bf16 v[180:183], v[216:219], v[192:195], v[84:87]
	v_mfma_f32_16x16x32_bf16 v[184:187], v[158:161], v[192:195], v[80:83]
	s_barrier
; #define LDA(dst, b, h) for (int m = 0; m < 4; ++m) for (int k = 0; k < 2; ++k) \
;     dst[m][k] = *reinterpret_cast<const bf16x8*>((char*)SA(b, h) + lds_byte(wr * 64 + m * 16 + fr, k * 32 + fq * 8))
; #define LDB(dst, b, h) for (int n = 0; n < 2; ++n) for (int k = 0; k < 2; ++k) \
;     dst[n][k] = *reinterpret_cast<const bf16x8*>((char*)SB(b, h) + lds_byte(wc * 32 + n * 16 + fr, k * 32 + fq * 8))
; #define MMA(ai, bj, At_, Bt_) do { __builtin_amdgcn_s_setprio(1); \
;     for (int k = 0; k < 2; ++k) for (int m = 0; m < 4; ++m) for (int n = 0; n < 2; ++n) \
;       acc[ai][bj][m][n] = __builtin_amdgcn_mfma_f32_16x16x32_bf16(At_[m][k], Bt_[n][k], acc[ai][bj][m][n], 0, 0, 0); \
;     __builtin_amdgcn_s_setprio(0); } while (0)
; #define WAIT_V(n) asm volatile("s_waitcnt vmcnt(" #n ")" ::: "memory")
; #define WAIT_L(n) asm volatile("s_waitcnt lgkmcnt(" #n ")" ::: "memory")
; #define BAR __builtin_amdgcn_s_barrier()
; template <int EPI, int lda, int ldb, int N, int K>
; __device__ __forceinline__ void gemm_phase(const u16* __restrict__ A, const u16* __restrict__ Bt, const GemmEpi ep, int wv) {
;     ...
;       LDB(B1, 0, 1); BAR; WAIT_L(0); MMA(0, 1, At, B1); BAR;
;       LDA(At, 0, 1); WAIT_V(4); BAR; WAIT_L(0); MMA(1, 0, At, B0); MMA(1, 1, At, B1); BAR; }
;     { LDB(B0, 1, 0); LDA(At, 1, 0); WAIT_V(2); BAR; WAIT_L(0); MMA(0, 0, At, B0); BAR;
	v_mfma_f32_16x16x32_bf16 v[188:191], v[216:219], v[208:211], v[68:71]
	v_mfma_f32_16x16x32_bf16 v[192:195], v[158:161], v[208:211], v[64:67]
	s_nop 0
	ds_read_b128 v[64:67], v152 offset:16384
	ds_read_b128 v[68:71], v152 offset:17408
	ds_read_b128 v[80:83], v151 offset:16384
	ds_read_b128 v[84:87], v151 offset:17408
	ds_read_b128 v[196:199], v150 offset:16384
	ds_read_b128 v[200:203], v150 offset:17408
	ds_read_b128 v[204:207], v149 offset:16384
	ds_read_b128 v[208:211], v149 offset:17408
	s_waitcnt vmcnt(4)
	s_barrier
	s_waitcnt lgkmcnt(0)
	v_mfma_f32_16x16x32_bf16 v[60:63], v[134:137], v[64:67], v[60:63]
	v_mfma_f32_16x16x32_bf16 v[56:59], v[172:175], v[64:67], v[56:59]
	v_mfma_f32_16x16x32_bf16 v[52:55], v[134:137], v[80:83], v[52:55]
	v_mfma_f32_16x16x32_bf16 v[48:51], v[172:175], v[80:83], v[48:51]
	v_mfma_f32_16x16x32_bf16 v[44:47], v[134:137], v[196:199], v[44:47]
	v_mfma_f32_16x16x32_bf16 v[40:43], v[172:175], v[196:199], v[40:43]
	v_mfma_f32_16x16x32_bf16 v[36:39], v[134:137], v[204:207], v[36:39]
	v_mfma_f32_16x16x32_bf16 v[32:35], v[172:175], v[204:207], v[32:35]
	v_mfma_f32_16x16x32_bf16 v[60:63], v[138:141], v[68:71], v[60:63]
	v_mfma_f32_16x16x32_bf16 v[56:59], v[176:179], v[68:71], v[56:59]
	v_mfma_f32_16x16x32_bf16 v[52:55], v[138:141], v[84:87], v[52:55]
	v_mfma_f32_16x16x32_bf16 v[48:51], v[176:179], v[84:87], v[48:51]
	v_mfma_f32_16x16x32_bf16 v[44:47], v[138:141], v[200:203], v[44:47]
	v_mfma_f32_16x16x32_bf16 v[40:43], v[176:179], v[200:203], v[40:43]
	v_mfma_f32_16x16x32_bf16 v[36:39], v[138:141], v[208:211], v[36:39]
	v_mfma_f32_16x16x32_bf16 v[32:35], v[176:179], v[208:211], v[32:35]
	v_mfma_f32_16x16x32_bf16 v[28:31], v[212:215], v[64:67], v[28:31]
	v_mfma_f32_16x16x32_bf16 v[24:27], v[220:223], v[64:67], v[24:27]
	v_mfma_f32_16x16x32_bf16 v[12:15], v[212:215], v[196:199], v[12:15]
	v_mfma_f32_16x16x32_bf16 v[8:11], v[220:223], v[196:199], v[8:11]
	v_mfma_f32_16x16x32_bf16 v[20:23], v[212:215], v[80:83], v[20:23]
	v_mfma_f32_16x16x32_bf16 v[16:19], v[220:223], v[80:83], v[16:19]
	v_mfma_f32_16x16x32_bf16 v[4:7], v[212:215], v[204:207], v[4:7]
	v_mfma_f32_16x16x32_bf16 v[0:3], v[220:223], v[204:207], v[0:3]
	v_mfma_f32_16x16x32_bf16 v[28:31], v[216:219], v[68:71], v[28:31]
	v_mfma_f32_16x16x32_bf16 v[24:27], v[158:161], v[68:71], v[24:27]
	v_mfma_f32_16x16x32_bf16 v[12:15], v[216:219], v[200:203], v[12:15]
	v_mfma_f32_16x16x32_bf16 v[8:11], v[158:161], v[200:203], v[8:11]
	v_mfma_f32_16x16x32_bf16 v[134:137], v[216:219], v[84:87], v[20:23]
	v_mfma_f32_16x16x32_bf16 v[138:141], v[158:161], v[84:87], v[16:19]
	s_barrier
	v_mfma_f32_16x16x32_bf16 v[170:173], v[216:219], v[208:211], v[4:7]
	v_mfma_f32_16x16x32_bf16 v[158:161], v[158:161], v[208:211], v[0:3]
	s_nop 0
	ds_read_b128 v[0:3], v156
	ds_read_b128 v[4:7], v156 offset:1024
	ds_read_b128 v[16:19], v156 offset:2048
	ds_read_b128 v[174:177], v156 offset:3072
	ds_read_b128 v[20:23], v152 offset:32768
	ds_read_b128 v[196:199], v152 offset:33792
	ds_read_b128 v[200:203], v151 offset:32768
	ds_read_b128 v[204:207], v151 offset:33792
	ds_read_b128 v[208:211], v150 offset:32768
	ds_read_b128 v[212:215], v150 offset:33792
	ds_read_b128 v[216:219], v149 offset:32768
	ds_read_b128 v[220:223], v149 offset:33792
	s_waitcnt vmcnt(2)
	s_barrier
	s_waitcnt lgkmcnt(0)
	v_mfma_f32_16x16x32_bf16 v[64:67], v[0:3], v[20:23], v[124:127]
	v_mfma_f32_16x16x32_bf16 v[68:71], v[16:19], v[20:23], v[120:123]
	v_mfma_f32_16x16x32_bf16 v[80:83], v[0:3], v[200:203], v[116:119]
	v_mfma_f32_16x16x32_bf16 v[84:87], v[16:19], v[200:203], v[112:115]
	v_mfma_f32_16x16x32_bf16 v[108:111], v[0:3], v[208:211], v[108:111]
	v_mfma_f32_16x16x32_bf16 v[104:107], v[16:19], v[208:211], v[104:107]
	v_mfma_f32_16x16x32_bf16 v[120:123], v[0:3], v[216:219], v[100:103]
	v_mfma_f32_16x16x32_bf16 v[124:127], v[16:19], v[216:219], v[96:99]
	v_mfma_f32_16x16x32_bf16 v[116:119], v[4:7], v[196:199], v[64:67]
	v_mfma_f32_16x16x32_bf16 v[112:115], v[174:177], v[196:199], v[68:71]
	v_mfma_f32_16x16x32_bf16 v[100:103], v[4:7], v[204:207], v[80:83]
	v_mfma_f32_16x16x32_bf16 v[96:99], v[174:177], v[204:207], v[84:87]
	v_mfma_f32_16x16x32_bf16 v[84:87], v[4:7], v[212:215], v[108:111]
	v_mfma_f32_16x16x32_bf16 v[80:83], v[174:177], v[212:215], v[104:107]
	s_barrier
; #define LDA(dst, b, h) for (int m = 0; m < 4; ++m) for (int k = 0; k < 2; ++k) \
;     dst[m][k] = *reinterpret_cast<const bf16x8*>((char*)SA(b, h) + lds_byte(wr * 64 + m * 16 + fr, k * 32 + fq * 8))
; #define LDB(dst, b, h) for (int n = 0; n < 2; ++n) for (int k = 0; k < 2; ++k) \
;     dst[n][k] = *reinterpret_cast<const bf16x8*>((char*)SB(b, h) + lds_byte(wc * 32 + n * 16 + fr, k * 32 + fq * 8))
; #define MMA(ai, bj, At_, Bt_) do { __builtin_amdgcn_s_setprio(1); \
;     for (int k = 0; k < 2; ++k) for (int m = 0; m < 4; ++m) for (int n = 0; n < 2; ++n) \
;       acc[ai][bj][m][n] = __builtin_amdgcn_mfma_f32_16x16x32_bf16(At_[m][k], Bt_[n][k], acc[ai][bj][m][n], 0, 0, 0); \
;     __builtin_amdgcn_s_setprio(0); } while (0)
; #define WAIT_V(n) asm volatile("s_waitcnt vmcnt(" #n ")" ::: "memory")
; #define WAIT_L(n) asm volatile("s_waitcnt lgkmcnt(" #n ")" ::: "memory")
; #define BAR __builtin_amdgcn_s_barrier()
; template <int EPI, int lda, int ldb, int N, int K>
; __device__ __forceinline__ void gemm_phase(const u16* __restrict__ A, const u16* __restrict__ Bt, const GemmEpi ep, int wv) {
;     ...
;     { LDB(B0, 1, 0); LDA(At, 1, 0); WAIT_V(2); BAR; WAIT_L(0); MMA(0, 0, At, B0); BAR;
;       LDB(B1, 1, 1); WAIT_V(0); BAR; WAIT_L(0); MMA(0, 1, At, B1); BAR;
;       LDA(At, 1, 1); BAR; WAIT_L(0); MMA(1, 0, At, B0); MMA(1, 1, At, B1); BAR; }
;     if (wr == 0) BAR;
	v_mfma_f32_16x16x32_bf16 v[68:71], v[4:7], v[220:223], v[120:123]
	v_mfma_f32_16x16x32_bf16 v[64:67], v[174:177], v[220:223], v[124:127]
	ds_read_b128 v[224:227], v154
	ds_read_b128 v[228:231], v154 offset:1024
	ds_read_b128 v[232:235], v154 offset:2048
	ds_read_b128 v[154:157], v154 offset:3072
	s_waitcnt vmcnt(0)
	s_barrier
	s_waitcnt lgkmcnt(0)
	v_mfma_f32_16x16x32_bf16 v[92:95], v[224:227], v[20:23], v[92:95]
	v_mfma_f32_16x16x32_bf16 v[20:23], v[232:235], v[20:23], v[88:91]
	v_mfma_f32_16x16x32_bf16 v[88:91], v[224:227], v[200:203], v[180:183]
	v_mfma_f32_16x16x32_bf16 v[104:107], v[232:235], v[200:203], v[184:187]
	v_mfma_f32_16x16x32_bf16 v[76:79], v[224:227], v[208:211], v[76:79]
	v_mfma_f32_16x16x32_bf16 v[72:75], v[232:235], v[208:211], v[72:75]
	v_mfma_f32_16x16x32_bf16 v[178:181], v[224:227], v[216:219], v[188:191]
	v_mfma_f32_16x16x32_bf16 v[182:185], v[232:235], v[216:219], v[192:195]
	v_mfma_f32_16x16x32_bf16 v[124:127], v[228:231], v[196:199], v[92:95]
	v_mfma_f32_16x16x32_bf16 v[120:123], v[154:157], v[196:199], v[20:23]
	v_mfma_f32_16x16x32_bf16 v[108:111], v[228:231], v[204:207], v[88:91]
	v_mfma_f32_16x16x32_bf16 v[104:107], v[154:157], v[204:207], v[104:107]
	v_mfma_f32_16x16x32_bf16 v[92:95], v[228:231], v[212:215], v[76:79]
	v_mfma_f32_16x16x32_bf16 v[88:91], v[154:157], v[212:215], v[72:75]
	s_barrier
	v_mfma_f32_16x16x32_bf16 v[76:79], v[228:231], v[220:223], v[178:181]
	v_mfma_f32_16x16x32_bf16 v[72:75], v[154:157], v[220:223], v[182:185]
	ds_read_b128 v[178:181], v152 offset:49152
	ds_read_b128 v[182:185], v152 offset:50176
	ds_read_b128 v[186:189], v151 offset:49152
	ds_read_b128 v[190:193], v151 offset:50176
	ds_read_b128 v[194:197], v150 offset:49152
	ds_read_b128 v[150:153], v150 offset:50176
	ds_read_b128 v[198:201], v149 offset:49152
	ds_read_b128 v[202:205], v149 offset:50176
	s_barrier
	s_waitcnt lgkmcnt(0)
	v_mfma_f32_16x16x32_bf16 v[20:23], v[0:3], v[178:181], v[60:63]
	v_mfma_f32_16x16x32_bf16 v[56:59], v[16:19], v[178:181], v[56:59]
	v_mfma_f32_16x16x32_bf16 v[60:63], v[0:3], v[186:189], v[52:55]
	v_mfma_f32_16x16x32_bf16 v[206:209], v[16:19], v[186:189], v[48:51]
	v_mfma_f32_16x16x32_bf16 v[44:47], v[0:3], v[194:197], v[44:47]
	v_mfma_f32_16x16x32_bf16 v[40:43], v[16:19], v[194:197], v[40:43]
	v_mfma_f32_16x16x32_bf16 v[0:3], v[0:3], v[198:201], v[36:39]
	v_mfma_f32_16x16x32_bf16 v[210:213], v[16:19], v[198:201], v[32:35]
	v_mfma_f32_16x16x32_bf16 v[52:55], v[4:7], v[182:185], v[20:23]
	v_mfma_f32_16x16x32_bf16 v[48:51], v[174:177], v[182:185], v[56:59]
	v_mfma_f32_16x16x32_bf16 v[36:39], v[4:7], v[190:193], v[60:63]
	v_mfma_f32_16x16x32_bf16 v[32:35], v[174:177], v[190:193], v[206:209]
	v_mfma_f32_16x16x32_bf16 v[20:23], v[4:7], v[150:153], v[44:47]
	v_mfma_f32_16x16x32_bf16 v[16:19], v[174:177], v[150:153], v[40:43]
	v_mfma_f32_16x16x32_bf16 v[4:7], v[4:7], v[202:205], v[0:3]
	v_mfma_f32_16x16x32_bf16 v[0:3], v[174:177], v[202:205], v[210:213]
	v_mfma_f32_16x16x32_bf16 v[28:31], v[224:227], v[178:181], v[28:31]
	v_mfma_f32_16x16x32_bf16 v[24:27], v[232:235], v[178:181], v[24:27]
	v_mfma_f32_16x16x32_bf16 v[40:43], v[224:227], v[186:189], v[134:137]
	v_mfma_f32_16x16x32_bf16 v[134:137], v[232:235], v[186:189], v[138:141]
	v_mfma_f32_16x16x32_bf16 v[12:15], v[224:227], v[194:197], v[12:15]
	v_mfma_f32_16x16x32_bf16 v[8:11], v[232:235], v[194:197], v[8:11]
	v_mfma_f32_16x16x32_bf16 v[138:141], v[224:227], v[198:201], v[170:173]
	v_mfma_f32_16x16x32_bf16 v[158:161], v[232:235], v[198:201], v[158:161]
	v_mfma_f32_16x16x32_bf16 v[60:63], v[228:231], v[182:185], v[28:31]
	v_mfma_f32_16x16x32_bf16 v[56:59], v[154:157], v[182:185], v[24:27]
	v_mfma_f32_16x16x32_bf16 v[44:47], v[228:231], v[190:193], v[40:43]
	v_mfma_f32_16x16x32_bf16 v[40:43], v[154:157], v[190:193], v[134:137]
	v_mfma_f32_16x16x32_bf16 v[28:31], v[228:231], v[150:153], v[12:15]
	v_mfma_f32_16x16x32_bf16 v[24:27], v[154:157], v[150:153], v[8:11]
	s_barrier
	v_mfma_f32_16x16x32_bf16 v[12:15], v[228:231], v[202:205], v[138:141]
	v_mfma_f32_16x16x32_bf16 v[8:11], v[154:157], v[202:205], v[158:161]
	v_cmp_gt_u32_e32 vcc, s66, v130
	s_and_saveexec_b64 s[50:51], vcc
	s_cbranch_execz .LBB0_773
	s_barrier

; #define STAGE(P, BASE, LD, br, kt) do { const char* _g = (const char*)((BASE) + (size_t)(br) * (LD) + (size_t)(kt) * 64); \
;     for (int _i = 0; _i < 2; ++_i) { int _b = tidx * 16 + _i * 8192; int _r, _c; stage_rc(_b, _r, _c); \
;       __builtin_amdgcn_global_load_lds((const unsigned*)(_g + (unsigned)((_r * (LD) + _c) * 2)), (unsigned*)((char*)(P) + _b), 16, 0, 0); } } while (0)
; #define LDA(dst, b, h) for (int m = 0; m < 4; ++m) for (int k = 0; k < 2; ++k) \
;     dst[m][k] = *reinterpret_cast<const bf16x8*>((char*)SA(b, h) + lds_byte(wr * 64 + m * 16 + fr, k * 32 + fq * 8))
; #define LDB(dst, b, h) for (int n = 0; n < 2; ++n) for (int k = 0; k < 2; ++k) \
;     dst[n][k] = *reinterpret_cast<const bf16x8*>((char*)SB(b, h) + lds_byte(wc * 32 + n * 16 + fr, k * 32 + fq * 8))
; #define MMA(ai, bj, At_, Bt_) do { __builtin_amdgcn_s_setprio(1); \
;     for (int k = 0; k < 2; ++k) for (int m = 0; m < 4; ++m) for (int n = 0; n < 2; ++n) \
;       acc[ai][bj][m][n] = __builtin_amdgcn_mfma_f32_16x16x32_bf16(At_[m][k], Bt_[n][k], acc[ai][bj][m][n], 0, 0, 0); \
;     __builtin_amdgcn_s_setprio(0); } while (0)
; #define WAIT_L(n) asm volatile("s_waitcnt lgkmcnt(" #n ")" ::: "memory")
; #define BAR __builtin_amdgcn_s_barrier()
; #define SCHED __builtin_amdgcn_sched_barrier(0)
; template <int EPI, int lda, int ldb, int N, int K>
; __device__ __forceinline__ void gemm_phase(const u16* __restrict__ A, const u16* __restrict__ Bt, const GemmEpi ep, int wv) {
;     ...
;       LDB(B0, 0, 0); SCHED; LDA(At, 0, 0); STAGE(SA(1, 1), Ab, lda, brow + HALF, t + 1);
;       WAIT_L(8); BAR; WAIT_L(0); MMA(0, 0, At, B0); BAR; SCHED;
;       LDB(B1, 0, 1); STAGE(SB(0, 0), Bt, ldb, bcol, t + 2);
;       BAR; WAIT_L(0); MMA(0, 1, At, B1); BAR;
;       LDA(At, 0, 1); STAGE(SA(0, 0), Ab, lda, brow, t + 2);
;       BAR; WAIT_L(0); MMA(1, 0, At, B0); BAR; SCHED;
.LBB0_838:
	ds_read_b128 v[168:171], v164
	ds_read_b128 v[174:177], v164 offset:1024
	ds_read_b128 v[178:181], v164 offset:2048
	ds_read_b128 v[182:185], v164 offset:3072
	v_add_u32_e32 v172, 0xc000, v147
	v_lshl_add_u64 v[238:239], v[136:137], 0, s[50:51]
	v_readfirstlane_b32 s73, v172
	v_add_u32_e32 v173, 0xe000, v147
	v_lshl_add_u64 v[166:167], v[238:239], 0, s[22:23]
	s_mov_b32 m0, s73
	v_lshl_add_u64 v[240:241], v[134:135], 0, s[50:51]
	v_readfirstlane_b32 s73, v173
	ds_read_b128 v[186:189], v155
	ds_read_b128 v[190:193], v155 offset:1024
	ds_read_b128 v[194:197], v154
	ds_read_b128 v[198:201], v154 offset:1024
	ds_read_b128 v[202:205], v153
	ds_read_b128 v[206:209], v153 offset:1024
	ds_read_b128 v[210:213], v152
	ds_read_b128 v[214:217], v152 offset:1024
	global_load_lds_dwordx4 v[166:167], off
	v_lshl_add_u64 v[166:167], v[240:241], 0, s[22:23]
	s_mov_b32 m0, s73
	s_nop 0
	global_load_lds_dwordx4 v[166:167], off
	s_waitcnt lgkmcnt(8)
	s_barrier
	s_waitcnt lgkmcnt(0)
	v_mfma_f32_16x16x32_bf16 v[124:127], v[168:171], v[186:189], v[124:127]
	v_mfma_f32_16x16x32_bf16 v[120:123], v[178:181], v[186:189], v[120:123]
	v_mfma_f32_16x16x32_bf16 v[116:119], v[168:171], v[194:197], v[116:119]
	v_mfma_f32_16x16x32_bf16 v[112:115], v[178:181], v[194:197], v[112:115]
	v_mfma_f32_16x16x32_bf16 v[108:111], v[168:171], v[202:205], v[108:111]
	v_mfma_f32_16x16x32_bf16 v[104:107], v[178:181], v[202:205], v[104:107]
	v_mfma_f32_16x16x32_bf16 v[100:103], v[168:171], v[210:213], v[100:103]
	v_mfma_f32_16x16x32_bf16 v[96:99], v[178:181], v[210:213], v[96:99]
	v_mfma_f32_16x16x32_bf16 v[124:127], v[174:177], v[190:193], v[124:127]
	v_mfma_f32_16x16x32_bf16 v[120:123], v[182:185], v[190:193], v[120:123]
	v_mfma_f32_16x16x32_bf16 v[116:119], v[174:177], v[198:201], v[116:119]
	v_mfma_f32_16x16x32_bf16 v[112:115], v[182:185], v[198:201], v[112:115]
	v_mfma_f32_16x16x32_bf16 v[108:111], v[174:177], v[206:209], v[108:111]
	v_mfma_f32_16x16x32_bf16 v[104:107], v[182:185], v[206:209], v[104:107]
	s_barrier
	v_mfma_f32_16x16x32_bf16 v[100:103], v[174:177], v[214:217], v[100:103]
	v_mfma_f32_16x16x32_bf16 v[96:99], v[182:185], v[214:217], v[96:99]
	v_add_u32_e32 v165, s63, v156
	v_lshl_add_u64 v[242:243], v[144:145], 0, s[50:51]
	v_readfirstlane_b32 s73, v165
	v_lshl_add_u64 v[166:167], v[242:243], 0, s[24:25]
	s_mov_b32 m0, s73
	ds_read_b128 v[218:221], v163
	ds_read_b128 v[222:225], v163 offset:1024
	ds_read_b128 v[226:229], v163 offset:2048
	ds_read_b128 v[230:233], v163 offset:3072
	global_load_lds_dwordx4 v[166:167], off
	v_add_u32_e32 v166, 0x2000, v165
	v_lshl_add_u64 v[244:245], v[142:143], 0, s[50:51]
	v_readfirstlane_b32 s73, v166
	v_lshl_add_u64 v[234:235], v[244:245], 0, s[24:25]
	s_mov_b32 m0, s73
	s_nop 0
	global_load_lds_dwordx4 v[234:235], off
	s_barrier
	s_waitcnt lgkmcnt(0)
	v_mfma_f32_16x16x32_bf16 v[92:95], v[218:221], v[186:189], v[92:95]
	v_mfma_f32_16x16x32_bf16 v[88:91], v[226:229], v[186:189], v[88:91]
	v_mfma_f32_16x16x32_bf16 v[84:87], v[218:221], v[194:197], v[84:87]
	v_mfma_f32_16x16x32_bf16 v[80:83], v[226:229], v[194:197], v[80:83]
	v_mfma_f32_16x16x32_bf16 v[76:79], v[218:221], v[202:205], v[76:79]
	v_mfma_f32_16x16x32_bf16 v[72:75], v[226:229], v[202:205], v[72:75]
	v_mfma_f32_16x16x32_bf16 v[68:71], v[218:221], v[210:213], v[68:71]
	v_mfma_f32_16x16x32_bf16 v[64:67], v[226:229], v[210:213], v[64:67]
	v_mfma_f32_16x16x32_bf16 v[92:95], v[222:225], v[190:193], v[92:95]
	v_mfma_f32_16x16x32_bf16 v[88:91], v[230:233], v[190:193], v[88:91]
	v_mfma_f32_16x16x32_bf16 v[84:87], v[222:225], v[198:201], v[84:87]
	v_mfma_f32_16x16x32_bf16 v[80:83], v[230:233], v[198:201], v[80:83]
	v_mfma_f32_16x16x32_bf16 v[76:79], v[222:225], v[206:209], v[76:79]
	v_mfma_f32_16x16x32_bf16 v[72:75], v[230:233], v[206:209], v[72:75]
	s_barrier
	v_mfma_f32_16x16x32_bf16 v[68:71], v[222:225], v[214:217], v[68:71]
	v_mfma_f32_16x16x32_bf16 v[64:67], v[230:233], v[214:217], v[64:67]
	v_readfirstlane_b32 s73, v147
	v_add_u32_e32 v167, 0x2000, v147
	v_lshl_add_u64 v[234:235], v[238:239], 0, s[26:27]
	s_mov_b32 m0, s73
	v_readfirstlane_b32 s73, v167
	ds_read_b128 v[186:189], v155 offset:16384
	ds_read_b128 v[190:193], v155 offset:17408
	ds_read_b128 v[194:197], v154 offset:16384
	ds_read_b128 v[198:201], v154 offset:17408
	ds_read_b128 v[202:205], v153 offset:16384
	ds_read_b128 v[206:209], v153 offset:17408
	ds_read_b128 v[210:213], v152 offset:16384
	ds_read_b128 v[214:217], v152 offset:17408
	global_load_lds_dwordx4 v[234:235], off
	v_lshl_add_u64 v[234:235], v[240:241], 0, s[26:27]
	s_mov_b32 m0, s73
	s_nop 0
	global_load_lds_dwordx4 v[234:235], off
	s_barrier
	s_waitcnt lgkmcnt(0)
	v_mfma_f32_16x16x32_bf16 v[60:63], v[168:171], v[186:189], v[60:63]
	v_mfma_f32_16x16x32_bf16 v[56:59], v[178:181], v[186:189], v[56:59]
	v_mfma_f32_16x16x32_bf16 v[52:55], v[168:171], v[194:197], v[52:55]
	v_mfma_f32_16x16x32_bf16 v[48:51], v[178:181], v[194:197], v[48:51]
	v_mfma_f32_16x16x32_bf16 v[44:47], v[168:171], v[202:205], v[44:47]
	v_mfma_f32_16x16x32_bf16 v[40:43], v[178:181], v[202:205], v[40:43]
	v_mfma_f32_16x16x32_bf16 v[36:39], v[168:171], v[210:213], v[36:39]
	v_mfma_f32_16x16x32_bf16 v[32:35], v[178:181], v[210:213], v[32:35]
	v_mfma_f32_16x16x32_bf16 v[60:63], v[174:177], v[190:193], v[60:63]
	v_mfma_f32_16x16x32_bf16 v[56:59], v[182:185], v[190:193], v[56:59]
	v_mfma_f32_16x16x32_bf16 v[52:55], v[174:177], v[198:201], v[52:55]
	v_mfma_f32_16x16x32_bf16 v[48:51], v[182:185], v[198:201], v[48:51]
	v_mfma_f32_16x16x32_bf16 v[44:47], v[174:177], v[206:209], v[44:47]
	v_mfma_f32_16x16x32_bf16 v[40:43], v[182:185], v[206:209], v[40:43]
	s_barrier
; #define STAGE(P, BASE, LD, br, kt) do { const char* _g = (const char*)((BASE) + (size_t)(br) * (LD) + (size_t)(kt) * 64); \
;     for (int _i = 0; _i < 2; ++_i) { int _b = tidx * 16 + _i * 8192; int _r, _c; stage_rc(_b, _r, _c); \
;       __builtin_amdgcn_global_load_lds((const unsigned*)(_g + (unsigned)((_r * (LD) + _c) * 2)), (unsigned*)((char*)(P) + _b), 16, 0, 0); } } while (0)
; #define LDA(dst, b, h) for (int m = 0; m < 4; ++m) for (int k = 0; k < 2; ++k) \
;     dst[m][k] = *reinterpret_cast<const bf16x8*>((char*)SA(b, h) + lds_byte(wr * 64 + m * 16 + fr, k * 32 + fq * 8))
; #define LDB(dst, b, h) for (int n = 0; n < 2; ++n) for (int k = 0; k < 2; ++k) \
;     dst[n][k] = *reinterpret_cast<const bf16x8*>((char*)SB(b, h) + lds_byte(wc * 32 + n * 16 + fr, k * 32 + fq * 8))
; #define MMA(ai, bj, At_, Bt_) do { __builtin_amdgcn_s_setprio(1); \
;     for (int k = 0; k < 2; ++k) for (int m = 0; m < 4; ++m) for (int n = 0; n < 2; ++n) \
;       acc[ai][bj][m][n] = __builtin_amdgcn_mfma_f32_16x16x32_bf16(At_[m][k], Bt_[n][k], acc[ai][bj][m][n], 0, 0, 0); \
;     __builtin_amdgcn_s_setprio(0); } while (0)
; #define WAIT_V(n) asm volatile("s_waitcnt vmcnt(" #n ")" ::: "memory")
; #define WAIT_L(n) asm volatile("s_waitcnt lgkmcnt(" #n ")" ::: "memory")
; #define BAR __builtin_amdgcn_s_barrier()
; #define SCHED __builtin_amdgcn_sched_barrier(0)
; template <int EPI, int lda, int ldb, int N, int K>
; __device__ __forceinline__ void gemm_phase(const u16* __restrict__ A, const u16* __restrict__ Bt, const GemmEpi ep, int wv) {
;     ...
;       BAR; WAIT_L(0); MMA(1, 0, At, B0); BAR; SCHED;
;       STAGE(SB(0, 1), Bt, ldb, bcol + HALF, t + 2);
;       WAIT_V(6); BAR; MMA(1, 1, At, B1); BAR;
;       LDB(B0, 1, 0); SCHED; LDA(At, 1, 0); STAGE(SA(0, 1), Ab, lda, brow + HALF, t + 2);
;       WAIT_L(8); BAR; WAIT_L(0); MMA(0, 0, At, B0); BAR; SCHED;
;       LDB(B1, 1, 1); STAGE(SB(1, 0), Bt, ldb, bcol, t + 3);
;       BAR; WAIT_L(0); MMA(0, 1, At, B1); BAR;
	v_mfma_f32_16x16x32_bf16 v[36:39], v[174:177], v[214:217], v[36:39]
	v_mfma_f32_16x16x32_bf16 v[32:35], v[182:185], v[214:217], v[32:35]
	v_add_u32_e32 v168, s64, v156
	v_lshl_add_u64 v[246:247], v[140:141], 0, s[50:51]
	v_readfirstlane_b32 s73, v168
	v_add_u32_e32 v169, 0x2000, v168
	v_lshl_add_u64 v[170:171], v[246:247], 0, s[40:41]
	s_mov_b32 m0, s73
	v_lshl_add_u64 v[248:249], v[138:139], 0, s[50:51]
	v_readfirstlane_b32 s73, v169
	global_load_lds_dwordx4 v[170:171], off
	v_lshl_add_u64 v[170:171], v[248:249], 0, s[40:41]
	s_mov_b32 m0, s73
	s_nop 0
	global_load_lds_dwordx4 v[170:171], off
	s_waitcnt vmcnt(6)
	s_barrier
	v_mfma_f32_16x16x32_bf16 v[28:31], v[218:221], v[186:189], v[28:31]
	v_mfma_f32_16x16x32_bf16 v[24:27], v[226:229], v[186:189], v[24:27]
	v_mfma_f32_16x16x32_bf16 v[20:23], v[218:221], v[194:197], v[20:23]
	v_mfma_f32_16x16x32_bf16 v[16:19], v[226:229], v[194:197], v[16:19]
	v_mfma_f32_16x16x32_bf16 v[12:15], v[218:221], v[202:205], v[12:15]
	v_mfma_f32_16x16x32_bf16 v[8:11], v[226:229], v[202:205], v[8:11]
	v_mfma_f32_16x16x32_bf16 v[4:7], v[218:221], v[210:213], v[4:7]
	v_mfma_f32_16x16x32_bf16 v[0:3], v[226:229], v[210:213], v[0:3]
	v_mfma_f32_16x16x32_bf16 v[28:31], v[222:225], v[190:193], v[28:31]
	v_mfma_f32_16x16x32_bf16 v[24:27], v[230:233], v[190:193], v[24:27]
	v_mfma_f32_16x16x32_bf16 v[20:23], v[222:225], v[198:201], v[20:23]
	v_mfma_f32_16x16x32_bf16 v[16:19], v[230:233], v[198:201], v[16:19]
	v_mfma_f32_16x16x32_bf16 v[12:15], v[222:225], v[206:209], v[12:15]
	v_mfma_f32_16x16x32_bf16 v[8:11], v[230:233], v[206:209], v[8:11]
	s_barrier
	v_mfma_f32_16x16x32_bf16 v[4:7], v[222:225], v[214:217], v[4:7]
	v_mfma_f32_16x16x32_bf16 v[0:3], v[230:233], v[214:217], v[0:3]
	ds_read_b128 v[174:177], v159
	ds_read_b128 v[178:181], v159 offset:1024
	ds_read_b128 v[182:185], v159 offset:2048
	ds_read_b128 v[186:189], v159 offset:3072
	v_add_u32_e32 v170, 0x4000, v147
	v_add_u32_e32 v171, 0x6000, v147
	v_readfirstlane_b32 s73, v170
	v_lshl_add_u64 v[222:223], v[238:239], 0, s[42:43]
	s_mov_b32 m0, s73
	v_readfirstlane_b32 s73, v171
	ds_read_b128 v[190:193], v155 offset:32768
	ds_read_b128 v[194:197], v155 offset:33792
	ds_read_b128 v[198:201], v154 offset:32768
	ds_read_b128 v[202:205], v154 offset:33792
	ds_read_b128 v[206:209], v153 offset:32768
	ds_read_b128 v[210:213], v153 offset:33792
	ds_read_b128 v[214:217], v152 offset:32768
	ds_read_b128 v[218:221], v152 offset:33792
	global_load_lds_dwordx4 v[222:223], off
	v_lshl_add_u64 v[222:223], v[240:241], 0, s[42:43]
	s_mov_b32 m0, s73
	s_nop 0
	global_load_lds_dwordx4 v[222:223], off
	s_waitcnt lgkmcnt(8)
	s_barrier
	s_waitcnt lgkmcnt(0)
	v_mfma_f32_16x16x32_bf16 v[124:127], v[174:177], v[190:193], v[124:127]
	v_mfma_f32_16x16x32_bf16 v[120:123], v[182:185], v[190:193], v[120:123]
	v_mfma_f32_16x16x32_bf16 v[116:119], v[174:177], v[198:201], v[116:119]
	v_mfma_f32_16x16x32_bf16 v[112:115], v[182:185], v[198:201], v[112:115]
	v_mfma_f32_16x16x32_bf16 v[108:111], v[174:177], v[206:209], v[108:111]
	v_mfma_f32_16x16x32_bf16 v[104:107], v[182:185], v[206:209], v[104:107]
	v_mfma_f32_16x16x32_bf16 v[100:103], v[174:177], v[214:217], v[100:103]
	v_mfma_f32_16x16x32_bf16 v[96:99], v[182:185], v[214:217], v[96:99]
	v_mfma_f32_16x16x32_bf16 v[124:127], v[178:181], v[194:197], v[124:127]
	v_mfma_f32_16x16x32_bf16 v[120:123], v[186:189], v[194:197], v[120:123]
	v_mfma_f32_16x16x32_bf16 v[116:119], v[178:181], v[202:205], v[116:119]
	v_mfma_f32_16x16x32_bf16 v[112:115], v[186:189], v[202:205], v[112:115]
	v_mfma_f32_16x16x32_bf16 v[108:111], v[178:181], v[210:213], v[108:111]
	v_mfma_f32_16x16x32_bf16 v[104:107], v[186:189], v[210:213], v[104:107]
	s_barrier
	v_mfma_f32_16x16x32_bf16 v[100:103], v[178:181], v[218:221], v[100:103]
	v_mfma_f32_16x16x32_bf16 v[96:99], v[186:189], v[218:221], v[96:99]
	v_readfirstlane_b32 s73, v158
	v_lshl_add_u64 v[242:243], v[242:243], 0, s[44:45]
	s_mov_b32 m0, s73
	ds_read_b128 v[222:225], v157
	ds_read_b128 v[226:229], v157 offset:1024
	ds_read_b128 v[230:233], v157 offset:2048
	ds_read_b128 v[234:237], v157 offset:3072
	global_load_lds_dwordx4 v[242:243], off
	v_lshl_add_u64 v[242:243], v[244:245], 0, s[44:45]
	v_add_u32_e32 v244, 0x2000, v158
	s_nop 0
	v_readfirstlane_b32 s73, v244
	s_mov_b32 m0, s73
	s_nop 0
	global_load_lds_dwordx4 v[242:243], off
	s_barrier
	s_waitcnt lgkmcnt(0)
	v_mfma_f32_16x16x32_bf16 v[92:95], v[222:225], v[190:193], v[92:95]
	v_mfma_f32_16x16x32_bf16 v[88:91], v[230:233], v[190:193], v[88:91]
	v_mfma_f32_16x16x32_bf16 v[84:87], v[222:225], v[198:201], v[84:87]
	v_mfma_f32_16x16x32_bf16 v[80:83], v[230:233], v[198:201], v[80:83]
	v_mfma_f32_16x16x32_bf16 v[76:79], v[222:225], v[206:209], v[76:79]
	v_mfma_f32_16x16x32_bf16 v[72:75], v[230:233], v[206:209], v[72:75]
	v_mfma_f32_16x16x32_bf16 v[68:71], v[222:225], v[214:217], v[68:71]
	v_mfma_f32_16x16x32_bf16 v[64:67], v[230:233], v[214:217], v[64:67]
	v_mfma_f32_16x16x32_bf16 v[92:95], v[226:229], v[194:197], v[92:95]
	v_mfma_f32_16x16x32_bf16 v[88:91], v[234:237], v[194:197], v[88:91]
	v_mfma_f32_16x16x32_bf16 v[84:87], v[226:229], v[202:205], v[84:87]
	v_mfma_f32_16x16x32_bf16 v[80:83], v[234:237], v[202:205], v[80:83]
	v_mfma_f32_16x16x32_bf16 v[76:79], v[226:229], v[210:213], v[76:79]
	v_mfma_f32_16x16x32_bf16 v[72:75], v[234:237], v[210:213], v[72:75]
	s_barrier
; #define STAGE(P, BASE, LD, br, kt) do { const char* _g = (const char*)((BASE) + (size_t)(br) * (LD) + (size_t)(kt) * 64); \
;     for (int _i = 0; _i < 2; ++_i) { int _b = tidx * 16 + _i * 8192; int _r, _c; stage_rc(_b, _r, _c); \
;       __builtin_amdgcn_global_load_lds((const unsigned*)(_g + (unsigned)((_r * (LD) + _c) * 2)), (unsigned*)((char*)(P) + _b), 16, 0, 0); } } while (0)
; #define LDA(dst, b, h) for (int m = 0; m < 4; ++m) for (int k = 0; k < 2; ++k) \
;     dst[m][k] = *reinterpret_cast<const bf16x8*>((char*)SA(b, h) + lds_byte(wr * 64 + m * 16 + fr, k * 32 + fq * 8))
; #define LDB(dst, b, h) for (int n = 0; n < 2; ++n) for (int k = 0; k < 2; ++k) \
;     dst[n][k] = *reinterpret_cast<const bf16x8*>((char*)SB(b, h) + lds_byte(wc * 32 + n * 16 + fr, k * 32 + fq * 8))
; #define MMA(ai, bj, At_, Bt_) do { __builtin_amdgcn_s_setprio(1); \
;     for (int k = 0; k < 2; ++k) for (int m = 0; m < 4; ++m) for (int n = 0; n < 2; ++n) \
;       acc[ai][bj][m][n] = __builtin_amdgcn_mfma_f32_16x16x32_bf16(At_[m][k], Bt_[n][k], acc[ai][bj][m][n], 0, 0, 0); \
;     __builtin_amdgcn_s_setprio(0); } while (0)
; #define WAIT_V(n) asm volatile("s_waitcnt vmcnt(" #n ")" ::: "memory")
; #define WAIT_L(n) asm volatile("s_waitcnt lgkmcnt(" #n ")" ::: "memory")
; #define BAR __builtin_amdgcn_s_barrier()
; #define SCHED __builtin_amdgcn_sched_barrier(0)
; template <int EPI, int lda, int ldb, int N, int K>
; __device__ __forceinline__ void gemm_phase(const u16* __restrict__ A, const u16* __restrict__ Bt, const GemmEpi ep, int wv) {
;     ...
;       BAR; WAIT_L(0); MMA(0, 1, At, B1); BAR;
;       LDA(At, 1, 1); STAGE(SA(1, 0), Ab, lda, brow, t + 3);
;       BAR; WAIT_L(0); MMA(1, 0, At, B0); BAR; SCHED;
;       STAGE(SB(1, 1), Bt, ldb, bcol + HALF, t + 3);
;       WAIT_V(6); BAR; MMA(1, 1, At, B1); BAR;
;     }
;     { LDB(B0, 0, 0); LDA(At, 0, 0); STAGE(SA(1, 1), Ab, lda, brow + HALF, nt - 1);
;       BAR; WAIT_L(0); MMA(0, 0, At, B0); BAR;
;       LDB(B1, 0, 1); BAR; WAIT_L(0); MMA(0, 1, At, B1); BAR;
	v_mfma_f32_16x16x32_bf16 v[68:71], v[226:229], v[218:221], v[68:71]
	v_mfma_f32_16x16x32_bf16 v[64:67], v[234:237], v[218:221], v[64:67]
	v_readfirstlane_b32 s73, v160
	v_lshl_add_u64 v[238:239], v[238:239], 0, s[46:47]
	s_mov_b32 m0, s73
	v_readfirstlane_b32 s73, v161
	ds_read_b128 v[190:193], v155 offset:49152
	ds_read_b128 v[194:197], v155 offset:50176
	ds_read_b128 v[198:201], v154 offset:49152
	ds_read_b128 v[202:205], v154 offset:50176
	ds_read_b128 v[206:209], v153 offset:49152
	ds_read_b128 v[210:213], v153 offset:50176
	ds_read_b128 v[214:217], v152 offset:49152
	ds_read_b128 v[218:221], v152 offset:50176
	global_load_lds_dwordx4 v[238:239], off
	v_lshl_add_u64 v[238:239], v[240:241], 0, s[46:47]
	s_mov_b32 m0, s73
	s_nop 0
	global_load_lds_dwordx4 v[238:239], off
	s_barrier
	s_waitcnt lgkmcnt(0)
	v_mfma_f32_16x16x32_bf16 v[60:63], v[174:177], v[190:193], v[60:63]
	v_mfma_f32_16x16x32_bf16 v[56:59], v[182:185], v[190:193], v[56:59]
	v_mfma_f32_16x16x32_bf16 v[52:55], v[174:177], v[198:201], v[52:55]
	v_mfma_f32_16x16x32_bf16 v[48:51], v[182:185], v[198:201], v[48:51]
	v_mfma_f32_16x16x32_bf16 v[44:47], v[174:177], v[206:209], v[44:47]
	v_mfma_f32_16x16x32_bf16 v[40:43], v[182:185], v[206:209], v[40:43]
	v_mfma_f32_16x16x32_bf16 v[36:39], v[174:177], v[214:217], v[36:39]
	v_mfma_f32_16x16x32_bf16 v[32:35], v[182:185], v[214:217], v[32:35]
	v_mfma_f32_16x16x32_bf16 v[60:63], v[178:181], v[194:197], v[60:63]
	v_mfma_f32_16x16x32_bf16 v[56:59], v[186:189], v[194:197], v[56:59]
	v_mfma_f32_16x16x32_bf16 v[52:55], v[178:181], v[202:205], v[52:55]
	v_mfma_f32_16x16x32_bf16 v[48:51], v[186:189], v[202:205], v[48:51]
	v_mfma_f32_16x16x32_bf16 v[44:47], v[178:181], v[210:213], v[44:47]
	v_mfma_f32_16x16x32_bf16 v[40:43], v[186:189], v[210:213], v[40:43]
	s_barrier
	v_mfma_f32_16x16x32_bf16 v[36:39], v[178:181], v[218:221], v[36:39]
	v_mfma_f32_16x16x32_bf16 v[32:35], v[186:189], v[218:221], v[32:35]
	v_readfirstlane_b32 s73, v162
	v_add_u32_e32 v176, 0x2000, v162
	v_lshl_add_u64 v[174:175], v[246:247], 0, s[48:49]
	s_mov_b32 m0, s73
	v_readfirstlane_b32 s73, v176
	global_load_lds_dwordx4 v[174:175], off
	v_lshl_add_u64 v[174:175], v[248:249], 0, s[48:49]
	s_mov_b32 m0, s73
	s_nop 0
	global_load_lds_dwordx4 v[174:175], off
	s_waitcnt vmcnt(6)
	s_barrier
	v_mfma_f32_16x16x32_bf16 v[28:31], v[222:225], v[190:193], v[28:31]
	v_mfma_f32_16x16x32_bf16 v[24:27], v[230:233], v[190:193], v[24:27]
	v_mfma_f32_16x16x32_bf16 v[20:23], v[222:225], v[198:201], v[20:23]
	v_mfma_f32_16x16x32_bf16 v[16:19], v[230:233], v[198:201], v[16:19]
	v_mfma_f32_16x16x32_bf16 v[12:15], v[222:225], v[206:209], v[12:15]
	v_mfma_f32_16x16x32_bf16 v[8:11], v[230:233], v[206:209], v[8:11]
	v_mfma_f32_16x16x32_bf16 v[4:7], v[222:225], v[214:217], v[4:7]
	v_mfma_f32_16x16x32_bf16 v[0:3], v[230:233], v[214:217], v[0:3]
	v_mfma_f32_16x16x32_bf16 v[28:31], v[226:229], v[194:197], v[28:31]
	v_mfma_f32_16x16x32_bf16 v[24:27], v[234:237], v[194:197], v[24:27]
	v_mfma_f32_16x16x32_bf16 v[20:23], v[226:229], v[202:205], v[20:23]
	v_mfma_f32_16x16x32_bf16 v[16:19], v[234:237], v[202:205], v[16:19]
	v_mfma_f32_16x16x32_bf16 v[12:15], v[226:229], v[210:213], v[12:15]
	v_mfma_f32_16x16x32_bf16 v[8:11], v[234:237], v[210:213], v[8:11]
	s_barrier
	v_mfma_f32_16x16x32_bf16 v[4:7], v[226:229], v[218:221], v[4:7]
	v_mfma_f32_16x16x32_bf16 v[0:3], v[234:237], v[218:221], v[0:3]
	s_add_i32 s72, s72, 2
	s_add_u32 s50, s50, 0x100
	s_addc_u32 s51, s51, 0
	s_cmpk_gt_u32 s72, 0x51
	s_cbranch_scc0 .LBB0_838
	s_add_i32 s50, s18, 0x80
	s_mul_hi_i32 s51, s50, 0x2b00
	s_mulk_i32 s50, 0x2b00
	s_add_u32 s50, s56, s50
	s_addc_u32 s51, s57, s51
	s_add_u32 s50, s50, 0x2a80
	s_addc_u32 s51, s51, 0
	v_readfirstlane_b32 s72, v172
	v_lshl_add_u64 v[160:161], s[50:51], 0, v[128:129]
	s_mov_b32 m0, s72
	ds_read_b128 v[134:137], v164
	ds_read_b128 v[138:141], v164 offset:1024
	ds_read_b128 v[142:145], v164 offset:2048
	ds_read_b128 v[174:177], v164 offset:3072
	ds_read_b128 v[178:181], v155
	ds_read_b128 v[182:185], v155 offset:1024
	ds_read_b128 v[186:189], v154
	ds_read_b128 v[190:193], v154 offset:1024
	ds_read_b128 v[194:197], v153
	ds_read_b128 v[198:201], v153 offset:1024
	ds_read_b128 v[202:205], v152
	ds_read_b128 v[206:209], v152 offset:1024
	global_load_lds_dwordx4 v[160:161], off
	v_lshl_add_u64 v[160:161], s[50:51], 0, v[132:133]
	v_readfirstlane_b32 s50, v173
	s_mov_b32 m0, s50
	s_nop 0
	global_load_lds_dwordx4 v[160:161], off
	s_barrier
	s_waitcnt lgkmcnt(0)
	v_mfma_f32_16x16x32_bf16 v[124:127], v[134:137], v[178:181], v[124:127]
	v_mfma_f32_16x16x32_bf16 v[120:123], v[142:145], v[178:181], v[120:123]
	v_mfma_f32_16x16x32_bf16 v[116:119], v[134:137], v[186:189], v[116:119]
	v_mfma_f32_16x16x32_bf16 v[112:115], v[142:145], v[186:189], v[112:115]
	v_mfma_f32_16x16x32_bf16 v[108:111], v[134:137], v[194:197], v[108:111]
	v_mfma_f32_16x16x32_bf16 v[104:107], v[142:145], v[194:197], v[104:107]
	v_mfma_f32_16x16x32_bf16 v[100:103], v[134:137], v[202:205], v[100:103]
	v_mfma_f32_16x16x32_bf16 v[96:99], v[142:145], v[202:205], v[96:99]
	v_mfma_f32_16x16x32_bf16 v[124:127], v[138:141], v[182:185], v[124:127]
	v_mfma_f32_16x16x32_bf16 v[120:123], v[174:177], v[182:185], v[120:123]
	v_mfma_f32_16x16x32_bf16 v[116:119], v[138:141], v[190:193], v[116:119]
	v_mfma_f32_16x16x32_bf16 v[112:115], v[174:177], v[190:193], v[112:115]
	v_mfma_f32_16x16x32_bf16 v[108:111], v[138:141], v[198:201], v[108:111]
	v_mfma_f32_16x16x32_bf16 v[104:107], v[174:177], v[198:201], v[104:107]
	s_barrier
; #define STAGE(P, BASE, LD, br, kt) do { const char* _g = (const char*)((BASE) + (size_t)(br) * (LD) + (size_t)(kt) * 64); \
;     for (int _i = 0; _i < 2; ++_i) { int _b = tidx * 16 + _i * 8192; int _r, _c; stage_rc(_b, _r, _c); \
;       __builtin_amdgcn_global_load_lds((const unsigned*)(_g + (unsigned)((_r * (LD) + _c) * 2)), (unsigned*)((char*)(P) + _b), 16, 0, 0); } } while (0)
; #define LDA(dst, b, h) for (int m = 0; m < 4; ++m) for (int k = 0; k < 2; ++k) \
;     dst[m][k] = *reinterpret_cast<const bf16x8*>((char*)SA(b, h) + lds_byte(wr * 64 + m * 16 + fr, k * 32 + fq * 8))
; #define LDB(dst, b, h) for (int n = 0; n < 2; ++n) for (int k = 0; k < 2; ++k) \
;     dst[n][k] = *reinterpret_cast<const bf16x8*>((char*)SB(b, h) + lds_byte(wc * 32 + n * 16 + fr, k * 32 + fq * 8))
; #define MMA(ai, bj, At_, Bt_) do { __builtin_amdgcn_s_setprio(1); \
;     for (int k = 0; k < 2; ++k) for (int m = 0; m < 4; ++m) for (int n = 0; n < 2; ++n) \
;       acc[ai][bj][m][n] = __builtin_amdgcn_mfma_f32_16x16x32_bf16(At_[m][k], Bt_[n][k], acc[ai][bj][m][n], 0, 0, 0); \
;     __builtin_amdgcn_s_setprio(0); } while (0)
; #define WAIT_V(n) asm volatile("s_waitcnt vmcnt(" #n ")" ::: "memory")
; #define WAIT_L(n) asm volatile("s_waitcnt lgkmcnt(" #n ")" ::: "memory")
; #define BAR __builtin_amdgcn_s_barrier()
; template <int EPI, int lda, int ldb, int N, int K>
; __device__ __forceinline__ void gemm_phase(const u16* __restrict__ A, const u16* __restrict__ Bt, const GemmEpi ep, int wv) {
;     ...
;     { LDB(B0, 0, 0); LDA(At, 0, 0); STAGE(SA(1, 1), Ab, lda, brow + HALF, nt - 1);
;       BAR; WAIT_L(0); MMA(0, 0, At, B0); BAR;
;       LDB(B1, 0, 1); BAR; WAIT_L(0); MMA(0, 1, At, B1); BAR;
;       LDA(At, 0, 1); WAIT_V(4); BAR; WAIT_L(0); MMA(1, 0, At, B0); MMA(1, 1, At, B1); BAR; }
;     { LDB(B0, 1, 0); LDA(At, 1, 0); WAIT_V(2); BAR; WAIT_L(0); MMA(0, 0, At, B0); BAR;
	v_mfma_f32_16x16x32_bf16 v[100:103], v[138:141], v[206:209], v[100:103]
	v_mfma_f32_16x16x32_bf16 v[96:99], v[174:177], v[206:209], v[96:99]
	ds_read_b128 v[210:213], v163
	ds_read_b128 v[214:217], v163 offset:1024
	ds_read_b128 v[218:221], v163 offset:2048
	ds_read_b128 v[160:163], v163 offset:3072
	s_barrier
	s_waitcnt lgkmcnt(0)
	v_mfma_f32_16x16x32_bf16 v[92:95], v[210:213], v[178:181], v[92:95]
	v_mfma_f32_16x16x32_bf16 v[88:91], v[218:221], v[178:181], v[88:91]
	v_mfma_f32_16x16x32_bf16 v[76:79], v[210:213], v[194:197], v[76:79]
	v_mfma_f32_16x16x32_bf16 v[72:75], v[218:221], v[194:197], v[72:75]
	v_mfma_f32_16x16x32_bf16 v[84:87], v[210:213], v[186:189], v[84:87]
	v_mfma_f32_16x16x32_bf16 v[80:83], v[218:221], v[186:189], v[80:83]
	v_mfma_f32_16x16x32_bf16 v[68:71], v[210:213], v[202:205], v[68:71]
	v_mfma_f32_16x16x32_bf16 v[64:67], v[218:221], v[202:205], v[64:67]
	v_mfma_f32_16x16x32_bf16 v[92:95], v[214:217], v[182:185], v[92:95]
	v_mfma_f32_16x16x32_bf16 v[88:91], v[160:163], v[182:185], v[88:91]
	v_mfma_f32_16x16x32_bf16 v[76:79], v[214:217], v[198:201], v[76:79]
	v_mfma_f32_16x16x32_bf16 v[72:75], v[160:163], v[198:201], v[72:75]
	v_mfma_f32_16x16x32_bf16 v[178:181], v[214:217], v[190:193], v[84:87]
	v_mfma_f32_16x16x32_bf16 v[182:185], v[160:163], v[190:193], v[80:83]
	s_barrier
	v_mfma_f32_16x16x32_bf16 v[186:189], v[214:217], v[206:209], v[68:71]
	v_mfma_f32_16x16x32_bf16 v[190:193], v[160:163], v[206:209], v[64:67]
	s_nop 0
	ds_read_b128 v[64:67], v155 offset:16384
	ds_read_b128 v[68:71], v155 offset:17408
	ds_read_b128 v[80:83], v154 offset:16384
	ds_read_b128 v[84:87], v154 offset:17408
	ds_read_b128 v[194:197], v153 offset:16384
	ds_read_b128 v[198:201], v153 offset:17408
	ds_read_b128 v[202:205], v152 offset:16384
	ds_read_b128 v[206:209], v152 offset:17408
	s_waitcnt vmcnt(4)
	s_barrier
	s_waitcnt lgkmcnt(0)
	v_mfma_f32_16x16x32_bf16 v[60:63], v[134:137], v[64:67], v[60:63]
	v_mfma_f32_16x16x32_bf16 v[56:59], v[142:145], v[64:67], v[56:59]
	v_mfma_f32_16x16x32_bf16 v[52:55], v[134:137], v[80:83], v[52:55]
	v_mfma_f32_16x16x32_bf16 v[48:51], v[142:145], v[80:83], v[48:51]
	v_mfma_f32_16x16x32_bf16 v[44:47], v[134:137], v[194:197], v[44:47]
	v_mfma_f32_16x16x32_bf16 v[40:43], v[142:145], v[194:197], v[40:43]
	v_mfma_f32_16x16x32_bf16 v[36:39], v[134:137], v[202:205], v[36:39]
	v_mfma_f32_16x16x32_bf16 v[32:35], v[142:145], v[202:205], v[32:35]
	v_mfma_f32_16x16x32_bf16 v[60:63], v[138:141], v[68:71], v[60:63]
	v_mfma_f32_16x16x32_bf16 v[56:59], v[174:177], v[68:71], v[56:59]
	v_mfma_f32_16x16x32_bf16 v[52:55], v[138:141], v[84:87], v[52:55]
	v_mfma_f32_16x16x32_bf16 v[48:51], v[174:177], v[84:87], v[48:51]
	v_mfma_f32_16x16x32_bf16 v[44:47], v[138:141], v[198:201], v[44:47]
	v_mfma_f32_16x16x32_bf16 v[40:43], v[174:177], v[198:201], v[40:43]
	v_mfma_f32_16x16x32_bf16 v[36:39], v[138:141], v[206:209], v[36:39]
	v_mfma_f32_16x16x32_bf16 v[32:35], v[174:177], v[206:209], v[32:35]
	v_mfma_f32_16x16x32_bf16 v[28:31], v[210:213], v[64:67], v[28:31]
	v_mfma_f32_16x16x32_bf16 v[16:19], v[218:221], v[80:83], v[16:19]
	v_mfma_f32_16x16x32_bf16 v[12:15], v[210:213], v[194:197], v[12:15]
	v_mfma_f32_16x16x32_bf16 v[0:3], v[218:221], v[202:205], v[0:3]
	v_mfma_f32_16x16x32_bf16 v[24:27], v[218:221], v[64:67], v[24:27]
	v_mfma_f32_16x16x32_bf16 v[20:23], v[210:213], v[80:83], v[20:23]
	v_mfma_f32_16x16x32_bf16 v[8:11], v[218:221], v[194:197], v[8:11]
	v_mfma_f32_16x16x32_bf16 v[4:7], v[210:213], v[202:205], v[4:7]
	v_mfma_f32_16x16x32_bf16 v[28:31], v[214:217], v[68:71], v[28:31]
	v_mfma_f32_16x16x32_bf16 v[16:19], v[160:163], v[84:87], v[16:19]
	v_mfma_f32_16x16x32_bf16 v[12:15], v[214:217], v[198:201], v[12:15]
	v_mfma_f32_16x16x32_bf16 v[0:3], v[160:163], v[206:209], v[0:3]
	v_mfma_f32_16x16x32_bf16 v[134:137], v[160:163], v[68:71], v[24:27]
	v_mfma_f32_16x16x32_bf16 v[138:141], v[214:217], v[84:87], v[20:23]
	s_barrier
	v_mfma_f32_16x16x32_bf16 v[142:145], v[160:163], v[198:201], v[8:11]
	v_mfma_f32_16x16x32_bf16 v[172:175], v[214:217], v[206:209], v[4:7]
	s_nop 0
	ds_read_b128 v[4:7], v159
	ds_read_b128 v[8:11], v159 offset:1024
	ds_read_b128 v[20:23], v159 offset:2048
	ds_read_b128 v[158:161], v159 offset:3072
	ds_read_b128 v[24:27], v155 offset:32768
	ds_read_b128 v[194:197], v155 offset:33792
	ds_read_b128 v[198:201], v154 offset:32768
	ds_read_b128 v[202:205], v154 offset:33792
	ds_read_b128 v[206:209], v153 offset:32768
	ds_read_b128 v[210:213], v153 offset:33792
	ds_read_b128 v[214:217], v152 offset:32768
	ds_read_b128 v[218:221], v152 offset:33792
	s_waitcnt vmcnt(2)
	s_barrier
; #define LDA(dst, b, h) for (int m = 0; m < 4; ++m) for (int k = 0; k < 2; ++k) \
;     dst[m][k] = *reinterpret_cast<const bf16x8*>((char*)SA(b, h) + lds_byte(wr * 64 + m * 16 + fr, k * 32 + fq * 8))
; #define LDB(dst, b, h) for (int n = 0; n < 2; ++n) for (int k = 0; k < 2; ++k) \
;     dst[n][k] = *reinterpret_cast<const bf16x8*>((char*)SB(b, h) + lds_byte(wc * 32 + n * 16 + fr, k * 32 + fq * 8))
; #define MMA(ai, bj, At_, Bt_) do { __builtin_amdgcn_s_setprio(1); \
;     for (int k = 0; k < 2; ++k) for (int m = 0; m < 4; ++m) for (int n = 0; n < 2; ++n) \
;       acc[ai][bj][m][n] = __builtin_amdgcn_mfma_f32_16x16x32_bf16(At_[m][k], Bt_[n][k], acc[ai][bj][m][n], 0, 0, 0); \
;     __builtin_amdgcn_s_setprio(0); } while (0)
; #define WAIT_V(n) asm volatile("s_waitcnt vmcnt(" #n ")" ::: "memory")
; #define WAIT_L(n) asm volatile("s_waitcnt lgkmcnt(" #n ")" ::: "memory")
; #define BAR __builtin_amdgcn_s_barrier()
; template <int EPI, int lda, int ldb, int N, int K>
; __device__ __forceinline__ void gemm_phase(const u16* __restrict__ A, const u16* __restrict__ Bt, const GemmEpi ep, int wv) {
;     ...
;       BAR; WAIT_L(0); MMA(0, 0, At, B0); BAR;
;       LDB(B1, 0, 1); BAR; WAIT_L(0); MMA(0, 1, At, B1); BAR;
;       LDA(At, 0, 1); WAIT_V(4); BAR; WAIT_L(0); MMA(1, 0, At, B0); MMA(1, 1, At, B1); BAR; }
;     { LDB(B0, 1, 0); LDA(At, 1, 0); WAIT_V(2); BAR; WAIT_L(0); MMA(0, 0, At, B0); BAR;
;       LDB(B1, 1, 1); WAIT_V(0); BAR; WAIT_L(0); MMA(0, 1, At, B1); BAR;
;       LDA(At, 1, 1); BAR; WAIT_L(0); MMA(1, 0, At, B0); MMA(1, 1, At, B1); BAR; }
;     if (wr == 0) BAR;
	s_waitcnt lgkmcnt(0)
	v_mfma_f32_16x16x32_bf16 v[64:67], v[4:7], v[24:27], v[124:127]
	v_mfma_f32_16x16x32_bf16 v[68:71], v[20:23], v[24:27], v[120:123]
	v_mfma_f32_16x16x32_bf16 v[80:83], v[4:7], v[198:201], v[116:119]
	v_mfma_f32_16x16x32_bf16 v[84:87], v[20:23], v[198:201], v[112:115]
	v_mfma_f32_16x16x32_bf16 v[108:111], v[4:7], v[206:209], v[108:111]
	v_mfma_f32_16x16x32_bf16 v[104:107], v[20:23], v[206:209], v[104:107]
	v_mfma_f32_16x16x32_bf16 v[120:123], v[4:7], v[214:217], v[100:103]
	v_mfma_f32_16x16x32_bf16 v[124:127], v[20:23], v[214:217], v[96:99]
	v_mfma_f32_16x16x32_bf16 v[116:119], v[8:11], v[194:197], v[64:67]
	v_mfma_f32_16x16x32_bf16 v[112:115], v[158:161], v[194:197], v[68:71]
	v_mfma_f32_16x16x32_bf16 v[100:103], v[8:11], v[202:205], v[80:83]
	v_mfma_f32_16x16x32_bf16 v[96:99], v[158:161], v[202:205], v[84:87]
	v_mfma_f32_16x16x32_bf16 v[84:87], v[8:11], v[210:213], v[108:111]
	v_mfma_f32_16x16x32_bf16 v[80:83], v[158:161], v[210:213], v[104:107]
	s_barrier
	v_mfma_f32_16x16x32_bf16 v[68:71], v[8:11], v[218:221], v[120:123]
	v_mfma_f32_16x16x32_bf16 v[64:67], v[158:161], v[218:221], v[124:127]
	ds_read_b128 v[222:225], v157
	ds_read_b128 v[226:229], v157 offset:1024
	ds_read_b128 v[230:233], v157 offset:2048
	ds_read_b128 v[234:237], v157 offset:3072
	s_waitcnt vmcnt(0)
	s_barrier
	s_waitcnt lgkmcnt(0)
	v_mfma_f32_16x16x32_bf16 v[92:95], v[222:225], v[24:27], v[92:95]
	v_mfma_f32_16x16x32_bf16 v[24:27], v[230:233], v[24:27], v[88:91]
	v_mfma_f32_16x16x32_bf16 v[88:91], v[222:225], v[198:201], v[178:181]
	v_mfma_f32_16x16x32_bf16 v[104:107], v[230:233], v[198:201], v[182:185]
	v_mfma_f32_16x16x32_bf16 v[76:79], v[222:225], v[206:209], v[76:79]
	v_mfma_f32_16x16x32_bf16 v[72:75], v[230:233], v[206:209], v[72:75]
	v_mfma_f32_16x16x32_bf16 v[176:179], v[222:225], v[214:217], v[186:189]
	v_mfma_f32_16x16x32_bf16 v[180:183], v[230:233], v[214:217], v[190:193]
	v_mfma_f32_16x16x32_bf16 v[124:127], v[226:229], v[194:197], v[92:95]
	v_mfma_f32_16x16x32_bf16 v[120:123], v[234:237], v[194:197], v[24:27]
	v_mfma_f32_16x16x32_bf16 v[108:111], v[226:229], v[202:205], v[88:91]
	v_mfma_f32_16x16x32_bf16 v[104:107], v[234:237], v[202:205], v[104:107]
	v_mfma_f32_16x16x32_bf16 v[92:95], v[226:229], v[210:213], v[76:79]
	v_mfma_f32_16x16x32_bf16 v[88:91], v[234:237], v[210:213], v[72:75]
	s_barrier
	v_mfma_f32_16x16x32_bf16 v[76:79], v[226:229], v[218:221], v[176:179]
	v_mfma_f32_16x16x32_bf16 v[72:75], v[234:237], v[218:221], v[180:183]
	ds_read_b128 v[176:179], v155 offset:49152
	ds_read_b128 v[180:183], v155 offset:50176
	ds_read_b128 v[184:187], v154 offset:49152
	ds_read_b128 v[154:157], v154 offset:50176
	ds_read_b128 v[188:191], v153 offset:49152
	ds_read_b128 v[192:195], v153 offset:50176
	ds_read_b128 v[196:199], v152 offset:49152
	ds_read_b128 v[200:203], v152 offset:50176
	s_barrier
	s_waitcnt lgkmcnt(0)
	v_mfma_f32_16x16x32_bf16 v[24:27], v[4:7], v[176:179], v[60:63]
	v_mfma_f32_16x16x32_bf16 v[60:63], v[20:23], v[176:179], v[56:59]
	v_mfma_f32_16x16x32_bf16 v[204:207], v[4:7], v[184:187], v[52:55]
	v_mfma_f32_16x16x32_bf16 v[48:51], v[20:23], v[184:187], v[48:51]
	v_mfma_f32_16x16x32_bf16 v[44:47], v[4:7], v[188:191], v[44:47]
	v_mfma_f32_16x16x32_bf16 v[208:211], v[20:23], v[188:191], v[40:43]
	v_mfma_f32_16x16x32_bf16 v[4:7], v[4:7], v[196:199], v[36:39]
	v_mfma_f32_16x16x32_bf16 v[32:35], v[20:23], v[196:199], v[32:35]
	v_mfma_f32_16x16x32_bf16 v[56:59], v[8:11], v[180:183], v[24:27]
	v_mfma_f32_16x16x32_bf16 v[52:55], v[158:161], v[180:183], v[60:63]
	v_mfma_f32_16x16x32_bf16 v[40:43], v[8:11], v[154:157], v[204:207]
	v_mfma_f32_16x16x32_bf16 v[36:39], v[158:161], v[154:157], v[48:51]
	v_mfma_f32_16x16x32_bf16 v[24:27], v[8:11], v[192:195], v[44:47]
	v_mfma_f32_16x16x32_bf16 v[20:23], v[158:161], v[192:195], v[208:211]
	v_mfma_f32_16x16x32_bf16 v[8:11], v[8:11], v[200:203], v[4:7]
	v_mfma_f32_16x16x32_bf16 v[4:7], v[158:161], v[200:203], v[32:35]
	v_mfma_f32_16x16x32_bf16 v[28:31], v[222:225], v[176:179], v[28:31]
	v_mfma_f32_16x16x32_bf16 v[32:35], v[230:233], v[176:179], v[134:137]
	v_mfma_f32_16x16x32_bf16 v[44:47], v[222:225], v[184:187], v[138:141]
	v_mfma_f32_16x16x32_bf16 v[16:19], v[230:233], v[184:187], v[16:19]
	v_mfma_f32_16x16x32_bf16 v[12:15], v[222:225], v[188:191], v[12:15]
	v_mfma_f32_16x16x32_bf16 v[134:137], v[230:233], v[188:191], v[142:145]
	v_mfma_f32_16x16x32_bf16 v[138:141], v[222:225], v[196:199], v[172:175]
	v_mfma_f32_16x16x32_bf16 v[0:3], v[230:233], v[196:199], v[0:3]
	v_mfma_f32_16x16x32_bf16 v[60:63], v[226:229], v[180:183], v[28:31]
	v_mfma_f32_16x16x32_bf16 v[48:51], v[234:237], v[180:183], v[32:35]
	v_mfma_f32_16x16x32_bf16 v[44:47], v[226:229], v[154:157], v[44:47]
	v_mfma_f32_16x16x32_bf16 v[32:35], v[234:237], v[154:157], v[16:19]
	v_mfma_f32_16x16x32_bf16 v[28:31], v[226:229], v[192:195], v[12:15]
	v_mfma_f32_16x16x32_bf16 v[16:19], v[234:237], v[192:195], v[134:137]
	s_barrier
	v_mfma_f32_16x16x32_bf16 v[12:15], v[226:229], v[200:203], v[138:141]
	v_mfma_f32_16x16x32_bf16 v[0:3], v[234:237], v[200:203], v[0:3]
	v_cmp_gt_u32_e32 vcc, s69, v130
	s_and_saveexec_b64 s[50:51], vcc
	s_cbranch_execz .LBB0_841
	s_barrier

; #define STAGE(P, BASE, LD, br, kt) do { const char* _g = (const char*)((BASE) + (size_t)(br) * (LD) + (size_t)(kt) * 64); \
;     for (int _i = 0; _i < 2; ++_i) { int _b = tidx * 16 + _i * 8192; int _r, _c; stage_rc(_b, _r, _c); \
;       __builtin_amdgcn_global_load_lds((const unsigned*)(_g + (unsigned)((_r * (LD) + _c) * 2)), (unsigned*)((char*)(P) + _b), 16, 0, 0); } } while (0)
; #define LDA(dst, b, h) for (int m = 0; m < 4; ++m) for (int k = 0; k < 2; ++k) \
;     dst[m][k] = *reinterpret_cast<const bf16x8*>((char*)SA(b, h) + lds_byte(wr * 64 + m * 16 + fr, k * 32 + fq * 8))
; #define LDB(dst, b, h) for (int n = 0; n < 2; ++n) for (int k = 0; k < 2; ++k) \
;     dst[n][k] = *reinterpret_cast<const bf16x8*>((char*)SB(b, h) + lds_byte(wc * 32 + n * 16 + fr, k * 32 + fq * 8))
; #define MMA(ai, bj, At_, Bt_) do { __builtin_amdgcn_s_setprio(1); \
;     for (int k = 0; k < 2; ++k) for (int m = 0; m < 4; ++m) for (int n = 0; n < 2; ++n) \
;       acc[ai][bj][m][n] = __builtin_amdgcn_mfma_f32_16x16x32_bf16(At_[m][k], Bt_[n][k], acc[ai][bj][m][n], 0, 0, 0); \
;     __builtin_amdgcn_s_setprio(0); } while (0)
; #define WAIT_V(n) asm volatile("s_waitcnt vmcnt(" #n ")" ::: "memory")
; #define WAIT_L(n) asm volatile("s_waitcnt lgkmcnt(" #n ")" ::: "memory")
; #define BAR __builtin_amdgcn_s_barrier()
; #define SCHED __builtin_amdgcn_sched_barrier(0)
; template <int EPI, int lda, int ldb, int N, int K>
; __device__ __forceinline__ void gemm_phase(const u16* __restrict__ A, const u16* __restrict__ Bt, const GemmEpi ep, int wv) {
;     ...
;     for (int t = 0; t < nt - 2; t += 2) {
;       LDB(B0, 0, 0); SCHED; LDA(At, 0, 0); STAGE(SA(1, 1), Ab, lda, brow + HALF, t + 1);
;       WAIT_L(8); BAR; WAIT_L(0); MMA(0, 0, At, B0); BAR; SCHED;
;       LDB(B1, 0, 1); STAGE(SB(0, 0), Bt, ldb, bcol, t + 2);
;       BAR; WAIT_L(0); MMA(0, 1, At, B1); BAR;
;       LDA(At, 0, 1); STAGE(SA(0, 0), Ab, lda, brow, t + 2);
;       BAR; WAIT_L(0); MMA(1, 0, At, B0); BAR; SCHED;
;       STAGE(SB(0, 1), Bt, ldb, bcol + HALF, t + 2);
;       WAIT_V(6); BAR; MMA(1, 1, At, B1); BAR;
.LBB0_1147:
	ds_read_b128 v[172:175], v161
	ds_read_b128 v[176:179], v161 offset:1024
	ds_read_b128 v[180:183], v161 offset:2048
	ds_read_b128 v[184:187], v161 offset:3072
	v_add_u32_e32 v169, 0xc000, v148
	v_lshl_add_u64 v[236:237], v[138:139], 0, s[60:61]
	v_readfirstlane_b32 s63, v169
	v_add_u32_e32 v170, 0xe000, v148
	v_lshl_add_u64 v[162:163], v[236:237], 0, s[22:23]
	s_mov_b32 m0, s63
	v_lshl_add_u64 v[238:239], v[140:141], 0, s[60:61]
	v_readfirstlane_b32 s63, v170
	ds_read_b128 v[164:167], v152
	ds_read_b128 v[188:191], v152 offset:1024
	ds_read_b128 v[192:195], v151
	ds_read_b128 v[196:199], v151 offset:1024
	ds_read_b128 v[200:203], v150
	ds_read_b128 v[204:207], v150 offset:1024
	ds_read_b128 v[208:211], v149
	ds_read_b128 v[212:215], v149 offset:1024
	global_load_lds_dwordx4 v[162:163], off
	v_lshl_add_u64 v[162:163], v[238:239], 0, s[22:23]
	s_mov_b32 m0, s63
	s_nop 0
	global_load_lds_dwordx4 v[162:163], off
	s_waitcnt lgkmcnt(8)
	s_barrier
	s_waitcnt lgkmcnt(0)
	v_mfma_f32_16x16x32_bf16 v[124:127], v[164:167], v[172:175], v[124:127]
	v_mfma_f32_16x16x32_bf16 v[120:123], v[164:167], v[180:183], v[120:123]
	v_mfma_f32_16x16x32_bf16 v[116:119], v[192:195], v[172:175], v[116:119]
	v_mfma_f32_16x16x32_bf16 v[112:115], v[192:195], v[180:183], v[112:115]
	v_mfma_f32_16x16x32_bf16 v[108:111], v[200:203], v[172:175], v[108:111]
	v_mfma_f32_16x16x32_bf16 v[104:107], v[200:203], v[180:183], v[104:107]
	v_mfma_f32_16x16x32_bf16 v[100:103], v[208:211], v[172:175], v[100:103]
	v_mfma_f32_16x16x32_bf16 v[96:99], v[208:211], v[180:183], v[96:99]
	v_mfma_f32_16x16x32_bf16 v[124:127], v[188:191], v[176:179], v[124:127]
	v_mfma_f32_16x16x32_bf16 v[120:123], v[188:191], v[184:187], v[120:123]
	v_mfma_f32_16x16x32_bf16 v[116:119], v[196:199], v[176:179], v[116:119]
	v_mfma_f32_16x16x32_bf16 v[112:115], v[196:199], v[184:187], v[112:115]
	v_mfma_f32_16x16x32_bf16 v[108:111], v[204:207], v[176:179], v[108:111]
	v_mfma_f32_16x16x32_bf16 v[104:107], v[204:207], v[184:187], v[104:107]
	s_barrier
	v_mfma_f32_16x16x32_bf16 v[100:103], v[212:215], v[176:179], v[100:103]
	v_mfma_f32_16x16x32_bf16 v[96:99], v[212:215], v[184:187], v[96:99]
	v_add_u32_e32 v162, s75, v154
	v_lshl_add_u64 v[240:241], v[134:135], 0, s[60:61]
	v_readfirstlane_b32 s63, v162
	v_add_u32_e32 v163, 0x2000, v162
	v_lshl_add_u64 v[232:233], v[240:241], 0, s[24:25]
	s_mov_b32 m0, s63
	v_lshl_add_u64 v[242:243], v[136:137], 0, s[60:61]
	v_readfirstlane_b32 s63, v163
	ds_read_b128 v[216:219], v160
	ds_read_b128 v[220:223], v160 offset:1024
	ds_read_b128 v[224:227], v160 offset:2048
	ds_read_b128 v[228:231], v160 offset:3072
	global_load_lds_dwordx4 v[232:233], off
	v_lshl_add_u64 v[232:233], v[242:243], 0, s[24:25]
	s_mov_b32 m0, s63
	s_nop 0
	global_load_lds_dwordx4 v[232:233], off
	s_barrier
	s_waitcnt lgkmcnt(0)
	v_mfma_f32_16x16x32_bf16 v[92:95], v[164:167], v[216:219], v[92:95]
	v_mfma_f32_16x16x32_bf16 v[88:91], v[164:167], v[224:227], v[88:91]
	v_mfma_f32_16x16x32_bf16 v[84:87], v[192:195], v[216:219], v[84:87]
	v_mfma_f32_16x16x32_bf16 v[80:83], v[192:195], v[224:227], v[80:83]
	v_mfma_f32_16x16x32_bf16 v[76:79], v[200:203], v[216:219], v[76:79]
	v_mfma_f32_16x16x32_bf16 v[72:75], v[200:203], v[224:227], v[72:75]
	v_mfma_f32_16x16x32_bf16 v[68:71], v[208:211], v[216:219], v[68:71]
	v_mfma_f32_16x16x32_bf16 v[64:67], v[208:211], v[224:227], v[64:67]
	v_mfma_f32_16x16x32_bf16 v[92:95], v[188:191], v[220:223], v[92:95]
	v_mfma_f32_16x16x32_bf16 v[88:91], v[188:191], v[228:231], v[88:91]
	v_mfma_f32_16x16x32_bf16 v[84:87], v[196:199], v[220:223], v[84:87]
	v_mfma_f32_16x16x32_bf16 v[80:83], v[196:199], v[228:231], v[80:83]
	v_mfma_f32_16x16x32_bf16 v[76:79], v[204:207], v[220:223], v[76:79]
	v_mfma_f32_16x16x32_bf16 v[72:75], v[204:207], v[228:231], v[72:75]
	s_barrier
	v_mfma_f32_16x16x32_bf16 v[68:71], v[212:215], v[220:223], v[68:71]
	v_mfma_f32_16x16x32_bf16 v[64:67], v[212:215], v[228:231], v[64:67]
	v_readfirstlane_b32 s63, v148
	v_lshl_add_u64 v[164:165], v[236:237], 0, s[26:27]
	s_mov_b32 m0, s63
	ds_read_b128 v[188:191], v152 offset:16384
	ds_read_b128 v[192:195], v152 offset:17408
	ds_read_b128 v[196:199], v151 offset:16384
	ds_read_b128 v[200:203], v151 offset:17408
	ds_read_b128 v[204:207], v150 offset:16384
	ds_read_b128 v[208:211], v150 offset:17408
	ds_read_b128 v[212:215], v149 offset:16384
	ds_read_b128 v[232:235], v149 offset:17408
	global_load_lds_dwordx4 v[164:165], off
	v_add_u32_e32 v164, 0x2000, v148
	v_lshl_add_u64 v[166:167], v[238:239], 0, s[26:27]
	v_readfirstlane_b32 s63, v164
	s_mov_b32 m0, s63
	s_nop 0
	global_load_lds_dwordx4 v[166:167], off
	s_barrier
	s_waitcnt lgkmcnt(0)
	v_mfma_f32_16x16x32_bf16 v[60:63], v[188:191], v[172:175], v[60:63]
	v_mfma_f32_16x16x32_bf16 v[56:59], v[188:191], v[180:183], v[56:59]
	v_mfma_f32_16x16x32_bf16 v[52:55], v[196:199], v[172:175], v[52:55]
	v_mfma_f32_16x16x32_bf16 v[48:51], v[196:199], v[180:183], v[48:51]
	v_mfma_f32_16x16x32_bf16 v[44:47], v[204:207], v[172:175], v[44:47]
	v_mfma_f32_16x16x32_bf16 v[40:43], v[204:207], v[180:183], v[40:43]
	v_mfma_f32_16x16x32_bf16 v[36:39], v[212:215], v[172:175], v[36:39]
	v_mfma_f32_16x16x32_bf16 v[32:35], v[212:215], v[180:183], v[32:35]
	v_mfma_f32_16x16x32_bf16 v[60:63], v[192:195], v[176:179], v[60:63]
	v_mfma_f32_16x16x32_bf16 v[56:59], v[192:195], v[184:187], v[56:59]
	v_mfma_f32_16x16x32_bf16 v[52:55], v[200:203], v[176:179], v[52:55]
	v_mfma_f32_16x16x32_bf16 v[48:51], v[200:203], v[184:187], v[48:51]
	v_mfma_f32_16x16x32_bf16 v[44:47], v[208:211], v[176:179], v[44:47]
	v_mfma_f32_16x16x32_bf16 v[40:43], v[208:211], v[184:187], v[40:43]
	s_barrier
; #define STAGE(P, BASE, LD, br, kt) do { const char* _g = (const char*)((BASE) + (size_t)(br) * (LD) + (size_t)(kt) * 64); \
;     for (int _i = 0; _i < 2; ++_i) { int _b = tidx * 16 + _i * 8192; int _r, _c; stage_rc(_b, _r, _c); \
;       __builtin_amdgcn_global_load_lds((const unsigned*)(_g + (unsigned)((_r * (LD) + _c) * 2)), (unsigned*)((char*)(P) + _b), 16, 0, 0); } } while (0)
; #define LDA(dst, b, h) for (int m = 0; m < 4; ++m) for (int k = 0; k < 2; ++k) \
;     dst[m][k] = *reinterpret_cast<const bf16x8*>((char*)SA(b, h) + lds_byte(wr * 64 + m * 16 + fr, k * 32 + fq * 8))
; #define LDB(dst, b, h) for (int n = 0; n < 2; ++n) for (int k = 0; k < 2; ++k) \
;     dst[n][k] = *reinterpret_cast<const bf16x8*>((char*)SB(b, h) + lds_byte(wc * 32 + n * 16 + fr, k * 32 + fq * 8))
; #define MMA(ai, bj, At_, Bt_) do { __builtin_amdgcn_s_setprio(1); \
;     for (int k = 0; k < 2; ++k) for (int m = 0; m < 4; ++m) for (int n = 0; n < 2; ++n) \
;       acc[ai][bj][m][n] = __builtin_amdgcn_mfma_f32_16x16x32_bf16(At_[m][k], Bt_[n][k], acc[ai][bj][m][n], 0, 0, 0); \
;     __builtin_amdgcn_s_setprio(0); } while (0)
; #define WAIT_V(n) asm volatile("s_waitcnt vmcnt(" #n ")" ::: "memory")
; #define WAIT_L(n) asm volatile("s_waitcnt lgkmcnt(" #n ")" ::: "memory")
; #define BAR __builtin_amdgcn_s_barrier()
; #define SCHED __builtin_amdgcn_sched_barrier(0)
; template <int EPI, int lda, int ldb, int N, int K>
; __device__ __forceinline__ void gemm_phase(const u16* __restrict__ A, const u16* __restrict__ Bt, const GemmEpi ep, int wv) {
;     ...
;       WAIT_V(6); BAR; MMA(1, 1, At, B1); BAR;
;       LDB(B0, 1, 0); SCHED; LDA(At, 1, 0); STAGE(SA(0, 1), Ab, lda, brow + HALF, t + 2);
;       WAIT_L(8); BAR; WAIT_L(0); MMA(0, 0, At, B0); BAR; SCHED;
;       LDB(B1, 1, 1); STAGE(SB(1, 0), Bt, ldb, bcol, t + 3);
;       BAR; WAIT_L(0); MMA(0, 1, At, B1); BAR;
;       LDA(At, 1, 1); STAGE(SA(1, 0), Ab, lda, brow, t + 3);
;       BAR; WAIT_L(0); MMA(1, 0, At, B0); BAR; SCHED;
	v_mfma_f32_16x16x32_bf16 v[36:39], v[232:235], v[176:179], v[36:39]
	v_mfma_f32_16x16x32_bf16 v[32:35], v[232:235], v[184:187], v[32:35]
	v_add_u32_e32 v165, s76, v154
	v_lshl_add_u64 v[166:167], v[240:241], 0, s[40:41]
	v_readfirstlane_b32 s63, v165
	s_mov_b32 m0, s63
	v_lshl_add_u64 v[172:173], v[242:243], 0, s[40:41]
	global_load_lds_dwordx4 v[166:167], off
	v_add_u32_e32 v166, 0x2000, v165
	s_nop 0
	v_readfirstlane_b32 s63, v166
	s_mov_b32 m0, s63
	s_nop 0
	global_load_lds_dwordx4 v[172:173], off
	s_waitcnt vmcnt(6)
	s_barrier
	v_mfma_f32_16x16x32_bf16 v[28:31], v[188:191], v[216:219], v[28:31]
	v_mfma_f32_16x16x32_bf16 v[24:27], v[188:191], v[224:227], v[24:27]
	v_mfma_f32_16x16x32_bf16 v[20:23], v[196:199], v[216:219], v[20:23]
	v_mfma_f32_16x16x32_bf16 v[16:19], v[196:199], v[224:227], v[16:19]
	v_mfma_f32_16x16x32_bf16 v[12:15], v[204:207], v[216:219], v[12:15]
	v_mfma_f32_16x16x32_bf16 v[8:11], v[204:207], v[224:227], v[8:11]
	v_mfma_f32_16x16x32_bf16 v[4:7], v[212:215], v[216:219], v[4:7]
	v_mfma_f32_16x16x32_bf16 v[0:3], v[212:215], v[224:227], v[0:3]
	v_mfma_f32_16x16x32_bf16 v[28:31], v[192:195], v[220:223], v[28:31]
	v_mfma_f32_16x16x32_bf16 v[24:27], v[192:195], v[228:231], v[24:27]
	v_mfma_f32_16x16x32_bf16 v[20:23], v[200:203], v[220:223], v[20:23]
	v_mfma_f32_16x16x32_bf16 v[16:19], v[200:203], v[228:231], v[16:19]
	v_mfma_f32_16x16x32_bf16 v[12:15], v[208:211], v[220:223], v[12:15]
	v_mfma_f32_16x16x32_bf16 v[8:11], v[208:211], v[228:231], v[8:11]
	s_barrier
	v_mfma_f32_16x16x32_bf16 v[4:7], v[232:235], v[220:223], v[4:7]
	v_mfma_f32_16x16x32_bf16 v[0:3], v[232:235], v[228:231], v[0:3]
	ds_read_b128 v[172:175], v155
	ds_read_b128 v[176:179], v155 offset:1024
	ds_read_b128 v[180:183], v155 offset:2048
	ds_read_b128 v[184:187], v155 offset:3072
	v_add_u32_e32 v167, 0x4000, v148
	v_add_u32_e32 v168, 0x6000, v148
	v_readfirstlane_b32 s63, v167
	v_lshl_add_u64 v[220:221], v[236:237], 0, s[42:43]
	s_mov_b32 m0, s63
	v_readfirstlane_b32 s63, v168
	ds_read_b128 v[188:191], v152 offset:32768
	ds_read_b128 v[192:195], v152 offset:33792
	ds_read_b128 v[196:199], v151 offset:32768
	ds_read_b128 v[200:203], v151 offset:33792
	ds_read_b128 v[204:207], v150 offset:32768
	ds_read_b128 v[208:211], v150 offset:33792
	ds_read_b128 v[212:215], v149 offset:32768
	ds_read_b128 v[216:219], v149 offset:33792
	global_load_lds_dwordx4 v[220:221], off
	v_lshl_add_u64 v[220:221], v[238:239], 0, s[42:43]
	s_mov_b32 m0, s63
	s_nop 0
	global_load_lds_dwordx4 v[220:221], off
	s_waitcnt lgkmcnt(8)
	s_barrier
	s_waitcnt lgkmcnt(0)
	v_mfma_f32_16x16x32_bf16 v[124:127], v[188:191], v[172:175], v[124:127]
	v_mfma_f32_16x16x32_bf16 v[120:123], v[188:191], v[180:183], v[120:123]
	v_mfma_f32_16x16x32_bf16 v[116:119], v[196:199], v[172:175], v[116:119]
	v_mfma_f32_16x16x32_bf16 v[112:115], v[196:199], v[180:183], v[112:115]
	v_mfma_f32_16x16x32_bf16 v[108:111], v[204:207], v[172:175], v[108:111]
	v_mfma_f32_16x16x32_bf16 v[104:107], v[204:207], v[180:183], v[104:107]
	v_mfma_f32_16x16x32_bf16 v[100:103], v[212:215], v[172:175], v[100:103]
	v_mfma_f32_16x16x32_bf16 v[96:99], v[212:215], v[180:183], v[96:99]
	v_mfma_f32_16x16x32_bf16 v[124:127], v[192:195], v[176:179], v[124:127]
	v_mfma_f32_16x16x32_bf16 v[120:123], v[192:195], v[184:187], v[120:123]
	v_mfma_f32_16x16x32_bf16 v[116:119], v[200:203], v[176:179], v[116:119]
	v_mfma_f32_16x16x32_bf16 v[112:115], v[200:203], v[184:187], v[112:115]
	v_mfma_f32_16x16x32_bf16 v[108:111], v[208:211], v[176:179], v[108:111]
	v_mfma_f32_16x16x32_bf16 v[104:107], v[208:211], v[184:187], v[104:107]
	s_barrier
	v_mfma_f32_16x16x32_bf16 v[100:103], v[216:219], v[176:179], v[100:103]
	v_mfma_f32_16x16x32_bf16 v[96:99], v[216:219], v[184:187], v[96:99]
	v_readfirstlane_b32 s63, v156
	v_add_u32_e32 v171, 0x2000, v156
	v_lshl_add_u64 v[244:245], v[240:241], 0, s[44:45]
	s_mov_b32 m0, s63
	v_readfirstlane_b32 s63, v171
	ds_read_b128 v[220:223], v153
	ds_read_b128 v[224:227], v153 offset:1024
	ds_read_b128 v[228:231], v153 offset:2048
	ds_read_b128 v[232:235], v153 offset:3072
	global_load_lds_dwordx4 v[244:245], off
	v_lshl_add_u64 v[244:245], v[242:243], 0, s[44:45]
	s_mov_b32 m0, s63
	s_nop 0
	global_load_lds_dwordx4 v[244:245], off
	s_barrier
	s_waitcnt lgkmcnt(0)
	v_mfma_f32_16x16x32_bf16 v[92:95], v[188:191], v[220:223], v[92:95]
	v_mfma_f32_16x16x32_bf16 v[88:91], v[188:191], v[228:231], v[88:91]
	v_mfma_f32_16x16x32_bf16 v[84:87], v[196:199], v[220:223], v[84:87]
	v_mfma_f32_16x16x32_bf16 v[80:83], v[196:199], v[228:231], v[80:83]
	v_mfma_f32_16x16x32_bf16 v[76:79], v[204:207], v[220:223], v[76:79]
	v_mfma_f32_16x16x32_bf16 v[72:75], v[204:207], v[228:231], v[72:75]
	v_mfma_f32_16x16x32_bf16 v[68:71], v[212:215], v[220:223], v[68:71]
	v_mfma_f32_16x16x32_bf16 v[64:67], v[212:215], v[228:231], v[64:67]
	v_mfma_f32_16x16x32_bf16 v[92:95], v[192:195], v[224:227], v[92:95]
	v_mfma_f32_16x16x32_bf16 v[88:91], v[192:195], v[232:235], v[88:91]
	v_mfma_f32_16x16x32_bf16 v[84:87], v[200:203], v[224:227], v[84:87]
	v_mfma_f32_16x16x32_bf16 v[80:83], v[200:203], v[232:235], v[80:83]
	v_mfma_f32_16x16x32_bf16 v[76:79], v[208:211], v[224:227], v[76:79]
	v_mfma_f32_16x16x32_bf16 v[72:75], v[208:211], v[232:235], v[72:75]
	s_barrier
	v_mfma_f32_16x16x32_bf16 v[68:71], v[216:219], v[224:227], v[68:71]
	v_mfma_f32_16x16x32_bf16 v[64:67], v[216:219], v[232:235], v[64:67]
	v_readfirstlane_b32 s63, v157
	v_lshl_add_u64 v[236:237], v[236:237], 0, s[46:47]
	s_mov_b32 m0, s63
	v_readfirstlane_b32 s63, v158
	ds_read_b128 v[188:191], v152 offset:49152
	ds_read_b128 v[192:195], v152 offset:50176
	ds_read_b128 v[196:199], v151 offset:49152
	ds_read_b128 v[200:203], v151 offset:50176
	ds_read_b128 v[204:207], v150 offset:49152
	ds_read_b128 v[208:211], v150 offset:50176
	ds_read_b128 v[212:215], v149 offset:49152
	ds_read_b128 v[216:219], v149 offset:50176
	global_load_lds_dwordx4 v[236:237], off
	v_lshl_add_u64 v[236:237], v[238:239], 0, s[46:47]
	s_mov_b32 m0, s63
	s_nop 0
	global_load_lds_dwordx4 v[236:237], off
	s_barrier
; #define STAGE(P, BASE, LD, br, kt) do { const char* _g = (const char*)((BASE) + (size_t)(br) * (LD) + (size_t)(kt) * 64); \
;     for (int _i = 0; _i < 2; ++_i) { int _b = tidx * 16 + _i * 8192; int _r, _c; stage_rc(_b, _r, _c); \
;       __builtin_amdgcn_global_load_lds((const unsigned*)(_g + (unsigned)((_r * (LD) + _c) * 2)), (unsigned*)((char*)(P) + _b), 16, 0, 0); } } while (0)
; #define LDA(dst, b, h) for (int m = 0; m < 4; ++m) for (int k = 0; k < 2; ++k) \
;     dst[m][k] = *reinterpret_cast<const bf16x8*>((char*)SA(b, h) + lds_byte(wr * 64 + m * 16 + fr, k * 32 + fq * 8))
; #define LDB(dst, b, h) for (int n = 0; n < 2; ++n) for (int k = 0; k < 2; ++k) \
;     dst[n][k] = *reinterpret_cast<const bf16x8*>((char*)SB(b, h) + lds_byte(wc * 32 + n * 16 + fr, k * 32 + fq * 8))
; #define MMA(ai, bj, At_, Bt_) do { __builtin_amdgcn_s_setprio(1); \
;     for (int k = 0; k < 2; ++k) for (int m = 0; m < 4; ++m) for (int n = 0; n < 2; ++n) \
;       acc[ai][bj][m][n] = __builtin_amdgcn_mfma_f32_16x16x32_bf16(At_[m][k], Bt_[n][k], acc[ai][bj][m][n], 0, 0, 0); \
;     __builtin_amdgcn_s_setprio(0); } while (0)
; #define WAIT_V(n) asm volatile("s_waitcnt vmcnt(" #n ")" ::: "memory")
; #define WAIT_L(n) asm volatile("s_waitcnt lgkmcnt(" #n ")" ::: "memory")
; #define BAR __builtin_amdgcn_s_barrier()
; #define SCHED __builtin_amdgcn_sched_barrier(0)
; template <int EPI, int lda, int ldb, int N, int K>
; __device__ __forceinline__ void gemm_phase(const u16* __restrict__ A, const u16* __restrict__ Bt, const GemmEpi ep, int wv) {
;     ...
;       BAR; WAIT_L(0); MMA(1, 0, At, B0); BAR; SCHED;
;       STAGE(SB(1, 1), Bt, ldb, bcol + HALF, t + 3);
;       WAIT_V(6); BAR; MMA(1, 1, At, B1); BAR;
;     }
;     { LDB(B0, 0, 0); LDA(At, 0, 0); STAGE(SA(1, 1), Ab, lda, brow + HALF, nt - 1);
;       BAR; WAIT_L(0); MMA(0, 0, At, B0); BAR;
;       LDB(B1, 0, 1); BAR; WAIT_L(0); MMA(0, 1, At, B1); BAR;
;       LDA(At, 0, 1); WAIT_V(4); BAR; WAIT_L(0); MMA(1, 0, At, B0); MMA(1, 1, At, B1); BAR; }
	s_waitcnt lgkmcnt(0)
	v_mfma_f32_16x16x32_bf16 v[60:63], v[188:191], v[172:175], v[60:63]
	v_mfma_f32_16x16x32_bf16 v[56:59], v[188:191], v[180:183], v[56:59]
	v_mfma_f32_16x16x32_bf16 v[52:55], v[196:199], v[172:175], v[52:55]
	v_mfma_f32_16x16x32_bf16 v[48:51], v[196:199], v[180:183], v[48:51]
	v_mfma_f32_16x16x32_bf16 v[44:47], v[204:207], v[172:175], v[44:47]
	v_mfma_f32_16x16x32_bf16 v[40:43], v[204:207], v[180:183], v[40:43]
	v_mfma_f32_16x16x32_bf16 v[36:39], v[212:215], v[172:175], v[36:39]
	v_mfma_f32_16x16x32_bf16 v[32:35], v[212:215], v[180:183], v[32:35]
	v_mfma_f32_16x16x32_bf16 v[60:63], v[192:195], v[176:179], v[60:63]
	v_mfma_f32_16x16x32_bf16 v[56:59], v[192:195], v[184:187], v[56:59]
	v_mfma_f32_16x16x32_bf16 v[52:55], v[200:203], v[176:179], v[52:55]
	v_mfma_f32_16x16x32_bf16 v[48:51], v[200:203], v[184:187], v[48:51]
	v_mfma_f32_16x16x32_bf16 v[44:47], v[208:211], v[176:179], v[44:47]
	v_mfma_f32_16x16x32_bf16 v[40:43], v[208:211], v[184:187], v[40:43]
	s_barrier
	v_mfma_f32_16x16x32_bf16 v[36:39], v[216:219], v[176:179], v[36:39]
	v_mfma_f32_16x16x32_bf16 v[32:35], v[216:219], v[184:187], v[32:35]
	v_readfirstlane_b32 s63, v159
	v_add_u32_e32 v171, 0x2000, v159
	v_lshl_add_u64 v[172:173], v[240:241], 0, s[48:49]
	s_mov_b32 m0, s63
	v_readfirstlane_b32 s63, v171
	global_load_lds_dwordx4 v[172:173], off
	v_lshl_add_u64 v[172:173], v[242:243], 0, s[48:49]
	s_mov_b32 m0, s63
	s_nop 0
	global_load_lds_dwordx4 v[172:173], off
	s_waitcnt vmcnt(6)
	s_barrier
	v_mfma_f32_16x16x32_bf16 v[28:31], v[188:191], v[220:223], v[28:31]
	v_mfma_f32_16x16x32_bf16 v[24:27], v[188:191], v[228:231], v[24:27]
	v_mfma_f32_16x16x32_bf16 v[20:23], v[196:199], v[220:223], v[20:23]
	v_mfma_f32_16x16x32_bf16 v[16:19], v[196:199], v[228:231], v[16:19]
	v_mfma_f32_16x16x32_bf16 v[12:15], v[204:207], v[220:223], v[12:15]
	v_mfma_f32_16x16x32_bf16 v[8:11], v[204:207], v[228:231], v[8:11]
	v_mfma_f32_16x16x32_bf16 v[4:7], v[212:215], v[220:223], v[4:7]
	v_mfma_f32_16x16x32_bf16 v[0:3], v[212:215], v[228:231], v[0:3]
	v_mfma_f32_16x16x32_bf16 v[28:31], v[192:195], v[224:227], v[28:31]
	v_mfma_f32_16x16x32_bf16 v[24:27], v[192:195], v[232:235], v[24:27]
	v_mfma_f32_16x16x32_bf16 v[20:23], v[200:203], v[224:227], v[20:23]
	v_mfma_f32_16x16x32_bf16 v[16:19], v[200:203], v[232:235], v[16:19]
	v_mfma_f32_16x16x32_bf16 v[12:15], v[208:211], v[224:227], v[12:15]
	v_mfma_f32_16x16x32_bf16 v[8:11], v[208:211], v[232:235], v[8:11]
	s_barrier
	v_mfma_f32_16x16x32_bf16 v[4:7], v[216:219], v[224:227], v[4:7]
	v_mfma_f32_16x16x32_bf16 v[0:3], v[216:219], v[232:235], v[0:3]
	s_add_i32 s62, s62, 2
	s_add_u32 s60, s60, 0x100
	s_addc_u32 s61, s61, 0
	s_cmp_gt_u32 s62, 27
	s_cbranch_scc0 .LBB0_1147
	s_add_i32 s60, s58, 0x80
	s_mul_hi_i32 s61, s60, 0x1080
	s_mulk_i32 s60, 0x1080
	s_add_u32 s60, s69, s60
	s_addc_u32 s61, s70, s61
	v_lshl_add_u64 v[208:209], s[60:61], 0, v[128:129]
	v_readfirstlane_b32 s62, v169
	v_lshl_add_u64 v[208:209], v[208:209], 0, s[50:51]
	s_mov_b32 m0, s62
	ds_read_b128 v[134:137], v161
	ds_read_b128 v[138:141], v161 offset:1024
	ds_read_b128 v[156:159], v161 offset:2048
	ds_read_b128 v[172:175], v161 offset:3072
	ds_read_b128 v[176:179], v152
	ds_read_b128 v[180:183], v152 offset:1024
	ds_read_b128 v[184:187], v151
	ds_read_b128 v[188:191], v151 offset:1024
	ds_read_b128 v[192:195], v150
	ds_read_b128 v[196:199], v150 offset:1024
	ds_read_b128 v[200:203], v149
	ds_read_b128 v[204:207], v149 offset:1024
	global_load_lds_dwordx4 v[208:209], off
	v_lshl_add_u64 v[208:209], s[60:61], 0, v[132:133]
	v_readfirstlane_b32 s60, v170
	v_lshl_add_u64 v[208:209], v[208:209], 0, s[50:51]
	s_mov_b32 m0, s60
	s_nop 0
	global_load_lds_dwordx4 v[208:209], off
	s_barrier
	s_waitcnt lgkmcnt(0)
	v_mfma_f32_16x16x32_bf16 v[124:127], v[176:179], v[134:137], v[124:127]
	v_mfma_f32_16x16x32_bf16 v[120:123], v[176:179], v[156:159], v[120:123]
	v_mfma_f32_16x16x32_bf16 v[116:119], v[184:187], v[134:137], v[116:119]
	v_mfma_f32_16x16x32_bf16 v[112:115], v[184:187], v[156:159], v[112:115]
	v_mfma_f32_16x16x32_bf16 v[108:111], v[192:195], v[134:137], v[108:111]
	v_mfma_f32_16x16x32_bf16 v[104:107], v[192:195], v[156:159], v[104:107]
	v_mfma_f32_16x16x32_bf16 v[100:103], v[200:203], v[134:137], v[100:103]
	v_mfma_f32_16x16x32_bf16 v[96:99], v[200:203], v[156:159], v[96:99]
	v_mfma_f32_16x16x32_bf16 v[124:127], v[180:183], v[138:141], v[124:127]
	v_mfma_f32_16x16x32_bf16 v[120:123], v[180:183], v[172:175], v[120:123]
	v_mfma_f32_16x16x32_bf16 v[116:119], v[188:191], v[138:141], v[116:119]
	v_mfma_f32_16x16x32_bf16 v[112:115], v[188:191], v[172:175], v[112:115]
	v_mfma_f32_16x16x32_bf16 v[108:111], v[196:199], v[138:141], v[108:111]
	v_mfma_f32_16x16x32_bf16 v[104:107], v[196:199], v[172:175], v[104:107]
	s_barrier
	v_mfma_f32_16x16x32_bf16 v[100:103], v[204:207], v[138:141], v[100:103]
	v_mfma_f32_16x16x32_bf16 v[96:99], v[204:207], v[172:175], v[96:99]
	ds_read_b128 v[208:211], v160
	ds_read_b128 v[212:215], v160 offset:1024
	ds_read_b128 v[216:219], v160 offset:2048
	ds_read_b128 v[220:223], v160 offset:3072
	s_barrier
	s_waitcnt lgkmcnt(0)
	v_mfma_f32_16x16x32_bf16 v[92:95], v[176:179], v[208:211], v[92:95]
	v_mfma_f32_16x16x32_bf16 v[88:91], v[176:179], v[216:219], v[88:91]
	v_mfma_f32_16x16x32_bf16 v[76:79], v[192:195], v[208:211], v[76:79]
	v_mfma_f32_16x16x32_bf16 v[72:75], v[192:195], v[216:219], v[72:75]
	v_mfma_f32_16x16x32_bf16 v[84:87], v[184:187], v[208:211], v[84:87]
	v_mfma_f32_16x16x32_bf16 v[80:83], v[184:187], v[216:219], v[80:83]
	v_mfma_f32_16x16x32_bf16 v[68:71], v[200:203], v[208:211], v[68:71]
	v_mfma_f32_16x16x32_bf16 v[64:67], v[200:203], v[216:219], v[64:67]
	v_mfma_f32_16x16x32_bf16 v[92:95], v[180:183], v[212:215], v[92:95]
	v_mfma_f32_16x16x32_bf16 v[88:91], v[180:183], v[220:223], v[88:91]
	v_mfma_f32_16x16x32_bf16 v[76:79], v[196:199], v[212:215], v[76:79]
	v_mfma_f32_16x16x32_bf16 v[72:75], v[196:199], v[220:223], v[72:75]
	v_mfma_f32_16x16x32_bf16 v[176:179], v[188:191], v[212:215], v[84:87]
	v_mfma_f32_16x16x32_bf16 v[180:183], v[188:191], v[220:223], v[80:83]
	s_barrier
; #define LDA(dst, b, h) for (int m = 0; m < 4; ++m) for (int k = 0; k < 2; ++k) \
;     dst[m][k] = *reinterpret_cast<const bf16x8*>((char*)SA(b, h) + lds_byte(wr * 64 + m * 16 + fr, k * 32 + fq * 8))
; #define LDB(dst, b, h) for (int n = 0; n < 2; ++n) for (int k = 0; k < 2; ++k) \
;     dst[n][k] = *reinterpret_cast<const bf16x8*>((char*)SB(b, h) + lds_byte(wc * 32 + n * 16 + fr, k * 32 + fq * 8))
; #define MMA(ai, bj, At_, Bt_) do { __builtin_amdgcn_s_setprio(1); \
;     for (int k = 0; k < 2; ++k) for (int m = 0; m < 4; ++m) for (int n = 0; n < 2; ++n) \
;       acc[ai][bj][m][n] = __builtin_amdgcn_mfma_f32_16x16x32_bf16(At_[m][k], Bt_[n][k], acc[ai][bj][m][n], 0, 0, 0); \
;     __builtin_amdgcn_s_setprio(0); } while (0)
; #define WAIT_V(n) asm volatile("s_waitcnt vmcnt(" #n ")" ::: "memory")
; #define WAIT_L(n) asm volatile("s_waitcnt lgkmcnt(" #n ")" ::: "memory")
; #define BAR __builtin_amdgcn_s_barrier()
; template <int EPI, int lda, int ldb, int N, int K>
; __device__ __forceinline__ void gemm_phase(const u16* __restrict__ A, const u16* __restrict__ Bt, const GemmEpi ep, int wv) {
;     ...
;       BAR; WAIT_L(0); MMA(0, 0, At, B0); BAR;
;       LDB(B1, 0, 1); BAR; WAIT_L(0); MMA(0, 1, At, B1); BAR;
;       LDA(At, 0, 1); WAIT_V(4); BAR; WAIT_L(0); MMA(1, 0, At, B0); MMA(1, 1, At, B1); BAR; }
;     { LDB(B0, 1, 0); LDA(At, 1, 0); WAIT_V(2); BAR; WAIT_L(0); MMA(0, 0, At, B0); BAR;
	v_mfma_f32_16x16x32_bf16 v[184:187], v[204:207], v[212:215], v[68:71]
	v_mfma_f32_16x16x32_bf16 v[188:191], v[204:207], v[220:223], v[64:67]
	s_nop 0
	ds_read_b128 v[64:67], v152 offset:16384
	ds_read_b128 v[68:71], v152 offset:17408
	ds_read_b128 v[80:83], v151 offset:16384
	ds_read_b128 v[84:87], v151 offset:17408
	ds_read_b128 v[192:195], v150 offset:16384
	ds_read_b128 v[196:199], v150 offset:17408
	ds_read_b128 v[200:203], v149 offset:16384
	ds_read_b128 v[204:207], v149 offset:17408
	s_waitcnt vmcnt(4)
	s_barrier
	s_waitcnt lgkmcnt(0)
	v_mfma_f32_16x16x32_bf16 v[60:63], v[64:67], v[134:137], v[60:63]
	v_mfma_f32_16x16x32_bf16 v[56:59], v[64:67], v[156:159], v[56:59]
	v_mfma_f32_16x16x32_bf16 v[52:55], v[80:83], v[134:137], v[52:55]
	v_mfma_f32_16x16x32_bf16 v[48:51], v[80:83], v[156:159], v[48:51]
	v_mfma_f32_16x16x32_bf16 v[44:47], v[192:195], v[134:137], v[44:47]
	v_mfma_f32_16x16x32_bf16 v[40:43], v[192:195], v[156:159], v[40:43]
	v_mfma_f32_16x16x32_bf16 v[36:39], v[200:203], v[134:137], v[36:39]
	v_mfma_f32_16x16x32_bf16 v[32:35], v[200:203], v[156:159], v[32:35]
	v_mfma_f32_16x16x32_bf16 v[60:63], v[68:71], v[138:141], v[60:63]
	v_mfma_f32_16x16x32_bf16 v[56:59], v[68:71], v[172:175], v[56:59]
	v_mfma_f32_16x16x32_bf16 v[52:55], v[84:87], v[138:141], v[52:55]
	v_mfma_f32_16x16x32_bf16 v[48:51], v[84:87], v[172:175], v[48:51]
	v_mfma_f32_16x16x32_bf16 v[44:47], v[196:199], v[138:141], v[44:47]
	v_mfma_f32_16x16x32_bf16 v[40:43], v[196:199], v[172:175], v[40:43]
	v_mfma_f32_16x16x32_bf16 v[36:39], v[204:207], v[138:141], v[36:39]
	v_mfma_f32_16x16x32_bf16 v[32:35], v[204:207], v[172:175], v[32:35]
	v_mfma_f32_16x16x32_bf16 v[28:31], v[64:67], v[208:211], v[28:31]
	v_mfma_f32_16x16x32_bf16 v[24:27], v[64:67], v[216:219], v[24:27]
	v_mfma_f32_16x16x32_bf16 v[12:15], v[192:195], v[208:211], v[12:15]
	v_mfma_f32_16x16x32_bf16 v[8:11], v[192:195], v[216:219], v[8:11]
	v_mfma_f32_16x16x32_bf16 v[20:23], v[80:83], v[208:211], v[20:23]
	v_mfma_f32_16x16x32_bf16 v[16:19], v[80:83], v[216:219], v[16:19]
	v_mfma_f32_16x16x32_bf16 v[4:7], v[200:203], v[208:211], v[4:7]
	v_mfma_f32_16x16x32_bf16 v[0:3], v[200:203], v[216:219], v[0:3]
	v_mfma_f32_16x16x32_bf16 v[28:31], v[68:71], v[212:215], v[28:31]
	v_mfma_f32_16x16x32_bf16 v[24:27], v[68:71], v[220:223], v[24:27]
	v_mfma_f32_16x16x32_bf16 v[12:15], v[196:199], v[212:215], v[12:15]
	v_mfma_f32_16x16x32_bf16 v[8:11], v[196:199], v[220:223], v[8:11]
	v_mfma_f32_16x16x32_bf16 v[134:137], v[84:87], v[212:215], v[20:23]
	v_mfma_f32_16x16x32_bf16 v[138:141], v[84:87], v[220:223], v[16:19]
	s_barrier
	v_mfma_f32_16x16x32_bf16 v[156:159], v[204:207], v[212:215], v[4:7]
	v_mfma_f32_16x16x32_bf16 v[170:173], v[204:207], v[220:223], v[0:3]
	s_nop 0
	ds_read_b128 v[0:3], v155
	ds_read_b128 v[4:7], v155 offset:1024
	ds_read_b128 v[16:19], v155 offset:2048
	ds_read_b128 v[192:195], v155 offset:3072
	ds_read_b128 v[20:23], v152 offset:32768
	ds_read_b128 v[196:199], v152 offset:33792
	ds_read_b128 v[200:203], v151 offset:32768
	ds_read_b128 v[204:207], v151 offset:33792
	ds_read_b128 v[208:211], v150 offset:32768
	ds_read_b128 v[212:215], v150 offset:33792
	ds_read_b128 v[216:219], v149 offset:32768
	ds_read_b128 v[220:223], v149 offset:33792
	s_waitcnt vmcnt(2)
	s_barrier
	s_waitcnt lgkmcnt(0)
	v_mfma_f32_16x16x32_bf16 v[64:67], v[20:23], v[0:3], v[124:127]
	v_mfma_f32_16x16x32_bf16 v[68:71], v[20:23], v[16:19], v[120:123]
	v_mfma_f32_16x16x32_bf16 v[80:83], v[200:203], v[0:3], v[116:119]
	v_mfma_f32_16x16x32_bf16 v[84:87], v[200:203], v[16:19], v[112:115]
	v_mfma_f32_16x16x32_bf16 v[108:111], v[208:211], v[0:3], v[108:111]
	v_mfma_f32_16x16x32_bf16 v[104:107], v[208:211], v[16:19], v[104:107]
	v_mfma_f32_16x16x32_bf16 v[120:123], v[216:219], v[0:3], v[100:103]
	v_mfma_f32_16x16x32_bf16 v[124:127], v[216:219], v[16:19], v[96:99]
	v_mfma_f32_16x16x32_bf16 v[116:119], v[196:199], v[4:7], v[64:67]
	v_mfma_f32_16x16x32_bf16 v[112:115], v[196:199], v[192:195], v[68:71]
	v_mfma_f32_16x16x32_bf16 v[100:103], v[204:207], v[4:7], v[80:83]
	v_mfma_f32_16x16x32_bf16 v[96:99], v[204:207], v[192:195], v[84:87]
	v_mfma_f32_16x16x32_bf16 v[84:87], v[212:215], v[4:7], v[108:111]
	v_mfma_f32_16x16x32_bf16 v[80:83], v[212:215], v[192:195], v[104:107]
	s_barrier
; #define LDA(dst, b, h) for (int m = 0; m < 4; ++m) for (int k = 0; k < 2; ++k) \
;     dst[m][k] = *reinterpret_cast<const bf16x8*>((char*)SA(b, h) + lds_byte(wr * 64 + m * 16 + fr, k * 32 + fq * 8))
; #define LDB(dst, b, h) for (int n = 0; n < 2; ++n) for (int k = 0; k < 2; ++k) \
;     dst[n][k] = *reinterpret_cast<const bf16x8*>((char*)SB(b, h) + lds_byte(wc * 32 + n * 16 + fr, k * 32 + fq * 8))
; #define MMA(ai, bj, At_, Bt_) do { __builtin_amdgcn_s_setprio(1); \
;     for (int k = 0; k < 2; ++k) for (int m = 0; m < 4; ++m) for (int n = 0; n < 2; ++n) \
;       acc[ai][bj][m][n] = __builtin_amdgcn_mfma_f32_16x16x32_bf16(At_[m][k], Bt_[n][k], acc[ai][bj][m][n], 0, 0, 0); \
;     __builtin_amdgcn_s_setprio(0); } while (0)
; #define WAIT_V(n) asm volatile("s_waitcnt vmcnt(" #n ")" ::: "memory")
; #define WAIT_L(n) asm volatile("s_waitcnt lgkmcnt(" #n ")" ::: "memory")
; #define BAR __builtin_amdgcn_s_barrier()
; template <int EPI, int lda, int ldb, int N, int K>
; __device__ __forceinline__ void gemm_phase(const u16* __restrict__ A, const u16* __restrict__ Bt, const GemmEpi ep, int wv) {
;     ...
;     { LDB(B0, 1, 0); LDA(At, 1, 0); WAIT_V(2); BAR; WAIT_L(0); MMA(0, 0, At, B0); BAR;
;       LDB(B1, 1, 1); WAIT_V(0); BAR; WAIT_L(0); MMA(0, 1, At, B1); BAR;
;       LDA(At, 1, 1); BAR; WAIT_L(0); MMA(1, 0, At, B0); MMA(1, 1, At, B1); BAR; }
;     if (wr == 0) BAR;
	v_mfma_f32_16x16x32_bf16 v[68:71], v[220:223], v[4:7], v[120:123]
	v_mfma_f32_16x16x32_bf16 v[64:67], v[220:223], v[192:195], v[124:127]
	ds_read_b128 v[224:227], v153
	ds_read_b128 v[228:231], v153 offset:1024
	ds_read_b128 v[232:235], v153 offset:2048
	ds_read_b128 v[236:239], v153 offset:3072
	s_waitcnt vmcnt(0)
	s_barrier
	s_waitcnt lgkmcnt(0)
	v_mfma_f32_16x16x32_bf16 v[92:95], v[20:23], v[224:227], v[92:95]
	v_mfma_f32_16x16x32_bf16 v[20:23], v[20:23], v[232:235], v[88:91]
	v_mfma_f32_16x16x32_bf16 v[88:91], v[200:203], v[224:227], v[176:179]
	v_mfma_f32_16x16x32_bf16 v[104:107], v[200:203], v[232:235], v[180:183]
	v_mfma_f32_16x16x32_bf16 v[76:79], v[208:211], v[224:227], v[76:79]
	v_mfma_f32_16x16x32_bf16 v[72:75], v[208:211], v[232:235], v[72:75]
	v_mfma_f32_16x16x32_bf16 v[174:177], v[216:219], v[224:227], v[184:187]
	v_mfma_f32_16x16x32_bf16 v[178:181], v[216:219], v[232:235], v[188:191]
	v_mfma_f32_16x16x32_bf16 v[124:127], v[196:199], v[228:231], v[92:95]
	v_mfma_f32_16x16x32_bf16 v[120:123], v[196:199], v[236:239], v[20:23]
	v_mfma_f32_16x16x32_bf16 v[108:111], v[204:207], v[228:231], v[88:91]
	v_mfma_f32_16x16x32_bf16 v[104:107], v[204:207], v[236:239], v[104:107]
	v_mfma_f32_16x16x32_bf16 v[92:95], v[212:215], v[228:231], v[76:79]
	v_mfma_f32_16x16x32_bf16 v[88:91], v[212:215], v[236:239], v[72:75]
	s_barrier
	v_mfma_f32_16x16x32_bf16 v[76:79], v[220:223], v[228:231], v[174:177]
	v_mfma_f32_16x16x32_bf16 v[72:75], v[220:223], v[236:239], v[178:181]
	ds_read_b128 v[174:177], v152 offset:49152
	ds_read_b128 v[152:155], v152 offset:50176
	ds_read_b128 v[178:181], v151 offset:49152
	ds_read_b128 v[182:185], v151 offset:50176
	ds_read_b128 v[186:189], v150 offset:49152
	ds_read_b128 v[196:199], v150 offset:50176
	ds_read_b128 v[200:203], v149 offset:49152
	ds_read_b128 v[204:207], v149 offset:50176
	s_barrier
	s_waitcnt lgkmcnt(0)
	v_mfma_f32_16x16x32_bf16 v[20:23], v[174:177], v[0:3], v[60:63]
	v_mfma_f32_16x16x32_bf16 v[56:59], v[174:177], v[16:19], v[56:59]
	v_mfma_f32_16x16x32_bf16 v[60:63], v[178:181], v[0:3], v[52:55]
	v_mfma_f32_16x16x32_bf16 v[208:211], v[178:181], v[16:19], v[48:51]
	v_mfma_f32_16x16x32_bf16 v[44:47], v[186:189], v[0:3], v[44:47]
	v_mfma_f32_16x16x32_bf16 v[40:43], v[186:189], v[16:19], v[40:43]
	v_mfma_f32_16x16x32_bf16 v[0:3], v[200:203], v[0:3], v[36:39]
	v_mfma_f32_16x16x32_bf16 v[212:215], v[200:203], v[16:19], v[32:35]
	v_mfma_f32_16x16x32_bf16 v[52:55], v[152:155], v[4:7], v[20:23]
	v_mfma_f32_16x16x32_bf16 v[48:51], v[152:155], v[192:195], v[56:59]
	v_mfma_f32_16x16x32_bf16 v[36:39], v[182:185], v[4:7], v[60:63]
	v_mfma_f32_16x16x32_bf16 v[32:35], v[182:185], v[192:195], v[208:211]
	v_mfma_f32_16x16x32_bf16 v[20:23], v[196:199], v[4:7], v[44:47]
	v_mfma_f32_16x16x32_bf16 v[16:19], v[196:199], v[192:195], v[40:43]
	v_mfma_f32_16x16x32_bf16 v[4:7], v[204:207], v[4:7], v[0:3]
	v_mfma_f32_16x16x32_bf16 v[0:3], v[204:207], v[192:195], v[212:215]
	v_mfma_f32_16x16x32_bf16 v[28:31], v[174:177], v[224:227], v[28:31]
	v_mfma_f32_16x16x32_bf16 v[24:27], v[174:177], v[232:235], v[24:27]
	v_mfma_f32_16x16x32_bf16 v[40:43], v[178:181], v[224:227], v[134:137]
	v_mfma_f32_16x16x32_bf16 v[134:137], v[178:181], v[232:235], v[138:141]
	v_mfma_f32_16x16x32_bf16 v[12:15], v[186:189], v[224:227], v[12:15]
	v_mfma_f32_16x16x32_bf16 v[8:11], v[186:189], v[232:235], v[8:11]
	v_mfma_f32_16x16x32_bf16 v[138:141], v[200:203], v[224:227], v[156:159]
	v_mfma_f32_16x16x32_bf16 v[156:159], v[200:203], v[232:235], v[170:173]
	v_mfma_f32_16x16x32_bf16 v[60:63], v[152:155], v[228:231], v[28:31]
	v_mfma_f32_16x16x32_bf16 v[56:59], v[152:155], v[236:239], v[24:27]
	v_mfma_f32_16x16x32_bf16 v[44:47], v[182:185], v[228:231], v[40:43]
	v_mfma_f32_16x16x32_bf16 v[40:43], v[182:185], v[236:239], v[134:137]
	v_mfma_f32_16x16x32_bf16 v[28:31], v[196:199], v[228:231], v[12:15]
	v_mfma_f32_16x16x32_bf16 v[24:27], v[196:199], v[236:239], v[8:11]
	s_barrier
	v_mfma_f32_16x16x32_bf16 v[12:15], v[204:207], v[228:231], v[138:141]
	v_mfma_f32_16x16x32_bf16 v[8:11], v[204:207], v[236:239], v[156:159]
	v_cmp_gt_u32_e32 vcc, s80, v130
	s_and_saveexec_b64 s[60:61], vcc
	s_cbranch_execz .LBB0_1150
	s_barrier

; #define STAGE(P, BASE, LD, br, kt) do { const char* _g = (const char*)((BASE) + (size_t)(br) * (LD) + (size_t)(kt) * 64); \
;     for (int _i = 0; _i < 2; ++_i) { int _b = tidx * 16 + _i * 8192; int _r, _c; stage_rc(_b, _r, _c); \
;       __builtin_amdgcn_global_load_lds((const unsigned*)(_g + (unsigned)((_r * (LD) + _c) * 2)), (unsigned*)((char*)(P) + _b), 16, 0, 0); } } while (0)
; #define LDA(dst, b, h) for (int m = 0; m < 4; ++m) for (int k = 0; k < 2; ++k) \
;     dst[m][k] = *reinterpret_cast<const bf16x8*>((char*)SA(b, h) + lds_byte(wr * 64 + m * 16 + fr, k * 32 + fq * 8))
; #define LDB(dst, b, h) for (int n = 0; n < 2; ++n) for (int k = 0; k < 2; ++k) \
;     dst[n][k] = *reinterpret_cast<const bf16x8*>((char*)SB(b, h) + lds_byte(wc * 32 + n * 16 + fr, k * 32 + fq * 8))
; #define MMA(ai, bj, At_, Bt_) do { __builtin_amdgcn_s_setprio(1); \
;     for (int k = 0; k < 2; ++k) for (int m = 0; m < 4; ++m) for (int n = 0; n < 2; ++n) \
;       acc[ai][bj][m][n] = __builtin_amdgcn_mfma_f32_16x16x32_bf16(At_[m][k], Bt_[n][k], acc[ai][bj][m][n], 0, 0, 0); \
;     __builtin_amdgcn_s_setprio(0); } while (0)
; #define WAIT_V(n) asm volatile("s_waitcnt vmcnt(" #n ")" ::: "memory")
; #define WAIT_L(n) asm volatile("s_waitcnt lgkmcnt(" #n ")" ::: "memory")
; #define BAR __builtin_amdgcn_s_barrier()
; template <int EPI, int lda, int ldb, int N, int K>
; __device__ __forceinline__ void gemm_phase(const u16* __restrict__ A, const u16* __restrict__ Bt, const GemmEpi ep, int wv) {
;     ...
;     if constexpr (!PF) { TILE_COORDS(tile, brow, bcol, pn); STAGE4(brow, bcol, pn); }
;     const int wid = tidx >> 6, lane = tidx & 63, wr = wid >> 2, wc = wid & 3, fr = lane & 15, fq = lane >> 4;
;     const u16* Ab = A + (EPI == EPI_RG ? (pn >> 1) * 256 : 0);
;     f32x4 acc[2][2][4][2] = {};
;     bf16x8 At[4][2], B0[2][2], B1[2][2];
;     constexpr int nt = K / 64;
;     if (wr == 1) BAR;
;     WAIT_V(4); BAR;
;     STAGE(SB(1, 0), Bt, ldb, bcol, 1); STAGE(SA(1, 0), Ab, lda, brow, 1); STAGE(SB(1, 1), Bt, ldb, bcol + HALF, 1);
;     WAIT_V(6); BAR;
;     for (int t = 0; t < nt - 2; t += 2) {
;       LDB(B0, 0, 0); SCHED; LDA(At, 0, 0); STAGE(SA(1, 1), Ab, lda, brow + HALF, t + 1);
;       WAIT_L(8); BAR; WAIT_L(0); MMA(0, 0, At, B0); BAR; SCHED;
;       LDB(B1, 0, 1); STAGE(SB(0, 0), Bt, ldb, bcol, t + 2);
;       BAR; WAIT_L(0); MMA(0, 1, At, B1); BAR;
.LBB0_1248:
	s_or_b64 exec, exec, s[54:55]
	v_mov_b32_e32 v1, v129
	v_add_u32_e32 v7, s60, v6
	v_lshl_add_u64 v[12:13], s[46:47], 0, v[128:129]
	v_lshl_add_u64 v[14:15], s[46:47], 0, v[0:1]
	v_lshl_add_u64 v[2:3], s[52:53], 0, v[128:129]
	v_lshl_add_u64 v[0:1], s[52:53], 0, v[0:1]
	v_readfirstlane_b32 s53, v7
	v_add_u32_e32 v7, 0x2000, v7
	v_mov_b32_e32 v5, v129
	v_mov_b32_e32 v17, v129
	v_lshl_add_u64 v[26:27], v[12:13], 0, s[40:41]
	s_mov_b32 m0, s53
	v_readfirstlane_b32 s52, v7
	v_add_u32_e32 v7, 0x8000, v23
	v_lshl_add_u64 v[8:9], s[50:51], 0, v[4:5]
	v_lshl_add_u64 v[10:11], s[50:51], 0, v[16:17]
	s_waitcnt vmcnt(4)
	s_barrier
	global_load_lds_dwordx4 v[26:27], off
	v_lshl_add_u64 v[26:27], v[14:15], 0, s[40:41]
	s_mov_b32 m0, s52
	v_readfirstlane_b32 s51, v7
	v_add_u32_e32 v7, 0xa000, v23
	global_load_lds_dwordx4 v[26:27], off
	v_lshl_add_u64 v[26:27], v[8:9], 0, s[40:41]
	s_mov_b32 m0, s51
	v_readfirstlane_b32 s50, v7
	v_add_u32_e32 v25, s61, v6
	global_load_lds_dwordx4 v[26:27], off
	v_lshl_add_u64 v[26:27], v[10:11], 0, s[40:41]
	s_mov_b32 m0, s50
	v_readfirstlane_b32 s13, v25
	v_add_u32_e32 v25, 0x2000, v25
	global_load_lds_dwordx4 v[26:27], off
	v_lshl_add_u64 v[26:27], v[2:3], 0, s[40:41]
	s_mov_b32 m0, s13
	v_readfirstlane_b32 s11, v25
	global_load_lds_dwordx4 v[26:27], off
	v_lshl_add_u64 v[6:7], v[0:1], 0, s[40:41]
	s_mov_b32 m0, s11
	v_and_b32_e32 v132, 15, v20
	global_load_lds_dwordx4 v[6:7], off
	v_bfe_u32 v128, v20, 4, 2
	v_lshlrev_b32_e32 v7, 2, v20
	v_bfe_u32 v131, v130, 6, 2
	v_lshlrev_b32_e32 v25, 4, v128
	v_lshlrev_b32_e32 v6, 6, v132
	v_and_b32_e32 v50, 32, v7
	v_lshlrev_b32_e32 v126, 12, v131
	v_bitop3_b32 v127, v25, v50, v6 bitop3:0x36
	v_add3_u32 v133, s58, v127, v126
	s_waitcnt vmcnt(6)
	s_barrier
	ds_read_b128 v[26:29], v133
	ds_read_b128 v[30:33], v133 offset:1024
	ds_read_b128 v[34:37], v133 offset:2048
	ds_read_b128 v[38:41], v133 offset:3072
	v_lshl_add_u64 v[6:7], s[48:49], 0, v[4:5]
	v_lshl_add_u64 v[4:5], s[48:49], 0, v[16:17]
	v_lshlrev_b32_e32 v17, 6, v20
	v_and_b32_e32 v17, 0x3c0, v17
	v_add_u32_e32 v20, 0xc000, v23
	v_lshlrev_b32_e32 v16, 13, v143
	v_bitop3_b32 v17, v17, v50, v25 bitop3:0x36
	v_readfirstlane_b32 s47, v20
	v_add_u32_e32 v20, 0xe000, v23
	v_add3_u32 v228, 0, v127, v16
	v_add3_u32 v229, 0, v17, v16
	v_lshl_add_u64 v[16:17], v[6:7], 0, s[40:41]
	s_mov_b32 m0, s47
	v_readfirstlane_b32 s46, v20
	ds_read_b128 v[42:45], v228
	ds_read_b128 v[46:49], v228 offset:1024
	ds_read_b128 v[50:53], v229 offset:2048
	ds_read_b128 v[54:57], v229 offset:3072
	ds_read_b128 v[58:61], v229 offset:4096
	ds_read_b128 v[62:65], v229 offset:5120
	ds_read_b128 v[66:69], v229 offset:6144
	ds_read_b128 v[70:73], v229 offset:7168
	global_load_lds_dwordx4 v[16:17], off
	v_lshl_add_u64 v[16:17], v[4:5], 0, s[40:41]
	s_mov_b32 m0, s46
	s_nop 0
	global_load_lds_dwordx4 v[16:17], off
	s_waitcnt lgkmcnt(8)
	s_barrier
	s_waitcnt lgkmcnt(0)
	v_mfma_f32_16x16x32_bf16 v[74:77], v[42:45], v[26:29], 0
	v_mfma_f32_16x16x32_bf16 v[78:81], v[42:45], v[34:37], 0
	v_mfma_f32_16x16x32_bf16 v[82:85], v[50:53], v[26:29], 0
	v_mfma_f32_16x16x32_bf16 v[86:89], v[50:53], v[34:37], 0
	v_mfma_f32_16x16x32_bf16 v[90:93], v[58:61], v[26:29], 0
	v_mfma_f32_16x16x32_bf16 v[94:97], v[58:61], v[34:37], 0
	v_mfma_f32_16x16x32_bf16 v[98:101], v[66:69], v[26:29], 0
	v_mfma_f32_16x16x32_bf16 v[102:105], v[66:69], v[34:37], 0
	v_mfma_f32_16x16x32_bf16 v[74:77], v[46:49], v[30:33], v[74:77]
	v_mfma_f32_16x16x32_bf16 v[78:81], v[46:49], v[38:41], v[78:81]
	v_mfma_f32_16x16x32_bf16 v[82:85], v[54:57], v[30:33], v[82:85]
	v_mfma_f32_16x16x32_bf16 v[86:89], v[54:57], v[38:41], v[86:89]
	v_mfma_f32_16x16x32_bf16 v[90:93], v[62:65], v[30:33], v[90:93]
	v_mfma_f32_16x16x32_bf16 v[94:97], v[62:65], v[38:41], v[94:97]
	s_barrier
	v_mfma_f32_16x16x32_bf16 v[98:101], v[70:73], v[30:33], v[98:101]
	v_mfma_f32_16x16x32_bf16 v[102:105], v[70:73], v[38:41], v[102:105]
	v_readfirstlane_b32 s48, v21
	v_add_u32_e32 v20, 0x2000, v21
	v_add3_u32 v224, s59, v127, v126
	v_lshl_add_u64 v[16:17], v[12:13], 0, s[42:43]
	s_mov_b32 m0, s48
	v_readfirstlane_b32 s48, v20
	ds_read_b128 v[106:109], v224
	ds_read_b128 v[110:113], v224 offset:1024
	ds_read_b128 v[114:117], v224 offset:2048
	ds_read_b128 v[118:121], v224 offset:3072
	global_load_lds_dwordx4 v[16:17], off
	v_lshl_add_u64 v[16:17], v[14:15], 0, s[42:43]
	s_mov_b32 m0, s48
	s_nop 0
	global_load_lds_dwordx4 v[16:17], off
	s_barrier
	s_waitcnt lgkmcnt(0)
	v_mfma_f32_16x16x32_bf16 v[122:125], v[42:45], v[106:109], 0
	v_mfma_f32_16x16x32_bf16 v[42:45], v[42:45], v[114:117], 0
	v_mfma_f32_16x16x32_bf16 v[134:137], v[50:53], v[106:109], 0
	v_mfma_f32_16x16x32_bf16 v[50:53], v[50:53], v[114:117], 0
	v_mfma_f32_16x16x32_bf16 v[144:147], v[58:61], v[106:109], 0
	v_mfma_f32_16x16x32_bf16 v[58:61], v[58:61], v[114:117], 0
	v_mfma_f32_16x16x32_bf16 v[148:151], v[66:69], v[106:109], 0
	v_mfma_f32_16x16x32_bf16 v[66:69], v[66:69], v[114:117], 0
	v_mfma_f32_16x16x32_bf16 v[122:125], v[46:49], v[110:113], v[122:125]
	v_mfma_f32_16x16x32_bf16 v[42:45], v[46:49], v[118:121], v[42:45]
	v_mfma_f32_16x16x32_bf16 v[46:49], v[54:57], v[110:113], v[134:137]
	v_mfma_f32_16x16x32_bf16 v[50:53], v[54:57], v[118:121], v[50:53]
	v_mfma_f32_16x16x32_bf16 v[54:57], v[62:65], v[110:113], v[144:147]
	v_mfma_f32_16x16x32_bf16 v[58:61], v[62:65], v[118:121], v[58:61]
	s_barrier
; #define STAGE(P, BASE, LD, br, kt) do { const char* _g = (const char*)((BASE) + (size_t)(br) * (LD) + (size_t)(kt) * 64); \
;     for (int _i = 0; _i < 2; ++_i) { int _b = tidx * 16 + _i * 8192; int _r, _c; stage_rc(_b, _r, _c); \
;       __builtin_amdgcn_global_load_lds((const unsigned*)(_g + (unsigned)((_r * (LD) + _c) * 2)), (unsigned*)((char*)(P) + _b), 16, 0, 0); } } while (0)
; #define LDA(dst, b, h) for (int m = 0; m < 4; ++m) for (int k = 0; k < 2; ++k) \
;     dst[m][k] = *reinterpret_cast<const bf16x8*>((char*)SA(b, h) + lds_byte(wr * 64 + m * 16 + fr, k * 32 + fq * 8))
; #define LDB(dst, b, h) for (int n = 0; n < 2; ++n) for (int k = 0; k < 2; ++k) \
;     dst[n][k] = *reinterpret_cast<const bf16x8*>((char*)SB(b, h) + lds_byte(wc * 32 + n * 16 + fr, k * 32 + fq * 8))
; #define MMA(ai, bj, At_, Bt_) do { __builtin_amdgcn_s_setprio(1); \
;     for (int k = 0; k < 2; ++k) for (int m = 0; m < 4; ++m) for (int n = 0; n < 2; ++n) \
;       acc[ai][bj][m][n] = __builtin_amdgcn_mfma_f32_16x16x32_bf16(At_[m][k], Bt_[n][k], acc[ai][bj][m][n], 0, 0, 0); \
;     __builtin_amdgcn_s_setprio(0); } while (0)
; #define WAIT_V(n) asm volatile("s_waitcnt vmcnt(" #n ")" ::: "memory")
; #define WAIT_L(n) asm volatile("s_waitcnt lgkmcnt(" #n ")" ::: "memory")
; #define BAR __builtin_amdgcn_s_barrier()
; #define SCHED __builtin_amdgcn_sched_barrier(0)
; template <int EPI, int lda, int ldb, int N, int K>
; __device__ __forceinline__ void gemm_phase(const u16* __restrict__ A, const u16* __restrict__ Bt, const GemmEpi ep, int wv) {
;     ...
;       BAR; WAIT_L(0); MMA(0, 1, At, B1); BAR;
;       LDA(At, 0, 1); STAGE(SA(0, 0), Ab, lda, brow, t + 2);
;       BAR; WAIT_L(0); MMA(1, 0, At, B0); BAR; SCHED;
;       STAGE(SB(0, 1), Bt, ldb, bcol + HALF, t + 2);
;       WAIT_V(6); BAR; MMA(1, 1, At, B1); BAR;
;       LDB(B0, 1, 0); SCHED; LDA(At, 1, 0); STAGE(SA(0, 1), Ab, lda, brow + HALF, t + 2);
;       WAIT_L(8); BAR; WAIT_L(0); MMA(0, 0, At, B0); BAR; SCHED;
;       LDB(B1, 1, 1); STAGE(SB(1, 0), Bt, ldb, bcol, t + 3);
;       BAR; WAIT_L(0); MMA(0, 1, At, B1); BAR;
	v_mfma_f32_16x16x32_bf16 v[62:65], v[70:73], v[110:113], v[148:151]
	v_mfma_f32_16x16x32_bf16 v[66:69], v[70:73], v[118:121], v[66:69]
	v_readfirstlane_b32 s48, v23
	v_lshl_add_u64 v[16:17], v[8:9], 0, s[42:43]
	s_mov_b32 m0, s48
	v_readfirstlane_b32 s48, v24
	ds_read_b128 v[70:73], v228 offset:16384
	ds_read_b128 v[134:137], v228 offset:17408
	ds_read_b128 v[144:147], v229 offset:18432
	ds_read_b128 v[148:151], v229 offset:19456
	ds_read_b128 v[152:155], v229 offset:20480
	ds_read_b128 v[156:159], v229 offset:21504
	ds_read_b128 v[160:163], v229 offset:22528
	ds_read_b128 v[164:167], v229 offset:23552
	global_load_lds_dwordx4 v[16:17], off
	v_lshl_add_u64 v[16:17], v[10:11], 0, s[42:43]
	s_mov_b32 m0, s48
	s_nop 0
	global_load_lds_dwordx4 v[16:17], off
	s_barrier
	s_waitcnt lgkmcnt(0)
	v_mfma_f32_16x16x32_bf16 v[168:171], v[70:73], v[26:29], 0
	v_mfma_f32_16x16x32_bf16 v[172:175], v[70:73], v[34:37], 0
	v_mfma_f32_16x16x32_bf16 v[176:179], v[144:147], v[26:29], 0
	v_mfma_f32_16x16x32_bf16 v[180:183], v[144:147], v[34:37], 0
	v_mfma_f32_16x16x32_bf16 v[184:187], v[152:155], v[26:29], 0
	v_mfma_f32_16x16x32_bf16 v[188:191], v[152:155], v[34:37], 0
	v_mfma_f32_16x16x32_bf16 v[24:27], v[160:163], v[26:29], 0
	v_mfma_f32_16x16x32_bf16 v[34:37], v[160:163], v[34:37], 0
	v_mfma_f32_16x16x32_bf16 v[168:171], v[134:137], v[30:33], v[168:171]
	v_mfma_f32_16x16x32_bf16 v[176:179], v[148:151], v[30:33], v[176:179]
	v_mfma_f32_16x16x32_bf16 v[184:187], v[156:159], v[30:33], v[184:187]
	v_mfma_f32_16x16x32_bf16 v[24:27], v[164:167], v[30:33], v[24:27]
	v_mfma_f32_16x16x32_bf16 v[28:31], v[164:167], v[38:41], v[34:37]
	v_mfma_f32_16x16x32_bf16 v[172:175], v[134:137], v[38:41], v[172:175]
	s_barrier
	v_mfma_f32_16x16x32_bf16 v[180:183], v[148:151], v[38:41], v[180:183]
	v_mfma_f32_16x16x32_bf16 v[188:191], v[156:159], v[38:41], v[188:191]
	v_readfirstlane_b32 s48, v22
	v_add_u32_e32 v20, 0x2000, v22
	v_lshl_add_u64 v[16:17], v[2:3], 0, s[42:43]
	s_mov_b32 m0, s48
	v_readfirstlane_b32 s48, v20
	global_load_lds_dwordx4 v[16:17], off
	v_lshl_add_u64 v[16:17], v[0:1], 0, s[42:43]
	s_mov_b32 m0, s48
	s_nop 0
	global_load_lds_dwordx4 v[16:17], off
	s_waitcnt vmcnt(6)
	s_barrier
	v_mfma_f32_16x16x32_bf16 v[20:23], v[70:73], v[106:109], 0
	v_mfma_f32_16x16x32_bf16 v[32:35], v[70:73], v[114:117], 0
	v_mfma_f32_16x16x32_bf16 v[36:39], v[144:147], v[106:109], 0
	v_mfma_f32_16x16x32_bf16 v[70:73], v[144:147], v[114:117], 0
	v_mfma_f32_16x16x32_bf16 v[144:147], v[152:155], v[106:109], 0
	v_mfma_f32_16x16x32_bf16 v[152:155], v[152:155], v[114:117], 0
	v_mfma_f32_16x16x32_bf16 v[106:109], v[160:163], v[106:109], 0
	v_mfma_f32_16x16x32_bf16 v[114:117], v[160:163], v[114:117], 0
	v_mfma_f32_16x16x32_bf16 v[20:23], v[134:137], v[110:113], v[20:23]
	v_mfma_f32_16x16x32_bf16 v[32:35], v[134:137], v[118:121], v[32:35]
	v_mfma_f32_16x16x32_bf16 v[36:39], v[148:151], v[110:113], v[36:39]
	v_mfma_f32_16x16x32_bf16 v[70:73], v[148:151], v[118:121], v[70:73]
	v_mfma_f32_16x16x32_bf16 v[134:137], v[156:159], v[110:113], v[144:147]
	v_mfma_f32_16x16x32_bf16 v[106:109], v[164:167], v[110:113], v[106:109]
	s_barrier
	v_mfma_f32_16x16x32_bf16 v[110:113], v[164:167], v[118:121], v[114:117]
	v_mfma_f32_16x16x32_bf16 v[144:147], v[156:159], v[118:121], v[152:155]
	v_add3_u32 v225, s60, v127, v126
	ds_read_b128 v[114:117], v225
	ds_read_b128 v[118:121], v225 offset:1024
	ds_read_b128 v[148:151], v225 offset:2048
	ds_read_b128 v[152:155], v225 offset:3072
	v_readfirstlane_b32 s48, v18
	v_lshl_add_u64 v[16:17], v[6:7], 0, s[42:43]
	s_mov_b32 m0, s48
	v_readfirstlane_b32 s48, v19
	ds_read_b128 v[156:159], v228 offset:32768
	ds_read_b128 v[160:163], v228 offset:33792
	ds_read_b128 v[164:167], v229 offset:34816
	ds_read_b128 v[192:195], v229 offset:35840
	ds_read_b128 v[196:199], v229 offset:36864
	ds_read_b128 v[200:203], v229 offset:37888
	ds_read_b128 v[204:207], v229 offset:38912
	ds_read_b128 v[208:211], v229 offset:39936
	global_load_lds_dwordx4 v[16:17], off
	v_lshl_add_u64 v[16:17], v[4:5], 0, s[42:43]
	s_mov_b32 m0, s48
	s_nop 0
	global_load_lds_dwordx4 v[16:17], off
	s_waitcnt lgkmcnt(8)
	s_barrier
	s_waitcnt lgkmcnt(0)
	v_mfma_f32_16x16x32_bf16 v[16:19], v[156:159], v[114:117], v[74:77]
	v_mfma_f32_16x16x32_bf16 v[74:77], v[156:159], v[148:151], v[78:81]
	v_mfma_f32_16x16x32_bf16 v[78:81], v[164:167], v[114:117], v[82:85]
	v_mfma_f32_16x16x32_bf16 v[82:85], v[164:167], v[148:151], v[86:89]
	v_mfma_f32_16x16x32_bf16 v[86:89], v[196:199], v[114:117], v[90:93]
	v_mfma_f32_16x16x32_bf16 v[90:93], v[196:199], v[148:151], v[94:97]
	v_mfma_f32_16x16x32_bf16 v[94:97], v[204:207], v[114:117], v[98:101]
	v_mfma_f32_16x16x32_bf16 v[98:101], v[204:207], v[148:151], v[102:105]
	v_mfma_f32_16x16x32_bf16 v[16:19], v[160:163], v[118:121], v[16:19]
	v_mfma_f32_16x16x32_bf16 v[74:77], v[160:163], v[152:155], v[74:77]
	v_mfma_f32_16x16x32_bf16 v[78:81], v[192:195], v[118:121], v[78:81]
	v_mfma_f32_16x16x32_bf16 v[82:85], v[192:195], v[152:155], v[82:85]
	v_mfma_f32_16x16x32_bf16 v[86:89], v[200:203], v[118:121], v[86:89]
	v_mfma_f32_16x16x32_bf16 v[90:93], v[200:203], v[152:155], v[90:93]
	s_barrier
	v_mfma_f32_16x16x32_bf16 v[94:97], v[208:211], v[118:121], v[94:97]
	v_mfma_f32_16x16x32_bf16 v[98:101], v[208:211], v[152:155], v[98:101]
	s_mov_b32 m0, s53
	v_add3_u32 v226, s61, v127, v126
	v_lshl_add_u64 v[12:13], v[12:13], 0, s[44:45]
	ds_read_b128 v[102:105], v226
	ds_read_b128 v[212:215], v226 offset:1024
	ds_read_b128 v[216:219], v226 offset:2048
	ds_read_b128 v[220:223], v226 offset:3072
	global_load_lds_dwordx4 v[12:13], off
	v_lshl_add_u64 v[12:13], v[14:15], 0, s[44:45]
	s_mov_b32 m0, s52
	s_nop 0
	global_load_lds_dwordx4 v[12:13], off
	s_barrier
; #define STAGE(P, BASE, LD, br, kt) do { const char* _g = (const char*)((BASE) + (size_t)(br) * (LD) + (size_t)(kt) * 64); \
;     for (int _i = 0; _i < 2; ++_i) { int _b = tidx * 16 + _i * 8192; int _r, _c; stage_rc(_b, _r, _c); \
;       __builtin_amdgcn_global_load_lds((const unsigned*)(_g + (unsigned)((_r * (LD) + _c) * 2)), (unsigned*)((char*)(P) + _b), 16, 0, 0); } } while (0)
; #define LDA(dst, b, h) for (int m = 0; m < 4; ++m) for (int k = 0; k < 2; ++k) \
;     dst[m][k] = *reinterpret_cast<const bf16x8*>((char*)SA(b, h) + lds_byte(wr * 64 + m * 16 + fr, k * 32 + fq * 8))
; #define LDB(dst, b, h) for (int n = 0; n < 2; ++n) for (int k = 0; k < 2; ++k) \
;     dst[n][k] = *reinterpret_cast<const bf16x8*>((char*)SB(b, h) + lds_byte(wc * 32 + n * 16 + fr, k * 32 + fq * 8))
; #define MMA(ai, bj, At_, Bt_) do { __builtin_amdgcn_s_setprio(1); \
;     for (int k = 0; k < 2; ++k) for (int m = 0; m < 4; ++m) for (int n = 0; n < 2; ++n) \
;       acc[ai][bj][m][n] = __builtin_amdgcn_mfma_f32_16x16x32_bf16(At_[m][k], Bt_[n][k], acc[ai][bj][m][n], 0, 0, 0); \
;     __builtin_amdgcn_s_setprio(0); } while (0)
; #define WAIT_V(n) asm volatile("s_waitcnt vmcnt(" #n ")" ::: "memory")
; #define WAIT_L(n) asm volatile("s_waitcnt lgkmcnt(" #n ")" ::: "memory")
; #define BAR __builtin_amdgcn_s_barrier()
; #define SCHED __builtin_amdgcn_sched_barrier(0)
; template <int EPI, int lda, int ldb, int N, int K>
; __device__ __forceinline__ void gemm_phase(const u16* __restrict__ A, const u16* __restrict__ Bt, const GemmEpi ep, int wv) {
;     ...
;       BAR; WAIT_L(0); MMA(0, 1, At, B1); BAR;
;       LDA(At, 1, 1); STAGE(SA(1, 0), Ab, lda, brow, t + 3);
;       BAR; WAIT_L(0); MMA(1, 0, At, B0); BAR; SCHED;
;       STAGE(SB(1, 1), Bt, ldb, bcol + HALF, t + 3);
;       WAIT_V(6); BAR; MMA(1, 1, At, B1); BAR;
;     }
;     { LDB(B0, 0, 0); LDA(At, 0, 0); STAGE(SA(1, 1), Ab, lda, brow + HALF, nt - 1);
	s_waitcnt lgkmcnt(0)
	v_mfma_f32_16x16x32_bf16 v[12:15], v[156:159], v[102:105], v[122:125]
	v_mfma_f32_16x16x32_bf16 v[40:43], v[156:159], v[216:219], v[42:45]
	v_mfma_f32_16x16x32_bf16 v[44:47], v[164:167], v[102:105], v[46:49]
	v_mfma_f32_16x16x32_bf16 v[48:51], v[164:167], v[216:219], v[50:53]
	v_mfma_f32_16x16x32_bf16 v[52:55], v[196:199], v[102:105], v[54:57]
	v_mfma_f32_16x16x32_bf16 v[56:59], v[196:199], v[216:219], v[58:61]
	v_mfma_f32_16x16x32_bf16 v[60:63], v[204:207], v[102:105], v[62:65]
	v_mfma_f32_16x16x32_bf16 v[64:67], v[204:207], v[216:219], v[66:69]
	v_mfma_f32_16x16x32_bf16 v[12:15], v[160:163], v[212:215], v[12:15]
	v_mfma_f32_16x16x32_bf16 v[40:43], v[160:163], v[220:223], v[40:43]
	v_mfma_f32_16x16x32_bf16 v[44:47], v[192:195], v[212:215], v[44:47]
	v_mfma_f32_16x16x32_bf16 v[48:51], v[192:195], v[220:223], v[48:51]
	v_mfma_f32_16x16x32_bf16 v[52:55], v[200:203], v[212:215], v[52:55]
	v_mfma_f32_16x16x32_bf16 v[56:59], v[200:203], v[220:223], v[56:59]
	s_barrier
	v_mfma_f32_16x16x32_bf16 v[60:63], v[208:211], v[212:215], v[60:63]
	v_mfma_f32_16x16x32_bf16 v[64:67], v[208:211], v[220:223], v[64:67]
	s_mov_b32 m0, s51
	v_lshl_add_u64 v[8:9], v[8:9], 0, s[44:45]
	ds_read_b128 v[122:125], v228 offset:49152
	ds_read_b128 v[156:159], v228 offset:50176
	ds_read_b128 v[160:163], v229 offset:51200
	ds_read_b128 v[164:167], v229 offset:52224
	ds_read_b128 v[192:195], v229 offset:53248
	ds_read_b128 v[196:199], v229 offset:54272
	ds_read_b128 v[200:203], v229 offset:55296
	ds_read_b128 v[204:207], v229 offset:56320
	global_load_lds_dwordx4 v[8:9], off
	v_lshl_add_u64 v[8:9], v[10:11], 0, s[44:45]
	s_mov_b32 m0, s50
	s_nop 0
	global_load_lds_dwordx4 v[8:9], off
	s_barrier
	s_waitcnt lgkmcnt(0)
	v_mfma_f32_16x16x32_bf16 v[8:11], v[122:125], v[114:117], v[168:171]
	v_mfma_f32_16x16x32_bf16 v[168:171], v[122:125], v[148:151], v[172:175]
	v_mfma_f32_16x16x32_bf16 v[24:27], v[200:203], v[114:117], v[24:27]
	v_mfma_f32_16x16x32_bf16 v[28:31], v[200:203], v[148:151], v[28:31]
	v_mfma_f32_16x16x32_bf16 v[172:175], v[160:163], v[114:117], v[176:179]
	v_mfma_f32_16x16x32_bf16 v[176:179], v[160:163], v[148:151], v[180:183]
	v_mfma_f32_16x16x32_bf16 v[180:183], v[192:195], v[114:117], v[184:187]
	v_mfma_f32_16x16x32_bf16 v[184:187], v[192:195], v[148:151], v[188:191]
	v_mfma_f32_16x16x32_bf16 v[8:11], v[156:159], v[118:121], v[8:11]
	v_mfma_f32_16x16x32_bf16 v[114:117], v[156:159], v[152:155], v[168:171]
	v_mfma_f32_16x16x32_bf16 v[24:27], v[204:207], v[118:121], v[24:27]
	v_mfma_f32_16x16x32_bf16 v[28:31], v[204:207], v[152:155], v[28:31]
	v_mfma_f32_16x16x32_bf16 v[148:151], v[164:167], v[118:121], v[172:175]
	v_mfma_f32_16x16x32_bf16 v[168:171], v[164:167], v[152:155], v[176:179]
	s_barrier
	v_mfma_f32_16x16x32_bf16 v[172:175], v[196:199], v[118:121], v[180:183]
	v_mfma_f32_16x16x32_bf16 v[176:179], v[196:199], v[152:155], v[184:187]
	s_mov_b32 m0, s13
	v_lshl_add_u64 v[2:3], v[2:3], 0, s[44:45]
	global_load_lds_dwordx4 v[2:3], off
	v_lshl_add_u64 v[0:1], v[0:1], 0, s[44:45]
	s_mov_b32 m0, s11
	s_nop 0
	global_load_lds_dwordx4 v[0:1], off
	s_waitcnt vmcnt(6)
	s_barrier
	v_mfma_f32_16x16x32_bf16 v[0:3], v[122:125], v[102:105], v[20:23]
	v_mfma_f32_16x16x32_bf16 v[20:23], v[122:125], v[216:219], v[32:35]
	v_mfma_f32_16x16x32_bf16 v[32:35], v[160:163], v[102:105], v[36:39]
	v_mfma_f32_16x16x32_bf16 v[36:39], v[160:163], v[216:219], v[70:73]
	v_mfma_f32_16x16x32_bf16 v[68:71], v[192:195], v[102:105], v[134:137]
	v_mfma_f32_16x16x32_bf16 v[118:121], v[192:195], v[216:219], v[144:147]
	v_mfma_f32_16x16x32_bf16 v[102:105], v[200:203], v[102:105], v[106:109]
	v_mfma_f32_16x16x32_bf16 v[106:109], v[200:203], v[216:219], v[110:113]
	v_mfma_f32_16x16x32_bf16 v[0:3], v[156:159], v[212:215], v[0:3]
	v_mfma_f32_16x16x32_bf16 v[20:23], v[156:159], v[220:223], v[20:23]
	v_mfma_f32_16x16x32_bf16 v[32:35], v[164:167], v[212:215], v[32:35]
	v_mfma_f32_16x16x32_bf16 v[36:39], v[164:167], v[220:223], v[36:39]
	v_mfma_f32_16x16x32_bf16 v[68:71], v[196:199], v[212:215], v[68:71]
	v_mfma_f32_16x16x32_bf16 v[110:113], v[196:199], v[220:223], v[118:121]
	s_barrier
	v_mfma_f32_16x16x32_bf16 v[102:105], v[204:207], v[212:215], v[102:105]
	v_mfma_f32_16x16x32_bf16 v[106:109], v[204:207], v[220:223], v[106:109]
	s_mov_b32 m0, s47
	v_lshl_add_u64 v[6:7], v[6:7], 0, s[44:45]
	ds_read_b128 v[118:121], v133
	ds_read_b128 v[122:125], v133 offset:1024
	ds_read_b128 v[134:137], v133 offset:2048
	ds_read_b128 v[144:147], v133 offset:3072
	ds_read_b128 v[152:155], v228
	ds_read_b128 v[156:159], v228 offset:1024
	ds_read_b128 v[160:163], v229 offset:2048
	ds_read_b128 v[164:167], v229 offset:3072
	ds_read_b128 v[180:183], v229 offset:4096
	ds_read_b128 v[184:187], v229 offset:5120
	ds_read_b128 v[188:191], v229 offset:6144
	ds_read_b128 v[192:195], v229 offset:7168
	global_load_lds_dwordx4 v[6:7], off
	v_lshl_add_u64 v[4:5], v[4:5], 0, s[44:45]
	s_mov_b32 m0, s46
	s_nop 0
	global_load_lds_dwordx4 v[4:5], off
	s_barrier
	s_waitcnt lgkmcnt(0)
	v_mfma_f32_16x16x32_bf16 v[4:7], v[152:155], v[118:121], v[16:19]
	v_mfma_f32_16x16x32_bf16 v[16:19], v[152:155], v[134:137], v[74:77]
	v_mfma_f32_16x16x32_bf16 v[72:75], v[160:163], v[118:121], v[78:81]
	v_mfma_f32_16x16x32_bf16 v[76:79], v[160:163], v[134:137], v[82:85]
	v_mfma_f32_16x16x32_bf16 v[80:83], v[180:183], v[118:121], v[86:89]
	v_mfma_f32_16x16x32_bf16 v[84:87], v[180:183], v[134:137], v[90:93]
	v_mfma_f32_16x16x32_bf16 v[88:91], v[188:191], v[118:121], v[94:97]
	v_mfma_f32_16x16x32_bf16 v[92:95], v[188:191], v[134:137], v[98:101]
	v_mfma_f32_16x16x32_bf16 v[4:7], v[156:159], v[122:125], v[4:7]
	v_mfma_f32_16x16x32_bf16 v[16:19], v[156:159], v[144:147], v[16:19]
	v_mfma_f32_16x16x32_bf16 v[72:75], v[164:167], v[122:125], v[72:75]
	v_mfma_f32_16x16x32_bf16 v[76:79], v[164:167], v[144:147], v[76:79]
	v_mfma_f32_16x16x32_bf16 v[80:83], v[184:187], v[122:125], v[80:83]
	v_mfma_f32_16x16x32_bf16 v[84:87], v[184:187], v[144:147], v[84:87]
	s_barrier
; #define STAGE(P, BASE, LD, br, kt) do { const char* _g = (const char*)((BASE) + (size_t)(br) * (LD) + (size_t)(kt) * 64); \
;     for (int _i = 0; _i < 2; ++_i) { int _b = tidx * 16 + _i * 8192; int _r, _c; stage_rc(_b, _r, _c); \
;       __builtin_amdgcn_global_load_lds((const unsigned*)(_g + (unsigned)((_r * (LD) + _c) * 2)), (unsigned*)((char*)(P) + _b), 16, 0, 0); } } while (0)
; #define LDA(dst, b, h) for (int m = 0; m < 4; ++m) for (int k = 0; k < 2; ++k) \
;     dst[m][k] = *reinterpret_cast<const bf16x8*>((char*)SA(b, h) + lds_byte(wr * 64 + m * 16 + fr, k * 32 + fq * 8))
; #define LDB(dst, b, h) for (int n = 0; n < 2; ++n) for (int k = 0; k < 2; ++k) \
;     dst[n][k] = *reinterpret_cast<const bf16x8*>((char*)SB(b, h) + lds_byte(wc * 32 + n * 16 + fr, k * 32 + fq * 8))
; #define MMA(ai, bj, At_, Bt_) do { __builtin_amdgcn_s_setprio(1); \
;     for (int k = 0; k < 2; ++k) for (int m = 0; m < 4; ++m) for (int n = 0; n < 2; ++n) \
;       acc[ai][bj][m][n] = __builtin_amdgcn_mfma_f32_16x16x32_bf16(At_[m][k], Bt_[n][k], acc[ai][bj][m][n], 0, 0, 0); \
;     __builtin_amdgcn_s_setprio(0); } while (0)
; #define WAIT_V(n) asm volatile("s_waitcnt vmcnt(" #n ")" ::: "memory")
; #define WAIT_L(n) asm volatile("s_waitcnt lgkmcnt(" #n ")" ::: "memory")
; #define BAR __builtin_amdgcn_s_barrier()
; template <int EPI, int lda, int ldb, int N, int K>
; __device__ __forceinline__ void gemm_phase(const u16* __restrict__ A, const u16* __restrict__ Bt, const GemmEpi ep, int wv) {
;     ...
;     { LDB(B0, 0, 0); LDA(At, 0, 0); STAGE(SA(1, 1), Ab, lda, brow + HALF, nt - 1);
;       BAR; WAIT_L(0); MMA(0, 0, At, B0); BAR;
;       LDB(B1, 0, 1); BAR; WAIT_L(0); MMA(0, 1, At, B1); BAR;
;       LDA(At, 0, 1); WAIT_V(4); BAR; WAIT_L(0); MMA(1, 0, At, B0); MMA(1, 1, At, B1); BAR; }
;     { LDB(B0, 1, 0); LDA(At, 1, 0); WAIT_V(2); BAR; WAIT_L(0); MMA(0, 0, At, B0); BAR;
	v_mfma_f32_16x16x32_bf16 v[88:91], v[192:195], v[122:125], v[88:91]
	v_mfma_f32_16x16x32_bf16 v[92:95], v[192:195], v[144:147], v[92:95]
	ds_read_b128 v[96:99], v224
	ds_read_b128 v[196:199], v224 offset:1024
	ds_read_b128 v[200:203], v224 offset:2048
	ds_read_b128 v[204:207], v224 offset:3072
	s_barrier
	s_waitcnt lgkmcnt(0)
	v_mfma_f32_16x16x32_bf16 v[12:15], v[152:155], v[96:99], v[12:15]
	v_mfma_f32_16x16x32_bf16 v[40:43], v[152:155], v[200:203], v[40:43]
	v_mfma_f32_16x16x32_bf16 v[52:55], v[180:183], v[96:99], v[52:55]
	v_mfma_f32_16x16x32_bf16 v[56:59], v[180:183], v[200:203], v[56:59]
	v_mfma_f32_16x16x32_bf16 v[64:67], v[188:191], v[200:203], v[64:67]
	v_mfma_f32_16x16x32_bf16 v[44:47], v[160:163], v[96:99], v[44:47]
	v_mfma_f32_16x16x32_bf16 v[48:51], v[160:163], v[200:203], v[48:51]
	v_mfma_f32_16x16x32_bf16 v[60:63], v[188:191], v[96:99], v[60:63]
	v_mfma_f32_16x16x32_bf16 v[12:15], v[156:159], v[196:199], v[12:15]
	v_mfma_f32_16x16x32_bf16 v[40:43], v[156:159], v[204:207], v[40:43]
	v_mfma_f32_16x16x32_bf16 v[52:55], v[184:187], v[196:199], v[52:55]
	v_mfma_f32_16x16x32_bf16 v[56:59], v[184:187], v[204:207], v[56:59]
	v_mfma_f32_16x16x32_bf16 v[64:67], v[192:195], v[204:207], v[64:67]
	v_mfma_f32_16x16x32_bf16 v[152:155], v[164:167], v[196:199], v[44:47]
	s_barrier
	v_mfma_f32_16x16x32_bf16 v[156:159], v[164:167], v[204:207], v[48:51]
	v_mfma_f32_16x16x32_bf16 v[160:163], v[192:195], v[196:199], v[60:63]
	ds_read_b128 v[44:47], v228 offset:16384
	ds_read_b128 v[48:51], v228 offset:17408
	ds_read_b128 v[60:63], v229 offset:18432
	ds_read_b128 v[164:167], v229 offset:19456
	ds_read_b128 v[180:183], v229 offset:20480
	ds_read_b128 v[184:187], v229 offset:21504
	ds_read_b128 v[188:191], v229 offset:22528
	ds_read_b128 v[192:195], v229 offset:23552
	s_waitcnt vmcnt(4)
	s_barrier
	s_waitcnt lgkmcnt(0)
	v_mfma_f32_16x16x32_bf16 v[8:11], v[44:47], v[118:121], v[8:11]
	v_mfma_f32_16x16x32_bf16 v[24:27], v[188:191], v[118:121], v[24:27]
	v_mfma_f32_16x16x32_bf16 v[28:31], v[188:191], v[134:137], v[28:31]
	v_mfma_f32_16x16x32_bf16 v[114:117], v[44:47], v[134:137], v[114:117]
	v_mfma_f32_16x16x32_bf16 v[148:151], v[60:63], v[118:121], v[148:151]
	v_mfma_f32_16x16x32_bf16 v[168:171], v[60:63], v[134:137], v[168:171]
	v_mfma_f32_16x16x32_bf16 v[172:175], v[180:183], v[118:121], v[172:175]
	v_mfma_f32_16x16x32_bf16 v[176:179], v[180:183], v[134:137], v[176:179]
	v_mfma_f32_16x16x32_bf16 v[8:11], v[48:51], v[122:125], v[8:11]
	v_mfma_f32_16x16x32_bf16 v[24:27], v[192:195], v[122:125], v[24:27]
	v_mfma_f32_16x16x32_bf16 v[28:31], v[192:195], v[144:147], v[28:31]
	v_mfma_f32_16x16x32_bf16 v[134:137], v[48:51], v[144:147], v[114:117]
	v_mfma_f32_16x16x32_bf16 v[148:151], v[164:167], v[122:125], v[148:151]
	v_mfma_f32_16x16x32_bf16 v[168:171], v[164:167], v[144:147], v[168:171]
	v_mfma_f32_16x16x32_bf16 v[172:175], v[184:187], v[122:125], v[172:175]
	v_mfma_f32_16x16x32_bf16 v[176:179], v[184:187], v[144:147], v[176:179]
	v_mfma_f32_16x16x32_bf16 v[0:3], v[44:47], v[96:99], v[0:3]
	v_mfma_f32_16x16x32_bf16 v[20:23], v[44:47], v[200:203], v[20:23]
	v_mfma_f32_16x16x32_bf16 v[44:47], v[180:183], v[96:99], v[68:71]
	v_mfma_f32_16x16x32_bf16 v[68:71], v[188:191], v[96:99], v[102:105]
	v_mfma_f32_16x16x32_bf16 v[32:35], v[60:63], v[96:99], v[32:35]
	v_mfma_f32_16x16x32_bf16 v[36:39], v[60:63], v[200:203], v[36:39]
	v_mfma_f32_16x16x32_bf16 v[60:63], v[180:183], v[200:203], v[110:113]
	v_mfma_f32_16x16x32_bf16 v[96:99], v[188:191], v[200:203], v[106:109]
	v_mfma_f32_16x16x32_bf16 v[20:23], v[48:51], v[204:207], v[20:23]
	v_mfma_f32_16x16x32_bf16 v[68:71], v[192:195], v[196:199], v[68:71]
	v_mfma_f32_16x16x32_bf16 v[144:147], v[48:51], v[196:199], v[0:3]
	v_mfma_f32_16x16x32_bf16 v[180:183], v[164:167], v[196:199], v[32:35]
	v_mfma_f32_16x16x32_bf16 v[164:167], v[164:167], v[204:207], v[36:39]
	v_mfma_f32_16x16x32_bf16 v[188:191], v[184:187], v[196:199], v[44:47]
	s_barrier
	v_mfma_f32_16x16x32_bf16 v[184:187], v[184:187], v[204:207], v[60:63]
	v_mfma_f32_16x16x32_bf16 v[192:195], v[192:195], v[204:207], v[96:99]
	ds_read_b128 v[0:3], v225
	ds_read_b128 v[196:199], v225 offset:1024
	ds_read_b128 v[200:203], v225 offset:2048
	ds_read_b128 v[204:207], v225 offset:3072
	ds_read_b128 v[36:39], v228 offset:32768
	ds_read_b128 v[100:103], v228 offset:33792
	ds_read_b128 v[108:111], v229 offset:34816
	ds_read_b128 v[208:211], v229 offset:35840
	ds_read_b128 v[116:119], v229 offset:36864
	ds_read_b128 v[212:215], v229 offset:37888
	ds_read_b128 v[124:127], v229 offset:38912
	ds_read_b128 v[216:219], v229 offset:39936
	s_waitcnt vmcnt(2)
	s_barrier
; #define LDA(dst, b, h) for (int m = 0; m < 4; ++m) for (int k = 0; k < 2; ++k) \
;     dst[m][k] = *reinterpret_cast<const bf16x8*>((char*)SA(b, h) + lds_byte(wr * 64 + m * 16 + fr, k * 32 + fq * 8))
; #define LDB(dst, b, h) for (int n = 0; n < 2; ++n) for (int k = 0; k < 2; ++k) \
;     dst[n][k] = *reinterpret_cast<const bf16x8*>((char*)SB(b, h) + lds_byte(wc * 32 + n * 16 + fr, k * 32 + fq * 8))
; #define MMA(ai, bj, At_, Bt_) do { __builtin_amdgcn_s_setprio(1); \
;     for (int k = 0; k < 2; ++k) for (int m = 0; m < 4; ++m) for (int n = 0; n < 2; ++n) \
;       acc[ai][bj][m][n] = __builtin_amdgcn_mfma_f32_16x16x32_bf16(At_[m][k], Bt_[n][k], acc[ai][bj][m][n], 0, 0, 0); \
;     __builtin_amdgcn_s_setprio(0); } while (0)
; #define WAIT_V(n) asm volatile("s_waitcnt vmcnt(" #n ")" ::: "memory")
; #define WAIT_L(n) asm volatile("s_waitcnt lgkmcnt(" #n ")" ::: "memory")
; #define BAR __builtin_amdgcn_s_barrier()
; template <int EPI, int lda, int ldb, int N, int K>
; __device__ __forceinline__ void gemm_phase(const u16* __restrict__ A, const u16* __restrict__ Bt, const GemmEpi ep, int wv) {
;     ...
;       LDA(At, 0, 1); WAIT_V(4); BAR; WAIT_L(0); MMA(1, 0, At, B0); MMA(1, 1, At, B1); BAR; }
;     { LDB(B0, 1, 0); LDA(At, 1, 0); WAIT_V(2); BAR; WAIT_L(0); MMA(0, 0, At, B0); BAR;
;       LDB(B1, 1, 1); WAIT_V(0); BAR; WAIT_L(0); MMA(0, 1, At, B1); BAR;
;       LDA(At, 1, 1); BAR; WAIT_L(0); MMA(1, 0, At, B0); MMA(1, 1, At, B1); BAR; }
;     if (wr == 0) BAR;
	s_waitcnt lgkmcnt(0)
	v_mfma_f32_16x16x32_bf16 v[4:7], v[36:39], v[0:3], v[4:7]
	v_mfma_f32_16x16x32_bf16 v[16:19], v[36:39], v[200:203], v[16:19]
	v_mfma_f32_16x16x32_bf16 v[32:35], v[108:111], v[0:3], v[72:75]
	v_mfma_f32_16x16x32_bf16 v[44:47], v[108:111], v[200:203], v[76:79]
	v_mfma_f32_16x16x32_bf16 v[72:75], v[116:119], v[0:3], v[80:83]
	v_mfma_f32_16x16x32_bf16 v[76:79], v[116:119], v[200:203], v[84:87]
	v_mfma_f32_16x16x32_bf16 v[80:83], v[124:127], v[0:3], v[88:91]
	v_mfma_f32_16x16x32_bf16 v[84:87], v[124:127], v[200:203], v[92:95]
	v_mfma_f32_16x16x32_bf16 v[120:123], v[100:103], v[196:199], v[4:7]
	v_mfma_f32_16x16x32_bf16 v[60:63], v[100:103], v[204:207], v[16:19]
	v_mfma_f32_16x16x32_bf16 v[112:115], v[208:211], v[196:199], v[32:35]
	v_mfma_f32_16x16x32_bf16 v[48:51], v[208:211], v[204:207], v[44:47]
	v_mfma_f32_16x16x32_bf16 v[104:107], v[212:215], v[196:199], v[72:75]
	v_mfma_f32_16x16x32_bf16 v[44:47], v[212:215], v[204:207], v[76:79]
	s_barrier
	v_mfma_f32_16x16x32_bf16 v[96:99], v[216:219], v[196:199], v[80:83]
	v_mfma_f32_16x16x32_bf16 v[32:35], v[216:219], v[204:207], v[84:87]
	ds_read_b128 v[4:7], v226
	ds_read_b128 v[220:223], v226 offset:1024
	ds_read_b128 v[76:79], v226 offset:2048
	ds_read_b128 v[224:227], v226 offset:3072
	s_waitcnt vmcnt(0)
	s_barrier
	s_waitcnt lgkmcnt(0)
	v_mfma_f32_16x16x32_bf16 v[12:15], v[36:39], v[4:7], v[12:15]
	v_mfma_f32_16x16x32_bf16 v[16:19], v[36:39], v[76:79], v[40:43]
	v_mfma_f32_16x16x32_bf16 v[36:39], v[108:111], v[4:7], v[152:155]
	v_mfma_f32_16x16x32_bf16 v[40:43], v[108:111], v[76:79], v[156:159]
	v_mfma_f32_16x16x32_bf16 v[72:75], v[116:119], v[4:7], v[52:55]
	v_mfma_f32_16x16x32_bf16 v[80:83], v[116:119], v[76:79], v[56:59]
	v_mfma_f32_16x16x32_bf16 v[84:87], v[124:127], v[4:7], v[160:163]
	v_mfma_f32_16x16x32_bf16 v[64:67], v[124:127], v[76:79], v[64:67]
	v_mfma_f32_16x16x32_bf16 v[124:127], v[100:103], v[220:223], v[12:15]
	v_mfma_f32_16x16x32_bf16 v[56:59], v[100:103], v[224:227], v[16:19]
	v_mfma_f32_16x16x32_bf16 v[116:119], v[208:211], v[220:223], v[36:39]
	v_mfma_f32_16x16x32_bf16 v[52:55], v[208:211], v[224:227], v[40:43]
	v_mfma_f32_16x16x32_bf16 v[108:111], v[212:215], v[220:223], v[72:75]
	v_mfma_f32_16x16x32_bf16 v[40:43], v[212:215], v[224:227], v[80:83]
	s_barrier
	v_mfma_f32_16x16x32_bf16 v[100:103], v[216:219], v[220:223], v[84:87]
	v_mfma_f32_16x16x32_bf16 v[36:39], v[216:219], v[224:227], v[64:67]
	ds_read_b128 v[84:87], v228 offset:49152
	ds_read_b128 v[152:155], v228 offset:50176
	ds_read_b128 v[92:95], v229 offset:51200
	ds_read_b128 v[156:159], v229 offset:52224
	ds_read_b128 v[160:163], v229 offset:53248
	ds_read_b128 v[208:211], v229 offset:54272
	ds_read_b128 v[212:215], v229 offset:55296
	ds_read_b128 v[216:219], v229 offset:56320
	s_barrier
	s_waitcnt lgkmcnt(0)
	v_mfma_f32_16x16x32_bf16 v[8:11], v[84:87], v[0:3], v[8:11]
	v_mfma_f32_16x16x32_bf16 v[12:15], v[84:87], v[200:203], v[134:137]
	v_mfma_f32_16x16x32_bf16 v[16:19], v[92:95], v[0:3], v[148:151]
	v_mfma_f32_16x16x32_bf16 v[64:67], v[92:95], v[200:203], v[168:171]
	v_mfma_f32_16x16x32_bf16 v[72:75], v[160:163], v[0:3], v[172:175]
	v_mfma_f32_16x16x32_bf16 v[134:137], v[160:163], v[200:203], v[176:179]
	v_mfma_f32_16x16x32_bf16 v[0:3], v[212:215], v[0:3], v[24:27]
	v_mfma_f32_16x16x32_bf16 v[24:27], v[212:215], v[200:203], v[28:31]
	v_mfma_f32_16x16x32_bf16 v[88:91], v[152:155], v[196:199], v[8:11]
	v_mfma_f32_16x16x32_bf16 v[28:31], v[152:155], v[204:207], v[12:15]
	v_mfma_f32_16x16x32_bf16 v[80:83], v[156:159], v[196:199], v[16:19]
	v_mfma_f32_16x16x32_bf16 v[16:19], v[156:159], v[204:207], v[64:67]
	v_mfma_f32_16x16x32_bf16 v[72:75], v[208:211], v[196:199], v[72:75]
	v_mfma_f32_16x16x32_bf16 v[12:15], v[208:211], v[204:207], v[134:137]
	v_mfma_f32_16x16x32_bf16 v[64:67], v[216:219], v[196:199], v[0:3]
	v_mfma_f32_16x16x32_bf16 v[0:3], v[216:219], v[204:207], v[24:27]
	v_mfma_f32_16x16x32_bf16 v[8:11], v[84:87], v[4:7], v[144:147]
	v_mfma_f32_16x16x32_bf16 v[20:23], v[84:87], v[76:79], v[20:23]
	v_mfma_f32_16x16x32_bf16 v[84:87], v[92:95], v[4:7], v[180:183]
	v_mfma_f32_16x16x32_bf16 v[134:137], v[92:95], v[76:79], v[164:167]
	v_mfma_f32_16x16x32_bf16 v[144:147], v[160:163], v[4:7], v[188:191]
	v_mfma_f32_16x16x32_bf16 v[148:151], v[160:163], v[76:79], v[184:187]
	v_mfma_f32_16x16x32_bf16 v[4:7], v[212:215], v[4:7], v[68:71]
	v_mfma_f32_16x16x32_bf16 v[160:163], v[212:215], v[76:79], v[192:195]
	v_mfma_f32_16x16x32_bf16 v[92:95], v[152:155], v[220:223], v[8:11]
	v_mfma_f32_16x16x32_bf16 v[24:27], v[152:155], v[224:227], v[20:23]
	v_mfma_f32_16x16x32_bf16 v[84:87], v[156:159], v[220:223], v[84:87]
	v_mfma_f32_16x16x32_bf16 v[20:23], v[156:159], v[224:227], v[134:137]
	v_mfma_f32_16x16x32_bf16 v[76:79], v[208:211], v[220:223], v[144:147]
	v_mfma_f32_16x16x32_bf16 v[8:11], v[208:211], v[224:227], v[148:151]
	s_barrier
	v_mfma_f32_16x16x32_bf16 v[68:71], v[216:219], v[220:223], v[4:7]
	v_mfma_f32_16x16x32_bf16 v[4:7], v[216:219], v[224:227], v[160:163]
	v_cmp_gt_u32_e32 vcc, s62, v130
	s_and_saveexec_b64 s[46:47], vcc
	s_cbranch_execz .LBB0_1245
	s_barrier
	s_branch .LBB0_1245

; #define STAGE(P, BASE, LD, br, kt) do { const char* _g = (const char*)((BASE) + (size_t)(br) * (LD) + (size_t)(kt) * 64); \
;     for (int _i = 0; _i < 2; ++_i) { int _b = tidx * 16 + _i * 8192; int _r, _c; stage_rc(_b, _r, _c); \
;       __builtin_amdgcn_global_load_lds((const unsigned*)(_g + (unsigned)((_r * (LD) + _c) * 2)), (unsigned*)((char*)(P) + _b), 16, 0, 0); } } while (0)
; #define LDA(dst, b, h) for (int m = 0; m < 4; ++m) for (int k = 0; k < 2; ++k) \
;     dst[m][k] = *reinterpret_cast<const bf16x8*>((char*)SA(b, h) + lds_byte(wr * 64 + m * 16 + fr, k * 32 + fq * 8))
; #define LDB(dst, b, h) for (int n = 0; n < 2; ++n) for (int k = 0; k < 2; ++k) \
;     dst[n][k] = *reinterpret_cast<const bf16x8*>((char*)SB(b, h) + lds_byte(wc * 32 + n * 16 + fr, k * 32 + fq * 8))
; #define MMA(ai, bj, At_, Bt_) do { __builtin_amdgcn_s_setprio(1); \
;     for (int k = 0; k < 2; ++k) for (int m = 0; m < 4; ++m) for (int n = 0; n < 2; ++n) \
;       acc[ai][bj][m][n] = __builtin_amdgcn_mfma_f32_16x16x32_bf16(At_[m][k], Bt_[n][k], acc[ai][bj][m][n], 0, 0, 0); \
;     __builtin_amdgcn_s_setprio(0); } while (0)
; #define WAIT_V(n) asm volatile("s_waitcnt vmcnt(" #n ")" ::: "memory")
; #define WAIT_L(n) asm volatile("s_waitcnt lgkmcnt(" #n ")" ::: "memory")
; #define BAR __builtin_amdgcn_s_barrier()
; template <int EPI, int lda, int ldb, int N, int K>
; __device__ __forceinline__ void gemm_phase(const u16* __restrict__ A, const u16* __restrict__ Bt, const GemmEpi ep, int wv) {
;     ...
;     if constexpr (!PF) { TILE_COORDS(tile, brow, bcol, pn); STAGE4(brow, bcol, pn); }
;     const int wid = tidx >> 6, lane = tidx & 63, wr = wid >> 2, wc = wid & 3, fr = lane & 15, fq = lane >> 4;
;     const u16* Ab = A + (EPI == EPI_RG ? (pn >> 1) * 256 : 0);
;     f32x4 acc[2][2][4][2] = {};
;     bf16x8 At[4][2], B0[2][2], B1[2][2];
;     constexpr int nt = K / 64;
;     if (wr == 1) BAR;
;     WAIT_V(4); BAR;
;     STAGE(SB(1, 0), Bt, ldb, bcol, 1); STAGE(SA(1, 0), Ab, lda, brow, 1); STAGE(SB(1, 1), Bt, ldb, bcol + HALF, 1);
;     WAIT_V(6); BAR;
;     for (int t = 0; t < nt - 2; t += 2) {
;       LDB(B0, 0, 0); SCHED; LDA(At, 0, 0); STAGE(SA(1, 1), Ab, lda, brow + HALF, t + 1);
;       WAIT_L(8); BAR; WAIT_L(0); MMA(0, 0, At, B0); BAR; SCHED;
;       LDB(B1, 0, 1); STAGE(SB(0, 0), Bt, ldb, bcol, t + 2);
;       BAR; WAIT_L(0); MMA(0, 1, At, B1); BAR;
.LBB0_1349:
	s_or_b64 exec, exec, s[54:55]
	v_mov_b32_e32 v1, v129
	v_add_u32_e32 v7, s58, v6
	v_lshl_add_u64 v[12:13], s[46:47], 0, v[128:129]
	v_lshl_add_u64 v[14:15], s[46:47], 0, v[0:1]
	v_lshl_add_u64 v[2:3], s[52:53], 0, v[128:129]
	v_lshl_add_u64 v[0:1], s[52:53], 0, v[0:1]
	v_readfirstlane_b32 s53, v7
	v_add_u32_e32 v7, 0x2000, v7
	v_mov_b32_e32 v5, v129
	v_mov_b32_e32 v17, v129
	v_lshl_add_u64 v[26:27], v[12:13], 0, s[36:37]
	s_mov_b32 m0, s53
	v_readfirstlane_b32 s52, v7
	v_add_u32_e32 v7, 0x8000, v23
	v_lshl_add_u64 v[8:9], s[50:51], 0, v[4:5]
	v_lshl_add_u64 v[10:11], s[50:51], 0, v[16:17]
	s_waitcnt vmcnt(4)
	s_barrier
	global_load_lds_dwordx4 v[26:27], off
	v_lshl_add_u64 v[26:27], v[14:15], 0, s[36:37]
	s_mov_b32 m0, s52
	v_readfirstlane_b32 s51, v7
	v_add_u32_e32 v7, 0xa000, v23
	global_load_lds_dwordx4 v[26:27], off
	v_lshl_add_u64 v[26:27], v[8:9], 0, s[36:37]
	s_mov_b32 m0, s51
	v_readfirstlane_b32 s50, v7
	v_add_u32_e32 v25, s59, v6
	global_load_lds_dwordx4 v[26:27], off
	v_lshl_add_u64 v[26:27], v[10:11], 0, s[36:37]
	s_mov_b32 m0, s50
	v_readfirstlane_b32 s11, v25
	v_add_u32_e32 v25, 0x2000, v25
	global_load_lds_dwordx4 v[26:27], off
	v_lshl_add_u64 v[26:27], v[2:3], 0, s[36:37]
	s_mov_b32 m0, s11
	v_readfirstlane_b32 s5, v25
	global_load_lds_dwordx4 v[26:27], off
	v_lshl_add_u64 v[6:7], v[0:1], 0, s[36:37]
	s_mov_b32 m0, s5
	v_and_b32_e32 v132, 15, v20
	global_load_lds_dwordx4 v[6:7], off
	v_bfe_u32 v128, v20, 4, 2
	v_lshlrev_b32_e32 v7, 2, v20
	v_bfe_u32 v131, v130, 6, 2
	v_lshlrev_b32_e32 v25, 4, v128
	v_lshlrev_b32_e32 v6, 6, v132
	v_and_b32_e32 v50, 32, v7
	v_lshlrev_b32_e32 v126, 12, v131
	v_bitop3_b32 v127, v25, v50, v6 bitop3:0x36
	v_add3_u32 v133, s56, v127, v126
	s_waitcnt vmcnt(6)
	s_barrier
	ds_read_b128 v[26:29], v133
	ds_read_b128 v[30:33], v133 offset:1024
	ds_read_b128 v[34:37], v133 offset:2048
	ds_read_b128 v[38:41], v133 offset:3072
	v_lshl_add_u64 v[6:7], s[48:49], 0, v[4:5]
	v_lshl_add_u64 v[4:5], s[48:49], 0, v[16:17]
	v_lshlrev_b32_e32 v17, 6, v20
	v_and_b32_e32 v17, 0x3c0, v17
	v_add_u32_e32 v20, 0xc000, v23
	v_lshlrev_b32_e32 v16, 13, v139
	v_bitop3_b32 v17, v17, v50, v25 bitop3:0x36
	v_readfirstlane_b32 s47, v20
	v_add_u32_e32 v20, 0xe000, v23
	v_add3_u32 v228, 0, v127, v16
	v_add3_u32 v229, 0, v17, v16
	v_lshl_add_u64 v[16:17], v[6:7], 0, s[36:37]
	s_mov_b32 m0, s47
	v_readfirstlane_b32 s46, v20
	ds_read_b128 v[42:45], v228
	ds_read_b128 v[46:49], v228 offset:1024
	ds_read_b128 v[50:53], v229 offset:2048
	ds_read_b128 v[54:57], v229 offset:3072
	ds_read_b128 v[58:61], v229 offset:4096
	ds_read_b128 v[62:65], v229 offset:5120
	ds_read_b128 v[66:69], v229 offset:6144
	ds_read_b128 v[70:73], v229 offset:7168
	global_load_lds_dwordx4 v[16:17], off
	v_lshl_add_u64 v[16:17], v[4:5], 0, s[36:37]
	s_mov_b32 m0, s46
	s_nop 0
	global_load_lds_dwordx4 v[16:17], off
	s_waitcnt lgkmcnt(8)
	s_barrier
	s_waitcnt lgkmcnt(0)
	v_mfma_f32_16x16x32_bf16 v[74:77], v[42:45], v[26:29], 0
	v_mfma_f32_16x16x32_bf16 v[78:81], v[42:45], v[34:37], 0
	v_mfma_f32_16x16x32_bf16 v[82:85], v[50:53], v[26:29], 0
	v_mfma_f32_16x16x32_bf16 v[86:89], v[50:53], v[34:37], 0
	v_mfma_f32_16x16x32_bf16 v[90:93], v[58:61], v[26:29], 0
	v_mfma_f32_16x16x32_bf16 v[94:97], v[58:61], v[34:37], 0
	v_mfma_f32_16x16x32_bf16 v[98:101], v[66:69], v[26:29], 0
	v_mfma_f32_16x16x32_bf16 v[102:105], v[66:69], v[34:37], 0
	v_mfma_f32_16x16x32_bf16 v[74:77], v[46:49], v[30:33], v[74:77]
	v_mfma_f32_16x16x32_bf16 v[78:81], v[46:49], v[38:41], v[78:81]
	v_mfma_f32_16x16x32_bf16 v[82:85], v[54:57], v[30:33], v[82:85]
	v_mfma_f32_16x16x32_bf16 v[86:89], v[54:57], v[38:41], v[86:89]
	v_mfma_f32_16x16x32_bf16 v[90:93], v[62:65], v[30:33], v[90:93]
	v_mfma_f32_16x16x32_bf16 v[94:97], v[62:65], v[38:41], v[94:97]
	s_barrier
	v_mfma_f32_16x16x32_bf16 v[98:101], v[70:73], v[30:33], v[98:101]
	v_mfma_f32_16x16x32_bf16 v[102:105], v[70:73], v[38:41], v[102:105]
	v_readfirstlane_b32 s48, v21
	v_add_u32_e32 v20, 0x2000, v21
	v_add3_u32 v224, s57, v127, v126
	v_lshl_add_u64 v[16:17], v[12:13], 0, s[38:39]
	s_mov_b32 m0, s48
	v_readfirstlane_b32 s48, v20
	ds_read_b128 v[106:109], v224
	ds_read_b128 v[110:113], v224 offset:1024
	ds_read_b128 v[114:117], v224 offset:2048
	ds_read_b128 v[118:121], v224 offset:3072
	global_load_lds_dwordx4 v[16:17], off
	v_lshl_add_u64 v[16:17], v[14:15], 0, s[38:39]
	s_mov_b32 m0, s48
	s_nop 0
	global_load_lds_dwordx4 v[16:17], off
	s_barrier
	s_waitcnt lgkmcnt(0)
	v_mfma_f32_16x16x32_bf16 v[122:125], v[42:45], v[106:109], 0
	v_mfma_f32_16x16x32_bf16 v[42:45], v[42:45], v[114:117], 0
	v_mfma_f32_16x16x32_bf16 v[140:143], v[50:53], v[106:109], 0
	v_mfma_f32_16x16x32_bf16 v[50:53], v[50:53], v[114:117], 0
	v_mfma_f32_16x16x32_bf16 v[144:147], v[58:61], v[106:109], 0
	v_mfma_f32_16x16x32_bf16 v[58:61], v[58:61], v[114:117], 0
	v_mfma_f32_16x16x32_bf16 v[148:151], v[66:69], v[106:109], 0
	v_mfma_f32_16x16x32_bf16 v[66:69], v[66:69], v[114:117], 0
	v_mfma_f32_16x16x32_bf16 v[122:125], v[46:49], v[110:113], v[122:125]
	v_mfma_f32_16x16x32_bf16 v[42:45], v[46:49], v[118:121], v[42:45]
	v_mfma_f32_16x16x32_bf16 v[46:49], v[54:57], v[110:113], v[140:143]
	v_mfma_f32_16x16x32_bf16 v[50:53], v[54:57], v[118:121], v[50:53]
	v_mfma_f32_16x16x32_bf16 v[54:57], v[62:65], v[110:113], v[144:147]
	v_mfma_f32_16x16x32_bf16 v[58:61], v[62:65], v[118:121], v[58:61]
	s_barrier
; #define STAGE(P, BASE, LD, br, kt) do { const char* _g = (const char*)((BASE) + (size_t)(br) * (LD) + (size_t)(kt) * 64); \
;     for (int _i = 0; _i < 2; ++_i) { int _b = tidx * 16 + _i * 8192; int _r, _c; stage_rc(_b, _r, _c); \
;       __builtin_amdgcn_global_load_lds((const unsigned*)(_g + (unsigned)((_r * (LD) + _c) * 2)), (unsigned*)((char*)(P) + _b), 16, 0, 0); } } while (0)
; #define LDA(dst, b, h) for (int m = 0; m < 4; ++m) for (int k = 0; k < 2; ++k) \
;     dst[m][k] = *reinterpret_cast<const bf16x8*>((char*)SA(b, h) + lds_byte(wr * 64 + m * 16 + fr, k * 32 + fq * 8))
; #define LDB(dst, b, h) for (int n = 0; n < 2; ++n) for (int k = 0; k < 2; ++k) \
;     dst[n][k] = *reinterpret_cast<const bf16x8*>((char*)SB(b, h) + lds_byte(wc * 32 + n * 16 + fr, k * 32 + fq * 8))
; #define MMA(ai, bj, At_, Bt_) do { __builtin_amdgcn_s_setprio(1); \
;     for (int k = 0; k < 2; ++k) for (int m = 0; m < 4; ++m) for (int n = 0; n < 2; ++n) \
;       acc[ai][bj][m][n] = __builtin_amdgcn_mfma_f32_16x16x32_bf16(At_[m][k], Bt_[n][k], acc[ai][bj][m][n], 0, 0, 0); \
;     __builtin_amdgcn_s_setprio(0); } while (0)
; #define WAIT_V(n) asm volatile("s_waitcnt vmcnt(" #n ")" ::: "memory")
; #define WAIT_L(n) asm volatile("s_waitcnt lgkmcnt(" #n ")" ::: "memory")
; #define BAR __builtin_amdgcn_s_barrier()
; #define SCHED __builtin_amdgcn_sched_barrier(0)
; template <int EPI, int lda, int ldb, int N, int K>
; __device__ __forceinline__ void gemm_phase(const u16* __restrict__ A, const u16* __restrict__ Bt, const GemmEpi ep, int wv) {
;     ...
;       BAR; WAIT_L(0); MMA(0, 1, At, B1); BAR;
;       LDA(At, 0, 1); STAGE(SA(0, 0), Ab, lda, brow, t + 2);
;       BAR; WAIT_L(0); MMA(1, 0, At, B0); BAR; SCHED;
;       STAGE(SB(0, 1), Bt, ldb, bcol + HALF, t + 2);
;       WAIT_V(6); BAR; MMA(1, 1, At, B1); BAR;
;       LDB(B0, 1, 0); SCHED; LDA(At, 1, 0); STAGE(SA(0, 1), Ab, lda, brow + HALF, t + 2);
;       WAIT_L(8); BAR; WAIT_L(0); MMA(0, 0, At, B0); BAR; SCHED;
;       LDB(B1, 1, 1); STAGE(SB(1, 0), Bt, ldb, bcol, t + 3);
;       BAR; WAIT_L(0); MMA(0, 1, At, B1); BAR;
	v_mfma_f32_16x16x32_bf16 v[62:65], v[70:73], v[110:113], v[148:151]
	v_mfma_f32_16x16x32_bf16 v[66:69], v[70:73], v[118:121], v[66:69]
	v_readfirstlane_b32 s48, v23
	v_lshl_add_u64 v[16:17], v[8:9], 0, s[38:39]
	s_mov_b32 m0, s48
	v_readfirstlane_b32 s48, v24
	ds_read_b128 v[70:73], v228 offset:16384
	ds_read_b128 v[140:143], v228 offset:17408
	ds_read_b128 v[144:147], v229 offset:18432
	ds_read_b128 v[148:151], v229 offset:19456
	ds_read_b128 v[152:155], v229 offset:20480
	ds_read_b128 v[156:159], v229 offset:21504
	ds_read_b128 v[160:163], v229 offset:22528
	ds_read_b128 v[164:167], v229 offset:23552
	global_load_lds_dwordx4 v[16:17], off
	v_lshl_add_u64 v[16:17], v[10:11], 0, s[38:39]
	s_mov_b32 m0, s48
	s_nop 0
	global_load_lds_dwordx4 v[16:17], off
	s_barrier
	s_waitcnt lgkmcnt(0)
	v_mfma_f32_16x16x32_bf16 v[168:171], v[70:73], v[26:29], 0
	v_mfma_f32_16x16x32_bf16 v[172:175], v[70:73], v[34:37], 0
	v_mfma_f32_16x16x32_bf16 v[176:179], v[144:147], v[26:29], 0
	v_mfma_f32_16x16x32_bf16 v[180:183], v[144:147], v[34:37], 0
	v_mfma_f32_16x16x32_bf16 v[184:187], v[152:155], v[26:29], 0
	v_mfma_f32_16x16x32_bf16 v[188:191], v[152:155], v[34:37], 0
	v_mfma_f32_16x16x32_bf16 v[24:27], v[160:163], v[26:29], 0
	v_mfma_f32_16x16x32_bf16 v[34:37], v[160:163], v[34:37], 0
	v_mfma_f32_16x16x32_bf16 v[168:171], v[140:143], v[30:33], v[168:171]
	v_mfma_f32_16x16x32_bf16 v[176:179], v[148:151], v[30:33], v[176:179]
	v_mfma_f32_16x16x32_bf16 v[184:187], v[156:159], v[30:33], v[184:187]
	v_mfma_f32_16x16x32_bf16 v[24:27], v[164:167], v[30:33], v[24:27]
	v_mfma_f32_16x16x32_bf16 v[28:31], v[164:167], v[38:41], v[34:37]
	v_mfma_f32_16x16x32_bf16 v[172:175], v[140:143], v[38:41], v[172:175]
	s_barrier
	v_mfma_f32_16x16x32_bf16 v[180:183], v[148:151], v[38:41], v[180:183]
	v_mfma_f32_16x16x32_bf16 v[188:191], v[156:159], v[38:41], v[188:191]
	v_readfirstlane_b32 s48, v22
	v_add_u32_e32 v20, 0x2000, v22
	v_lshl_add_u64 v[16:17], v[2:3], 0, s[38:39]
	s_mov_b32 m0, s48
	v_readfirstlane_b32 s48, v20
	global_load_lds_dwordx4 v[16:17], off
	v_lshl_add_u64 v[16:17], v[0:1], 0, s[38:39]
	s_mov_b32 m0, s48
	s_nop 0
	global_load_lds_dwordx4 v[16:17], off
	s_waitcnt vmcnt(6)
	s_barrier
	v_mfma_f32_16x16x32_bf16 v[20:23], v[70:73], v[106:109], 0
	v_mfma_f32_16x16x32_bf16 v[32:35], v[70:73], v[114:117], 0
	v_mfma_f32_16x16x32_bf16 v[36:39], v[144:147], v[106:109], 0
	v_mfma_f32_16x16x32_bf16 v[70:73], v[144:147], v[114:117], 0
	v_mfma_f32_16x16x32_bf16 v[144:147], v[152:155], v[106:109], 0
	v_mfma_f32_16x16x32_bf16 v[152:155], v[152:155], v[114:117], 0
	v_mfma_f32_16x16x32_bf16 v[106:109], v[160:163], v[106:109], 0
	v_mfma_f32_16x16x32_bf16 v[114:117], v[160:163], v[114:117], 0
	v_mfma_f32_16x16x32_bf16 v[20:23], v[140:143], v[110:113], v[20:23]
	v_mfma_f32_16x16x32_bf16 v[32:35], v[140:143], v[118:121], v[32:35]
	v_mfma_f32_16x16x32_bf16 v[36:39], v[148:151], v[110:113], v[36:39]
	v_mfma_f32_16x16x32_bf16 v[70:73], v[148:151], v[118:121], v[70:73]
	v_mfma_f32_16x16x32_bf16 v[140:143], v[156:159], v[110:113], v[144:147]
	v_mfma_f32_16x16x32_bf16 v[106:109], v[164:167], v[110:113], v[106:109]
	s_barrier
	v_mfma_f32_16x16x32_bf16 v[110:113], v[164:167], v[118:121], v[114:117]
	v_mfma_f32_16x16x32_bf16 v[144:147], v[156:159], v[118:121], v[152:155]
	v_add3_u32 v225, s58, v127, v126
	ds_read_b128 v[114:117], v225
	ds_read_b128 v[118:121], v225 offset:1024
	ds_read_b128 v[148:151], v225 offset:2048
	ds_read_b128 v[152:155], v225 offset:3072
	v_readfirstlane_b32 s48, v18
	v_lshl_add_u64 v[16:17], v[6:7], 0, s[38:39]
	s_mov_b32 m0, s48
	v_readfirstlane_b32 s48, v19
	ds_read_b128 v[156:159], v228 offset:32768
	ds_read_b128 v[160:163], v228 offset:33792
	ds_read_b128 v[164:167], v229 offset:34816
	ds_read_b128 v[192:195], v229 offset:35840
	ds_read_b128 v[196:199], v229 offset:36864
	ds_read_b128 v[200:203], v229 offset:37888
	ds_read_b128 v[204:207], v229 offset:38912
	ds_read_b128 v[208:211], v229 offset:39936
	global_load_lds_dwordx4 v[16:17], off
	v_lshl_add_u64 v[16:17], v[4:5], 0, s[38:39]
	s_mov_b32 m0, s48
	s_nop 0
	global_load_lds_dwordx4 v[16:17], off
	s_waitcnt lgkmcnt(8)
	s_barrier
	s_waitcnt lgkmcnt(0)
	v_mfma_f32_16x16x32_bf16 v[16:19], v[156:159], v[114:117], v[74:77]
	v_mfma_f32_16x16x32_bf16 v[74:77], v[156:159], v[148:151], v[78:81]
	v_mfma_f32_16x16x32_bf16 v[78:81], v[164:167], v[114:117], v[82:85]
	v_mfma_f32_16x16x32_bf16 v[82:85], v[164:167], v[148:151], v[86:89]
	v_mfma_f32_16x16x32_bf16 v[86:89], v[196:199], v[114:117], v[90:93]
	v_mfma_f32_16x16x32_bf16 v[90:93], v[196:199], v[148:151], v[94:97]
	v_mfma_f32_16x16x32_bf16 v[94:97], v[204:207], v[114:117], v[98:101]
	v_mfma_f32_16x16x32_bf16 v[98:101], v[204:207], v[148:151], v[102:105]
	v_mfma_f32_16x16x32_bf16 v[16:19], v[160:163], v[118:121], v[16:19]
	v_mfma_f32_16x16x32_bf16 v[74:77], v[160:163], v[152:155], v[74:77]
	v_mfma_f32_16x16x32_bf16 v[78:81], v[192:195], v[118:121], v[78:81]
	v_mfma_f32_16x16x32_bf16 v[82:85], v[192:195], v[152:155], v[82:85]
	v_mfma_f32_16x16x32_bf16 v[86:89], v[200:203], v[118:121], v[86:89]
	v_mfma_f32_16x16x32_bf16 v[90:93], v[200:203], v[152:155], v[90:93]
	s_barrier
	v_mfma_f32_16x16x32_bf16 v[94:97], v[208:211], v[118:121], v[94:97]
	v_mfma_f32_16x16x32_bf16 v[98:101], v[208:211], v[152:155], v[98:101]
	s_mov_b32 m0, s53
	v_add3_u32 v226, s59, v127, v126
	v_lshl_add_u64 v[12:13], v[12:13], 0, s[40:41]
	ds_read_b128 v[102:105], v226
	ds_read_b128 v[212:215], v226 offset:1024
	ds_read_b128 v[216:219], v226 offset:2048
	ds_read_b128 v[220:223], v226 offset:3072
	global_load_lds_dwordx4 v[12:13], off
	v_lshl_add_u64 v[12:13], v[14:15], 0, s[40:41]
	s_mov_b32 m0, s52
	s_nop 0
	global_load_lds_dwordx4 v[12:13], off
	s_barrier
; #define STAGE(P, BASE, LD, br, kt) do { const char* _g = (const char*)((BASE) + (size_t)(br) * (LD) + (size_t)(kt) * 64); \
;     for (int _i = 0; _i < 2; ++_i) { int _b = tidx * 16 + _i * 8192; int _r, _c; stage_rc(_b, _r, _c); \
;       __builtin_amdgcn_global_load_lds((const unsigned*)(_g + (unsigned)((_r * (LD) + _c) * 2)), (unsigned*)((char*)(P) + _b), 16, 0, 0); } } while (0)
; #define LDA(dst, b, h) for (int m = 0; m < 4; ++m) for (int k = 0; k < 2; ++k) \
;     dst[m][k] = *reinterpret_cast<const bf16x8*>((char*)SA(b, h) + lds_byte(wr * 64 + m * 16 + fr, k * 32 + fq * 8))
; #define LDB(dst, b, h) for (int n = 0; n < 2; ++n) for (int k = 0; k < 2; ++k) \
;     dst[n][k] = *reinterpret_cast<const bf16x8*>((char*)SB(b, h) + lds_byte(wc * 32 + n * 16 + fr, k * 32 + fq * 8))
; #define MMA(ai, bj, At_, Bt_) do { __builtin_amdgcn_s_setprio(1); \
;     for (int k = 0; k < 2; ++k) for (int m = 0; m < 4; ++m) for (int n = 0; n < 2; ++n) \
;       acc[ai][bj][m][n] = __builtin_amdgcn_mfma_f32_16x16x32_bf16(At_[m][k], Bt_[n][k], acc[ai][bj][m][n], 0, 0, 0); \
;     __builtin_amdgcn_s_setprio(0); } while (0)
; #define WAIT_V(n) asm volatile("s_waitcnt vmcnt(" #n ")" ::: "memory")
; #define WAIT_L(n) asm volatile("s_waitcnt lgkmcnt(" #n ")" ::: "memory")
; #define BAR __builtin_amdgcn_s_barrier()
; #define SCHED __builtin_amdgcn_sched_barrier(0)
; template <int EPI, int lda, int ldb, int N, int K>
; __device__ __forceinline__ void gemm_phase(const u16* __restrict__ A, const u16* __restrict__ Bt, const GemmEpi ep, int wv) {
;     ...
;       BAR; WAIT_L(0); MMA(0, 1, At, B1); BAR;
;       LDA(At, 1, 1); STAGE(SA(1, 0), Ab, lda, brow, t + 3);
;       BAR; WAIT_L(0); MMA(1, 0, At, B0); BAR; SCHED;
;       STAGE(SB(1, 1), Bt, ldb, bcol + HALF, t + 3);
;       WAIT_V(6); BAR; MMA(1, 1, At, B1); BAR;
;     }
;     { LDB(B0, 0, 0); LDA(At, 0, 0); STAGE(SA(1, 1), Ab, lda, brow + HALF, nt - 1);
	s_waitcnt lgkmcnt(0)
	v_mfma_f32_16x16x32_bf16 v[12:15], v[156:159], v[102:105], v[122:125]
	v_mfma_f32_16x16x32_bf16 v[40:43], v[156:159], v[216:219], v[42:45]
	v_mfma_f32_16x16x32_bf16 v[44:47], v[164:167], v[102:105], v[46:49]
	v_mfma_f32_16x16x32_bf16 v[48:51], v[164:167], v[216:219], v[50:53]
	v_mfma_f32_16x16x32_bf16 v[52:55], v[196:199], v[102:105], v[54:57]
	v_mfma_f32_16x16x32_bf16 v[56:59], v[196:199], v[216:219], v[58:61]
	v_mfma_f32_16x16x32_bf16 v[60:63], v[204:207], v[102:105], v[62:65]
	v_mfma_f32_16x16x32_bf16 v[64:67], v[204:207], v[216:219], v[66:69]
	v_mfma_f32_16x16x32_bf16 v[12:15], v[160:163], v[212:215], v[12:15]
	v_mfma_f32_16x16x32_bf16 v[40:43], v[160:163], v[220:223], v[40:43]
	v_mfma_f32_16x16x32_bf16 v[44:47], v[192:195], v[212:215], v[44:47]
	v_mfma_f32_16x16x32_bf16 v[48:51], v[192:195], v[220:223], v[48:51]
	v_mfma_f32_16x16x32_bf16 v[52:55], v[200:203], v[212:215], v[52:55]
	v_mfma_f32_16x16x32_bf16 v[56:59], v[200:203], v[220:223], v[56:59]
	s_barrier
	v_mfma_f32_16x16x32_bf16 v[60:63], v[208:211], v[212:215], v[60:63]
	v_mfma_f32_16x16x32_bf16 v[64:67], v[208:211], v[220:223], v[64:67]
	s_mov_b32 m0, s51
	v_lshl_add_u64 v[8:9], v[8:9], 0, s[40:41]
	ds_read_b128 v[122:125], v228 offset:49152
	ds_read_b128 v[156:159], v228 offset:50176
	ds_read_b128 v[160:163], v229 offset:51200
	ds_read_b128 v[164:167], v229 offset:52224
	ds_read_b128 v[192:195], v229 offset:53248
	ds_read_b128 v[196:199], v229 offset:54272
	ds_read_b128 v[200:203], v229 offset:55296
	ds_read_b128 v[204:207], v229 offset:56320
	global_load_lds_dwordx4 v[8:9], off
	v_lshl_add_u64 v[8:9], v[10:11], 0, s[40:41]
	s_mov_b32 m0, s50
	s_nop 0
	global_load_lds_dwordx4 v[8:9], off
	s_barrier
	s_waitcnt lgkmcnt(0)
	v_mfma_f32_16x16x32_bf16 v[8:11], v[122:125], v[114:117], v[168:171]
	v_mfma_f32_16x16x32_bf16 v[168:171], v[122:125], v[148:151], v[172:175]
	v_mfma_f32_16x16x32_bf16 v[24:27], v[200:203], v[114:117], v[24:27]
	v_mfma_f32_16x16x32_bf16 v[28:31], v[200:203], v[148:151], v[28:31]
	v_mfma_f32_16x16x32_bf16 v[172:175], v[160:163], v[114:117], v[176:179]
	v_mfma_f32_16x16x32_bf16 v[176:179], v[160:163], v[148:151], v[180:183]
	v_mfma_f32_16x16x32_bf16 v[180:183], v[192:195], v[114:117], v[184:187]
	v_mfma_f32_16x16x32_bf16 v[184:187], v[192:195], v[148:151], v[188:191]
	v_mfma_f32_16x16x32_bf16 v[8:11], v[156:159], v[118:121], v[8:11]
	v_mfma_f32_16x16x32_bf16 v[114:117], v[156:159], v[152:155], v[168:171]
	v_mfma_f32_16x16x32_bf16 v[24:27], v[204:207], v[118:121], v[24:27]
	v_mfma_f32_16x16x32_bf16 v[28:31], v[204:207], v[152:155], v[28:31]
	v_mfma_f32_16x16x32_bf16 v[148:151], v[164:167], v[118:121], v[172:175]
	v_mfma_f32_16x16x32_bf16 v[168:171], v[164:167], v[152:155], v[176:179]
	s_barrier
	v_mfma_f32_16x16x32_bf16 v[172:175], v[196:199], v[118:121], v[180:183]
	v_mfma_f32_16x16x32_bf16 v[176:179], v[196:199], v[152:155], v[184:187]
	s_mov_b32 m0, s11
	v_lshl_add_u64 v[2:3], v[2:3], 0, s[40:41]
	global_load_lds_dwordx4 v[2:3], off
	v_lshl_add_u64 v[0:1], v[0:1], 0, s[40:41]
	s_mov_b32 m0, s5
	s_nop 0
	global_load_lds_dwordx4 v[0:1], off
	s_waitcnt vmcnt(6)
	s_barrier
	v_mfma_f32_16x16x32_bf16 v[0:3], v[122:125], v[102:105], v[20:23]
	v_mfma_f32_16x16x32_bf16 v[20:23], v[122:125], v[216:219], v[32:35]
	v_mfma_f32_16x16x32_bf16 v[32:35], v[160:163], v[102:105], v[36:39]
	v_mfma_f32_16x16x32_bf16 v[36:39], v[160:163], v[216:219], v[70:73]
	v_mfma_f32_16x16x32_bf16 v[68:71], v[192:195], v[102:105], v[140:143]
	v_mfma_f32_16x16x32_bf16 v[118:121], v[192:195], v[216:219], v[144:147]
	v_mfma_f32_16x16x32_bf16 v[102:105], v[200:203], v[102:105], v[106:109]
	v_mfma_f32_16x16x32_bf16 v[106:109], v[200:203], v[216:219], v[110:113]
	v_mfma_f32_16x16x32_bf16 v[0:3], v[156:159], v[212:215], v[0:3]
	v_mfma_f32_16x16x32_bf16 v[20:23], v[156:159], v[220:223], v[20:23]
	v_mfma_f32_16x16x32_bf16 v[32:35], v[164:167], v[212:215], v[32:35]
	v_mfma_f32_16x16x32_bf16 v[36:39], v[164:167], v[220:223], v[36:39]
	v_mfma_f32_16x16x32_bf16 v[68:71], v[196:199], v[212:215], v[68:71]
	v_mfma_f32_16x16x32_bf16 v[110:113], v[196:199], v[220:223], v[118:121]
	s_barrier
	v_mfma_f32_16x16x32_bf16 v[102:105], v[204:207], v[212:215], v[102:105]
	v_mfma_f32_16x16x32_bf16 v[106:109], v[204:207], v[220:223], v[106:109]
	s_mov_b32 m0, s47
	v_lshl_add_u64 v[6:7], v[6:7], 0, s[40:41]
	ds_read_b128 v[118:121], v133
	ds_read_b128 v[122:125], v133 offset:1024
	ds_read_b128 v[140:143], v133 offset:2048
	ds_read_b128 v[144:147], v133 offset:3072
	ds_read_b128 v[152:155], v228
	ds_read_b128 v[156:159], v228 offset:1024
	ds_read_b128 v[160:163], v229 offset:2048
	ds_read_b128 v[164:167], v229 offset:3072
	ds_read_b128 v[180:183], v229 offset:4096
	ds_read_b128 v[184:187], v229 offset:5120
	ds_read_b128 v[188:191], v229 offset:6144
	ds_read_b128 v[192:195], v229 offset:7168
	global_load_lds_dwordx4 v[6:7], off
	v_lshl_add_u64 v[4:5], v[4:5], 0, s[40:41]
	s_mov_b32 m0, s46
	s_nop 0
	global_load_lds_dwordx4 v[4:5], off
	s_barrier
	s_waitcnt lgkmcnt(0)
	v_mfma_f32_16x16x32_bf16 v[4:7], v[152:155], v[118:121], v[16:19]
	v_mfma_f32_16x16x32_bf16 v[16:19], v[152:155], v[140:143], v[74:77]
	v_mfma_f32_16x16x32_bf16 v[72:75], v[160:163], v[118:121], v[78:81]
	v_mfma_f32_16x16x32_bf16 v[76:79], v[160:163], v[140:143], v[82:85]
	v_mfma_f32_16x16x32_bf16 v[80:83], v[180:183], v[118:121], v[86:89]
	v_mfma_f32_16x16x32_bf16 v[84:87], v[180:183], v[140:143], v[90:93]
	v_mfma_f32_16x16x32_bf16 v[88:91], v[188:191], v[118:121], v[94:97]
	v_mfma_f32_16x16x32_bf16 v[92:95], v[188:191], v[140:143], v[98:101]
	v_mfma_f32_16x16x32_bf16 v[4:7], v[156:159], v[122:125], v[4:7]
	v_mfma_f32_16x16x32_bf16 v[16:19], v[156:159], v[144:147], v[16:19]
	v_mfma_f32_16x16x32_bf16 v[72:75], v[164:167], v[122:125], v[72:75]
	v_mfma_f32_16x16x32_bf16 v[76:79], v[164:167], v[144:147], v[76:79]
	v_mfma_f32_16x16x32_bf16 v[80:83], v[184:187], v[122:125], v[80:83]
	v_mfma_f32_16x16x32_bf16 v[84:87], v[184:187], v[144:147], v[84:87]
	s_barrier
; #define STAGE(P, BASE, LD, br, kt) do { const char* _g = (const char*)((BASE) + (size_t)(br) * (LD) + (size_t)(kt) * 64); \
;     for (int _i = 0; _i < 2; ++_i) { int _b = tidx * 16 + _i * 8192; int _r, _c; stage_rc(_b, _r, _c); \
;       __builtin_amdgcn_global_load_lds((const unsigned*)(_g + (unsigned)((_r * (LD) + _c) * 2)), (unsigned*)((char*)(P) + _b), 16, 0, 0); } } while (0)
; #define LDA(dst, b, h) for (int m = 0; m < 4; ++m) for (int k = 0; k < 2; ++k) \
;     dst[m][k] = *reinterpret_cast<const bf16x8*>((char*)SA(b, h) + lds_byte(wr * 64 + m * 16 + fr, k * 32 + fq * 8))
; #define LDB(dst, b, h) for (int n = 0; n < 2; ++n) for (int k = 0; k < 2; ++k) \
;     dst[n][k] = *reinterpret_cast<const bf16x8*>((char*)SB(b, h) + lds_byte(wc * 32 + n * 16 + fr, k * 32 + fq * 8))
; #define MMA(ai, bj, At_, Bt_) do { __builtin_amdgcn_s_setprio(1); \
;     for (int k = 0; k < 2; ++k) for (int m = 0; m < 4; ++m) for (int n = 0; n < 2; ++n) \
;       acc[ai][bj][m][n] = __builtin_amdgcn_mfma_f32_16x16x32_bf16(At_[m][k], Bt_[n][k], acc[ai][bj][m][n], 0, 0, 0); \
;     __builtin_amdgcn_s_setprio(0); } while (0)
; #define WAIT_V(n) asm volatile("s_waitcnt vmcnt(" #n ")" ::: "memory")
; #define WAIT_L(n) asm volatile("s_waitcnt lgkmcnt(" #n ")" ::: "memory")
; #define BAR __builtin_amdgcn_s_barrier()
; template <int EPI, int lda, int ldb, int N, int K>
; __device__ __forceinline__ void gemm_phase(const u16* __restrict__ A, const u16* __restrict__ Bt, const GemmEpi ep, int wv) {
;     ...
;     { LDB(B0, 0, 0); LDA(At, 0, 0); STAGE(SA(1, 1), Ab, lda, brow + HALF, nt - 1);
;       BAR; WAIT_L(0); MMA(0, 0, At, B0); BAR;
;       LDB(B1, 0, 1); BAR; WAIT_L(0); MMA(0, 1, At, B1); BAR;
;       LDA(At, 0, 1); WAIT_V(4); BAR; WAIT_L(0); MMA(1, 0, At, B0); MMA(1, 1, At, B1); BAR; }
;     { LDB(B0, 1, 0); LDA(At, 1, 0); WAIT_V(2); BAR; WAIT_L(0); MMA(0, 0, At, B0); BAR;
	v_mfma_f32_16x16x32_bf16 v[88:91], v[192:195], v[122:125], v[88:91]
	v_mfma_f32_16x16x32_bf16 v[92:95], v[192:195], v[144:147], v[92:95]
	ds_read_b128 v[96:99], v224
	ds_read_b128 v[196:199], v224 offset:1024
	ds_read_b128 v[200:203], v224 offset:2048
	ds_read_b128 v[204:207], v224 offset:3072
	s_barrier
	s_waitcnt lgkmcnt(0)
	v_mfma_f32_16x16x32_bf16 v[12:15], v[152:155], v[96:99], v[12:15]
	v_mfma_f32_16x16x32_bf16 v[40:43], v[152:155], v[200:203], v[40:43]
	v_mfma_f32_16x16x32_bf16 v[52:55], v[180:183], v[96:99], v[52:55]
	v_mfma_f32_16x16x32_bf16 v[56:59], v[180:183], v[200:203], v[56:59]
	v_mfma_f32_16x16x32_bf16 v[64:67], v[188:191], v[200:203], v[64:67]
	v_mfma_f32_16x16x32_bf16 v[44:47], v[160:163], v[96:99], v[44:47]
	v_mfma_f32_16x16x32_bf16 v[48:51], v[160:163], v[200:203], v[48:51]
	v_mfma_f32_16x16x32_bf16 v[60:63], v[188:191], v[96:99], v[60:63]
	v_mfma_f32_16x16x32_bf16 v[12:15], v[156:159], v[196:199], v[12:15]
	v_mfma_f32_16x16x32_bf16 v[40:43], v[156:159], v[204:207], v[40:43]
	v_mfma_f32_16x16x32_bf16 v[52:55], v[184:187], v[196:199], v[52:55]
	v_mfma_f32_16x16x32_bf16 v[56:59], v[184:187], v[204:207], v[56:59]
	v_mfma_f32_16x16x32_bf16 v[64:67], v[192:195], v[204:207], v[64:67]
	v_mfma_f32_16x16x32_bf16 v[152:155], v[164:167], v[196:199], v[44:47]
	s_barrier
	v_mfma_f32_16x16x32_bf16 v[156:159], v[164:167], v[204:207], v[48:51]
	v_mfma_f32_16x16x32_bf16 v[160:163], v[192:195], v[196:199], v[60:63]
	ds_read_b128 v[44:47], v228 offset:16384
	ds_read_b128 v[48:51], v228 offset:17408
	ds_read_b128 v[60:63], v229 offset:18432
	ds_read_b128 v[164:167], v229 offset:19456
	ds_read_b128 v[180:183], v229 offset:20480
	ds_read_b128 v[184:187], v229 offset:21504
	ds_read_b128 v[188:191], v229 offset:22528
	ds_read_b128 v[192:195], v229 offset:23552
	s_waitcnt vmcnt(4)
	s_barrier
	s_waitcnt lgkmcnt(0)
	v_mfma_f32_16x16x32_bf16 v[8:11], v[44:47], v[118:121], v[8:11]
	v_mfma_f32_16x16x32_bf16 v[24:27], v[188:191], v[118:121], v[24:27]
	v_mfma_f32_16x16x32_bf16 v[28:31], v[188:191], v[140:143], v[28:31]
	v_mfma_f32_16x16x32_bf16 v[114:117], v[44:47], v[140:143], v[114:117]
	v_mfma_f32_16x16x32_bf16 v[148:151], v[60:63], v[118:121], v[148:151]
	v_mfma_f32_16x16x32_bf16 v[168:171], v[60:63], v[140:143], v[168:171]
	v_mfma_f32_16x16x32_bf16 v[172:175], v[180:183], v[118:121], v[172:175]
	v_mfma_f32_16x16x32_bf16 v[176:179], v[180:183], v[140:143], v[176:179]
	v_mfma_f32_16x16x32_bf16 v[8:11], v[48:51], v[122:125], v[8:11]
	v_mfma_f32_16x16x32_bf16 v[24:27], v[192:195], v[122:125], v[24:27]
	v_mfma_f32_16x16x32_bf16 v[28:31], v[192:195], v[144:147], v[28:31]
	v_mfma_f32_16x16x32_bf16 v[140:143], v[48:51], v[144:147], v[114:117]
	v_mfma_f32_16x16x32_bf16 v[148:151], v[164:167], v[122:125], v[148:151]
	v_mfma_f32_16x16x32_bf16 v[168:171], v[164:167], v[144:147], v[168:171]
	v_mfma_f32_16x16x32_bf16 v[172:175], v[184:187], v[122:125], v[172:175]
	v_mfma_f32_16x16x32_bf16 v[176:179], v[184:187], v[144:147], v[176:179]
	v_mfma_f32_16x16x32_bf16 v[0:3], v[44:47], v[96:99], v[0:3]
	v_mfma_f32_16x16x32_bf16 v[20:23], v[44:47], v[200:203], v[20:23]
	v_mfma_f32_16x16x32_bf16 v[44:47], v[180:183], v[96:99], v[68:71]
	v_mfma_f32_16x16x32_bf16 v[68:71], v[188:191], v[96:99], v[102:105]
	v_mfma_f32_16x16x32_bf16 v[32:35], v[60:63], v[96:99], v[32:35]
	v_mfma_f32_16x16x32_bf16 v[36:39], v[60:63], v[200:203], v[36:39]
	v_mfma_f32_16x16x32_bf16 v[60:63], v[180:183], v[200:203], v[110:113]
	v_mfma_f32_16x16x32_bf16 v[96:99], v[188:191], v[200:203], v[106:109]
	v_mfma_f32_16x16x32_bf16 v[20:23], v[48:51], v[204:207], v[20:23]
	v_mfma_f32_16x16x32_bf16 v[68:71], v[192:195], v[196:199], v[68:71]
	v_mfma_f32_16x16x32_bf16 v[144:147], v[48:51], v[196:199], v[0:3]
	v_mfma_f32_16x16x32_bf16 v[180:183], v[164:167], v[196:199], v[32:35]
	v_mfma_f32_16x16x32_bf16 v[164:167], v[164:167], v[204:207], v[36:39]
	v_mfma_f32_16x16x32_bf16 v[188:191], v[184:187], v[196:199], v[44:47]
	s_barrier
	v_mfma_f32_16x16x32_bf16 v[184:187], v[184:187], v[204:207], v[60:63]
	v_mfma_f32_16x16x32_bf16 v[192:195], v[192:195], v[204:207], v[96:99]
	ds_read_b128 v[0:3], v225
	ds_read_b128 v[196:199], v225 offset:1024
	ds_read_b128 v[200:203], v225 offset:2048
	ds_read_b128 v[204:207], v225 offset:3072
	ds_read_b128 v[36:39], v228 offset:32768
	ds_read_b128 v[100:103], v228 offset:33792
	ds_read_b128 v[108:111], v229 offset:34816
	ds_read_b128 v[208:211], v229 offset:35840
	ds_read_b128 v[116:119], v229 offset:36864
	ds_read_b128 v[212:215], v229 offset:37888
	ds_read_b128 v[124:127], v229 offset:38912
	ds_read_b128 v[216:219], v229 offset:39936
	s_waitcnt vmcnt(2)
	s_barrier
; #define LDA(dst, b, h) for (int m = 0; m < 4; ++m) for (int k = 0; k < 2; ++k) \
;     dst[m][k] = *reinterpret_cast<const bf16x8*>((char*)SA(b, h) + lds_byte(wr * 64 + m * 16 + fr, k * 32 + fq * 8))
; #define LDB(dst, b, h) for (int n = 0; n < 2; ++n) for (int k = 0; k < 2; ++k) \
;     dst[n][k] = *reinterpret_cast<const bf16x8*>((char*)SB(b, h) + lds_byte(wc * 32 + n * 16 + fr, k * 32 + fq * 8))
; #define MMA(ai, bj, At_, Bt_) do { __builtin_amdgcn_s_setprio(1); \
;     for (int k = 0; k < 2; ++k) for (int m = 0; m < 4; ++m) for (int n = 0; n < 2; ++n) \
;       acc[ai][bj][m][n] = __builtin_amdgcn_mfma_f32_16x16x32_bf16(At_[m][k], Bt_[n][k], acc[ai][bj][m][n], 0, 0, 0); \
;     __builtin_amdgcn_s_setprio(0); } while (0)
; #define WAIT_V(n) asm volatile("s_waitcnt vmcnt(" #n ")" ::: "memory")
; #define WAIT_L(n) asm volatile("s_waitcnt lgkmcnt(" #n ")" ::: "memory")
; #define BAR __builtin_amdgcn_s_barrier()
; template <int EPI, int lda, int ldb, int N, int K>
; __device__ __forceinline__ void gemm_phase(const u16* __restrict__ A, const u16* __restrict__ Bt, const GemmEpi ep, int wv) {
;     ...
;       LDA(At, 0, 1); WAIT_V(4); BAR; WAIT_L(0); MMA(1, 0, At, B0); MMA(1, 1, At, B1); BAR; }
;     { LDB(B0, 1, 0); LDA(At, 1, 0); WAIT_V(2); BAR; WAIT_L(0); MMA(0, 0, At, B0); BAR;
;       LDB(B1, 1, 1); WAIT_V(0); BAR; WAIT_L(0); MMA(0, 1, At, B1); BAR;
;       LDA(At, 1, 1); BAR; WAIT_L(0); MMA(1, 0, At, B0); MMA(1, 1, At, B1); BAR; }
;     if (wr == 0) BAR;
	s_waitcnt lgkmcnt(0)
	v_mfma_f32_16x16x32_bf16 v[4:7], v[36:39], v[0:3], v[4:7]
	v_mfma_f32_16x16x32_bf16 v[16:19], v[36:39], v[200:203], v[16:19]
	v_mfma_f32_16x16x32_bf16 v[32:35], v[108:111], v[0:3], v[72:75]
	v_mfma_f32_16x16x32_bf16 v[44:47], v[108:111], v[200:203], v[76:79]
	v_mfma_f32_16x16x32_bf16 v[72:75], v[116:119], v[0:3], v[80:83]
	v_mfma_f32_16x16x32_bf16 v[76:79], v[116:119], v[200:203], v[84:87]
	v_mfma_f32_16x16x32_bf16 v[80:83], v[124:127], v[0:3], v[88:91]
	v_mfma_f32_16x16x32_bf16 v[84:87], v[124:127], v[200:203], v[92:95]
	v_mfma_f32_16x16x32_bf16 v[120:123], v[100:103], v[196:199], v[4:7]
	v_mfma_f32_16x16x32_bf16 v[60:63], v[100:103], v[204:207], v[16:19]
	v_mfma_f32_16x16x32_bf16 v[112:115], v[208:211], v[196:199], v[32:35]
	v_mfma_f32_16x16x32_bf16 v[48:51], v[208:211], v[204:207], v[44:47]
	v_mfma_f32_16x16x32_bf16 v[104:107], v[212:215], v[196:199], v[72:75]
	v_mfma_f32_16x16x32_bf16 v[44:47], v[212:215], v[204:207], v[76:79]
	s_barrier
	v_mfma_f32_16x16x32_bf16 v[96:99], v[216:219], v[196:199], v[80:83]
	v_mfma_f32_16x16x32_bf16 v[32:35], v[216:219], v[204:207], v[84:87]
	ds_read_b128 v[4:7], v226
	ds_read_b128 v[220:223], v226 offset:1024
	ds_read_b128 v[76:79], v226 offset:2048
	ds_read_b128 v[224:227], v226 offset:3072
	s_waitcnt vmcnt(0)
	s_barrier
	s_waitcnt lgkmcnt(0)
	v_mfma_f32_16x16x32_bf16 v[12:15], v[36:39], v[4:7], v[12:15]
	v_mfma_f32_16x16x32_bf16 v[16:19], v[36:39], v[76:79], v[40:43]
	v_mfma_f32_16x16x32_bf16 v[36:39], v[108:111], v[4:7], v[152:155]
	v_mfma_f32_16x16x32_bf16 v[40:43], v[108:111], v[76:79], v[156:159]
	v_mfma_f32_16x16x32_bf16 v[72:75], v[116:119], v[4:7], v[52:55]
	v_mfma_f32_16x16x32_bf16 v[80:83], v[116:119], v[76:79], v[56:59]
	v_mfma_f32_16x16x32_bf16 v[84:87], v[124:127], v[4:7], v[160:163]
	v_mfma_f32_16x16x32_bf16 v[64:67], v[124:127], v[76:79], v[64:67]
	v_mfma_f32_16x16x32_bf16 v[124:127], v[100:103], v[220:223], v[12:15]
	v_mfma_f32_16x16x32_bf16 v[56:59], v[100:103], v[224:227], v[16:19]
	v_mfma_f32_16x16x32_bf16 v[116:119], v[208:211], v[220:223], v[36:39]
	v_mfma_f32_16x16x32_bf16 v[52:55], v[208:211], v[224:227], v[40:43]
	v_mfma_f32_16x16x32_bf16 v[108:111], v[212:215], v[220:223], v[72:75]
	v_mfma_f32_16x16x32_bf16 v[40:43], v[212:215], v[224:227], v[80:83]
	s_barrier
	v_mfma_f32_16x16x32_bf16 v[100:103], v[216:219], v[220:223], v[84:87]
	v_mfma_f32_16x16x32_bf16 v[36:39], v[216:219], v[224:227], v[64:67]
	ds_read_b128 v[84:87], v228 offset:49152
	ds_read_b128 v[152:155], v228 offset:50176
	ds_read_b128 v[92:95], v229 offset:51200
	ds_read_b128 v[156:159], v229 offset:52224
	ds_read_b128 v[160:163], v229 offset:53248
	ds_read_b128 v[208:211], v229 offset:54272
	ds_read_b128 v[212:215], v229 offset:55296
	ds_read_b128 v[216:219], v229 offset:56320
	s_barrier
	s_waitcnt lgkmcnt(0)
	v_mfma_f32_16x16x32_bf16 v[8:11], v[84:87], v[0:3], v[8:11]
	v_mfma_f32_16x16x32_bf16 v[12:15], v[84:87], v[200:203], v[140:143]
	v_mfma_f32_16x16x32_bf16 v[16:19], v[92:95], v[0:3], v[148:151]
	v_mfma_f32_16x16x32_bf16 v[64:67], v[92:95], v[200:203], v[168:171]
	v_mfma_f32_16x16x32_bf16 v[72:75], v[160:163], v[0:3], v[172:175]
	v_mfma_f32_16x16x32_bf16 v[140:143], v[160:163], v[200:203], v[176:179]
	v_mfma_f32_16x16x32_bf16 v[0:3], v[212:215], v[0:3], v[24:27]
	v_mfma_f32_16x16x32_bf16 v[24:27], v[212:215], v[200:203], v[28:31]
	v_mfma_f32_16x16x32_bf16 v[88:91], v[152:155], v[196:199], v[8:11]
	v_mfma_f32_16x16x32_bf16 v[28:31], v[152:155], v[204:207], v[12:15]
	v_mfma_f32_16x16x32_bf16 v[80:83], v[156:159], v[196:199], v[16:19]
	v_mfma_f32_16x16x32_bf16 v[16:19], v[156:159], v[204:207], v[64:67]
	v_mfma_f32_16x16x32_bf16 v[72:75], v[208:211], v[196:199], v[72:75]
	v_mfma_f32_16x16x32_bf16 v[12:15], v[208:211], v[204:207], v[140:143]
	v_mfma_f32_16x16x32_bf16 v[64:67], v[216:219], v[196:199], v[0:3]
	v_mfma_f32_16x16x32_bf16 v[0:3], v[216:219], v[204:207], v[24:27]
	v_mfma_f32_16x16x32_bf16 v[8:11], v[84:87], v[4:7], v[144:147]
	v_mfma_f32_16x16x32_bf16 v[20:23], v[84:87], v[76:79], v[20:23]
	v_mfma_f32_16x16x32_bf16 v[84:87], v[92:95], v[4:7], v[180:183]
	v_mfma_f32_16x16x32_bf16 v[140:143], v[92:95], v[76:79], v[164:167]
	v_mfma_f32_16x16x32_bf16 v[144:147], v[160:163], v[4:7], v[188:191]
	v_mfma_f32_16x16x32_bf16 v[148:151], v[160:163], v[76:79], v[184:187]
	v_mfma_f32_16x16x32_bf16 v[4:7], v[212:215], v[4:7], v[68:71]
	v_mfma_f32_16x16x32_bf16 v[160:163], v[212:215], v[76:79], v[192:195]
	v_mfma_f32_16x16x32_bf16 v[92:95], v[152:155], v[220:223], v[8:11]
	v_mfma_f32_16x16x32_bf16 v[24:27], v[152:155], v[224:227], v[20:23]
	v_mfma_f32_16x16x32_bf16 v[84:87], v[156:159], v[220:223], v[84:87]
	v_mfma_f32_16x16x32_bf16 v[20:23], v[156:159], v[224:227], v[140:143]
	v_mfma_f32_16x16x32_bf16 v[76:79], v[208:211], v[220:223], v[144:147]
	v_mfma_f32_16x16x32_bf16 v[8:11], v[208:211], v[224:227], v[148:151]
	s_barrier
	v_mfma_f32_16x16x32_bf16 v[68:71], v[216:219], v[220:223], v[4:7]
	v_mfma_f32_16x16x32_bf16 v[4:7], v[216:219], v[224:227], v[160:163]
	v_cmp_gt_u32_e32 vcc, s60, v130
	s_and_saveexec_b64 s[46:47], vcc
	s_cbranch_execz .LBB0_1346
	s_barrier
	s_branch .LBB0_1346

; #define STAGE(P, BASE, LD, br, kt) do { const char* _g = (const char*)((BASE) + (size_t)(br) * (LD) + (size_t)(kt) * 64); \
;     for (int _i = 0; _i < 2; ++_i) { int _b = tidx * 16 + _i * 8192; int _r, _c; stage_rc(_b, _r, _c); \
;       __builtin_amdgcn_global_load_lds((const unsigned*)(_g + (unsigned)((_r * (LD) + _c) * 2)), (unsigned*)((char*)(P) + _b), 16, 0, 0); } } while (0)
; #define LDA(dst, b, h) for (int m = 0; m < 4; ++m) for (int k = 0; k < 2; ++k) \
;     dst[m][k] = *reinterpret_cast<const bf16x8*>((char*)SA(b, h) + lds_byte(wr * 64 + m * 16 + fr, k * 32 + fq * 8))
; #define LDB(dst, b, h) for (int n = 0; n < 2; ++n) for (int k = 0; k < 2; ++k) \
;     dst[n][k] = *reinterpret_cast<const bf16x8*>((char*)SB(b, h) + lds_byte(wc * 32 + n * 16 + fr, k * 32 + fq * 8))
; #define MMA(ai, bj, At_, Bt_) do { __builtin_amdgcn_s_setprio(1); \
;     for (int k = 0; k < 2; ++k) for (int m = 0; m < 4; ++m) for (int n = 0; n < 2; ++n) \
;       acc[ai][bj][m][n] = __builtin_amdgcn_mfma_f32_16x16x32_bf16(At_[m][k], Bt_[n][k], acc[ai][bj][m][n], 0, 0, 0); \
;     __builtin_amdgcn_s_setprio(0); } while (0)
; #define WAIT_L(n) asm volatile("s_waitcnt lgkmcnt(" #n ")" ::: "memory")
; #define BAR __builtin_amdgcn_s_barrier()
; #define SCHED __builtin_amdgcn_sched_barrier(0)
; template <int EPI, int lda, int ldb, int N, int K>
; __device__ __forceinline__ void gemm_phase(const u16* __restrict__ A, const u16* __restrict__ Bt, const GemmEpi ep, int wv) {
;     ...
;     for (int t = 0; t < nt - 2; t += 2) {
;       LDB(B0, 0, 0); SCHED; LDA(At, 0, 0); STAGE(SA(1, 1), Ab, lda, brow + HALF, t + 1);
;       WAIT_L(8); BAR; WAIT_L(0); MMA(0, 0, At, B0); BAR; SCHED;
;       LDB(B1, 0, 1); STAGE(SB(0, 0), Bt, ldb, bcol, t + 2);
;       BAR; WAIT_L(0); MMA(0, 1, At, B1); BAR;
;       LDA(At, 0, 1); STAGE(SA(0, 0), Ab, lda, brow, t + 2);
;       BAR; WAIT_L(0); MMA(1, 0, At, B0); BAR; SCHED;
;       STAGE(SB(0, 1), Bt, ldb, bcol + HALF, t + 2);
.LBB0_1448:
	ds_read_b128 v[164:167], v160
	ds_read_b128 v[170:173], v160 offset:1024
	ds_read_b128 v[174:177], v160 offset:2048
	ds_read_b128 v[178:181], v160 offset:3072
	v_add_u32_e32 v168, 0xc000, v143
	v_lshl_add_u64 v[234:235], v[138:139], 0, s[44:45]
	v_readfirstlane_b32 s47, v168
	v_add_u32_e32 v169, 0xe000, v143
	v_lshl_add_u64 v[162:163], v[234:235], 0, s[20:21]
	s_mov_b32 m0, s47
	v_lshl_add_u64 v[236:237], v[140:141], 0, s[44:45]
	v_readfirstlane_b32 s47, v169
	ds_read_b128 v[182:185], v151
	ds_read_b128 v[186:189], v151 offset:1024
	ds_read_b128 v[190:193], v150
	ds_read_b128 v[194:197], v150 offset:1024
	ds_read_b128 v[198:201], v149
	ds_read_b128 v[202:205], v149 offset:1024
	ds_read_b128 v[206:209], v148
	ds_read_b128 v[210:213], v148 offset:1024
	global_load_lds_dwordx4 v[162:163], off
	v_lshl_add_u64 v[162:163], v[236:237], 0, s[20:21]
	s_mov_b32 m0, s47
	s_nop 0
	global_load_lds_dwordx4 v[162:163], off
	s_waitcnt lgkmcnt(8)
	s_barrier
	s_waitcnt lgkmcnt(0)
	v_mfma_f32_16x16x32_bf16 v[124:127], v[164:167], v[182:185], v[124:127]
	v_mfma_f32_16x16x32_bf16 v[120:123], v[174:177], v[182:185], v[120:123]
	v_mfma_f32_16x16x32_bf16 v[116:119], v[164:167], v[190:193], v[116:119]
	v_mfma_f32_16x16x32_bf16 v[112:115], v[174:177], v[190:193], v[112:115]
	v_mfma_f32_16x16x32_bf16 v[108:111], v[164:167], v[198:201], v[108:111]
	v_mfma_f32_16x16x32_bf16 v[104:107], v[174:177], v[198:201], v[104:107]
	v_mfma_f32_16x16x32_bf16 v[100:103], v[164:167], v[206:209], v[100:103]
	v_mfma_f32_16x16x32_bf16 v[96:99], v[174:177], v[206:209], v[96:99]
	v_mfma_f32_16x16x32_bf16 v[124:127], v[170:173], v[186:189], v[124:127]
	v_mfma_f32_16x16x32_bf16 v[120:123], v[178:181], v[186:189], v[120:123]
	v_mfma_f32_16x16x32_bf16 v[116:119], v[170:173], v[194:197], v[116:119]
	v_mfma_f32_16x16x32_bf16 v[112:115], v[178:181], v[194:197], v[112:115]
	v_mfma_f32_16x16x32_bf16 v[108:111], v[170:173], v[202:205], v[108:111]
	v_mfma_f32_16x16x32_bf16 v[104:107], v[178:181], v[202:205], v[104:107]
	s_barrier
	v_mfma_f32_16x16x32_bf16 v[100:103], v[170:173], v[210:213], v[100:103]
	v_mfma_f32_16x16x32_bf16 v[96:99], v[178:181], v[210:213], v[96:99]
	v_add_u32_e32 v161, s55, v153
	v_lshl_add_u64 v[238:239], v[134:135], 0, s[44:45]
	v_readfirstlane_b32 s47, v161
	v_lshl_add_u64 v[162:163], v[238:239], 0, s[22:23]
	s_mov_b32 m0, s47
	ds_read_b128 v[214:217], v159
	ds_read_b128 v[218:221], v159 offset:1024
	ds_read_b128 v[222:225], v159 offset:2048
	ds_read_b128 v[226:229], v159 offset:3072
	global_load_lds_dwordx4 v[162:163], off
	v_add_u32_e32 v162, 0x2000, v161
	v_lshl_add_u64 v[240:241], v[136:137], 0, s[44:45]
	v_readfirstlane_b32 s47, v162
	v_lshl_add_u64 v[230:231], v[240:241], 0, s[22:23]
	s_mov_b32 m0, s47
	s_nop 0
	global_load_lds_dwordx4 v[230:231], off
	s_barrier
	s_waitcnt lgkmcnt(0)
	v_mfma_f32_16x16x32_bf16 v[92:95], v[214:217], v[182:185], v[92:95]
	v_mfma_f32_16x16x32_bf16 v[88:91], v[222:225], v[182:185], v[88:91]
	v_mfma_f32_16x16x32_bf16 v[84:87], v[214:217], v[190:193], v[84:87]
	v_mfma_f32_16x16x32_bf16 v[80:83], v[222:225], v[190:193], v[80:83]
	v_mfma_f32_16x16x32_bf16 v[76:79], v[214:217], v[198:201], v[76:79]
	v_mfma_f32_16x16x32_bf16 v[72:75], v[222:225], v[198:201], v[72:75]
	v_mfma_f32_16x16x32_bf16 v[68:71], v[214:217], v[206:209], v[68:71]
	v_mfma_f32_16x16x32_bf16 v[64:67], v[222:225], v[206:209], v[64:67]
	v_mfma_f32_16x16x32_bf16 v[92:95], v[218:221], v[186:189], v[92:95]
	v_mfma_f32_16x16x32_bf16 v[88:91], v[226:229], v[186:189], v[88:91]
	v_mfma_f32_16x16x32_bf16 v[84:87], v[218:221], v[194:197], v[84:87]
	v_mfma_f32_16x16x32_bf16 v[80:83], v[226:229], v[194:197], v[80:83]
	v_mfma_f32_16x16x32_bf16 v[76:79], v[218:221], v[202:205], v[76:79]
	v_mfma_f32_16x16x32_bf16 v[72:75], v[226:229], v[202:205], v[72:75]
	s_barrier
	v_mfma_f32_16x16x32_bf16 v[68:71], v[218:221], v[210:213], v[68:71]
	v_mfma_f32_16x16x32_bf16 v[64:67], v[226:229], v[210:213], v[64:67]
	v_readfirstlane_b32 s47, v143
	v_add_u32_e32 v163, 0x2000, v143
	v_lshl_add_u64 v[230:231], v[234:235], 0, s[24:25]
	s_mov_b32 m0, s47
	v_readfirstlane_b32 s47, v163
	ds_read_b128 v[182:185], v151 offset:16384
	ds_read_b128 v[186:189], v151 offset:17408
	ds_read_b128 v[190:193], v150 offset:16384
	ds_read_b128 v[194:197], v150 offset:17408
	ds_read_b128 v[198:201], v149 offset:16384
	ds_read_b128 v[202:205], v149 offset:17408
	ds_read_b128 v[206:209], v148 offset:16384
	ds_read_b128 v[210:213], v148 offset:17408
	global_load_lds_dwordx4 v[230:231], off
	v_lshl_add_u64 v[230:231], v[236:237], 0, s[24:25]
	s_mov_b32 m0, s47
	s_nop 0
	global_load_lds_dwordx4 v[230:231], off
	s_barrier
	s_waitcnt lgkmcnt(0)
	v_mfma_f32_16x16x32_bf16 v[60:63], v[164:167], v[182:185], v[60:63]
	v_mfma_f32_16x16x32_bf16 v[56:59], v[174:177], v[182:185], v[56:59]
	v_mfma_f32_16x16x32_bf16 v[52:55], v[164:167], v[190:193], v[52:55]
	v_mfma_f32_16x16x32_bf16 v[48:51], v[174:177], v[190:193], v[48:51]
	v_mfma_f32_16x16x32_bf16 v[44:47], v[164:167], v[198:201], v[44:47]
	v_mfma_f32_16x16x32_bf16 v[40:43], v[174:177], v[198:201], v[40:43]
	v_mfma_f32_16x16x32_bf16 v[36:39], v[164:167], v[206:209], v[36:39]
	v_mfma_f32_16x16x32_bf16 v[32:35], v[174:177], v[206:209], v[32:35]
	v_mfma_f32_16x16x32_bf16 v[60:63], v[170:173], v[186:189], v[60:63]
	v_mfma_f32_16x16x32_bf16 v[56:59], v[178:181], v[186:189], v[56:59]
	v_mfma_f32_16x16x32_bf16 v[52:55], v[170:173], v[194:197], v[52:55]
	v_mfma_f32_16x16x32_bf16 v[48:51], v[178:181], v[194:197], v[48:51]
	v_mfma_f32_16x16x32_bf16 v[44:47], v[170:173], v[202:205], v[44:47]
	v_mfma_f32_16x16x32_bf16 v[40:43], v[178:181], v[202:205], v[40:43]
	s_barrier
; #define STAGE(P, BASE, LD, br, kt) do { const char* _g = (const char*)((BASE) + (size_t)(br) * (LD) + (size_t)(kt) * 64); \
;     for (int _i = 0; _i < 2; ++_i) { int _b = tidx * 16 + _i * 8192; int _r, _c; stage_rc(_b, _r, _c); \
;       __builtin_amdgcn_global_load_lds((const unsigned*)(_g + (unsigned)((_r * (LD) + _c) * 2)), (unsigned*)((char*)(P) + _b), 16, 0, 0); } } while (0)
; #define LDA(dst, b, h) for (int m = 0; m < 4; ++m) for (int k = 0; k < 2; ++k) \
;     dst[m][k] = *reinterpret_cast<const bf16x8*>((char*)SA(b, h) + lds_byte(wr * 64 + m * 16 + fr, k * 32 + fq * 8))
; #define LDB(dst, b, h) for (int n = 0; n < 2; ++n) for (int k = 0; k < 2; ++k) \
;     dst[n][k] = *reinterpret_cast<const bf16x8*>((char*)SB(b, h) + lds_byte(wc * 32 + n * 16 + fr, k * 32 + fq * 8))
; #define MMA(ai, bj, At_, Bt_) do { __builtin_amdgcn_s_setprio(1); \
;     for (int k = 0; k < 2; ++k) for (int m = 0; m < 4; ++m) for (int n = 0; n < 2; ++n) \
;       acc[ai][bj][m][n] = __builtin_amdgcn_mfma_f32_16x16x32_bf16(At_[m][k], Bt_[n][k], acc[ai][bj][m][n], 0, 0, 0); \
;     __builtin_amdgcn_s_setprio(0); } while (0)
; #define WAIT_V(n) asm volatile("s_waitcnt vmcnt(" #n ")" ::: "memory")
; #define WAIT_L(n) asm volatile("s_waitcnt lgkmcnt(" #n ")" ::: "memory")
; #define BAR __builtin_amdgcn_s_barrier()
; #define SCHED __builtin_amdgcn_sched_barrier(0)
; template <int EPI, int lda, int ldb, int N, int K>
; __device__ __forceinline__ void gemm_phase(const u16* __restrict__ A, const u16* __restrict__ Bt, const GemmEpi ep, int wv) {
;     ...
;       STAGE(SB(0, 1), Bt, ldb, bcol + HALF, t + 2);
;       WAIT_V(6); BAR; MMA(1, 1, At, B1); BAR;
;       LDB(B0, 1, 0); SCHED; LDA(At, 1, 0); STAGE(SA(0, 1), Ab, lda, brow + HALF, t + 2);
;       WAIT_L(8); BAR; WAIT_L(0); MMA(0, 0, At, B0); BAR; SCHED;
;       LDB(B1, 1, 1); STAGE(SB(1, 0), Bt, ldb, bcol, t + 3);
;       BAR; WAIT_L(0); MMA(0, 1, At, B1); BAR;
;       LDA(At, 1, 1); STAGE(SA(1, 0), Ab, lda, brow, t + 3);
;       BAR; WAIT_L(0); MMA(1, 0, At, B0); BAR; SCHED;
	v_mfma_f32_16x16x32_bf16 v[36:39], v[170:173], v[210:213], v[36:39]
	v_mfma_f32_16x16x32_bf16 v[32:35], v[178:181], v[210:213], v[32:35]
	v_add_u32_e32 v164, s56, v153
	v_add_u32_e32 v165, 0x2000, v164
	v_readfirstlane_b32 s47, v164
	v_lshl_add_u64 v[166:167], v[238:239], 0, s[26:27]
	s_mov_b32 m0, s47
	v_readfirstlane_b32 s47, v165
	global_load_lds_dwordx4 v[166:167], off
	v_lshl_add_u64 v[166:167], v[240:241], 0, s[26:27]
	s_mov_b32 m0, s47
	s_nop 0
	global_load_lds_dwordx4 v[166:167], off
	s_waitcnt vmcnt(6)
	s_barrier
	v_mfma_f32_16x16x32_bf16 v[28:31], v[214:217], v[182:185], v[28:31]
	v_mfma_f32_16x16x32_bf16 v[24:27], v[222:225], v[182:185], v[24:27]
	v_mfma_f32_16x16x32_bf16 v[20:23], v[214:217], v[190:193], v[20:23]
	v_mfma_f32_16x16x32_bf16 v[16:19], v[222:225], v[190:193], v[16:19]
	v_mfma_f32_16x16x32_bf16 v[12:15], v[214:217], v[198:201], v[12:15]
	v_mfma_f32_16x16x32_bf16 v[8:11], v[222:225], v[198:201], v[8:11]
	v_mfma_f32_16x16x32_bf16 v[4:7], v[214:217], v[206:209], v[4:7]
	v_mfma_f32_16x16x32_bf16 v[0:3], v[222:225], v[206:209], v[0:3]
	v_mfma_f32_16x16x32_bf16 v[28:31], v[218:221], v[186:189], v[28:31]
	v_mfma_f32_16x16x32_bf16 v[24:27], v[226:229], v[186:189], v[24:27]
	v_mfma_f32_16x16x32_bf16 v[20:23], v[218:221], v[194:197], v[20:23]
	v_mfma_f32_16x16x32_bf16 v[16:19], v[226:229], v[194:197], v[16:19]
	v_mfma_f32_16x16x32_bf16 v[12:15], v[218:221], v[202:205], v[12:15]
	v_mfma_f32_16x16x32_bf16 v[8:11], v[226:229], v[202:205], v[8:11]
	s_barrier
	v_mfma_f32_16x16x32_bf16 v[4:7], v[218:221], v[210:213], v[4:7]
	v_mfma_f32_16x16x32_bf16 v[0:3], v[226:229], v[210:213], v[0:3]
	ds_read_b128 v[170:173], v154
	ds_read_b128 v[174:177], v154 offset:1024
	ds_read_b128 v[178:181], v154 offset:2048
	ds_read_b128 v[182:185], v154 offset:3072
	v_add_u32_e32 v166, 0x4000, v143
	v_add_u32_e32 v167, 0x6000, v143
	v_readfirstlane_b32 s47, v166
	v_lshl_add_u64 v[218:219], v[234:235], 0, s[34:35]
	s_mov_b32 m0, s47
	v_readfirstlane_b32 s47, v167
	ds_read_b128 v[186:189], v151 offset:32768
	ds_read_b128 v[190:193], v151 offset:33792
	ds_read_b128 v[194:197], v150 offset:32768
	ds_read_b128 v[198:201], v150 offset:33792
	ds_read_b128 v[202:205], v149 offset:32768
	ds_read_b128 v[206:209], v149 offset:33792
	ds_read_b128 v[210:213], v148 offset:32768
	ds_read_b128 v[214:217], v148 offset:33792
	global_load_lds_dwordx4 v[218:219], off
	v_lshl_add_u64 v[218:219], v[236:237], 0, s[34:35]
	s_mov_b32 m0, s47
	s_nop 0
	global_load_lds_dwordx4 v[218:219], off
	s_waitcnt lgkmcnt(8)
	s_barrier
	s_waitcnt lgkmcnt(0)
	v_mfma_f32_16x16x32_bf16 v[124:127], v[170:173], v[186:189], v[124:127]
	v_mfma_f32_16x16x32_bf16 v[120:123], v[178:181], v[186:189], v[120:123]
	v_mfma_f32_16x16x32_bf16 v[116:119], v[170:173], v[194:197], v[116:119]
	v_mfma_f32_16x16x32_bf16 v[112:115], v[178:181], v[194:197], v[112:115]
	v_mfma_f32_16x16x32_bf16 v[108:111], v[170:173], v[202:205], v[108:111]
	v_mfma_f32_16x16x32_bf16 v[104:107], v[178:181], v[202:205], v[104:107]
	v_mfma_f32_16x16x32_bf16 v[100:103], v[170:173], v[210:213], v[100:103]
	v_mfma_f32_16x16x32_bf16 v[96:99], v[178:181], v[210:213], v[96:99]
	v_mfma_f32_16x16x32_bf16 v[124:127], v[174:177], v[190:193], v[124:127]
	v_mfma_f32_16x16x32_bf16 v[120:123], v[182:185], v[190:193], v[120:123]
	v_mfma_f32_16x16x32_bf16 v[116:119], v[174:177], v[198:201], v[116:119]
	v_mfma_f32_16x16x32_bf16 v[112:115], v[182:185], v[198:201], v[112:115]
	v_mfma_f32_16x16x32_bf16 v[108:111], v[174:177], v[206:209], v[108:111]
	v_mfma_f32_16x16x32_bf16 v[104:107], v[182:185], v[206:209], v[104:107]
	s_barrier
	v_mfma_f32_16x16x32_bf16 v[100:103], v[174:177], v[214:217], v[100:103]
	v_mfma_f32_16x16x32_bf16 v[96:99], v[182:185], v[214:217], v[96:99]
	v_readfirstlane_b32 s47, v155
	v_add_u32_e32 v244, 0x2000, v155
	v_lshl_add_u64 v[242:243], v[238:239], 0, s[36:37]
	s_mov_b32 m0, s47
	v_readfirstlane_b32 s47, v244
	ds_read_b128 v[218:221], v152
	ds_read_b128 v[222:225], v152 offset:1024
	ds_read_b128 v[226:229], v152 offset:2048
	ds_read_b128 v[230:233], v152 offset:3072
	global_load_lds_dwordx4 v[242:243], off
	v_lshl_add_u64 v[242:243], v[240:241], 0, s[36:37]
	s_mov_b32 m0, s47
	s_nop 0
	global_load_lds_dwordx4 v[242:243], off
	s_barrier
	s_waitcnt lgkmcnt(0)
	v_mfma_f32_16x16x32_bf16 v[92:95], v[218:221], v[186:189], v[92:95]
	v_mfma_f32_16x16x32_bf16 v[88:91], v[226:229], v[186:189], v[88:91]
	v_mfma_f32_16x16x32_bf16 v[84:87], v[218:221], v[194:197], v[84:87]
	v_mfma_f32_16x16x32_bf16 v[80:83], v[226:229], v[194:197], v[80:83]
	v_mfma_f32_16x16x32_bf16 v[76:79], v[218:221], v[202:205], v[76:79]
	v_mfma_f32_16x16x32_bf16 v[72:75], v[226:229], v[202:205], v[72:75]
	v_mfma_f32_16x16x32_bf16 v[68:71], v[218:221], v[210:213], v[68:71]
	v_mfma_f32_16x16x32_bf16 v[64:67], v[226:229], v[210:213], v[64:67]
	v_mfma_f32_16x16x32_bf16 v[92:95], v[222:225], v[190:193], v[92:95]
	v_mfma_f32_16x16x32_bf16 v[88:91], v[230:233], v[190:193], v[88:91]
	v_mfma_f32_16x16x32_bf16 v[84:87], v[222:225], v[198:201], v[84:87]
	v_mfma_f32_16x16x32_bf16 v[80:83], v[230:233], v[198:201], v[80:83]
	v_mfma_f32_16x16x32_bf16 v[76:79], v[222:225], v[206:209], v[76:79]
	v_mfma_f32_16x16x32_bf16 v[72:75], v[230:233], v[206:209], v[72:75]
	s_barrier
	v_mfma_f32_16x16x32_bf16 v[68:71], v[222:225], v[214:217], v[68:71]
	v_mfma_f32_16x16x32_bf16 v[64:67], v[230:233], v[214:217], v[64:67]
	v_readfirstlane_b32 s47, v156
	v_lshl_add_u64 v[234:235], v[234:235], 0, s[38:39]
	s_mov_b32 m0, s47
	v_readfirstlane_b32 s47, v157
	ds_read_b128 v[186:189], v151 offset:49152
	ds_read_b128 v[190:193], v151 offset:50176
	ds_read_b128 v[194:197], v150 offset:49152
	ds_read_b128 v[198:201], v150 offset:50176
	ds_read_b128 v[202:205], v149 offset:49152
	ds_read_b128 v[206:209], v149 offset:50176
	ds_read_b128 v[210:213], v148 offset:49152
	ds_read_b128 v[214:217], v148 offset:50176
	global_load_lds_dwordx4 v[234:235], off
	v_lshl_add_u64 v[234:235], v[236:237], 0, s[38:39]
	s_mov_b32 m0, s47
	s_nop 0
	global_load_lds_dwordx4 v[234:235], off
	s_barrier
; #define STAGE(P, BASE, LD, br, kt) do { const char* _g = (const char*)((BASE) + (size_t)(br) * (LD) + (size_t)(kt) * 64); \
;     for (int _i = 0; _i < 2; ++_i) { int _b = tidx * 16 + _i * 8192; int _r, _c; stage_rc(_b, _r, _c); \
;       __builtin_amdgcn_global_load_lds((const unsigned*)(_g + (unsigned)((_r * (LD) + _c) * 2)), (unsigned*)((char*)(P) + _b), 16, 0, 0); } } while (0)
; #define LDA(dst, b, h) for (int m = 0; m < 4; ++m) for (int k = 0; k < 2; ++k) \
;     dst[m][k] = *reinterpret_cast<const bf16x8*>((char*)SA(b, h) + lds_byte(wr * 64 + m * 16 + fr, k * 32 + fq * 8))
; #define LDB(dst, b, h) for (int n = 0; n < 2; ++n) for (int k = 0; k < 2; ++k) \
;     dst[n][k] = *reinterpret_cast<const bf16x8*>((char*)SB(b, h) + lds_byte(wc * 32 + n * 16 + fr, k * 32 + fq * 8))
; #define MMA(ai, bj, At_, Bt_) do { __builtin_amdgcn_s_setprio(1); \
;     for (int k = 0; k < 2; ++k) for (int m = 0; m < 4; ++m) for (int n = 0; n < 2; ++n) \
;       acc[ai][bj][m][n] = __builtin_amdgcn_mfma_f32_16x16x32_bf16(At_[m][k], Bt_[n][k], acc[ai][bj][m][n], 0, 0, 0); \
;     __builtin_amdgcn_s_setprio(0); } while (0)
; #define WAIT_V(n) asm volatile("s_waitcnt vmcnt(" #n ")" ::: "memory")
; #define WAIT_L(n) asm volatile("s_waitcnt lgkmcnt(" #n ")" ::: "memory")
; #define BAR __builtin_amdgcn_s_barrier()
; #define SCHED __builtin_amdgcn_sched_barrier(0)
; template <int EPI, int lda, int ldb, int N, int K>
; __device__ __forceinline__ void gemm_phase(const u16* __restrict__ A, const u16* __restrict__ Bt, const GemmEpi ep, int wv) {
;     ...
;       BAR; WAIT_L(0); MMA(1, 0, At, B0); BAR; SCHED;
;       STAGE(SB(1, 1), Bt, ldb, bcol + HALF, t + 3);
;       WAIT_V(6); BAR; MMA(1, 1, At, B1); BAR;
;     }
;     { LDB(B0, 0, 0); LDA(At, 0, 0); STAGE(SA(1, 1), Ab, lda, brow + HALF, nt - 1);
;       BAR; WAIT_L(0); MMA(0, 0, At, B0); BAR;
;       LDB(B1, 0, 1); BAR; WAIT_L(0); MMA(0, 1, At, B1); BAR;
;       LDA(At, 0, 1); WAIT_V(4); BAR; WAIT_L(0); MMA(1, 0, At, B0); MMA(1, 1, At, B1); BAR; }
	s_waitcnt lgkmcnt(0)
	v_mfma_f32_16x16x32_bf16 v[60:63], v[170:173], v[186:189], v[60:63]
	v_mfma_f32_16x16x32_bf16 v[56:59], v[178:181], v[186:189], v[56:59]
	v_mfma_f32_16x16x32_bf16 v[52:55], v[170:173], v[194:197], v[52:55]
	v_mfma_f32_16x16x32_bf16 v[48:51], v[178:181], v[194:197], v[48:51]
	v_mfma_f32_16x16x32_bf16 v[44:47], v[170:173], v[202:205], v[44:47]
	v_mfma_f32_16x16x32_bf16 v[40:43], v[178:181], v[202:205], v[40:43]
	v_mfma_f32_16x16x32_bf16 v[36:39], v[170:173], v[210:213], v[36:39]
	v_mfma_f32_16x16x32_bf16 v[32:35], v[178:181], v[210:213], v[32:35]
	v_mfma_f32_16x16x32_bf16 v[60:63], v[174:177], v[190:193], v[60:63]
	v_mfma_f32_16x16x32_bf16 v[56:59], v[182:185], v[190:193], v[56:59]
	v_mfma_f32_16x16x32_bf16 v[52:55], v[174:177], v[198:201], v[52:55]
	v_mfma_f32_16x16x32_bf16 v[48:51], v[182:185], v[198:201], v[48:51]
	v_mfma_f32_16x16x32_bf16 v[44:47], v[174:177], v[206:209], v[44:47]
	v_mfma_f32_16x16x32_bf16 v[40:43], v[182:185], v[206:209], v[40:43]
	s_barrier
	v_mfma_f32_16x16x32_bf16 v[36:39], v[174:177], v[214:217], v[36:39]
	v_mfma_f32_16x16x32_bf16 v[32:35], v[182:185], v[214:217], v[32:35]
	v_readfirstlane_b32 s47, v158
	v_add_u32_e32 v172, 0x2000, v158
	v_lshl_add_u64 v[170:171], v[238:239], 0, s[40:41]
	s_mov_b32 m0, s47
	v_readfirstlane_b32 s47, v172
	global_load_lds_dwordx4 v[170:171], off
	v_lshl_add_u64 v[170:171], v[240:241], 0, s[40:41]
	s_mov_b32 m0, s47
	s_nop 0
	global_load_lds_dwordx4 v[170:171], off
	s_waitcnt vmcnt(6)
	s_barrier
	v_mfma_f32_16x16x32_bf16 v[28:31], v[218:221], v[186:189], v[28:31]
	v_mfma_f32_16x16x32_bf16 v[24:27], v[226:229], v[186:189], v[24:27]
	v_mfma_f32_16x16x32_bf16 v[20:23], v[218:221], v[194:197], v[20:23]
	v_mfma_f32_16x16x32_bf16 v[16:19], v[226:229], v[194:197], v[16:19]
	v_mfma_f32_16x16x32_bf16 v[12:15], v[218:221], v[202:205], v[12:15]
	v_mfma_f32_16x16x32_bf16 v[8:11], v[226:229], v[202:205], v[8:11]
	v_mfma_f32_16x16x32_bf16 v[4:7], v[218:221], v[210:213], v[4:7]
	v_mfma_f32_16x16x32_bf16 v[0:3], v[226:229], v[210:213], v[0:3]
	v_mfma_f32_16x16x32_bf16 v[28:31], v[222:225], v[190:193], v[28:31]
	v_mfma_f32_16x16x32_bf16 v[24:27], v[230:233], v[190:193], v[24:27]
	v_mfma_f32_16x16x32_bf16 v[20:23], v[222:225], v[198:201], v[20:23]
	v_mfma_f32_16x16x32_bf16 v[16:19], v[230:233], v[198:201], v[16:19]
	v_mfma_f32_16x16x32_bf16 v[12:15], v[222:225], v[206:209], v[12:15]
	v_mfma_f32_16x16x32_bf16 v[8:11], v[230:233], v[206:209], v[8:11]
	s_barrier
	v_mfma_f32_16x16x32_bf16 v[4:7], v[222:225], v[214:217], v[4:7]
	v_mfma_f32_16x16x32_bf16 v[0:3], v[230:233], v[214:217], v[0:3]
	s_add_i32 s46, s46, 2
	s_add_u32 s44, s44, 0x100
	s_addc_u32 s45, s45, 0
	s_cmp_gt_u32 s46, 27
	s_cbranch_scc0 .LBB0_1448
	s_lshl_b64 s[44:45], s[16:17], 12
	s_add_u32 s44, s14, s44
	s_addc_u32 s45, s15, s45
	s_add_u32 s44, s44, 0x80000
	s_addc_u32 s45, s45, 0
	v_lshl_add_u64 v[156:157], s[44:45], 0, v[128:129]
	v_readfirstlane_b32 s46, v168
	v_lshl_add_u64 v[156:157], v[156:157], 0, s[42:43]
	s_mov_b32 m0, s46
	ds_read_b128 v[134:137], v160
	ds_read_b128 v[138:141], v160 offset:1024
	ds_read_b128 v[170:173], v160 offset:2048
	ds_read_b128 v[174:177], v160 offset:3072
	ds_read_b128 v[178:181], v151
	ds_read_b128 v[182:185], v151 offset:1024
	ds_read_b128 v[186:189], v150
	ds_read_b128 v[190:193], v150 offset:1024
	ds_read_b128 v[194:197], v149
	ds_read_b128 v[198:201], v149 offset:1024
	ds_read_b128 v[202:205], v148
	ds_read_b128 v[206:209], v148 offset:1024
	global_load_lds_dwordx4 v[156:157], off
	v_lshl_add_u64 v[156:157], s[44:45], 0, v[132:133]
	v_readfirstlane_b32 s44, v169
	v_lshl_add_u64 v[156:157], v[156:157], 0, s[42:43]
	s_mov_b32 m0, s44
	s_nop 0
	global_load_lds_dwordx4 v[156:157], off
	s_barrier
	s_waitcnt lgkmcnt(0)
	v_mfma_f32_16x16x32_bf16 v[124:127], v[134:137], v[178:181], v[124:127]
	v_mfma_f32_16x16x32_bf16 v[120:123], v[170:173], v[178:181], v[120:123]
	v_mfma_f32_16x16x32_bf16 v[116:119], v[134:137], v[186:189], v[116:119]
	v_mfma_f32_16x16x32_bf16 v[112:115], v[170:173], v[186:189], v[112:115]
	v_mfma_f32_16x16x32_bf16 v[108:111], v[134:137], v[194:197], v[108:111]
	v_mfma_f32_16x16x32_bf16 v[104:107], v[170:173], v[194:197], v[104:107]
	v_mfma_f32_16x16x32_bf16 v[100:103], v[134:137], v[202:205], v[100:103]
	v_mfma_f32_16x16x32_bf16 v[96:99], v[170:173], v[202:205], v[96:99]
	v_mfma_f32_16x16x32_bf16 v[124:127], v[138:141], v[182:185], v[124:127]
	v_mfma_f32_16x16x32_bf16 v[120:123], v[174:177], v[182:185], v[120:123]
	v_mfma_f32_16x16x32_bf16 v[116:119], v[138:141], v[190:193], v[116:119]
	v_mfma_f32_16x16x32_bf16 v[112:115], v[174:177], v[190:193], v[112:115]
	v_mfma_f32_16x16x32_bf16 v[108:111], v[138:141], v[198:201], v[108:111]
	v_mfma_f32_16x16x32_bf16 v[104:107], v[174:177], v[198:201], v[104:107]
	s_barrier
	v_mfma_f32_16x16x32_bf16 v[100:103], v[138:141], v[206:209], v[100:103]
	v_mfma_f32_16x16x32_bf16 v[96:99], v[174:177], v[206:209], v[96:99]
	ds_read_b128 v[210:213], v159
	ds_read_b128 v[214:217], v159 offset:1024
	ds_read_b128 v[218:221], v159 offset:2048
	ds_read_b128 v[156:159], v159 offset:3072
	s_barrier
	s_waitcnt lgkmcnt(0)
	v_mfma_f32_16x16x32_bf16 v[92:95], v[210:213], v[178:181], v[92:95]
	v_mfma_f32_16x16x32_bf16 v[88:91], v[218:221], v[178:181], v[88:91]
	v_mfma_f32_16x16x32_bf16 v[76:79], v[210:213], v[194:197], v[76:79]
	v_mfma_f32_16x16x32_bf16 v[72:75], v[218:221], v[194:197], v[72:75]
	v_mfma_f32_16x16x32_bf16 v[84:87], v[210:213], v[186:189], v[84:87]
	v_mfma_f32_16x16x32_bf16 v[80:83], v[218:221], v[186:189], v[80:83]
	v_mfma_f32_16x16x32_bf16 v[68:71], v[210:213], v[202:205], v[68:71]
	v_mfma_f32_16x16x32_bf16 v[64:67], v[218:221], v[202:205], v[64:67]
	v_mfma_f32_16x16x32_bf16 v[92:95], v[214:217], v[182:185], v[92:95]
	v_mfma_f32_16x16x32_bf16 v[88:91], v[156:159], v[182:185], v[88:91]
	v_mfma_f32_16x16x32_bf16 v[76:79], v[214:217], v[198:201], v[76:79]
	v_mfma_f32_16x16x32_bf16 v[72:75], v[156:159], v[198:201], v[72:75]
	v_mfma_f32_16x16x32_bf16 v[178:181], v[214:217], v[190:193], v[84:87]
	v_mfma_f32_16x16x32_bf16 v[182:185], v[156:159], v[190:193], v[80:83]
	s_barrier
; #define LDA(dst, b, h) for (int m = 0; m < 4; ++m) for (int k = 0; k < 2; ++k) \
;     dst[m][k] = *reinterpret_cast<const bf16x8*>((char*)SA(b, h) + lds_byte(wr * 64 + m * 16 + fr, k * 32 + fq * 8))
; #define LDB(dst, b, h) for (int n = 0; n < 2; ++n) for (int k = 0; k < 2; ++k) \
;     dst[n][k] = *reinterpret_cast<const bf16x8*>((char*)SB(b, h) + lds_byte(wc * 32 + n * 16 + fr, k * 32 + fq * 8))
; #define MMA(ai, bj, At_, Bt_) do { __builtin_amdgcn_s_setprio(1); \
;     for (int k = 0; k < 2; ++k) for (int m = 0; m < 4; ++m) for (int n = 0; n < 2; ++n) \
;       acc[ai][bj][m][n] = __builtin_amdgcn_mfma_f32_16x16x32_bf16(At_[m][k], Bt_[n][k], acc[ai][bj][m][n], 0, 0, 0); \
;     __builtin_amdgcn_s_setprio(0); } while (0)
; #define WAIT_V(n) asm volatile("s_waitcnt vmcnt(" #n ")" ::: "memory")
; #define WAIT_L(n) asm volatile("s_waitcnt lgkmcnt(" #n ")" ::: "memory")
; #define BAR __builtin_amdgcn_s_barrier()
; template <int EPI, int lda, int ldb, int N, int K>
; __device__ __forceinline__ void gemm_phase(const u16* __restrict__ A, const u16* __restrict__ Bt, const GemmEpi ep, int wv) {
;     ...
;       BAR; WAIT_L(0); MMA(0, 0, At, B0); BAR;
;       LDB(B1, 0, 1); BAR; WAIT_L(0); MMA(0, 1, At, B1); BAR;
;       LDA(At, 0, 1); WAIT_V(4); BAR; WAIT_L(0); MMA(1, 0, At, B0); MMA(1, 1, At, B1); BAR; }
;     { LDB(B0, 1, 0); LDA(At, 1, 0); WAIT_V(2); BAR; WAIT_L(0); MMA(0, 0, At, B0); BAR;
	v_mfma_f32_16x16x32_bf16 v[186:189], v[214:217], v[206:209], v[68:71]
	v_mfma_f32_16x16x32_bf16 v[190:193], v[156:159], v[206:209], v[64:67]
	s_nop 0
	ds_read_b128 v[64:67], v151 offset:16384
	ds_read_b128 v[68:71], v151 offset:17408
	ds_read_b128 v[80:83], v150 offset:16384
	ds_read_b128 v[84:87], v150 offset:17408
	ds_read_b128 v[194:197], v149 offset:16384
	ds_read_b128 v[198:201], v149 offset:17408
	ds_read_b128 v[202:205], v148 offset:16384
	ds_read_b128 v[206:209], v148 offset:17408
	s_waitcnt vmcnt(4)
	s_barrier
	s_waitcnt lgkmcnt(0)
	v_mfma_f32_16x16x32_bf16 v[60:63], v[134:137], v[64:67], v[60:63]
	v_mfma_f32_16x16x32_bf16 v[56:59], v[170:173], v[64:67], v[56:59]
	v_mfma_f32_16x16x32_bf16 v[52:55], v[134:137], v[80:83], v[52:55]
	v_mfma_f32_16x16x32_bf16 v[48:51], v[170:173], v[80:83], v[48:51]
	v_mfma_f32_16x16x32_bf16 v[44:47], v[134:137], v[194:197], v[44:47]
	v_mfma_f32_16x16x32_bf16 v[40:43], v[170:173], v[194:197], v[40:43]
	v_mfma_f32_16x16x32_bf16 v[36:39], v[134:137], v[202:205], v[36:39]
	v_mfma_f32_16x16x32_bf16 v[32:35], v[170:173], v[202:205], v[32:35]
	v_mfma_f32_16x16x32_bf16 v[60:63], v[138:141], v[68:71], v[60:63]
	v_mfma_f32_16x16x32_bf16 v[56:59], v[174:177], v[68:71], v[56:59]
	v_mfma_f32_16x16x32_bf16 v[52:55], v[138:141], v[84:87], v[52:55]
	v_mfma_f32_16x16x32_bf16 v[48:51], v[174:177], v[84:87], v[48:51]
	v_mfma_f32_16x16x32_bf16 v[44:47], v[138:141], v[198:201], v[44:47]
	v_mfma_f32_16x16x32_bf16 v[40:43], v[174:177], v[198:201], v[40:43]
	v_mfma_f32_16x16x32_bf16 v[36:39], v[138:141], v[206:209], v[36:39]
	v_mfma_f32_16x16x32_bf16 v[32:35], v[174:177], v[206:209], v[32:35]
	v_mfma_f32_16x16x32_bf16 v[28:31], v[210:213], v[64:67], v[28:31]
	v_mfma_f32_16x16x32_bf16 v[20:23], v[210:213], v[80:83], v[20:23]
	v_mfma_f32_16x16x32_bf16 v[12:15], v[210:213], v[194:197], v[12:15]
	v_mfma_f32_16x16x32_bf16 v[4:7], v[210:213], v[202:205], v[4:7]
	v_mfma_f32_16x16x32_bf16 v[24:27], v[218:221], v[64:67], v[24:27]
	v_mfma_f32_16x16x32_bf16 v[16:19], v[218:221], v[80:83], v[16:19]
	v_mfma_f32_16x16x32_bf16 v[8:11], v[218:221], v[194:197], v[8:11]
	v_mfma_f32_16x16x32_bf16 v[0:3], v[218:221], v[202:205], v[0:3]
	v_mfma_f32_16x16x32_bf16 v[28:31], v[214:217], v[68:71], v[28:31]
	v_mfma_f32_16x16x32_bf16 v[20:23], v[214:217], v[84:87], v[20:23]
	v_mfma_f32_16x16x32_bf16 v[12:15], v[214:217], v[198:201], v[12:15]
	v_mfma_f32_16x16x32_bf16 v[4:7], v[214:217], v[206:209], v[4:7]
	v_mfma_f32_16x16x32_bf16 v[134:137], v[156:159], v[68:71], v[24:27]
	v_mfma_f32_16x16x32_bf16 v[138:141], v[156:159], v[84:87], v[16:19]
	s_barrier
	v_mfma_f32_16x16x32_bf16 v[168:171], v[156:159], v[198:201], v[8:11]
	v_mfma_f32_16x16x32_bf16 v[156:159], v[156:159], v[206:209], v[0:3]
	s_nop 0
	ds_read_b128 v[0:3], v154
	ds_read_b128 v[8:11], v154 offset:1024
	ds_read_b128 v[16:19], v154 offset:2048
	ds_read_b128 v[172:175], v154 offset:3072
	ds_read_b128 v[24:27], v151 offset:32768
	ds_read_b128 v[194:197], v151 offset:33792
	ds_read_b128 v[198:201], v150 offset:32768
	ds_read_b128 v[202:205], v150 offset:33792
	ds_read_b128 v[206:209], v149 offset:32768
	ds_read_b128 v[210:213], v149 offset:33792
	ds_read_b128 v[214:217], v148 offset:32768
	ds_read_b128 v[218:221], v148 offset:33792
	s_waitcnt vmcnt(2)
	s_barrier
	s_waitcnt lgkmcnt(0)
	v_mfma_f32_16x16x32_bf16 v[64:67], v[0:3], v[24:27], v[124:127]
	v_mfma_f32_16x16x32_bf16 v[68:71], v[16:19], v[24:27], v[120:123]
	v_mfma_f32_16x16x32_bf16 v[80:83], v[0:3], v[198:201], v[116:119]
	v_mfma_f32_16x16x32_bf16 v[84:87], v[16:19], v[198:201], v[112:115]
	v_mfma_f32_16x16x32_bf16 v[108:111], v[0:3], v[206:209], v[108:111]
	v_mfma_f32_16x16x32_bf16 v[104:107], v[16:19], v[206:209], v[104:107]
	v_mfma_f32_16x16x32_bf16 v[120:123], v[0:3], v[214:217], v[100:103]
	v_mfma_f32_16x16x32_bf16 v[124:127], v[16:19], v[214:217], v[96:99]
	v_mfma_f32_16x16x32_bf16 v[116:119], v[8:11], v[194:197], v[64:67]
	v_mfma_f32_16x16x32_bf16 v[112:115], v[172:175], v[194:197], v[68:71]
	v_mfma_f32_16x16x32_bf16 v[100:103], v[8:11], v[202:205], v[80:83]
	v_mfma_f32_16x16x32_bf16 v[96:99], v[172:175], v[202:205], v[84:87]
	v_mfma_f32_16x16x32_bf16 v[84:87], v[8:11], v[210:213], v[108:111]
	v_mfma_f32_16x16x32_bf16 v[80:83], v[172:175], v[210:213], v[104:107]
	s_barrier
; #define LDA(dst, b, h) for (int m = 0; m < 4; ++m) for (int k = 0; k < 2; ++k) \
;     dst[m][k] = *reinterpret_cast<const bf16x8*>((char*)SA(b, h) + lds_byte(wr * 64 + m * 16 + fr, k * 32 + fq * 8))
; #define LDB(dst, b, h) for (int n = 0; n < 2; ++n) for (int k = 0; k < 2; ++k) \
;     dst[n][k] = *reinterpret_cast<const bf16x8*>((char*)SB(b, h) + lds_byte(wc * 32 + n * 16 + fr, k * 32 + fq * 8))
; #define MMA(ai, bj, At_, Bt_) do { __builtin_amdgcn_s_setprio(1); \
;     for (int k = 0; k < 2; ++k) for (int m = 0; m < 4; ++m) for (int n = 0; n < 2; ++n) \
;       acc[ai][bj][m][n] = __builtin_amdgcn_mfma_f32_16x16x32_bf16(At_[m][k], Bt_[n][k], acc[ai][bj][m][n], 0, 0, 0); \
;     __builtin_amdgcn_s_setprio(0); } while (0)
; #define WAIT_V(n) asm volatile("s_waitcnt vmcnt(" #n ")" ::: "memory")
; #define WAIT_L(n) asm volatile("s_waitcnt lgkmcnt(" #n ")" ::: "memory")
; #define BAR __builtin_amdgcn_s_barrier()
; template <int EPI, int lda, int ldb, int N, int K>
; __device__ __forceinline__ void gemm_phase(const u16* __restrict__ A, const u16* __restrict__ Bt, const GemmEpi ep, int wv) {
;     ...
;     { LDB(B0, 1, 0); LDA(At, 1, 0); WAIT_V(2); BAR; WAIT_L(0); MMA(0, 0, At, B0); BAR;
;       LDB(B1, 1, 1); WAIT_V(0); BAR; WAIT_L(0); MMA(0, 1, At, B1); BAR;
;       LDA(At, 1, 1); BAR; WAIT_L(0); MMA(1, 0, At, B0); MMA(1, 1, At, B1); BAR; }
;     if (wr == 0) BAR;
	v_mfma_f32_16x16x32_bf16 v[68:71], v[8:11], v[218:221], v[120:123]
	v_mfma_f32_16x16x32_bf16 v[64:67], v[172:175], v[218:221], v[124:127]
	ds_read_b128 v[222:225], v152
	ds_read_b128 v[226:229], v152 offset:1024
	ds_read_b128 v[230:233], v152 offset:2048
	ds_read_b128 v[152:155], v152 offset:3072
	s_waitcnt vmcnt(0)
	s_barrier
	s_waitcnt lgkmcnt(0)
	v_mfma_f32_16x16x32_bf16 v[92:95], v[222:225], v[24:27], v[92:95]
	v_mfma_f32_16x16x32_bf16 v[24:27], v[230:233], v[24:27], v[88:91]
	v_mfma_f32_16x16x32_bf16 v[88:91], v[222:225], v[198:201], v[178:181]
	v_mfma_f32_16x16x32_bf16 v[104:107], v[230:233], v[198:201], v[182:185]
	v_mfma_f32_16x16x32_bf16 v[76:79], v[222:225], v[206:209], v[76:79]
	v_mfma_f32_16x16x32_bf16 v[72:75], v[230:233], v[206:209], v[72:75]
	v_mfma_f32_16x16x32_bf16 v[176:179], v[222:225], v[214:217], v[186:189]
	v_mfma_f32_16x16x32_bf16 v[180:183], v[230:233], v[214:217], v[190:193]
	v_mfma_f32_16x16x32_bf16 v[124:127], v[226:229], v[194:197], v[92:95]
	v_mfma_f32_16x16x32_bf16 v[120:123], v[152:155], v[194:197], v[24:27]
	v_mfma_f32_16x16x32_bf16 v[108:111], v[226:229], v[202:205], v[88:91]
	v_mfma_f32_16x16x32_bf16 v[104:107], v[152:155], v[202:205], v[104:107]
	v_mfma_f32_16x16x32_bf16 v[92:95], v[226:229], v[210:213], v[76:79]
	v_mfma_f32_16x16x32_bf16 v[88:91], v[152:155], v[210:213], v[72:75]
	s_barrier
	v_mfma_f32_16x16x32_bf16 v[76:79], v[226:229], v[218:221], v[176:179]
	v_mfma_f32_16x16x32_bf16 v[72:75], v[152:155], v[218:221], v[180:183]
	ds_read_b128 v[176:179], v151 offset:49152
	ds_read_b128 v[180:183], v151 offset:50176
	ds_read_b128 v[184:187], v150 offset:49152
	ds_read_b128 v[188:191], v150 offset:50176
	ds_read_b128 v[192:195], v149 offset:49152
	ds_read_b128 v[196:199], v149 offset:50176
	ds_read_b128 v[200:203], v148 offset:49152
	ds_read_b128 v[148:151], v148 offset:50176
	s_barrier
	s_waitcnt lgkmcnt(0)
	v_mfma_f32_16x16x32_bf16 v[24:27], v[0:3], v[176:179], v[60:63]
	v_mfma_f32_16x16x32_bf16 v[60:63], v[16:19], v[176:179], v[56:59]
	v_mfma_f32_16x16x32_bf16 v[52:55], v[0:3], v[184:187], v[52:55]
	v_mfma_f32_16x16x32_bf16 v[204:207], v[16:19], v[184:187], v[48:51]
	v_mfma_f32_16x16x32_bf16 v[44:47], v[0:3], v[192:195], v[44:47]
	v_mfma_f32_16x16x32_bf16 v[208:211], v[16:19], v[192:195], v[40:43]
	v_mfma_f32_16x16x32_bf16 v[0:3], v[0:3], v[200:203], v[36:39]
	v_mfma_f32_16x16x32_bf16 v[36:39], v[16:19], v[200:203], v[32:35]
	v_mfma_f32_16x16x32_bf16 v[56:59], v[8:11], v[180:183], v[24:27]
	v_mfma_f32_16x16x32_bf16 v[48:51], v[172:175], v[180:183], v[60:63]
	v_mfma_f32_16x16x32_bf16 v[40:43], v[8:11], v[188:191], v[52:55]
	v_mfma_f32_16x16x32_bf16 v[32:35], v[172:175], v[188:191], v[204:207]
	v_mfma_f32_16x16x32_bf16 v[24:27], v[8:11], v[196:199], v[44:47]
	v_mfma_f32_16x16x32_bf16 v[16:19], v[172:175], v[196:199], v[208:211]
	v_mfma_f32_16x16x32_bf16 v[8:11], v[8:11], v[148:151], v[0:3]
	v_mfma_f32_16x16x32_bf16 v[0:3], v[172:175], v[148:151], v[36:39]
	v_mfma_f32_16x16x32_bf16 v[28:31], v[222:225], v[176:179], v[28:31]
	v_mfma_f32_16x16x32_bf16 v[36:39], v[230:233], v[176:179], v[134:137]
	v_mfma_f32_16x16x32_bf16 v[20:23], v[222:225], v[184:187], v[20:23]
	v_mfma_f32_16x16x32_bf16 v[134:137], v[230:233], v[184:187], v[138:141]
	v_mfma_f32_16x16x32_bf16 v[12:15], v[222:225], v[192:195], v[12:15]
	v_mfma_f32_16x16x32_bf16 v[138:141], v[230:233], v[192:195], v[168:171]
	v_mfma_f32_16x16x32_bf16 v[4:7], v[222:225], v[200:203], v[4:7]
	v_mfma_f32_16x16x32_bf16 v[156:159], v[230:233], v[200:203], v[156:159]
	v_mfma_f32_16x16x32_bf16 v[60:63], v[226:229], v[180:183], v[28:31]
	v_mfma_f32_16x16x32_bf16 v[52:55], v[152:155], v[180:183], v[36:39]
	v_mfma_f32_16x16x32_bf16 v[44:47], v[226:229], v[188:191], v[20:23]
	v_mfma_f32_16x16x32_bf16 v[36:39], v[152:155], v[188:191], v[134:137]
	v_mfma_f32_16x16x32_bf16 v[28:31], v[226:229], v[196:199], v[12:15]
	v_mfma_f32_16x16x32_bf16 v[20:23], v[152:155], v[196:199], v[138:141]
	s_barrier
	v_mfma_f32_16x16x32_bf16 v[12:15], v[226:229], v[148:151], v[4:7]
	v_mfma_f32_16x16x32_bf16 v[4:7], v[152:155], v[148:151], v[156:159]
	v_cmp_gt_u32_e32 vcc, s60, v130
	s_and_saveexec_b64 s[44:45], vcc
	s_cbranch_execz .LBB0_1451
	s_barrier

; #define STAGE(P, BASE, LD, br, kt) do { const char* _g = (const char*)((BASE) + (size_t)(br) * (LD) + (size_t)(kt) * 64); \
;     for (int _i = 0; _i < 2; ++_i) { int _b = tidx * 16 + _i * 8192; int _r, _c; stage_rc(_b, _r, _c); \
;       __builtin_amdgcn_global_load_lds((const unsigned*)(_g + (unsigned)((_r * (LD) + _c) * 2)), (unsigned*)((char*)(P) + _b), 16, 0, 0); } } while (0)
; #define LDA(dst, b, h) for (int m = 0; m < 4; ++m) for (int k = 0; k < 2; ++k) \
;     dst[m][k] = *reinterpret_cast<const bf16x8*>((char*)SA(b, h) + lds_byte(wr * 64 + m * 16 + fr, k * 32 + fq * 8))
; #define LDB(dst, b, h) for (int n = 0; n < 2; ++n) for (int k = 0; k < 2; ++k) \
;     dst[n][k] = *reinterpret_cast<const bf16x8*>((char*)SB(b, h) + lds_byte(wc * 32 + n * 16 + fr, k * 32 + fq * 8))
; #define MMA(ai, bj, At_, Bt_) do { __builtin_amdgcn_s_setprio(1); \
;     for (int k = 0; k < 2; ++k) for (int m = 0; m < 4; ++m) for (int n = 0; n < 2; ++n) \
;       acc[ai][bj][m][n] = __builtin_amdgcn_mfma_f32_16x16x32_bf16(At_[m][k], Bt_[n][k], acc[ai][bj][m][n], 0, 0, 0); \
;     __builtin_amdgcn_s_setprio(0); } while (0)
; #define WAIT_L(n) asm volatile("s_waitcnt lgkmcnt(" #n ")" ::: "memory")
; #define BAR __builtin_amdgcn_s_barrier()
; #define SCHED __builtin_amdgcn_sched_barrier(0)
; template <int EPI, int lda, int ldb, int N, int K>
; __device__ __forceinline__ void gemm_phase(const u16* __restrict__ A, const u16* __restrict__ Bt, const GemmEpi ep, int wv) {
;     ...
;     for (int t = 0; t < nt - 2; t += 2) {
;       LDB(B0, 0, 0); SCHED; LDA(At, 0, 0); STAGE(SA(1, 1), Ab, lda, brow + HALF, t + 1);
;       WAIT_L(8); BAR; WAIT_L(0); MMA(0, 0, At, B0); BAR; SCHED;
;       LDB(B1, 0, 1); STAGE(SB(0, 0), Bt, ldb, bcol, t + 2);
;       BAR; WAIT_L(0); MMA(0, 1, At, B1); BAR;
;       LDA(At, 0, 1); STAGE(SA(0, 0), Ab, lda, brow, t + 2);
;       BAR; WAIT_L(0); MMA(1, 0, At, B0); BAR; SCHED;
;       STAGE(SB(0, 1), Bt, ldb, bcol + HALF, t + 2);
.LBB0_1564:
	ds_read_b128 v[172:175], v161
	ds_read_b128 v[176:179], v161 offset:1024
	ds_read_b128 v[180:183], v161 offset:2048
	ds_read_b128 v[184:187], v161 offset:3072
	v_add_u32_e32 v169, 0xc000, v148
	v_lshl_add_u64 v[236:237], v[136:137], 0, s[40:41]
	v_readfirstlane_b32 s43, v169
	v_add_u32_e32 v170, 0xe000, v148
	v_lshl_add_u64 v[162:163], v[236:237], 0, s[14:15]
	s_mov_b32 m0, s43
	v_lshl_add_u64 v[238:239], v[134:135], 0, s[40:41]
	v_readfirstlane_b32 s43, v170
	ds_read_b128 v[164:167], v152
	ds_read_b128 v[188:191], v152 offset:1024
	ds_read_b128 v[192:195], v151
	ds_read_b128 v[196:199], v151 offset:1024
	ds_read_b128 v[200:203], v150
	ds_read_b128 v[204:207], v150 offset:1024
	ds_read_b128 v[208:211], v149
	ds_read_b128 v[212:215], v149 offset:1024
	global_load_lds_dwordx4 v[162:163], off
	v_lshl_add_u64 v[162:163], v[238:239], 0, s[14:15]
	s_mov_b32 m0, s43
	s_nop 0
	global_load_lds_dwordx4 v[162:163], off
	s_waitcnt lgkmcnt(8)
	s_barrier
	s_waitcnt lgkmcnt(0)
	v_mfma_f32_16x16x32_bf16 v[124:127], v[172:175], v[164:167], v[124:127]
	v_mfma_f32_16x16x32_bf16 v[120:123], v[180:183], v[164:167], v[120:123]
	v_mfma_f32_16x16x32_bf16 v[116:119], v[172:175], v[192:195], v[116:119]
	v_mfma_f32_16x16x32_bf16 v[112:115], v[180:183], v[192:195], v[112:115]
	v_mfma_f32_16x16x32_bf16 v[108:111], v[172:175], v[200:203], v[108:111]
	v_mfma_f32_16x16x32_bf16 v[104:107], v[180:183], v[200:203], v[104:107]
	v_mfma_f32_16x16x32_bf16 v[100:103], v[172:175], v[208:211], v[100:103]
	v_mfma_f32_16x16x32_bf16 v[96:99], v[180:183], v[208:211], v[96:99]
	v_mfma_f32_16x16x32_bf16 v[124:127], v[176:179], v[188:191], v[124:127]
	v_mfma_f32_16x16x32_bf16 v[120:123], v[184:187], v[188:191], v[120:123]
	v_mfma_f32_16x16x32_bf16 v[116:119], v[176:179], v[196:199], v[116:119]
	v_mfma_f32_16x16x32_bf16 v[112:115], v[184:187], v[196:199], v[112:115]
	v_mfma_f32_16x16x32_bf16 v[108:111], v[176:179], v[204:207], v[108:111]
	v_mfma_f32_16x16x32_bf16 v[104:107], v[184:187], v[204:207], v[104:107]
	s_barrier
	v_mfma_f32_16x16x32_bf16 v[100:103], v[176:179], v[212:215], v[100:103]
	v_mfma_f32_16x16x32_bf16 v[96:99], v[184:187], v[212:215], v[96:99]
	v_add_u32_e32 v162, s52, v153
	v_lshl_add_u64 v[240:241], v[140:141], 0, s[40:41]
	v_readfirstlane_b32 s43, v162
	v_add_u32_e32 v163, 0x2000, v162
	v_lshl_add_u64 v[232:233], v[240:241], 0, s[16:17]
	s_mov_b32 m0, s43
	v_lshl_add_u64 v[242:243], v[138:139], 0, s[40:41]
	v_readfirstlane_b32 s43, v163
	ds_read_b128 v[216:219], v160
	ds_read_b128 v[220:223], v160 offset:1024
	ds_read_b128 v[224:227], v160 offset:2048
	ds_read_b128 v[228:231], v160 offset:3072
	global_load_lds_dwordx4 v[232:233], off
	v_lshl_add_u64 v[232:233], v[242:243], 0, s[16:17]
	s_mov_b32 m0, s43
	s_nop 0
	global_load_lds_dwordx4 v[232:233], off
	s_barrier
	s_waitcnt lgkmcnt(0)
	v_mfma_f32_16x16x32_bf16 v[92:95], v[216:219], v[164:167], v[92:95]
	v_mfma_f32_16x16x32_bf16 v[88:91], v[224:227], v[164:167], v[88:91]
	v_mfma_f32_16x16x32_bf16 v[84:87], v[216:219], v[192:195], v[84:87]
	v_mfma_f32_16x16x32_bf16 v[80:83], v[224:227], v[192:195], v[80:83]
	v_mfma_f32_16x16x32_bf16 v[76:79], v[216:219], v[200:203], v[76:79]
	v_mfma_f32_16x16x32_bf16 v[72:75], v[224:227], v[200:203], v[72:75]
	v_mfma_f32_16x16x32_bf16 v[68:71], v[216:219], v[208:211], v[68:71]
	v_mfma_f32_16x16x32_bf16 v[64:67], v[224:227], v[208:211], v[64:67]
	v_mfma_f32_16x16x32_bf16 v[92:95], v[220:223], v[188:191], v[92:95]
	v_mfma_f32_16x16x32_bf16 v[88:91], v[228:231], v[188:191], v[88:91]
	v_mfma_f32_16x16x32_bf16 v[84:87], v[220:223], v[196:199], v[84:87]
	v_mfma_f32_16x16x32_bf16 v[80:83], v[228:231], v[196:199], v[80:83]
	v_mfma_f32_16x16x32_bf16 v[76:79], v[220:223], v[204:207], v[76:79]
	v_mfma_f32_16x16x32_bf16 v[72:75], v[228:231], v[204:207], v[72:75]
	s_barrier
	v_mfma_f32_16x16x32_bf16 v[68:71], v[220:223], v[212:215], v[68:71]
	v_mfma_f32_16x16x32_bf16 v[64:67], v[228:231], v[212:215], v[64:67]
	v_readfirstlane_b32 s43, v148
	v_lshl_add_u64 v[164:165], v[236:237], 0, s[18:19]
	s_mov_b32 m0, s43
	ds_read_b128 v[188:191], v152 offset:16384
	ds_read_b128 v[192:195], v152 offset:17408
	ds_read_b128 v[196:199], v151 offset:16384
	ds_read_b128 v[200:203], v151 offset:17408
	ds_read_b128 v[204:207], v150 offset:16384
	ds_read_b128 v[208:211], v150 offset:17408
	ds_read_b128 v[212:215], v149 offset:16384
	ds_read_b128 v[232:235], v149 offset:17408
	global_load_lds_dwordx4 v[164:165], off
	v_add_u32_e32 v164, 0x2000, v148
	v_lshl_add_u64 v[166:167], v[238:239], 0, s[18:19]
	v_readfirstlane_b32 s43, v164
	s_mov_b32 m0, s43
	s_nop 0
	global_load_lds_dwordx4 v[166:167], off
	s_barrier
	s_waitcnt lgkmcnt(0)
	v_mfma_f32_16x16x32_bf16 v[60:63], v[172:175], v[188:191], v[60:63]
	v_mfma_f32_16x16x32_bf16 v[56:59], v[180:183], v[188:191], v[56:59]
	v_mfma_f32_16x16x32_bf16 v[52:55], v[172:175], v[196:199], v[52:55]
	v_mfma_f32_16x16x32_bf16 v[48:51], v[180:183], v[196:199], v[48:51]
	v_mfma_f32_16x16x32_bf16 v[44:47], v[172:175], v[204:207], v[44:47]
	v_mfma_f32_16x16x32_bf16 v[40:43], v[180:183], v[204:207], v[40:43]
	v_mfma_f32_16x16x32_bf16 v[36:39], v[172:175], v[212:215], v[36:39]
	v_mfma_f32_16x16x32_bf16 v[32:35], v[180:183], v[212:215], v[32:35]
	v_mfma_f32_16x16x32_bf16 v[60:63], v[176:179], v[192:195], v[60:63]
	v_mfma_f32_16x16x32_bf16 v[56:59], v[184:187], v[192:195], v[56:59]
	v_mfma_f32_16x16x32_bf16 v[52:55], v[176:179], v[200:203], v[52:55]
	v_mfma_f32_16x16x32_bf16 v[48:51], v[184:187], v[200:203], v[48:51]
	v_mfma_f32_16x16x32_bf16 v[44:47], v[176:179], v[208:211], v[44:47]
	v_mfma_f32_16x16x32_bf16 v[40:43], v[184:187], v[208:211], v[40:43]
	s_barrier
; #define STAGE(P, BASE, LD, br, kt) do { const char* _g = (const char*)((BASE) + (size_t)(br) * (LD) + (size_t)(kt) * 64); \
;     for (int _i = 0; _i < 2; ++_i) { int _b = tidx * 16 + _i * 8192; int _r, _c; stage_rc(_b, _r, _c); \
;       __builtin_amdgcn_global_load_lds((const unsigned*)(_g + (unsigned)((_r * (LD) + _c) * 2)), (unsigned*)((char*)(P) + _b), 16, 0, 0); } } while (0)
; #define LDA(dst, b, h) for (int m = 0; m < 4; ++m) for (int k = 0; k < 2; ++k) \
;     dst[m][k] = *reinterpret_cast<const bf16x8*>((char*)SA(b, h) + lds_byte(wr * 64 + m * 16 + fr, k * 32 + fq * 8))
; #define LDB(dst, b, h) for (int n = 0; n < 2; ++n) for (int k = 0; k < 2; ++k) \
;     dst[n][k] = *reinterpret_cast<const bf16x8*>((char*)SB(b, h) + lds_byte(wc * 32 + n * 16 + fr, k * 32 + fq * 8))
; #define MMA(ai, bj, At_, Bt_) do { __builtin_amdgcn_s_setprio(1); \
;     for (int k = 0; k < 2; ++k) for (int m = 0; m < 4; ++m) for (int n = 0; n < 2; ++n) \
;       acc[ai][bj][m][n] = __builtin_amdgcn_mfma_f32_16x16x32_bf16(At_[m][k], Bt_[n][k], acc[ai][bj][m][n], 0, 0, 0); \
;     __builtin_amdgcn_s_setprio(0); } while (0)
; #define WAIT_V(n) asm volatile("s_waitcnt vmcnt(" #n ")" ::: "memory")
; #define WAIT_L(n) asm volatile("s_waitcnt lgkmcnt(" #n ")" ::: "memory")
; #define BAR __builtin_amdgcn_s_barrier()
; #define SCHED __builtin_amdgcn_sched_barrier(0)
; template <int EPI, int lda, int ldb, int N, int K>
; __device__ __forceinline__ void gemm_phase(const u16* __restrict__ A, const u16* __restrict__ Bt, const GemmEpi ep, int wv) {
;     ...
;       LDA(At, 0, 1); STAGE(SA(0, 0), Ab, lda, brow, t + 2);
;       BAR; WAIT_L(0); MMA(1, 0, At, B0); BAR; SCHED;
;       STAGE(SB(0, 1), Bt, ldb, bcol + HALF, t + 2);
;       WAIT_V(6); BAR; MMA(1, 1, At, B1); BAR;
;       LDB(B0, 1, 0); SCHED; LDA(At, 1, 0); STAGE(SA(0, 1), Ab, lda, brow + HALF, t + 2);
;       WAIT_L(8); BAR; WAIT_L(0); MMA(0, 0, At, B0); BAR; SCHED;
;       LDB(B1, 1, 1); STAGE(SB(1, 0), Bt, ldb, bcol, t + 3);
;       BAR; WAIT_L(0); MMA(0, 1, At, B1); BAR;
;       LDA(At, 1, 1); STAGE(SA(1, 0), Ab, lda, brow, t + 3);
	v_mfma_f32_16x16x32_bf16 v[36:39], v[176:179], v[232:235], v[36:39]
	v_mfma_f32_16x16x32_bf16 v[32:35], v[184:187], v[232:235], v[32:35]
	v_add_u32_e32 v165, s53, v153
	v_lshl_add_u64 v[166:167], v[240:241], 0, s[20:21]
	v_readfirstlane_b32 s43, v165
	s_mov_b32 m0, s43
	v_lshl_add_u64 v[172:173], v[242:243], 0, s[20:21]
	global_load_lds_dwordx4 v[166:167], off
	v_add_u32_e32 v166, 0x2000, v165
	s_nop 0
	v_readfirstlane_b32 s43, v166
	s_mov_b32 m0, s43
	s_nop 0
	global_load_lds_dwordx4 v[172:173], off
	s_waitcnt vmcnt(6)
	s_barrier
	v_mfma_f32_16x16x32_bf16 v[28:31], v[216:219], v[188:191], v[28:31]
	v_mfma_f32_16x16x32_bf16 v[24:27], v[224:227], v[188:191], v[24:27]
	v_mfma_f32_16x16x32_bf16 v[20:23], v[216:219], v[196:199], v[20:23]
	v_mfma_f32_16x16x32_bf16 v[16:19], v[224:227], v[196:199], v[16:19]
	v_mfma_f32_16x16x32_bf16 v[12:15], v[216:219], v[204:207], v[12:15]
	v_mfma_f32_16x16x32_bf16 v[8:11], v[224:227], v[204:207], v[8:11]
	v_mfma_f32_16x16x32_bf16 v[4:7], v[216:219], v[212:215], v[4:7]
	v_mfma_f32_16x16x32_bf16 v[0:3], v[224:227], v[212:215], v[0:3]
	v_mfma_f32_16x16x32_bf16 v[28:31], v[220:223], v[192:195], v[28:31]
	v_mfma_f32_16x16x32_bf16 v[24:27], v[228:231], v[192:195], v[24:27]
	v_mfma_f32_16x16x32_bf16 v[20:23], v[220:223], v[200:203], v[20:23]
	v_mfma_f32_16x16x32_bf16 v[16:19], v[228:231], v[200:203], v[16:19]
	v_mfma_f32_16x16x32_bf16 v[12:15], v[220:223], v[208:211], v[12:15]
	v_mfma_f32_16x16x32_bf16 v[8:11], v[228:231], v[208:211], v[8:11]
	s_barrier
	v_mfma_f32_16x16x32_bf16 v[4:7], v[220:223], v[232:235], v[4:7]
	v_mfma_f32_16x16x32_bf16 v[0:3], v[228:231], v[232:235], v[0:3]
	ds_read_b128 v[172:175], v156
	ds_read_b128 v[176:179], v156 offset:1024
	ds_read_b128 v[180:183], v156 offset:2048
	ds_read_b128 v[184:187], v156 offset:3072
	v_add_u32_e32 v167, 0x4000, v148
	v_add_u32_e32 v168, 0x6000, v148
	v_readfirstlane_b32 s43, v167
	v_lshl_add_u64 v[220:221], v[236:237], 0, s[22:23]
	s_mov_b32 m0, s43
	v_readfirstlane_b32 s43, v168
	ds_read_b128 v[188:191], v152 offset:32768
	ds_read_b128 v[192:195], v152 offset:33792
	ds_read_b128 v[196:199], v151 offset:32768
	ds_read_b128 v[200:203], v151 offset:33792
	ds_read_b128 v[204:207], v150 offset:32768
	ds_read_b128 v[208:211], v150 offset:33792
	ds_read_b128 v[212:215], v149 offset:32768
	ds_read_b128 v[216:219], v149 offset:33792
	global_load_lds_dwordx4 v[220:221], off
	v_lshl_add_u64 v[220:221], v[238:239], 0, s[22:23]
	s_mov_b32 m0, s43
	s_nop 0
	global_load_lds_dwordx4 v[220:221], off
	s_waitcnt lgkmcnt(8)
	s_barrier
	s_waitcnt lgkmcnt(0)
	v_mfma_f32_16x16x32_bf16 v[124:127], v[172:175], v[188:191], v[124:127]
	v_mfma_f32_16x16x32_bf16 v[120:123], v[180:183], v[188:191], v[120:123]
	v_mfma_f32_16x16x32_bf16 v[116:119], v[172:175], v[196:199], v[116:119]
	v_mfma_f32_16x16x32_bf16 v[112:115], v[180:183], v[196:199], v[112:115]
	v_mfma_f32_16x16x32_bf16 v[108:111], v[172:175], v[204:207], v[108:111]
	v_mfma_f32_16x16x32_bf16 v[104:107], v[180:183], v[204:207], v[104:107]
	v_mfma_f32_16x16x32_bf16 v[100:103], v[172:175], v[212:215], v[100:103]
	v_mfma_f32_16x16x32_bf16 v[96:99], v[180:183], v[212:215], v[96:99]
	v_mfma_f32_16x16x32_bf16 v[124:127], v[176:179], v[192:195], v[124:127]
	v_mfma_f32_16x16x32_bf16 v[120:123], v[184:187], v[192:195], v[120:123]
	v_mfma_f32_16x16x32_bf16 v[116:119], v[176:179], v[200:203], v[116:119]
	v_mfma_f32_16x16x32_bf16 v[112:115], v[184:187], v[200:203], v[112:115]
	v_mfma_f32_16x16x32_bf16 v[108:111], v[176:179], v[208:211], v[108:111]
	v_mfma_f32_16x16x32_bf16 v[104:107], v[184:187], v[208:211], v[104:107]
	s_barrier
	v_mfma_f32_16x16x32_bf16 v[100:103], v[176:179], v[216:219], v[100:103]
	v_mfma_f32_16x16x32_bf16 v[96:99], v[184:187], v[216:219], v[96:99]
	v_readfirstlane_b32 s43, v155
	v_add_u32_e32 v171, 0x2000, v155
	v_lshl_add_u64 v[244:245], v[240:241], 0, s[24:25]
	s_mov_b32 m0, s43
	v_readfirstlane_b32 s43, v171
	ds_read_b128 v[220:223], v154
	ds_read_b128 v[224:227], v154 offset:1024
	ds_read_b128 v[228:231], v154 offset:2048
	ds_read_b128 v[232:235], v154 offset:3072
	global_load_lds_dwordx4 v[244:245], off
	v_lshl_add_u64 v[244:245], v[242:243], 0, s[24:25]
	s_mov_b32 m0, s43
	s_nop 0
	global_load_lds_dwordx4 v[244:245], off
	s_barrier
	s_waitcnt lgkmcnt(0)
	v_mfma_f32_16x16x32_bf16 v[92:95], v[220:223], v[188:191], v[92:95]
	v_mfma_f32_16x16x32_bf16 v[88:91], v[228:231], v[188:191], v[88:91]
	v_mfma_f32_16x16x32_bf16 v[84:87], v[220:223], v[196:199], v[84:87]
	v_mfma_f32_16x16x32_bf16 v[80:83], v[228:231], v[196:199], v[80:83]
	v_mfma_f32_16x16x32_bf16 v[76:79], v[220:223], v[204:207], v[76:79]
	v_mfma_f32_16x16x32_bf16 v[72:75], v[228:231], v[204:207], v[72:75]
	v_mfma_f32_16x16x32_bf16 v[68:71], v[220:223], v[212:215], v[68:71]
	v_mfma_f32_16x16x32_bf16 v[64:67], v[228:231], v[212:215], v[64:67]
	v_mfma_f32_16x16x32_bf16 v[92:95], v[224:227], v[192:195], v[92:95]
	v_mfma_f32_16x16x32_bf16 v[88:91], v[232:235], v[192:195], v[88:91]
	v_mfma_f32_16x16x32_bf16 v[84:87], v[224:227], v[200:203], v[84:87]
	v_mfma_f32_16x16x32_bf16 v[80:83], v[232:235], v[200:203], v[80:83]
	v_mfma_f32_16x16x32_bf16 v[76:79], v[224:227], v[208:211], v[76:79]
	v_mfma_f32_16x16x32_bf16 v[72:75], v[232:235], v[208:211], v[72:75]
	s_barrier
	v_mfma_f32_16x16x32_bf16 v[68:71], v[224:227], v[216:219], v[68:71]
	v_mfma_f32_16x16x32_bf16 v[64:67], v[232:235], v[216:219], v[64:67]
	v_readfirstlane_b32 s43, v157
	v_lshl_add_u64 v[236:237], v[236:237], 0, s[26:27]
	s_mov_b32 m0, s43
	v_readfirstlane_b32 s43, v158
	ds_read_b128 v[188:191], v152 offset:49152
	ds_read_b128 v[192:195], v152 offset:50176
	ds_read_b128 v[196:199], v151 offset:49152
	ds_read_b128 v[200:203], v151 offset:50176
	ds_read_b128 v[204:207], v150 offset:49152
	ds_read_b128 v[208:211], v150 offset:50176
	ds_read_b128 v[212:215], v149 offset:49152
	ds_read_b128 v[216:219], v149 offset:50176
	global_load_lds_dwordx4 v[236:237], off
	v_lshl_add_u64 v[236:237], v[238:239], 0, s[26:27]
	s_mov_b32 m0, s43
	s_nop 0
	global_load_lds_dwordx4 v[236:237], off
	s_barrier
; #define STAGE(P, BASE, LD, br, kt) do { const char* _g = (const char*)((BASE) + (size_t)(br) * (LD) + (size_t)(kt) * 64); \
;     for (int _i = 0; _i < 2; ++_i) { int _b = tidx * 16 + _i * 8192; int _r, _c; stage_rc(_b, _r, _c); \
;       __builtin_amdgcn_global_load_lds((const unsigned*)(_g + (unsigned)((_r * (LD) + _c) * 2)), (unsigned*)((char*)(P) + _b), 16, 0, 0); } } while (0)
; #define LDA(dst, b, h) for (int m = 0; m < 4; ++m) for (int k = 0; k < 2; ++k) \
;     dst[m][k] = *reinterpret_cast<const bf16x8*>((char*)SA(b, h) + lds_byte(wr * 64 + m * 16 + fr, k * 32 + fq * 8))
; #define LDB(dst, b, h) for (int n = 0; n < 2; ++n) for (int k = 0; k < 2; ++k) \
;     dst[n][k] = *reinterpret_cast<const bf16x8*>((char*)SB(b, h) + lds_byte(wc * 32 + n * 16 + fr, k * 32 + fq * 8))
; #define MMA(ai, bj, At_, Bt_) do { __builtin_amdgcn_s_setprio(1); \
;     for (int k = 0; k < 2; ++k) for (int m = 0; m < 4; ++m) for (int n = 0; n < 2; ++n) \
;       acc[ai][bj][m][n] = __builtin_amdgcn_mfma_f32_16x16x32_bf16(At_[m][k], Bt_[n][k], acc[ai][bj][m][n], 0, 0, 0); \
;     __builtin_amdgcn_s_setprio(0); } while (0)
; #define WAIT_V(n) asm volatile("s_waitcnt vmcnt(" #n ")" ::: "memory")
; #define WAIT_L(n) asm volatile("s_waitcnt lgkmcnt(" #n ")" ::: "memory")
; #define BAR __builtin_amdgcn_s_barrier()
; #define SCHED __builtin_amdgcn_sched_barrier(0)
; template <int EPI, int lda, int ldb, int N, int K>
; __device__ __forceinline__ void gemm_phase(const u16* __restrict__ A, const u16* __restrict__ Bt, const GemmEpi ep, int wv) {
;     ...
;       LDA(At, 1, 1); STAGE(SA(1, 0), Ab, lda, brow, t + 3);
;       BAR; WAIT_L(0); MMA(1, 0, At, B0); BAR; SCHED;
;       STAGE(SB(1, 1), Bt, ldb, bcol + HALF, t + 3);
;       WAIT_V(6); BAR; MMA(1, 1, At, B1); BAR;
;     }
;     { LDB(B0, 0, 0); LDA(At, 0, 0); STAGE(SA(1, 1), Ab, lda, brow + HALF, nt - 1);
;       BAR; WAIT_L(0); MMA(0, 0, At, B0); BAR;
;       LDB(B1, 0, 1); BAR; WAIT_L(0); MMA(0, 1, At, B1); BAR;
	s_waitcnt lgkmcnt(0)
	v_mfma_f32_16x16x32_bf16 v[60:63], v[172:175], v[188:191], v[60:63]
	v_mfma_f32_16x16x32_bf16 v[56:59], v[180:183], v[188:191], v[56:59]
	v_mfma_f32_16x16x32_bf16 v[52:55], v[172:175], v[196:199], v[52:55]
	v_mfma_f32_16x16x32_bf16 v[48:51], v[180:183], v[196:199], v[48:51]
	v_mfma_f32_16x16x32_bf16 v[44:47], v[172:175], v[204:207], v[44:47]
	v_mfma_f32_16x16x32_bf16 v[40:43], v[180:183], v[204:207], v[40:43]
	v_mfma_f32_16x16x32_bf16 v[36:39], v[172:175], v[212:215], v[36:39]
	v_mfma_f32_16x16x32_bf16 v[32:35], v[180:183], v[212:215], v[32:35]
	v_mfma_f32_16x16x32_bf16 v[60:63], v[176:179], v[192:195], v[60:63]
	v_mfma_f32_16x16x32_bf16 v[56:59], v[184:187], v[192:195], v[56:59]
	v_mfma_f32_16x16x32_bf16 v[52:55], v[176:179], v[200:203], v[52:55]
	v_mfma_f32_16x16x32_bf16 v[48:51], v[184:187], v[200:203], v[48:51]
	v_mfma_f32_16x16x32_bf16 v[44:47], v[176:179], v[208:211], v[44:47]
	v_mfma_f32_16x16x32_bf16 v[40:43], v[184:187], v[208:211], v[40:43]
	s_barrier
	v_mfma_f32_16x16x32_bf16 v[36:39], v[176:179], v[216:219], v[36:39]
	v_mfma_f32_16x16x32_bf16 v[32:35], v[184:187], v[216:219], v[32:35]
	v_readfirstlane_b32 s43, v159
	v_add_u32_e32 v171, 0x2000, v159
	v_lshl_add_u64 v[172:173], v[240:241], 0, s[34:35]
	s_mov_b32 m0, s43
	v_readfirstlane_b32 s43, v171
	global_load_lds_dwordx4 v[172:173], off
	v_lshl_add_u64 v[172:173], v[242:243], 0, s[34:35]
	s_mov_b32 m0, s43
	s_nop 0
	global_load_lds_dwordx4 v[172:173], off
	s_waitcnt vmcnt(6)
	s_barrier
	v_mfma_f32_16x16x32_bf16 v[28:31], v[220:223], v[188:191], v[28:31]
	v_mfma_f32_16x16x32_bf16 v[24:27], v[228:231], v[188:191], v[24:27]
	v_mfma_f32_16x16x32_bf16 v[20:23], v[220:223], v[196:199], v[20:23]
	v_mfma_f32_16x16x32_bf16 v[16:19], v[228:231], v[196:199], v[16:19]
	v_mfma_f32_16x16x32_bf16 v[12:15], v[220:223], v[204:207], v[12:15]
	v_mfma_f32_16x16x32_bf16 v[8:11], v[228:231], v[204:207], v[8:11]
	v_mfma_f32_16x16x32_bf16 v[4:7], v[220:223], v[212:215], v[4:7]
	v_mfma_f32_16x16x32_bf16 v[0:3], v[228:231], v[212:215], v[0:3]
	v_mfma_f32_16x16x32_bf16 v[28:31], v[224:227], v[192:195], v[28:31]
	v_mfma_f32_16x16x32_bf16 v[24:27], v[232:235], v[192:195], v[24:27]
	v_mfma_f32_16x16x32_bf16 v[20:23], v[224:227], v[200:203], v[20:23]
	v_mfma_f32_16x16x32_bf16 v[16:19], v[232:235], v[200:203], v[16:19]
	v_mfma_f32_16x16x32_bf16 v[12:15], v[224:227], v[208:211], v[12:15]
	v_mfma_f32_16x16x32_bf16 v[8:11], v[232:235], v[208:211], v[8:11]
	s_barrier
	v_mfma_f32_16x16x32_bf16 v[4:7], v[224:227], v[216:219], v[4:7]
	v_mfma_f32_16x16x32_bf16 v[0:3], v[232:235], v[216:219], v[0:3]
	s_add_i32 s42, s42, 2
	s_add_u32 s40, s40, 0x100
	s_addc_u32 s41, s41, 0
	s_cmp_gt_u32 s42, 27
	s_cbranch_scc0 .LBB0_1564
	s_add_i32 s40, s38, 0x80
	s_mul_hi_i32 s41, s40, 0x1080
	s_mulk_i32 s40, 0x1080
	s_add_u32 s40, s49, s40
	s_addc_u32 s41, s50, s41
	v_lshl_add_u64 v[158:159], s[40:41], 0, v[128:129]
	v_readfirstlane_b32 s42, v169
	v_lshl_add_u64 v[158:159], v[158:159], 0, s[36:37]
	s_mov_b32 m0, s42
	ds_read_b128 v[134:137], v161
	ds_read_b128 v[138:141], v161 offset:1024
	ds_read_b128 v[172:175], v161 offset:2048
	ds_read_b128 v[176:179], v161 offset:3072
	ds_read_b128 v[180:183], v152
	ds_read_b128 v[184:187], v152 offset:1024
	ds_read_b128 v[188:191], v151
	ds_read_b128 v[192:195], v151 offset:1024
	ds_read_b128 v[196:199], v150
	ds_read_b128 v[200:203], v150 offset:1024
	ds_read_b128 v[204:207], v149
	ds_read_b128 v[208:211], v149 offset:1024
	global_load_lds_dwordx4 v[158:159], off
	v_lshl_add_u64 v[158:159], s[40:41], 0, v[132:133]
	v_readfirstlane_b32 s40, v170
	v_lshl_add_u64 v[158:159], v[158:159], 0, s[36:37]
	s_mov_b32 m0, s40
	s_nop 0
	global_load_lds_dwordx4 v[158:159], off
	s_barrier
	s_waitcnt lgkmcnt(0)
	v_mfma_f32_16x16x32_bf16 v[124:127], v[134:137], v[180:183], v[124:127]
	v_mfma_f32_16x16x32_bf16 v[120:123], v[172:175], v[180:183], v[120:123]
	v_mfma_f32_16x16x32_bf16 v[116:119], v[134:137], v[188:191], v[116:119]
	v_mfma_f32_16x16x32_bf16 v[112:115], v[172:175], v[188:191], v[112:115]
	v_mfma_f32_16x16x32_bf16 v[108:111], v[134:137], v[196:199], v[108:111]
	v_mfma_f32_16x16x32_bf16 v[104:107], v[172:175], v[196:199], v[104:107]
	v_mfma_f32_16x16x32_bf16 v[100:103], v[134:137], v[204:207], v[100:103]
	v_mfma_f32_16x16x32_bf16 v[96:99], v[172:175], v[204:207], v[96:99]
	v_mfma_f32_16x16x32_bf16 v[124:127], v[138:141], v[184:187], v[124:127]
	v_mfma_f32_16x16x32_bf16 v[120:123], v[176:179], v[184:187], v[120:123]
	v_mfma_f32_16x16x32_bf16 v[116:119], v[138:141], v[192:195], v[116:119]
	v_mfma_f32_16x16x32_bf16 v[112:115], v[176:179], v[192:195], v[112:115]
	v_mfma_f32_16x16x32_bf16 v[108:111], v[138:141], v[200:203], v[108:111]
	v_mfma_f32_16x16x32_bf16 v[104:107], v[176:179], v[200:203], v[104:107]
	s_barrier
	v_mfma_f32_16x16x32_bf16 v[100:103], v[138:141], v[208:211], v[100:103]
	v_mfma_f32_16x16x32_bf16 v[96:99], v[176:179], v[208:211], v[96:99]
	ds_read_b128 v[212:215], v160
	ds_read_b128 v[216:219], v160 offset:1024
	ds_read_b128 v[220:223], v160 offset:2048
	ds_read_b128 v[158:161], v160 offset:3072
	s_barrier
	s_waitcnt lgkmcnt(0)
	v_mfma_f32_16x16x32_bf16 v[92:95], v[212:215], v[180:183], v[92:95]
	v_mfma_f32_16x16x32_bf16 v[88:91], v[220:223], v[180:183], v[88:91]
	v_mfma_f32_16x16x32_bf16 v[76:79], v[212:215], v[196:199], v[76:79]
	v_mfma_f32_16x16x32_bf16 v[72:75], v[220:223], v[196:199], v[72:75]
	v_mfma_f32_16x16x32_bf16 v[84:87], v[212:215], v[188:191], v[84:87]
	v_mfma_f32_16x16x32_bf16 v[80:83], v[220:223], v[188:191], v[80:83]
	v_mfma_f32_16x16x32_bf16 v[68:71], v[212:215], v[204:207], v[68:71]
	v_mfma_f32_16x16x32_bf16 v[64:67], v[220:223], v[204:207], v[64:67]
	v_mfma_f32_16x16x32_bf16 v[92:95], v[216:219], v[184:187], v[92:95]
	v_mfma_f32_16x16x32_bf16 v[88:91], v[158:161], v[184:187], v[88:91]
	v_mfma_f32_16x16x32_bf16 v[76:79], v[216:219], v[200:203], v[76:79]
	v_mfma_f32_16x16x32_bf16 v[72:75], v[158:161], v[200:203], v[72:75]
	v_mfma_f32_16x16x32_bf16 v[180:183], v[216:219], v[192:195], v[84:87]
	v_mfma_f32_16x16x32_bf16 v[184:187], v[158:161], v[192:195], v[80:83]
	s_barrier
; #define LDA(dst, b, h) for (int m = 0; m < 4; ++m) for (int k = 0; k < 2; ++k) \
;     dst[m][k] = *reinterpret_cast<const bf16x8*>((char*)SA(b, h) + lds_byte(wr * 64 + m * 16 + fr, k * 32 + fq * 8))
; #define LDB(dst, b, h) for (int n = 0; n < 2; ++n) for (int k = 0; k < 2; ++k) \
;     dst[n][k] = *reinterpret_cast<const bf16x8*>((char*)SB(b, h) + lds_byte(wc * 32 + n * 16 + fr, k * 32 + fq * 8))
; #define MMA(ai, bj, At_, Bt_) do { __builtin_amdgcn_s_setprio(1); \
;     for (int k = 0; k < 2; ++k) for (int m = 0; m < 4; ++m) for (int n = 0; n < 2; ++n) \
;       acc[ai][bj][m][n] = __builtin_amdgcn_mfma_f32_16x16x32_bf16(At_[m][k], Bt_[n][k], acc[ai][bj][m][n], 0, 0, 0); \
;     __builtin_amdgcn_s_setprio(0); } while (0)
; #define WAIT_V(n) asm volatile("s_waitcnt vmcnt(" #n ")" ::: "memory")
; #define WAIT_L(n) asm volatile("s_waitcnt lgkmcnt(" #n ")" ::: "memory")
; #define BAR __builtin_amdgcn_s_barrier()
; template <int EPI, int lda, int ldb, int N, int K>
; __device__ __forceinline__ void gemm_phase(const u16* __restrict__ A, const u16* __restrict__ Bt, const GemmEpi ep, int wv) {
;     ...
;       LDB(B1, 0, 1); BAR; WAIT_L(0); MMA(0, 1, At, B1); BAR;
;       LDA(At, 0, 1); WAIT_V(4); BAR; WAIT_L(0); MMA(1, 0, At, B0); MMA(1, 1, At, B1); BAR; }
;     { LDB(B0, 1, 0); LDA(At, 1, 0); WAIT_V(2); BAR; WAIT_L(0); MMA(0, 0, At, B0); BAR;
	v_mfma_f32_16x16x32_bf16 v[188:191], v[216:219], v[208:211], v[68:71]
	v_mfma_f32_16x16x32_bf16 v[192:195], v[158:161], v[208:211], v[64:67]
	s_nop 0
	ds_read_b128 v[64:67], v152 offset:16384
	ds_read_b128 v[68:71], v152 offset:17408
	ds_read_b128 v[80:83], v151 offset:16384
	ds_read_b128 v[84:87], v151 offset:17408
	ds_read_b128 v[196:199], v150 offset:16384
	ds_read_b128 v[200:203], v150 offset:17408
	ds_read_b128 v[204:207], v149 offset:16384
	ds_read_b128 v[208:211], v149 offset:17408
	s_waitcnt vmcnt(4)
	s_barrier
	s_waitcnt lgkmcnt(0)
	v_mfma_f32_16x16x32_bf16 v[60:63], v[134:137], v[64:67], v[60:63]
	v_mfma_f32_16x16x32_bf16 v[56:59], v[172:175], v[64:67], v[56:59]
	v_mfma_f32_16x16x32_bf16 v[52:55], v[134:137], v[80:83], v[52:55]
	v_mfma_f32_16x16x32_bf16 v[48:51], v[172:175], v[80:83], v[48:51]
	v_mfma_f32_16x16x32_bf16 v[44:47], v[134:137], v[196:199], v[44:47]
	v_mfma_f32_16x16x32_bf16 v[40:43], v[172:175], v[196:199], v[40:43]
	v_mfma_f32_16x16x32_bf16 v[36:39], v[134:137], v[204:207], v[36:39]
	v_mfma_f32_16x16x32_bf16 v[32:35], v[172:175], v[204:207], v[32:35]
	v_mfma_f32_16x16x32_bf16 v[60:63], v[138:141], v[68:71], v[60:63]
	v_mfma_f32_16x16x32_bf16 v[56:59], v[176:179], v[68:71], v[56:59]
	v_mfma_f32_16x16x32_bf16 v[52:55], v[138:141], v[84:87], v[52:55]
	v_mfma_f32_16x16x32_bf16 v[48:51], v[176:179], v[84:87], v[48:51]
	v_mfma_f32_16x16x32_bf16 v[44:47], v[138:141], v[200:203], v[44:47]
	v_mfma_f32_16x16x32_bf16 v[40:43], v[176:179], v[200:203], v[40:43]
	v_mfma_f32_16x16x32_bf16 v[36:39], v[138:141], v[208:211], v[36:39]
	v_mfma_f32_16x16x32_bf16 v[32:35], v[176:179], v[208:211], v[32:35]
	v_mfma_f32_16x16x32_bf16 v[28:31], v[212:215], v[64:67], v[28:31]
	v_mfma_f32_16x16x32_bf16 v[24:27], v[220:223], v[64:67], v[24:27]
	v_mfma_f32_16x16x32_bf16 v[12:15], v[212:215], v[196:199], v[12:15]
	v_mfma_f32_16x16x32_bf16 v[8:11], v[220:223], v[196:199], v[8:11]
	v_mfma_f32_16x16x32_bf16 v[20:23], v[212:215], v[80:83], v[20:23]
	v_mfma_f32_16x16x32_bf16 v[16:19], v[220:223], v[80:83], v[16:19]
	v_mfma_f32_16x16x32_bf16 v[4:7], v[212:215], v[204:207], v[4:7]
	v_mfma_f32_16x16x32_bf16 v[0:3], v[220:223], v[204:207], v[0:3]
	v_mfma_f32_16x16x32_bf16 v[28:31], v[216:219], v[68:71], v[28:31]
	v_mfma_f32_16x16x32_bf16 v[24:27], v[158:161], v[68:71], v[24:27]
	v_mfma_f32_16x16x32_bf16 v[12:15], v[216:219], v[200:203], v[12:15]
	v_mfma_f32_16x16x32_bf16 v[8:11], v[158:161], v[200:203], v[8:11]
	v_mfma_f32_16x16x32_bf16 v[134:137], v[216:219], v[84:87], v[20:23]
	v_mfma_f32_16x16x32_bf16 v[138:141], v[158:161], v[84:87], v[16:19]
	s_barrier
	v_mfma_f32_16x16x32_bf16 v[170:173], v[216:219], v[208:211], v[4:7]
	v_mfma_f32_16x16x32_bf16 v[158:161], v[158:161], v[208:211], v[0:3]
	s_nop 0
	ds_read_b128 v[0:3], v156
	ds_read_b128 v[4:7], v156 offset:1024
	ds_read_b128 v[16:19], v156 offset:2048
	ds_read_b128 v[174:177], v156 offset:3072
	ds_read_b128 v[20:23], v152 offset:32768
	ds_read_b128 v[196:199], v152 offset:33792
	ds_read_b128 v[200:203], v151 offset:32768
	ds_read_b128 v[204:207], v151 offset:33792
	ds_read_b128 v[208:211], v150 offset:32768
	ds_read_b128 v[212:215], v150 offset:33792
	ds_read_b128 v[216:219], v149 offset:32768
	ds_read_b128 v[220:223], v149 offset:33792
	s_waitcnt vmcnt(2)
	s_barrier
	s_waitcnt lgkmcnt(0)
	v_mfma_f32_16x16x32_bf16 v[64:67], v[0:3], v[20:23], v[124:127]
	v_mfma_f32_16x16x32_bf16 v[68:71], v[16:19], v[20:23], v[120:123]
	v_mfma_f32_16x16x32_bf16 v[80:83], v[0:3], v[200:203], v[116:119]
	v_mfma_f32_16x16x32_bf16 v[84:87], v[16:19], v[200:203], v[112:115]
	v_mfma_f32_16x16x32_bf16 v[108:111], v[0:3], v[208:211], v[108:111]
	v_mfma_f32_16x16x32_bf16 v[104:107], v[16:19], v[208:211], v[104:107]
	v_mfma_f32_16x16x32_bf16 v[120:123], v[0:3], v[216:219], v[100:103]
	v_mfma_f32_16x16x32_bf16 v[124:127], v[16:19], v[216:219], v[96:99]
	v_mfma_f32_16x16x32_bf16 v[116:119], v[4:7], v[196:199], v[64:67]
	v_mfma_f32_16x16x32_bf16 v[112:115], v[174:177], v[196:199], v[68:71]
	v_mfma_f32_16x16x32_bf16 v[100:103], v[4:7], v[204:207], v[80:83]
	v_mfma_f32_16x16x32_bf16 v[96:99], v[174:177], v[204:207], v[84:87]
	v_mfma_f32_16x16x32_bf16 v[84:87], v[4:7], v[212:215], v[108:111]
	v_mfma_f32_16x16x32_bf16 v[80:83], v[174:177], v[212:215], v[104:107]
	s_barrier
; #define LDA(dst, b, h) for (int m = 0; m < 4; ++m) for (int k = 0; k < 2; ++k) \
;     dst[m][k] = *reinterpret_cast<const bf16x8*>((char*)SA(b, h) + lds_byte(wr * 64 + m * 16 + fr, k * 32 + fq * 8))
; #define LDB(dst, b, h) for (int n = 0; n < 2; ++n) for (int k = 0; k < 2; ++k) \
;     dst[n][k] = *reinterpret_cast<const bf16x8*>((char*)SB(b, h) + lds_byte(wc * 32 + n * 16 + fr, k * 32 + fq * 8))
; #define MMA(ai, bj, At_, Bt_) do { __builtin_amdgcn_s_setprio(1); \
;     for (int k = 0; k < 2; ++k) for (int m = 0; m < 4; ++m) for (int n = 0; n < 2; ++n) \
;       acc[ai][bj][m][n] = __builtin_amdgcn_mfma_f32_16x16x32_bf16(At_[m][k], Bt_[n][k], acc[ai][bj][m][n], 0, 0, 0); \
;     __builtin_amdgcn_s_setprio(0); } while (0)
; #define WAIT_V(n) asm volatile("s_waitcnt vmcnt(" #n ")" ::: "memory")
; #define WAIT_L(n) asm volatile("s_waitcnt lgkmcnt(" #n ")" ::: "memory")
; #define BAR __builtin_amdgcn_s_barrier()
; template <int EPI, int lda, int ldb, int N, int K>
; __device__ __forceinline__ void gemm_phase(const u16* __restrict__ A, const u16* __restrict__ Bt, const GemmEpi ep, int wv) {
;     ...
;     { LDB(B0, 1, 0); LDA(At, 1, 0); WAIT_V(2); BAR; WAIT_L(0); MMA(0, 0, At, B0); BAR;
;       LDB(B1, 1, 1); WAIT_V(0); BAR; WAIT_L(0); MMA(0, 1, At, B1); BAR;
;       LDA(At, 1, 1); BAR; WAIT_L(0); MMA(1, 0, At, B0); MMA(1, 1, At, B1); BAR; }
;     if (wr == 0) BAR;
	v_mfma_f32_16x16x32_bf16 v[68:71], v[4:7], v[220:223], v[120:123]
	v_mfma_f32_16x16x32_bf16 v[64:67], v[174:177], v[220:223], v[124:127]
	ds_read_b128 v[224:227], v154
	ds_read_b128 v[228:231], v154 offset:1024
	ds_read_b128 v[232:235], v154 offset:2048
	ds_read_b128 v[154:157], v154 offset:3072
	s_waitcnt vmcnt(0)
	s_barrier
	s_waitcnt lgkmcnt(0)
	v_mfma_f32_16x16x32_bf16 v[92:95], v[224:227], v[20:23], v[92:95]
	v_mfma_f32_16x16x32_bf16 v[20:23], v[232:235], v[20:23], v[88:91]
	v_mfma_f32_16x16x32_bf16 v[88:91], v[224:227], v[200:203], v[180:183]
	v_mfma_f32_16x16x32_bf16 v[104:107], v[232:235], v[200:203], v[184:187]
	v_mfma_f32_16x16x32_bf16 v[76:79], v[224:227], v[208:211], v[76:79]
	v_mfma_f32_16x16x32_bf16 v[72:75], v[232:235], v[208:211], v[72:75]
	v_mfma_f32_16x16x32_bf16 v[178:181], v[224:227], v[216:219], v[188:191]
	v_mfma_f32_16x16x32_bf16 v[182:185], v[232:235], v[216:219], v[192:195]
	v_mfma_f32_16x16x32_bf16 v[124:127], v[228:231], v[196:199], v[92:95]
	v_mfma_f32_16x16x32_bf16 v[120:123], v[154:157], v[196:199], v[20:23]
	v_mfma_f32_16x16x32_bf16 v[108:111], v[228:231], v[204:207], v[88:91]
	v_mfma_f32_16x16x32_bf16 v[104:107], v[154:157], v[204:207], v[104:107]
	v_mfma_f32_16x16x32_bf16 v[92:95], v[228:231], v[212:215], v[76:79]
	v_mfma_f32_16x16x32_bf16 v[88:91], v[154:157], v[212:215], v[72:75]
	s_barrier
	v_mfma_f32_16x16x32_bf16 v[76:79], v[228:231], v[220:223], v[178:181]
	v_mfma_f32_16x16x32_bf16 v[72:75], v[154:157], v[220:223], v[182:185]
	ds_read_b128 v[178:181], v152 offset:49152
	ds_read_b128 v[182:185], v152 offset:50176
	ds_read_b128 v[186:189], v151 offset:49152
	ds_read_b128 v[190:193], v151 offset:50176
	ds_read_b128 v[194:197], v150 offset:49152
	ds_read_b128 v[150:153], v150 offset:50176
	ds_read_b128 v[198:201], v149 offset:49152
	ds_read_b128 v[202:205], v149 offset:50176
	s_barrier
	s_waitcnt lgkmcnt(0)
	v_mfma_f32_16x16x32_bf16 v[20:23], v[0:3], v[178:181], v[60:63]
	v_mfma_f32_16x16x32_bf16 v[56:59], v[16:19], v[178:181], v[56:59]
	v_mfma_f32_16x16x32_bf16 v[60:63], v[0:3], v[186:189], v[52:55]
	v_mfma_f32_16x16x32_bf16 v[206:209], v[16:19], v[186:189], v[48:51]
	v_mfma_f32_16x16x32_bf16 v[44:47], v[0:3], v[194:197], v[44:47]
	v_mfma_f32_16x16x32_bf16 v[40:43], v[16:19], v[194:197], v[40:43]
	v_mfma_f32_16x16x32_bf16 v[0:3], v[0:3], v[198:201], v[36:39]
	v_mfma_f32_16x16x32_bf16 v[210:213], v[16:19], v[198:201], v[32:35]
	v_mfma_f32_16x16x32_bf16 v[52:55], v[4:7], v[182:185], v[20:23]
	v_mfma_f32_16x16x32_bf16 v[48:51], v[174:177], v[182:185], v[56:59]
	v_mfma_f32_16x16x32_bf16 v[36:39], v[4:7], v[190:193], v[60:63]
	v_mfma_f32_16x16x32_bf16 v[32:35], v[174:177], v[190:193], v[206:209]
	v_mfma_f32_16x16x32_bf16 v[20:23], v[4:7], v[150:153], v[44:47]
	v_mfma_f32_16x16x32_bf16 v[16:19], v[174:177], v[150:153], v[40:43]
	v_mfma_f32_16x16x32_bf16 v[4:7], v[4:7], v[202:205], v[0:3]
	v_mfma_f32_16x16x32_bf16 v[0:3], v[174:177], v[202:205], v[210:213]
	v_mfma_f32_16x16x32_bf16 v[28:31], v[224:227], v[178:181], v[28:31]
	v_mfma_f32_16x16x32_bf16 v[24:27], v[232:235], v[178:181], v[24:27]
	v_mfma_f32_16x16x32_bf16 v[40:43], v[224:227], v[186:189], v[134:137]
	v_mfma_f32_16x16x32_bf16 v[134:137], v[232:235], v[186:189], v[138:141]
	v_mfma_f32_16x16x32_bf16 v[12:15], v[224:227], v[194:197], v[12:15]
	v_mfma_f32_16x16x32_bf16 v[8:11], v[232:235], v[194:197], v[8:11]
	v_mfma_f32_16x16x32_bf16 v[138:141], v[224:227], v[198:201], v[170:173]
	v_mfma_f32_16x16x32_bf16 v[158:161], v[232:235], v[198:201], v[158:161]
	v_mfma_f32_16x16x32_bf16 v[60:63], v[228:231], v[182:185], v[28:31]
	v_mfma_f32_16x16x32_bf16 v[56:59], v[154:157], v[182:185], v[24:27]
	v_mfma_f32_16x16x32_bf16 v[44:47], v[228:231], v[190:193], v[40:43]
	v_mfma_f32_16x16x32_bf16 v[40:43], v[154:157], v[190:193], v[134:137]
	v_mfma_f32_16x16x32_bf16 v[28:31], v[228:231], v[150:153], v[12:15]
	v_mfma_f32_16x16x32_bf16 v[24:27], v[154:157], v[150:153], v[8:11]
	s_barrier
	v_mfma_f32_16x16x32_bf16 v[12:15], v[228:231], v[202:205], v[138:141]
	v_mfma_f32_16x16x32_bf16 v[8:11], v[154:157], v[202:205], v[158:161]
	v_cmp_gt_u32_e32 vcc, s54, v130
	s_and_saveexec_b64 s[40:41], vcc
	s_cbranch_execz .LBB0_1567
	s_barrier

; #define STAGE(P, BASE, LD, br, kt) do { const char* _g = (const char*)((BASE) + (size_t)(br) * (LD) + (size_t)(kt) * 64); \
;     for (int _i = 0; _i < 2; ++_i) { int _b = tidx * 16 + _i * 8192; int _r, _c; stage_rc(_b, _r, _c); \
;       __builtin_amdgcn_global_load_lds((const unsigned*)(_g + (unsigned)((_r * (LD) + _c) * 2)), (unsigned*)((char*)(P) + _b), 16, 0, 0); } } while (0)
; #define LDA(dst, b, h) for (int m = 0; m < 4; ++m) for (int k = 0; k < 2; ++k) \
;     dst[m][k] = *reinterpret_cast<const bf16x8*>((char*)SA(b, h) + lds_byte(wr * 64 + m * 16 + fr, k * 32 + fq * 8))
; #define LDB(dst, b, h) for (int n = 0; n < 2; ++n) for (int k = 0; k < 2; ++k) \
;     dst[n][k] = *reinterpret_cast<const bf16x8*>((char*)SB(b, h) + lds_byte(wc * 32 + n * 16 + fr, k * 32 + fq * 8))
; #define MMA(ai, bj, At_, Bt_) do { __builtin_amdgcn_s_setprio(1); \
;     for (int k = 0; k < 2; ++k) for (int m = 0; m < 4; ++m) for (int n = 0; n < 2; ++n) \
;       acc[ai][bj][m][n] = __builtin_amdgcn_mfma_f32_16x16x32_bf16(At_[m][k], Bt_[n][k], acc[ai][bj][m][n], 0, 0, 0); \
;     __builtin_amdgcn_s_setprio(0); } while (0)
; #define WAIT_L(n) asm volatile("s_waitcnt lgkmcnt(" #n ")" ::: "memory")
; #define BAR __builtin_amdgcn_s_barrier()
; #define SCHED __builtin_amdgcn_sched_barrier(0)
; template <int EPI, int lda, int ldb, int N, int K>
; __device__ __forceinline__ void gemm_phase(const u16* __restrict__ A, const u16* __restrict__ Bt, const GemmEpi ep, int wv) {
;     ...
;       LDB(B0, 0, 0); SCHED; LDA(At, 0, 0); STAGE(SA(1, 1), Ab, lda, brow + HALF, t + 1);
;       WAIT_L(8); BAR; WAIT_L(0); MMA(0, 0, At, B0); BAR; SCHED;
;       LDB(B1, 0, 1); STAGE(SB(0, 0), Bt, ldb, bcol, t + 2);
;       BAR; WAIT_L(0); MMA(0, 1, At, B1); BAR;
;       LDA(At, 0, 1); STAGE(SA(0, 0), Ab, lda, brow, t + 2);
;       BAR; WAIT_L(0); MMA(1, 0, At, B0); BAR; SCHED;
.LBB0_1624:
	ds_read_b128 v[174:177], v163
	ds_read_b128 v[178:181], v163 offset:1024
	ds_read_b128 v[182:185], v163 offset:2048
	ds_read_b128 v[186:189], v163 offset:3072
	v_add_u32_e32 v171, 0xc000, v149
	v_lshl_add_u64 v[238:239], v[134:135], 0, s[28:29]
	v_readfirstlane_b32 s50, v171
	v_add_u32_e32 v172, 0xe000, v149
	v_lshl_add_u64 v[164:165], v[238:239], 0, s[10:11]
	s_mov_b32 m0, s50
	v_lshl_add_u64 v[240:241], v[132:133], 0, s[28:29]
	v_readfirstlane_b32 s50, v172
	ds_read_b128 v[166:169], v154
	ds_read_b128 v[190:193], v154 offset:1024
	ds_read_b128 v[194:197], v153
	ds_read_b128 v[198:201], v153 offset:1024
	ds_read_b128 v[202:205], v151
	ds_read_b128 v[206:209], v151 offset:1024
	ds_read_b128 v[210:213], v150
	ds_read_b128 v[214:217], v150 offset:1024
	global_load_lds_dwordx4 v[164:165], off
	v_lshl_add_u64 v[164:165], v[240:241], 0, s[10:11]
	s_mov_b32 m0, s50
	s_nop 0
	global_load_lds_dwordx4 v[164:165], off
	s_waitcnt lgkmcnt(8)
	s_barrier
	s_waitcnt lgkmcnt(0)
	v_mfma_f32_16x16x32_bf16 v[124:127], v[166:169], v[174:177], v[124:127]
	v_mfma_f32_16x16x32_bf16 v[120:123], v[166:169], v[182:185], v[120:123]
	v_mfma_f32_16x16x32_bf16 v[116:119], v[194:197], v[174:177], v[116:119]
	v_mfma_f32_16x16x32_bf16 v[112:115], v[194:197], v[182:185], v[112:115]
	v_mfma_f32_16x16x32_bf16 v[108:111], v[202:205], v[174:177], v[108:111]
	v_mfma_f32_16x16x32_bf16 v[104:107], v[202:205], v[182:185], v[104:107]
	v_mfma_f32_16x16x32_bf16 v[100:103], v[210:213], v[174:177], v[100:103]
	v_mfma_f32_16x16x32_bf16 v[96:99], v[210:213], v[182:185], v[96:99]
	v_mfma_f32_16x16x32_bf16 v[124:127], v[190:193], v[178:181], v[124:127]
	v_mfma_f32_16x16x32_bf16 v[120:123], v[190:193], v[186:189], v[120:123]
	v_mfma_f32_16x16x32_bf16 v[116:119], v[198:201], v[178:181], v[116:119]
	v_mfma_f32_16x16x32_bf16 v[112:115], v[198:201], v[186:189], v[112:115]
	v_mfma_f32_16x16x32_bf16 v[108:111], v[206:209], v[178:181], v[108:111]
	v_mfma_f32_16x16x32_bf16 v[104:107], v[206:209], v[186:189], v[104:107]
	s_barrier
	v_mfma_f32_16x16x32_bf16 v[100:103], v[214:217], v[178:181], v[100:103]
	v_mfma_f32_16x16x32_bf16 v[96:99], v[214:217], v[186:189], v[96:99]
	v_add_u32_e32 v164, s40, v155
	v_lshl_add_u64 v[242:243], v[142:143], 0, s[28:29]
	v_readfirstlane_b32 s50, v164
	v_add_u32_e32 v165, 0x2000, v164
	v_lshl_add_u64 v[234:235], v[242:243], 0, s[12:13]
	s_mov_b32 m0, s50
	v_lshl_add_u64 v[244:245], v[140:141], 0, s[28:29]
	v_readfirstlane_b32 s50, v165
	ds_read_b128 v[218:221], v162
	ds_read_b128 v[222:225], v162 offset:1024
	ds_read_b128 v[226:229], v162 offset:2048
	ds_read_b128 v[230:233], v162 offset:3072
	global_load_lds_dwordx4 v[234:235], off
	v_lshl_add_u64 v[234:235], v[244:245], 0, s[12:13]
	s_mov_b32 m0, s50
	s_nop 0
	global_load_lds_dwordx4 v[234:235], off
	s_barrier
	s_waitcnt lgkmcnt(0)
	v_mfma_f32_16x16x32_bf16 v[92:95], v[166:169], v[218:221], v[92:95]
	v_mfma_f32_16x16x32_bf16 v[88:91], v[166:169], v[226:229], v[88:91]
	v_mfma_f32_16x16x32_bf16 v[84:87], v[194:197], v[218:221], v[84:87]
	v_mfma_f32_16x16x32_bf16 v[80:83], v[194:197], v[226:229], v[80:83]
	v_mfma_f32_16x16x32_bf16 v[76:79], v[202:205], v[218:221], v[76:79]
	v_mfma_f32_16x16x32_bf16 v[72:75], v[202:205], v[226:229], v[72:75]
	v_mfma_f32_16x16x32_bf16 v[68:71], v[210:213], v[218:221], v[68:71]
	v_mfma_f32_16x16x32_bf16 v[64:67], v[210:213], v[226:229], v[64:67]
	v_mfma_f32_16x16x32_bf16 v[92:95], v[190:193], v[222:225], v[92:95]
	v_mfma_f32_16x16x32_bf16 v[88:91], v[190:193], v[230:233], v[88:91]
	v_mfma_f32_16x16x32_bf16 v[84:87], v[198:201], v[222:225], v[84:87]
	v_mfma_f32_16x16x32_bf16 v[80:83], v[198:201], v[230:233], v[80:83]
	v_mfma_f32_16x16x32_bf16 v[76:79], v[206:209], v[222:225], v[76:79]
	v_mfma_f32_16x16x32_bf16 v[72:75], v[206:209], v[230:233], v[72:75]
	s_barrier
	v_mfma_f32_16x16x32_bf16 v[68:71], v[214:217], v[222:225], v[68:71]
	v_mfma_f32_16x16x32_bf16 v[64:67], v[214:217], v[230:233], v[64:67]
	v_readfirstlane_b32 s50, v149
	v_lshl_add_u64 v[166:167], v[238:239], 0, s[14:15]
	s_mov_b32 m0, s50
	ds_read_b128 v[190:193], v154 offset:16384
	ds_read_b128 v[194:197], v154 offset:17408
	ds_read_b128 v[198:201], v153 offset:16384
	ds_read_b128 v[202:205], v153 offset:17408
	ds_read_b128 v[206:209], v151 offset:16384
	ds_read_b128 v[210:213], v151 offset:17408
	ds_read_b128 v[214:217], v150 offset:16384
	ds_read_b128 v[234:237], v150 offset:17408
	global_load_lds_dwordx4 v[166:167], off
	v_add_u32_e32 v166, 0x2000, v149
	v_lshl_add_u64 v[168:169], v[240:241], 0, s[14:15]
	v_readfirstlane_b32 s50, v166
	s_mov_b32 m0, s50
	s_nop 0
	global_load_lds_dwordx4 v[168:169], off
	s_barrier
	s_waitcnt lgkmcnt(0)
	v_mfma_f32_16x16x32_bf16 v[60:63], v[190:193], v[174:177], v[60:63]
	v_mfma_f32_16x16x32_bf16 v[56:59], v[190:193], v[182:185], v[56:59]
	v_mfma_f32_16x16x32_bf16 v[52:55], v[198:201], v[174:177], v[52:55]
	v_mfma_f32_16x16x32_bf16 v[48:51], v[198:201], v[182:185], v[48:51]
	v_mfma_f32_16x16x32_bf16 v[44:47], v[206:209], v[174:177], v[44:47]
	v_mfma_f32_16x16x32_bf16 v[40:43], v[206:209], v[182:185], v[40:43]
	v_mfma_f32_16x16x32_bf16 v[36:39], v[214:217], v[174:177], v[36:39]
	v_mfma_f32_16x16x32_bf16 v[32:35], v[214:217], v[182:185], v[32:35]
	v_mfma_f32_16x16x32_bf16 v[60:63], v[194:197], v[178:181], v[60:63]
	v_mfma_f32_16x16x32_bf16 v[56:59], v[194:197], v[186:189], v[56:59]
	v_mfma_f32_16x16x32_bf16 v[52:55], v[202:205], v[178:181], v[52:55]
	v_mfma_f32_16x16x32_bf16 v[48:51], v[202:205], v[186:189], v[48:51]
	v_mfma_f32_16x16x32_bf16 v[44:47], v[210:213], v[178:181], v[44:47]
	v_mfma_f32_16x16x32_bf16 v[40:43], v[210:213], v[186:189], v[40:43]
	s_barrier
; #define STAGE(P, BASE, LD, br, kt) do { const char* _g = (const char*)((BASE) + (size_t)(br) * (LD) + (size_t)(kt) * 64); \
;     for (int _i = 0; _i < 2; ++_i) { int _b = tidx * 16 + _i * 8192; int _r, _c; stage_rc(_b, _r, _c); \
;       __builtin_amdgcn_global_load_lds((const unsigned*)(_g + (unsigned)((_r * (LD) + _c) * 2)), (unsigned*)((char*)(P) + _b), 16, 0, 0); } } while (0)
; #define LDA(dst, b, h) for (int m = 0; m < 4; ++m) for (int k = 0; k < 2; ++k) \
;     dst[m][k] = *reinterpret_cast<const bf16x8*>((char*)SA(b, h) + lds_byte(wr * 64 + m * 16 + fr, k * 32 + fq * 8))
; #define LDB(dst, b, h) for (int n = 0; n < 2; ++n) for (int k = 0; k < 2; ++k) \
;     dst[n][k] = *reinterpret_cast<const bf16x8*>((char*)SB(b, h) + lds_byte(wc * 32 + n * 16 + fr, k * 32 + fq * 8))
; #define MMA(ai, bj, At_, Bt_) do { __builtin_amdgcn_s_setprio(1); \
;     for (int k = 0; k < 2; ++k) for (int m = 0; m < 4; ++m) for (int n = 0; n < 2; ++n) \
;       acc[ai][bj][m][n] = __builtin_amdgcn_mfma_f32_16x16x32_bf16(At_[m][k], Bt_[n][k], acc[ai][bj][m][n], 0, 0, 0); \
;     __builtin_amdgcn_s_setprio(0); } while (0)
; #define WAIT_V(n) asm volatile("s_waitcnt vmcnt(" #n ")" ::: "memory")
; #define WAIT_L(n) asm volatile("s_waitcnt lgkmcnt(" #n ")" ::: "memory")
; #define BAR __builtin_amdgcn_s_barrier()
; #define SCHED __builtin_amdgcn_sched_barrier(0)
; template <int EPI, int lda, int ldb, int N, int K>
; __device__ __forceinline__ void gemm_phase(const u16* __restrict__ A, const u16* __restrict__ Bt, const GemmEpi ep, int wv) {
;     ...
;       STAGE(SB(0, 1), Bt, ldb, bcol + HALF, t + 2);
;       WAIT_V(6); BAR; MMA(1, 1, At, B1); BAR;
;       LDB(B0, 1, 0); SCHED; LDA(At, 1, 0); STAGE(SA(0, 1), Ab, lda, brow + HALF, t + 2);
;       WAIT_L(8); BAR; WAIT_L(0); MMA(0, 0, At, B0); BAR; SCHED;
;       LDB(B1, 1, 1); STAGE(SB(1, 0), Bt, ldb, bcol, t + 3);
;       BAR; WAIT_L(0); MMA(0, 1, At, B1); BAR;
;       LDA(At, 1, 1); STAGE(SA(1, 0), Ab, lda, brow, t + 3);
	v_mfma_f32_16x16x32_bf16 v[36:39], v[234:237], v[178:181], v[36:39]
	v_mfma_f32_16x16x32_bf16 v[32:35], v[234:237], v[186:189], v[32:35]
	v_add_u32_e32 v167, s41, v155
	v_lshl_add_u64 v[246:247], v[138:139], 0, s[28:29]
	v_readfirstlane_b32 s50, v167
	v_lshl_add_u64 v[168:169], v[246:247], 0, s[16:17]
	s_mov_b32 m0, s50
	v_lshl_add_u64 v[248:249], v[136:137], 0, s[28:29]
	global_load_lds_dwordx4 v[168:169], off
	v_add_u32_e32 v168, 0x2000, v167
	v_lshl_add_u64 v[174:175], v[248:249], 0, s[16:17]
	v_readfirstlane_b32 s50, v168
	s_mov_b32 m0, s50
	s_nop 0
	global_load_lds_dwordx4 v[174:175], off
	s_waitcnt vmcnt(6)
	s_barrier
	v_mfma_f32_16x16x32_bf16 v[28:31], v[190:193], v[218:221], v[28:31]
	v_mfma_f32_16x16x32_bf16 v[24:27], v[190:193], v[226:229], v[24:27]
	v_mfma_f32_16x16x32_bf16 v[20:23], v[198:201], v[218:221], v[20:23]
	v_mfma_f32_16x16x32_bf16 v[16:19], v[198:201], v[226:229], v[16:19]
	v_mfma_f32_16x16x32_bf16 v[12:15], v[206:209], v[218:221], v[12:15]
	v_mfma_f32_16x16x32_bf16 v[8:11], v[206:209], v[226:229], v[8:11]
	v_mfma_f32_16x16x32_bf16 v[4:7], v[214:217], v[218:221], v[4:7]
	v_mfma_f32_16x16x32_bf16 v[0:3], v[214:217], v[226:229], v[0:3]
	v_mfma_f32_16x16x32_bf16 v[28:31], v[194:197], v[222:225], v[28:31]
	v_mfma_f32_16x16x32_bf16 v[24:27], v[194:197], v[230:233], v[24:27]
	v_mfma_f32_16x16x32_bf16 v[20:23], v[202:205], v[222:225], v[20:23]
	v_mfma_f32_16x16x32_bf16 v[16:19], v[202:205], v[230:233], v[16:19]
	v_mfma_f32_16x16x32_bf16 v[12:15], v[210:213], v[222:225], v[12:15]
	v_mfma_f32_16x16x32_bf16 v[8:11], v[210:213], v[230:233], v[8:11]
	s_barrier
	v_mfma_f32_16x16x32_bf16 v[4:7], v[234:237], v[222:225], v[4:7]
	v_mfma_f32_16x16x32_bf16 v[0:3], v[234:237], v[230:233], v[0:3]
	ds_read_b128 v[174:177], v158
	ds_read_b128 v[178:181], v158 offset:1024
	ds_read_b128 v[182:185], v158 offset:2048
	ds_read_b128 v[186:189], v158 offset:3072
	v_add_u32_e32 v169, 0x4000, v149
	v_add_u32_e32 v170, 0x6000, v149
	v_readfirstlane_b32 s50, v169
	v_lshl_add_u64 v[222:223], v[238:239], 0, s[18:19]
	s_mov_b32 m0, s50
	v_readfirstlane_b32 s50, v170
	ds_read_b128 v[190:193], v154 offset:32768
	ds_read_b128 v[194:197], v154 offset:33792
	ds_read_b128 v[198:201], v153 offset:32768
	ds_read_b128 v[202:205], v153 offset:33792
	ds_read_b128 v[206:209], v151 offset:32768
	ds_read_b128 v[210:213], v151 offset:33792
	ds_read_b128 v[214:217], v150 offset:32768
	ds_read_b128 v[218:221], v150 offset:33792
	global_load_lds_dwordx4 v[222:223], off
	v_lshl_add_u64 v[222:223], v[240:241], 0, s[18:19]
	s_mov_b32 m0, s50
	s_nop 0
	global_load_lds_dwordx4 v[222:223], off
	s_waitcnt lgkmcnt(8)
	s_barrier
	s_waitcnt lgkmcnt(0)
	v_mfma_f32_16x16x32_bf16 v[124:127], v[190:193], v[174:177], v[124:127]
	v_mfma_f32_16x16x32_bf16 v[120:123], v[190:193], v[182:185], v[120:123]
	v_mfma_f32_16x16x32_bf16 v[116:119], v[198:201], v[174:177], v[116:119]
	v_mfma_f32_16x16x32_bf16 v[112:115], v[198:201], v[182:185], v[112:115]
	v_mfma_f32_16x16x32_bf16 v[108:111], v[206:209], v[174:177], v[108:111]
	v_mfma_f32_16x16x32_bf16 v[104:107], v[206:209], v[182:185], v[104:107]
	v_mfma_f32_16x16x32_bf16 v[100:103], v[214:217], v[174:177], v[100:103]
	v_mfma_f32_16x16x32_bf16 v[96:99], v[214:217], v[182:185], v[96:99]
	v_mfma_f32_16x16x32_bf16 v[124:127], v[194:197], v[178:181], v[124:127]
	v_mfma_f32_16x16x32_bf16 v[120:123], v[194:197], v[186:189], v[120:123]
	v_mfma_f32_16x16x32_bf16 v[116:119], v[202:205], v[178:181], v[116:119]
	v_mfma_f32_16x16x32_bf16 v[112:115], v[202:205], v[186:189], v[112:115]
	v_mfma_f32_16x16x32_bf16 v[108:111], v[210:213], v[178:181], v[108:111]
	v_mfma_f32_16x16x32_bf16 v[104:107], v[210:213], v[186:189], v[104:107]
	s_barrier
	v_mfma_f32_16x16x32_bf16 v[100:103], v[218:221], v[178:181], v[100:103]
	v_mfma_f32_16x16x32_bf16 v[96:99], v[218:221], v[186:189], v[96:99]
	v_readfirstlane_b32 s50, v157
	v_add_u32_e32 v173, 0x2000, v157
	v_lshl_add_u64 v[242:243], v[242:243], 0, s[20:21]
	s_mov_b32 m0, s50
	v_readfirstlane_b32 s50, v173
	ds_read_b128 v[222:225], v156
	ds_read_b128 v[226:229], v156 offset:1024
	ds_read_b128 v[230:233], v156 offset:2048
	ds_read_b128 v[234:237], v156 offset:3072
	global_load_lds_dwordx4 v[242:243], off
	v_lshl_add_u64 v[242:243], v[244:245], 0, s[20:21]
	s_mov_b32 m0, s50
	s_nop 0
	global_load_lds_dwordx4 v[242:243], off
	s_barrier
	s_waitcnt lgkmcnt(0)
	v_mfma_f32_16x16x32_bf16 v[92:95], v[190:193], v[222:225], v[92:95]
	v_mfma_f32_16x16x32_bf16 v[88:91], v[190:193], v[230:233], v[88:91]
	v_mfma_f32_16x16x32_bf16 v[84:87], v[198:201], v[222:225], v[84:87]
	v_mfma_f32_16x16x32_bf16 v[80:83], v[198:201], v[230:233], v[80:83]
	v_mfma_f32_16x16x32_bf16 v[76:79], v[206:209], v[222:225], v[76:79]
	v_mfma_f32_16x16x32_bf16 v[72:75], v[206:209], v[230:233], v[72:75]
	v_mfma_f32_16x16x32_bf16 v[68:71], v[214:217], v[222:225], v[68:71]
	v_mfma_f32_16x16x32_bf16 v[64:67], v[214:217], v[230:233], v[64:67]
	v_mfma_f32_16x16x32_bf16 v[92:95], v[194:197], v[226:229], v[92:95]
	v_mfma_f32_16x16x32_bf16 v[88:91], v[194:197], v[234:237], v[88:91]
	v_mfma_f32_16x16x32_bf16 v[84:87], v[202:205], v[226:229], v[84:87]
	v_mfma_f32_16x16x32_bf16 v[80:83], v[202:205], v[234:237], v[80:83]
	v_mfma_f32_16x16x32_bf16 v[76:79], v[210:213], v[226:229], v[76:79]
	v_mfma_f32_16x16x32_bf16 v[72:75], v[210:213], v[234:237], v[72:75]
	s_barrier
; #define STAGE(P, BASE, LD, br, kt) do { const char* _g = (const char*)((BASE) + (size_t)(br) * (LD) + (size_t)(kt) * 64); \
;     for (int _i = 0; _i < 2; ++_i) { int _b = tidx * 16 + _i * 8192; int _r, _c; stage_rc(_b, _r, _c); \
;       __builtin_amdgcn_global_load_lds((const unsigned*)(_g + (unsigned)((_r * (LD) + _c) * 2)), (unsigned*)((char*)(P) + _b), 16, 0, 0); } } while (0)
; #define LDA(dst, b, h) for (int m = 0; m < 4; ++m) for (int k = 0; k < 2; ++k) \
;     dst[m][k] = *reinterpret_cast<const bf16x8*>((char*)SA(b, h) + lds_byte(wr * 64 + m * 16 + fr, k * 32 + fq * 8))
; #define LDB(dst, b, h) for (int n = 0; n < 2; ++n) for (int k = 0; k < 2; ++k) \
;     dst[n][k] = *reinterpret_cast<const bf16x8*>((char*)SB(b, h) + lds_byte(wc * 32 + n * 16 + fr, k * 32 + fq * 8))
; #define MMA(ai, bj, At_, Bt_) do { __builtin_amdgcn_s_setprio(1); \
;     for (int k = 0; k < 2; ++k) for (int m = 0; m < 4; ++m) for (int n = 0; n < 2; ++n) \
;       acc[ai][bj][m][n] = __builtin_amdgcn_mfma_f32_16x16x32_bf16(At_[m][k], Bt_[n][k], acc[ai][bj][m][n], 0, 0, 0); \
;     __builtin_amdgcn_s_setprio(0); } while (0)
; #define WAIT_V(n) asm volatile("s_waitcnt vmcnt(" #n ")" ::: "memory")
; #define WAIT_L(n) asm volatile("s_waitcnt lgkmcnt(" #n ")" ::: "memory")
; #define BAR __builtin_amdgcn_s_barrier()
; #define SCHED __builtin_amdgcn_sched_barrier(0)
; template <int EPI, int lda, int ldb, int N, int K>
; __device__ __forceinline__ void gemm_phase(const u16* __restrict__ A, const u16* __restrict__ Bt, const GemmEpi ep, int wv) {
;     ...
;       LDA(At, 1, 1); STAGE(SA(1, 0), Ab, lda, brow, t + 3);
;       BAR; WAIT_L(0); MMA(1, 0, At, B0); BAR; SCHED;
;       STAGE(SB(1, 1), Bt, ldb, bcol + HALF, t + 3);
;       WAIT_V(6); BAR; MMA(1, 1, At, B1); BAR;
;     }
;     { LDB(B0, 0, 0); LDA(At, 0, 0); STAGE(SA(1, 1), Ab, lda, brow + HALF, nt - 1);
;       BAR; WAIT_L(0); MMA(0, 0, At, B0); BAR;
;       LDB(B1, 0, 1); BAR; WAIT_L(0); MMA(0, 1, At, B1); BAR;
	v_mfma_f32_16x16x32_bf16 v[68:71], v[218:221], v[226:229], v[68:71]
	v_mfma_f32_16x16x32_bf16 v[64:67], v[218:221], v[234:237], v[64:67]
	v_readfirstlane_b32 s50, v159
	v_lshl_add_u64 v[238:239], v[238:239], 0, s[22:23]
	s_mov_b32 m0, s50
	v_readfirstlane_b32 s50, v160
	ds_read_b128 v[190:193], v154 offset:49152
	ds_read_b128 v[194:197], v154 offset:50176
	ds_read_b128 v[198:201], v153 offset:49152
	ds_read_b128 v[202:205], v153 offset:50176
	ds_read_b128 v[206:209], v151 offset:49152
	ds_read_b128 v[210:213], v151 offset:50176
	ds_read_b128 v[214:217], v150 offset:49152
	ds_read_b128 v[218:221], v150 offset:50176
	global_load_lds_dwordx4 v[238:239], off
	v_lshl_add_u64 v[238:239], v[240:241], 0, s[22:23]
	s_mov_b32 m0, s50
	s_nop 0
	global_load_lds_dwordx4 v[238:239], off
	s_barrier
	s_waitcnt lgkmcnt(0)
	v_mfma_f32_16x16x32_bf16 v[60:63], v[190:193], v[174:177], v[60:63]
	v_mfma_f32_16x16x32_bf16 v[56:59], v[190:193], v[182:185], v[56:59]
	v_mfma_f32_16x16x32_bf16 v[52:55], v[198:201], v[174:177], v[52:55]
	v_mfma_f32_16x16x32_bf16 v[48:51], v[198:201], v[182:185], v[48:51]
	v_mfma_f32_16x16x32_bf16 v[44:47], v[206:209], v[174:177], v[44:47]
	v_mfma_f32_16x16x32_bf16 v[40:43], v[206:209], v[182:185], v[40:43]
	v_mfma_f32_16x16x32_bf16 v[36:39], v[214:217], v[174:177], v[36:39]
	v_mfma_f32_16x16x32_bf16 v[32:35], v[214:217], v[182:185], v[32:35]
	v_mfma_f32_16x16x32_bf16 v[60:63], v[194:197], v[178:181], v[60:63]
	v_mfma_f32_16x16x32_bf16 v[56:59], v[194:197], v[186:189], v[56:59]
	v_mfma_f32_16x16x32_bf16 v[52:55], v[202:205], v[178:181], v[52:55]
	v_mfma_f32_16x16x32_bf16 v[48:51], v[202:205], v[186:189], v[48:51]
	v_mfma_f32_16x16x32_bf16 v[44:47], v[210:213], v[178:181], v[44:47]
	v_mfma_f32_16x16x32_bf16 v[40:43], v[210:213], v[186:189], v[40:43]
	s_barrier
	v_mfma_f32_16x16x32_bf16 v[36:39], v[218:221], v[178:181], v[36:39]
	v_mfma_f32_16x16x32_bf16 v[32:35], v[218:221], v[186:189], v[32:35]
	v_readfirstlane_b32 s50, v161
	v_add_u32_e32 v173, 0x2000, v161
	v_lshl_add_u64 v[174:175], v[246:247], 0, s[24:25]
	s_mov_b32 m0, s50
	v_readfirstlane_b32 s50, v173
	global_load_lds_dwordx4 v[174:175], off
	v_lshl_add_u64 v[174:175], v[248:249], 0, s[24:25]
	s_mov_b32 m0, s50
	s_nop 0
	global_load_lds_dwordx4 v[174:175], off
	s_waitcnt vmcnt(6)
	s_barrier
	v_mfma_f32_16x16x32_bf16 v[28:31], v[190:193], v[222:225], v[28:31]
	v_mfma_f32_16x16x32_bf16 v[24:27], v[190:193], v[230:233], v[24:27]
	v_mfma_f32_16x16x32_bf16 v[20:23], v[198:201], v[222:225], v[20:23]
	v_mfma_f32_16x16x32_bf16 v[16:19], v[198:201], v[230:233], v[16:19]
	v_mfma_f32_16x16x32_bf16 v[12:15], v[206:209], v[222:225], v[12:15]
	v_mfma_f32_16x16x32_bf16 v[8:11], v[206:209], v[230:233], v[8:11]
	v_mfma_f32_16x16x32_bf16 v[4:7], v[214:217], v[222:225], v[4:7]
	v_mfma_f32_16x16x32_bf16 v[0:3], v[214:217], v[230:233], v[0:3]
	v_mfma_f32_16x16x32_bf16 v[28:31], v[194:197], v[226:229], v[28:31]
	v_mfma_f32_16x16x32_bf16 v[24:27], v[194:197], v[234:237], v[24:27]
	v_mfma_f32_16x16x32_bf16 v[20:23], v[202:205], v[226:229], v[20:23]
	v_mfma_f32_16x16x32_bf16 v[16:19], v[202:205], v[234:237], v[16:19]
	v_mfma_f32_16x16x32_bf16 v[12:15], v[210:213], v[226:229], v[12:15]
	v_mfma_f32_16x16x32_bf16 v[8:11], v[210:213], v[234:237], v[8:11]
	s_barrier
	v_mfma_f32_16x16x32_bf16 v[4:7], v[218:221], v[226:229], v[4:7]
	v_mfma_f32_16x16x32_bf16 v[0:3], v[218:221], v[234:237], v[0:3]
	s_add_i32 s49, s49, 2
	s_add_u32 s28, s28, 0x100
	s_addc_u32 s29, s29, 0
	s_cmpk_gt_u32 s49, 0x51
	s_cbranch_scc0 .LBB0_1624
	s_add_i32 s28, s48, 0x80
	s_mul_hi_i32 s29, s28, 0x2b00
	s_mulk_i32 s28, 0x2b00
	s_add_u32 s28, s34, s28
	s_addc_u32 s29, s35, s29
	s_add_u32 s28, s28, 0x2a80
	s_addc_u32 s29, s29, 0
	v_readfirstlane_b32 s49, v171
	v_lshl_add_u64 v[160:161], s[28:29], 0, v[128:129]
	s_mov_b32 m0, s49
	ds_read_b128 v[132:135], v163
	ds_read_b128 v[136:139], v163 offset:1024
	ds_read_b128 v[140:143], v163 offset:2048
	ds_read_b128 v[174:177], v163 offset:3072
	ds_read_b128 v[178:181], v154
	ds_read_b128 v[182:185], v154 offset:1024
	ds_read_b128 v[186:189], v153
	ds_read_b128 v[190:193], v153 offset:1024
	ds_read_b128 v[194:197], v151
	ds_read_b128 v[198:201], v151 offset:1024
	ds_read_b128 v[202:205], v150
	ds_read_b128 v[206:209], v150 offset:1024
	global_load_lds_dwordx4 v[160:161], off
	v_lshl_add_u64 v[160:161], s[28:29], 0, v[130:131]
	v_readfirstlane_b32 s28, v172
	s_mov_b32 m0, s28
	s_nop 0
	global_load_lds_dwordx4 v[160:161], off
	s_barrier
	s_waitcnt lgkmcnt(0)
	v_mfma_f32_16x16x32_bf16 v[124:127], v[178:181], v[132:135], v[124:127]
	v_mfma_f32_16x16x32_bf16 v[120:123], v[178:181], v[140:143], v[120:123]
	v_mfma_f32_16x16x32_bf16 v[116:119], v[186:189], v[132:135], v[116:119]
	v_mfma_f32_16x16x32_bf16 v[112:115], v[186:189], v[140:143], v[112:115]
	v_mfma_f32_16x16x32_bf16 v[108:111], v[194:197], v[132:135], v[108:111]
	v_mfma_f32_16x16x32_bf16 v[104:107], v[194:197], v[140:143], v[104:107]
	v_mfma_f32_16x16x32_bf16 v[100:103], v[202:205], v[132:135], v[100:103]
	v_mfma_f32_16x16x32_bf16 v[96:99], v[202:205], v[140:143], v[96:99]
	v_mfma_f32_16x16x32_bf16 v[124:127], v[182:185], v[136:139], v[124:127]
	v_mfma_f32_16x16x32_bf16 v[120:123], v[182:185], v[174:177], v[120:123]
	v_mfma_f32_16x16x32_bf16 v[116:119], v[190:193], v[136:139], v[116:119]
	v_mfma_f32_16x16x32_bf16 v[112:115], v[190:193], v[174:177], v[112:115]
	v_mfma_f32_16x16x32_bf16 v[108:111], v[198:201], v[136:139], v[108:111]
	v_mfma_f32_16x16x32_bf16 v[104:107], v[198:201], v[174:177], v[104:107]
	s_barrier
; #define LDA(dst, b, h) for (int m = 0; m < 4; ++m) for (int k = 0; k < 2; ++k) \
;     dst[m][k] = *reinterpret_cast<const bf16x8*>((char*)SA(b, h) + lds_byte(wr * 64 + m * 16 + fr, k * 32 + fq * 8))
; #define LDB(dst, b, h) for (int n = 0; n < 2; ++n) for (int k = 0; k < 2; ++k) \
;     dst[n][k] = *reinterpret_cast<const bf16x8*>((char*)SB(b, h) + lds_byte(wc * 32 + n * 16 + fr, k * 32 + fq * 8))
; #define MMA(ai, bj, At_, Bt_) do { __builtin_amdgcn_s_setprio(1); \
;     for (int k = 0; k < 2; ++k) for (int m = 0; m < 4; ++m) for (int n = 0; n < 2; ++n) \
;       acc[ai][bj][m][n] = __builtin_amdgcn_mfma_f32_16x16x32_bf16(At_[m][k], Bt_[n][k], acc[ai][bj][m][n], 0, 0, 0); \
;     __builtin_amdgcn_s_setprio(0); } while (0)
; #define WAIT_V(n) asm volatile("s_waitcnt vmcnt(" #n ")" ::: "memory")
; #define WAIT_L(n) asm volatile("s_waitcnt lgkmcnt(" #n ")" ::: "memory")
; #define BAR __builtin_amdgcn_s_barrier()
; template <int EPI, int lda, int ldb, int N, int K>
; __device__ __forceinline__ void gemm_phase(const u16* __restrict__ A, const u16* __restrict__ Bt, const GemmEpi ep, int wv) {
;     ...
;       LDB(B1, 0, 1); BAR; WAIT_L(0); MMA(0, 1, At, B1); BAR;
;       LDA(At, 0, 1); WAIT_V(4); BAR; WAIT_L(0); MMA(1, 0, At, B0); MMA(1, 1, At, B1); BAR; }
;     { LDB(B0, 1, 0); LDA(At, 1, 0); WAIT_V(2); BAR; WAIT_L(0); MMA(0, 0, At, B0); BAR;
	v_mfma_f32_16x16x32_bf16 v[100:103], v[206:209], v[136:139], v[100:103]
	v_mfma_f32_16x16x32_bf16 v[96:99], v[206:209], v[174:177], v[96:99]
	ds_read_b128 v[210:213], v162
	ds_read_b128 v[214:217], v162 offset:1024
	ds_read_b128 v[218:221], v162 offset:2048
	ds_read_b128 v[160:163], v162 offset:3072
	s_barrier
	s_waitcnt lgkmcnt(0)
	v_mfma_f32_16x16x32_bf16 v[92:95], v[178:181], v[210:213], v[92:95]
	v_mfma_f32_16x16x32_bf16 v[88:91], v[178:181], v[218:221], v[88:91]
	v_mfma_f32_16x16x32_bf16 v[72:75], v[194:197], v[218:221], v[72:75]
	v_mfma_f32_16x16x32_bf16 v[68:71], v[202:205], v[210:213], v[68:71]
	v_mfma_f32_16x16x32_bf16 v[84:87], v[186:189], v[210:213], v[84:87]
	v_mfma_f32_16x16x32_bf16 v[80:83], v[186:189], v[218:221], v[80:83]
	v_mfma_f32_16x16x32_bf16 v[76:79], v[194:197], v[210:213], v[76:79]
	v_mfma_f32_16x16x32_bf16 v[64:67], v[202:205], v[218:221], v[64:67]
	v_mfma_f32_16x16x32_bf16 v[92:95], v[182:185], v[214:217], v[92:95]
	v_mfma_f32_16x16x32_bf16 v[88:91], v[182:185], v[160:163], v[88:91]
	v_mfma_f32_16x16x32_bf16 v[72:75], v[198:201], v[160:163], v[72:75]
	v_mfma_f32_16x16x32_bf16 v[68:71], v[206:209], v[214:217], v[68:71]
	v_mfma_f32_16x16x32_bf16 v[178:181], v[190:193], v[214:217], v[84:87]
	v_mfma_f32_16x16x32_bf16 v[182:185], v[190:193], v[160:163], v[80:83]
	s_barrier
	v_mfma_f32_16x16x32_bf16 v[186:189], v[198:201], v[214:217], v[76:79]
	v_mfma_f32_16x16x32_bf16 v[190:193], v[206:209], v[160:163], v[64:67]
	s_nop 0
	ds_read_b128 v[64:67], v154 offset:16384
	ds_read_b128 v[76:79], v154 offset:17408
	ds_read_b128 v[80:83], v153 offset:16384
	ds_read_b128 v[84:87], v153 offset:17408
	ds_read_b128 v[194:197], v151 offset:16384
	ds_read_b128 v[198:201], v151 offset:17408
	ds_read_b128 v[202:205], v150 offset:16384
	ds_read_b128 v[206:209], v150 offset:17408
	s_waitcnt vmcnt(4)
	s_barrier
	s_waitcnt lgkmcnt(0)
	v_mfma_f32_16x16x32_bf16 v[60:63], v[64:67], v[132:135], v[60:63]
	v_mfma_f32_16x16x32_bf16 v[56:59], v[64:67], v[140:143], v[56:59]
	v_mfma_f32_16x16x32_bf16 v[52:55], v[80:83], v[132:135], v[52:55]
	v_mfma_f32_16x16x32_bf16 v[48:51], v[80:83], v[140:143], v[48:51]
	v_mfma_f32_16x16x32_bf16 v[44:47], v[194:197], v[132:135], v[44:47]
	v_mfma_f32_16x16x32_bf16 v[40:43], v[194:197], v[140:143], v[40:43]
	v_mfma_f32_16x16x32_bf16 v[36:39], v[202:205], v[132:135], v[36:39]
	v_mfma_f32_16x16x32_bf16 v[32:35], v[202:205], v[140:143], v[32:35]
	v_mfma_f32_16x16x32_bf16 v[60:63], v[76:79], v[136:139], v[60:63]
	v_mfma_f32_16x16x32_bf16 v[56:59], v[76:79], v[174:177], v[56:59]
	v_mfma_f32_16x16x32_bf16 v[52:55], v[84:87], v[136:139], v[52:55]
	v_mfma_f32_16x16x32_bf16 v[48:51], v[84:87], v[174:177], v[48:51]
	v_mfma_f32_16x16x32_bf16 v[44:47], v[198:201], v[136:139], v[44:47]
	v_mfma_f32_16x16x32_bf16 v[40:43], v[198:201], v[174:177], v[40:43]
	v_mfma_f32_16x16x32_bf16 v[36:39], v[206:209], v[136:139], v[36:39]
	v_mfma_f32_16x16x32_bf16 v[32:35], v[206:209], v[174:177], v[32:35]
	v_mfma_f32_16x16x32_bf16 v[28:31], v[64:67], v[210:213], v[28:31]
	v_mfma_f32_16x16x32_bf16 v[24:27], v[64:67], v[218:221], v[24:27]
	v_mfma_f32_16x16x32_bf16 v[12:15], v[194:197], v[210:213], v[12:15]
	v_mfma_f32_16x16x32_bf16 v[8:11], v[194:197], v[218:221], v[8:11]
	v_mfma_f32_16x16x32_bf16 v[20:23], v[80:83], v[210:213], v[20:23]
	v_mfma_f32_16x16x32_bf16 v[16:19], v[80:83], v[218:221], v[16:19]
	v_mfma_f32_16x16x32_bf16 v[4:7], v[202:205], v[210:213], v[4:7]
	v_mfma_f32_16x16x32_bf16 v[0:3], v[202:205], v[218:221], v[0:3]
	v_mfma_f32_16x16x32_bf16 v[28:31], v[76:79], v[214:217], v[28:31]
	v_mfma_f32_16x16x32_bf16 v[24:27], v[76:79], v[160:163], v[24:27]
	v_mfma_f32_16x16x32_bf16 v[12:15], v[198:201], v[214:217], v[12:15]
	v_mfma_f32_16x16x32_bf16 v[8:11], v[198:201], v[160:163], v[8:11]
	v_mfma_f32_16x16x32_bf16 v[132:135], v[84:87], v[214:217], v[20:23]
	v_mfma_f32_16x16x32_bf16 v[136:139], v[84:87], v[160:163], v[16:19]
	s_barrier
	v_mfma_f32_16x16x32_bf16 v[140:143], v[206:209], v[214:217], v[4:7]
	v_mfma_f32_16x16x32_bf16 v[160:163], v[206:209], v[160:163], v[0:3]
	s_nop 0
	ds_read_b128 v[0:3], v158
	ds_read_b128 v[4:7], v158 offset:1024
	ds_read_b128 v[16:19], v158 offset:2048
	ds_read_b128 v[172:175], v158 offset:3072
	ds_read_b128 v[20:23], v154 offset:32768
	ds_read_b128 v[194:197], v154 offset:33792
	ds_read_b128 v[198:201], v153 offset:32768
	ds_read_b128 v[202:205], v153 offset:33792
	ds_read_b128 v[206:209], v151 offset:32768
	ds_read_b128 v[210:213], v151 offset:33792
	ds_read_b128 v[214:217], v150 offset:32768
	ds_read_b128 v[218:221], v150 offset:33792
	s_waitcnt vmcnt(2)
	s_barrier
; #define LDA(dst, b, h) for (int m = 0; m < 4; ++m) for (int k = 0; k < 2; ++k) \
;     dst[m][k] = *reinterpret_cast<const bf16x8*>((char*)SA(b, h) + lds_byte(wr * 64 + m * 16 + fr, k * 32 + fq * 8))
; #define LDB(dst, b, h) for (int n = 0; n < 2; ++n) for (int k = 0; k < 2; ++k) \
;     dst[n][k] = *reinterpret_cast<const bf16x8*>((char*)SB(b, h) + lds_byte(wc * 32 + n * 16 + fr, k * 32 + fq * 8))
; #define MMA(ai, bj, At_, Bt_) do { __builtin_amdgcn_s_setprio(1); \
;     for (int k = 0; k < 2; ++k) for (int m = 0; m < 4; ++m) for (int n = 0; n < 2; ++n) \
;       acc[ai][bj][m][n] = __builtin_amdgcn_mfma_f32_16x16x32_bf16(At_[m][k], Bt_[n][k], acc[ai][bj][m][n], 0, 0, 0); \
;     __builtin_amdgcn_s_setprio(0); } while (0)
; #define WAIT_V(n) asm volatile("s_waitcnt vmcnt(" #n ")" ::: "memory")
; #define WAIT_L(n) asm volatile("s_waitcnt lgkmcnt(" #n ")" ::: "memory")
; #define BAR __builtin_amdgcn_s_barrier()
; template <int EPI, int lda, int ldb, int N, int K>
; __device__ __forceinline__ void gemm_phase(const u16* __restrict__ A, const u16* __restrict__ Bt, const GemmEpi ep, int wv) {
;     ...
;     { LDB(B0, 1, 0); LDA(At, 1, 0); WAIT_V(2); BAR; WAIT_L(0); MMA(0, 0, At, B0); BAR;
;       LDB(B1, 1, 1); WAIT_V(0); BAR; WAIT_L(0); MMA(0, 1, At, B1); BAR;
;       LDA(At, 1, 1); BAR; WAIT_L(0); MMA(1, 0, At, B0); MMA(1, 1, At, B1); BAR; }
;     if (wr == 0) BAR;
	s_waitcnt lgkmcnt(0)
	v_mfma_f32_16x16x32_bf16 v[64:67], v[20:23], v[0:3], v[124:127]
	v_mfma_f32_16x16x32_bf16 v[76:79], v[20:23], v[16:19], v[120:123]
	v_mfma_f32_16x16x32_bf16 v[80:83], v[198:201], v[0:3], v[116:119]
	v_mfma_f32_16x16x32_bf16 v[84:87], v[198:201], v[16:19], v[112:115]
	v_mfma_f32_16x16x32_bf16 v[108:111], v[206:209], v[0:3], v[108:111]
	v_mfma_f32_16x16x32_bf16 v[104:107], v[206:209], v[16:19], v[104:107]
	v_mfma_f32_16x16x32_bf16 v[120:123], v[214:217], v[0:3], v[100:103]
	v_mfma_f32_16x16x32_bf16 v[124:127], v[214:217], v[16:19], v[96:99]
	v_mfma_f32_16x16x32_bf16 v[116:119], v[194:197], v[4:7], v[64:67]
	v_mfma_f32_16x16x32_bf16 v[112:115], v[194:197], v[172:175], v[76:79]
	v_mfma_f32_16x16x32_bf16 v[100:103], v[202:205], v[4:7], v[80:83]
	v_mfma_f32_16x16x32_bf16 v[96:99], v[202:205], v[172:175], v[84:87]
	v_mfma_f32_16x16x32_bf16 v[84:87], v[210:213], v[4:7], v[108:111]
	v_mfma_f32_16x16x32_bf16 v[80:83], v[210:213], v[172:175], v[104:107]
	s_barrier
	v_mfma_f32_16x16x32_bf16 v[76:79], v[218:221], v[4:7], v[120:123]
	v_mfma_f32_16x16x32_bf16 v[64:67], v[218:221], v[172:175], v[124:127]
	ds_read_b128 v[222:225], v156
	ds_read_b128 v[226:229], v156 offset:1024
	ds_read_b128 v[230:233], v156 offset:2048
	ds_read_b128 v[156:159], v156 offset:3072
	s_waitcnt vmcnt(0)
	s_barrier
	s_waitcnt lgkmcnt(0)
	v_mfma_f32_16x16x32_bf16 v[92:95], v[20:23], v[222:225], v[92:95]
	v_mfma_f32_16x16x32_bf16 v[20:23], v[20:23], v[230:233], v[88:91]
	v_mfma_f32_16x16x32_bf16 v[88:91], v[198:201], v[222:225], v[178:181]
	v_mfma_f32_16x16x32_bf16 v[104:107], v[198:201], v[230:233], v[182:185]
	v_mfma_f32_16x16x32_bf16 v[176:179], v[206:209], v[222:225], v[186:189]
	v_mfma_f32_16x16x32_bf16 v[72:75], v[206:209], v[230:233], v[72:75]
	v_mfma_f32_16x16x32_bf16 v[68:71], v[214:217], v[222:225], v[68:71]
	v_mfma_f32_16x16x32_bf16 v[180:183], v[214:217], v[230:233], v[190:193]
	v_mfma_f32_16x16x32_bf16 v[124:127], v[194:197], v[226:229], v[92:95]
	v_mfma_f32_16x16x32_bf16 v[120:123], v[194:197], v[156:159], v[20:23]
	v_mfma_f32_16x16x32_bf16 v[108:111], v[202:205], v[226:229], v[88:91]
	v_mfma_f32_16x16x32_bf16 v[104:107], v[202:205], v[156:159], v[104:107]
	v_mfma_f32_16x16x32_bf16 v[92:95], v[210:213], v[226:229], v[176:179]
	v_mfma_f32_16x16x32_bf16 v[88:91], v[210:213], v[156:159], v[72:75]
	s_barrier
	v_mfma_f32_16x16x32_bf16 v[72:75], v[218:221], v[226:229], v[68:71]
	v_mfma_f32_16x16x32_bf16 v[68:71], v[218:221], v[156:159], v[180:183]
	ds_read_b128 v[176:179], v154 offset:49152
	ds_read_b128 v[180:183], v154 offset:50176
	ds_read_b128 v[184:187], v153 offset:49152
	ds_read_b128 v[188:191], v153 offset:50176
	ds_read_b128 v[192:195], v151 offset:49152
	ds_read_b128 v[196:199], v151 offset:50176
	ds_read_b128 v[200:203], v150 offset:49152
	ds_read_b128 v[204:207], v150 offset:50176
	s_barrier
	s_waitcnt lgkmcnt(0)
	v_mfma_f32_16x16x32_bf16 v[20:23], v[176:179], v[0:3], v[60:63]
	v_mfma_f32_16x16x32_bf16 v[56:59], v[176:179], v[16:19], v[56:59]
	v_mfma_f32_16x16x32_bf16 v[60:63], v[184:187], v[0:3], v[52:55]
	v_mfma_f32_16x16x32_bf16 v[208:211], v[184:187], v[16:19], v[48:51]
	v_mfma_f32_16x16x32_bf16 v[44:47], v[192:195], v[0:3], v[44:47]
	v_mfma_f32_16x16x32_bf16 v[40:43], v[192:195], v[16:19], v[40:43]
	v_mfma_f32_16x16x32_bf16 v[0:3], v[200:203], v[0:3], v[36:39]
	v_mfma_f32_16x16x32_bf16 v[212:215], v[200:203], v[16:19], v[32:35]
	v_mfma_f32_16x16x32_bf16 v[52:55], v[180:183], v[4:7], v[20:23]
	v_mfma_f32_16x16x32_bf16 v[48:51], v[180:183], v[172:175], v[56:59]
	v_mfma_f32_16x16x32_bf16 v[36:39], v[188:191], v[4:7], v[60:63]
	v_mfma_f32_16x16x32_bf16 v[32:35], v[188:191], v[172:175], v[208:211]
	v_mfma_f32_16x16x32_bf16 v[20:23], v[196:199], v[4:7], v[44:47]
	v_mfma_f32_16x16x32_bf16 v[16:19], v[196:199], v[172:175], v[40:43]
	v_mfma_f32_16x16x32_bf16 v[4:7], v[204:207], v[4:7], v[0:3]
	v_mfma_f32_16x16x32_bf16 v[0:3], v[204:207], v[172:175], v[212:215]
	v_mfma_f32_16x16x32_bf16 v[28:31], v[176:179], v[222:225], v[28:31]
	v_mfma_f32_16x16x32_bf16 v[24:27], v[176:179], v[230:233], v[24:27]
	v_mfma_f32_16x16x32_bf16 v[40:43], v[184:187], v[222:225], v[132:135]
	v_mfma_f32_16x16x32_bf16 v[132:135], v[184:187], v[230:233], v[136:139]
	v_mfma_f32_16x16x32_bf16 v[12:15], v[192:195], v[222:225], v[12:15]
	v_mfma_f32_16x16x32_bf16 v[8:11], v[192:195], v[230:233], v[8:11]
	v_mfma_f32_16x16x32_bf16 v[136:139], v[200:203], v[222:225], v[140:143]
	v_mfma_f32_16x16x32_bf16 v[140:143], v[200:203], v[230:233], v[160:163]
	v_mfma_f32_16x16x32_bf16 v[60:63], v[180:183], v[226:229], v[28:31]
	v_mfma_f32_16x16x32_bf16 v[56:59], v[180:183], v[156:159], v[24:27]
	v_mfma_f32_16x16x32_bf16 v[44:47], v[188:191], v[226:229], v[40:43]
	v_mfma_f32_16x16x32_bf16 v[40:43], v[188:191], v[156:159], v[132:135]
	v_mfma_f32_16x16x32_bf16 v[28:31], v[196:199], v[226:229], v[12:15]
	v_mfma_f32_16x16x32_bf16 v[24:27], v[196:199], v[156:159], v[8:11]
	s_barrier
	v_mfma_f32_16x16x32_bf16 v[12:15], v[204:207], v[226:229], v[136:139]
	v_mfma_f32_16x16x32_bf16 v[8:11], v[204:207], v[156:159], v[140:143]
	v_cmp_gt_u32_e32 vcc, s46, v147
	s_and_saveexec_b64 s[28:29], vcc
	s_cbranch_execz .LBB0_1627
	s_barrier
